# all 16 GEMM K loops: loop-edge SALU block (pointer bumps, counter, exit compare) moved in front of the loop-back barrier, on top of the stacked file
# baseline (speedup 1.0000x reference)
; #define PG8_STAGE(bufoff, gbase, voff) do { _Pragma("unroll") for (int _i = 0; _i < 2; ++_i) \
;         __builtin_amdgcn_global_load_lds((const unsigned*)((const char*)(gbase) + (voff)[_i]), (PG8_LAS unsigned*)(lds + (bufoff) + ldsw + _i * 8192), 16, 0, 0); } while (0)
; #define PG8_LDA(dst, b, h) do { _Pragma("unroll") for (int m = 0; m < 4; ++m) _Pragma("unroll") for (int k = 0; k < 2; ++k) dst[m][k] = *(const PG8_LAS bf16x8*)(lds + PG8_SA(b, h) + aoff + m * 2048 + k * 1024); } while (0)
; #define PG8_LDB(dst, b, h) do { _Pragma("unroll") for (int n = 0; n < 2; ++n) _Pragma("unroll") for (int k = 0; k < 2; ++k) dst[n][k] = *(const PG8_LAS bf16x8*)(lds + PG8_SB(b, h) + boff + n * 2048 + k * 1024); } while (0)
; #define PG8_MMA(ai, bj, At, Bt) do { __builtin_amdgcn_s_setprio(1); _Pragma("unroll") for (int m = 0; m < 4; ++m) _Pragma("unroll") for (int n = 0; n < 2; ++n) _Pragma("unroll") for (int k = 0; k < 2; ++k) \
;         acc[ai][bj][m][n] = __builtin_amdgcn_mfma_f32_16x16x32_bf16(Bt[n][k], At[m][k], acc[ai][bj][m][n], 0, 0, 0); __builtin_amdgcn_s_setprio(0); } while (0)
; #define PG8_WAIT_V(n) asm volatile("s_waitcnt vmcnt(" #n ")" ::: "memory")
; #define PG8_WAIT_L(n) asm volatile("s_waitcnt lgkmcnt(" #n ")" ::: "memory")
; #define PG8_BAR __builtin_amdgcn_s_barrier()
; #define PG8_SCHED __builtin_amdgcn_sched_barrier(0)
; template <class Epi, class Sched, bool ALIGN_EPI = false, bool SP2 = false>
; __device__ __forceinline__ void gemm_phase(PG8_LAS unsigned char* lds, const Gemm g, const Sched& S, const Epi& E) {
;     ...
;         for (int t = 0; t < nt; t += 2) {
;             const bool last = (t == nt - 2);
;             const char* a1 = cA + (size_t)(t + 1) * kstep;
;             const char* a2 = last ? nA : cA + (size_t)(t + 2) * kstep; const char* b2 = last ? nB : cB + (size_t)(t + 2) * kstep;
;             const char* a3 = a2 + kstep; const char* b3 = b2 + kstep;
;             if (last && has_next) S.a_ready(nxt);
;             if constexpr (SP2) {
;             PG8_LDB(B0, 0, 0); PG8_LDB(B1, 0, 1); PG8_SCHED; PG8_LDA(At, 0, 0); PG8_STAGE(PG8_SA(1, 1), a1 + hstep, voffA);
;             PG8_WAIT_V(8); PG8_WAIT_L(0); PG8_BAR; PG8_MMA(0, 0, At, B0); PG8_MMA(0, 1, At, B1); PG8_BAR; PG8_SCHED;
;             PG8_LDA(At, 0, 1); PG8_STAGE(PG8_SB(0, 0), b2, voffB); PG8_STAGE(PG8_SB(0, 1), b2 + hstep, voffB); PG8_STAGE(PG8_SA(0, 0), a2, voffA);
.LBB0_85:
	ds_read_b128 v[146:149], v152
	ds_read_b128 v[156:159], v152 offset:1024
	ds_read_b128 v[160:163], v152 offset:2048
	ds_read_b128 v[164:167], v152 offset:3072
	ds_read_b128 v[168:171], v153
	ds_read_b128 v[172:175], v153 offset:1024
	ds_read_b128 v[176:179], v153 offset:2048
	ds_read_b128 v[180:183], v153 offset:3072
	s_add_u32 s22, s20, 0xfffc0080
	s_addc_u32 s23, s21, -1
	s_cmp_eq_u32 s50, 12
	s_cselect_b32 s25, s13, s23
	s_cselect_b32 s24, s42, s22
	s_cselect_b32 s23, s11, s49
	s_cselect_b32 s22, s43, s48
	v_lshl_add_u64 v[184:185], s[20:21], 0, v[138:139]
	s_add_i32 m0, s19, 0xc000
	ds_read_b128 v[188:191], v154
	ds_read_b128 v[192:195], v154 offset:1024
	ds_read_b128 v[196:199], v154 offset:2048
	ds_read_b128 v[200:203], v154 offset:3072
	ds_read_b128 v[204:207], v154 offset:4096
	ds_read_b128 v[208:211], v154 offset:5120
	ds_read_b128 v[212:215], v154 offset:6144
	ds_read_b128 v[216:219], v154 offset:7168
	global_load_lds_dwordx4 v[184:185], off
	v_lshl_add_u64 v[184:185], s[20:21], 0, v[140:141]
	s_add_i32 m0, s19, 0xe000
	s_nop 0
	global_load_lds_dwordx4 v[184:185], off
	s_waitcnt vmcnt(8)
	s_waitcnt lgkmcnt(0)
	s_barrier
	s_setprio 1
	s_waitcnt lgkmcnt(0)
	v_mfma_f32_16x16x32_bf16 v[126:129], v[146:149], v[188:191], v[126:129]
	v_mfma_f32_16x16x32_bf16 v[122:125], v[160:163], v[188:191], v[122:125]
	v_mfma_f32_16x16x32_bf16 v[110:113], v[146:149], v[196:199], v[110:113]
	v_mfma_f32_16x16x32_bf16 v[106:109], v[160:163], v[196:199], v[106:109]
	v_mfma_f32_16x16x32_bf16 v[94:97], v[146:149], v[204:207], v[94:97]
	v_mfma_f32_16x16x32_bf16 v[90:93], v[160:163], v[204:207], v[90:93]
	v_mfma_f32_16x16x32_bf16 v[78:81], v[146:149], v[212:215], v[78:81]
	v_mfma_f32_16x16x32_bf16 v[74:77], v[160:163], v[212:215], v[74:77]
	v_mfma_f32_16x16x32_bf16 v[126:129], v[156:159], v[192:195], v[126:129]
	v_mfma_f32_16x16x32_bf16 v[122:125], v[164:167], v[192:195], v[122:125]
	v_mfma_f32_16x16x32_bf16 v[110:113], v[156:159], v[200:203], v[110:113]
	v_mfma_f32_16x16x32_bf16 v[106:109], v[164:167], v[200:203], v[106:109]
	v_mfma_f32_16x16x32_bf16 v[94:97], v[156:159], v[208:211], v[94:97]
	v_mfma_f32_16x16x32_bf16 v[90:93], v[164:167], v[208:211], v[90:93]
	v_mfma_f32_16x16x32_bf16 v[78:81], v[156:159], v[216:219], v[78:81]
	v_mfma_f32_16x16x32_bf16 v[74:77], v[164:167], v[216:219], v[74:77]
	s_setprio 0
	s_setprio 1
	v_mfma_f32_16x16x32_bf16 v[118:121], v[168:171], v[188:191], v[118:121]
	v_mfma_f32_16x16x32_bf16 v[114:117], v[176:179], v[188:191], v[114:117]
	v_mfma_f32_16x16x32_bf16 v[102:105], v[168:171], v[196:199], v[102:105]
	v_mfma_f32_16x16x32_bf16 v[98:101], v[176:179], v[196:199], v[98:101]
	v_mfma_f32_16x16x32_bf16 v[86:89], v[168:171], v[204:207], v[86:89]
	v_mfma_f32_16x16x32_bf16 v[82:85], v[176:179], v[204:207], v[82:85]
	v_mfma_f32_16x16x32_bf16 v[70:73], v[168:171], v[212:215], v[70:73]
	v_mfma_f32_16x16x32_bf16 v[66:69], v[176:179], v[212:215], v[66:69]
	v_mfma_f32_16x16x32_bf16 v[118:121], v[172:175], v[192:195], v[118:121]
	v_mfma_f32_16x16x32_bf16 v[114:117], v[180:183], v[192:195], v[114:117]
	v_mfma_f32_16x16x32_bf16 v[102:105], v[172:175], v[200:203], v[102:105]
	v_mfma_f32_16x16x32_bf16 v[98:101], v[180:183], v[200:203], v[98:101]
	v_mfma_f32_16x16x32_bf16 v[86:89], v[172:175], v[208:211], v[86:89]
	v_mfma_f32_16x16x32_bf16 v[82:85], v[180:183], v[208:211], v[82:85]
	v_mfma_f32_16x16x32_bf16 v[70:73], v[172:175], v[216:219], v[70:73]
	v_mfma_f32_16x16x32_bf16 v[66:69], v[180:183], v[216:219], v[66:69]
	s_setprio 0
	s_barrier
	s_add_i32 s51, s38, s26
	v_lshl_add_u64 v[184:185], s[22:23], 0, v[134:135]
	s_mov_b32 m0, s51
	ds_read_b128 v[188:191], v154 offset:16384
	ds_read_b128 v[192:195], v154 offset:17408
	ds_read_b128 v[196:199], v154 offset:18432
	ds_read_b128 v[200:203], v154 offset:19456
	ds_read_b128 v[204:207], v154 offset:20480
	ds_read_b128 v[208:211], v154 offset:21504
	ds_read_b128 v[212:215], v154 offset:22528
	ds_read_b128 v[216:219], v154 offset:23552
	global_load_lds_dwordx4 v[184:185], off
	s_add_i32 m0, s51, 0x2000
	s_add_u32 s52, s22, 0x40000
	v_lshl_add_u64 v[220:221], s[22:23], 0, v[130:131]
	s_addc_u32 s53, s23, 0
	s_add_i32 s51, s39, s26
	global_load_lds_dwordx4 v[220:221], off
	v_lshl_add_u64 v[222:223], s[52:53], 0, v[134:135]
	s_mov_b32 m0, s51
	v_lshl_add_u64 v[224:225], s[24:25], 0, v[132:133]
	global_load_lds_dwordx4 v[222:223], off
	v_lshl_add_u64 v[222:223], s[52:53], 0, v[130:131]
	s_add_i32 m0, s51, 0x2000
	s_nop 0
	global_load_lds_dwordx4 v[222:223], off
	v_lshl_add_u64 v[222:223], s[24:25], 0, v[136:137]
	s_mov_b32 m0, s19
	s_nop 0
	global_load_lds_dwordx4 v[222:223], off
	s_mov_b32 m0, s29
	s_nop 0
	global_load_lds_dwordx4 v[224:225], off
	s_waitcnt vmcnt(8)
	s_waitcnt lgkmcnt(0)
	s_barrier
; #define PG8_STAGE(bufoff, gbase, voff) do { _Pragma("unroll") for (int _i = 0; _i < 2; ++_i) \
;         __builtin_amdgcn_global_load_lds((const unsigned*)((const char*)(gbase) + (voff)[_i]), (PG8_LAS unsigned*)(lds + (bufoff) + ldsw + _i * 8192), 16, 0, 0); } while (0)
; #define PG8_LDA(dst, b, h) do { _Pragma("unroll") for (int m = 0; m < 4; ++m) _Pragma("unroll") for (int k = 0; k < 2; ++k) dst[m][k] = *(const PG8_LAS bf16x8*)(lds + PG8_SA(b, h) + aoff + m * 2048 + k * 1024); } while (0)
; #define PG8_LDB(dst, b, h) do { _Pragma("unroll") for (int n = 0; n < 2; ++n) _Pragma("unroll") for (int k = 0; k < 2; ++k) dst[n][k] = *(const PG8_LAS bf16x8*)(lds + PG8_SB(b, h) + boff + n * 2048 + k * 1024); } while (0)
; #define PG8_MMA(ai, bj, At, Bt) do { __builtin_amdgcn_s_setprio(1); _Pragma("unroll") for (int m = 0; m < 4; ++m) _Pragma("unroll") for (int n = 0; n < 2; ++n) _Pragma("unroll") for (int k = 0; k < 2; ++k) \
;         acc[ai][bj][m][n] = __builtin_amdgcn_mfma_f32_16x16x32_bf16(Bt[n][k], At[m][k], acc[ai][bj][m][n], 0, 0, 0); __builtin_amdgcn_s_setprio(0); } while (0)
; #define PG8_WAIT_V(n) asm volatile("s_waitcnt vmcnt(" #n ")" ::: "memory")
; #define PG8_WAIT_L(n) asm volatile("s_waitcnt lgkmcnt(" #n ")" ::: "memory")
; #define PG8_BAR __builtin_amdgcn_s_barrier()
; #define PG8_SCHED __builtin_amdgcn_sched_barrier(0)
; template <class Epi, class Sched, bool ALIGN_EPI = false, bool SP2 = false>
; __device__ __forceinline__ void gemm_phase(PG8_LAS unsigned char* lds, const Gemm g, const Sched& S, const Epi& E) {
;     ...
;             PG8_WAIT_V(8); PG8_WAIT_L(0); PG8_BAR; PG8_MMA(1, 0, At, B0); PG8_MMA(1, 1, At, B1); PG8_BAR; PG8_SCHED;
;             PG8_LDB(B0, 1, 0); PG8_LDB(B1, 1, 1); PG8_SCHED; PG8_LDA(At, 1, 0); PG8_STAGE(PG8_SA(0, 1), a2 + hstep, voffA);
;             PG8_WAIT_V(8); PG8_WAIT_L(0); PG8_BAR; PG8_MMA(0, 0, At, B0); PG8_MMA(0, 1, At, B1); PG8_BAR; PG8_SCHED;
	s_setprio 1
	s_waitcnt lgkmcnt(0)
	v_mfma_f32_16x16x32_bf16 v[62:65], v[146:149], v[188:191], v[62:65]
	v_mfma_f32_16x16x32_bf16 v[58:61], v[160:163], v[188:191], v[58:61]
	v_mfma_f32_16x16x32_bf16 v[46:49], v[146:149], v[196:199], v[46:49]
	v_mfma_f32_16x16x32_bf16 v[42:45], v[160:163], v[196:199], v[42:45]
	v_mfma_f32_16x16x32_bf16 v[30:33], v[146:149], v[204:207], v[30:33]
	v_mfma_f32_16x16x32_bf16 v[26:29], v[160:163], v[204:207], v[26:29]
	v_mfma_f32_16x16x32_bf16 v[14:17], v[146:149], v[212:215], v[14:17]
	v_mfma_f32_16x16x32_bf16 v[10:13], v[160:163], v[212:215], v[10:13]
	v_mfma_f32_16x16x32_bf16 v[62:65], v[156:159], v[192:195], v[62:65]
	v_mfma_f32_16x16x32_bf16 v[58:61], v[164:167], v[192:195], v[58:61]
	v_mfma_f32_16x16x32_bf16 v[46:49], v[156:159], v[200:203], v[46:49]
	v_mfma_f32_16x16x32_bf16 v[42:45], v[164:167], v[200:203], v[42:45]
	v_mfma_f32_16x16x32_bf16 v[30:33], v[156:159], v[208:211], v[30:33]
	v_mfma_f32_16x16x32_bf16 v[26:29], v[164:167], v[208:211], v[26:29]
	v_mfma_f32_16x16x32_bf16 v[14:17], v[156:159], v[216:219], v[14:17]
	v_mfma_f32_16x16x32_bf16 v[10:13], v[164:167], v[216:219], v[10:13]
	s_setprio 0
	s_setprio 1
	v_mfma_f32_16x16x32_bf16 v[54:57], v[168:171], v[188:191], v[54:57]
	v_mfma_f32_16x16x32_bf16 v[50:53], v[176:179], v[188:191], v[50:53]
	v_mfma_f32_16x16x32_bf16 v[38:41], v[168:171], v[196:199], v[38:41]
	v_mfma_f32_16x16x32_bf16 v[34:37], v[176:179], v[196:199], v[34:37]
	v_mfma_f32_16x16x32_bf16 v[22:25], v[168:171], v[204:207], v[22:25]
	v_mfma_f32_16x16x32_bf16 v[18:21], v[176:179], v[204:207], v[18:21]
	v_mfma_f32_16x16x32_bf16 v[6:9], v[168:171], v[212:215], v[6:9]
	v_mfma_f32_16x16x32_bf16 v[2:5], v[176:179], v[212:215], v[2:5]
	v_mfma_f32_16x16x32_bf16 v[54:57], v[172:175], v[192:195], v[54:57]
	v_mfma_f32_16x16x32_bf16 v[50:53], v[180:183], v[192:195], v[50:53]
	v_mfma_f32_16x16x32_bf16 v[38:41], v[172:175], v[200:203], v[38:41]
	v_mfma_f32_16x16x32_bf16 v[34:37], v[180:183], v[200:203], v[34:37]
	v_mfma_f32_16x16x32_bf16 v[22:25], v[172:175], v[208:211], v[22:25]
	v_mfma_f32_16x16x32_bf16 v[18:21], v[180:183], v[208:211], v[18:21]
	v_mfma_f32_16x16x32_bf16 v[6:9], v[172:175], v[216:219], v[6:9]
	v_mfma_f32_16x16x32_bf16 v[2:5], v[180:183], v[216:219], v[2:5]
	s_setprio 0
	s_barrier
	s_add_i32 s51, 0, 0x18000
	v_add_u32_e32 v155, s51, v150
	s_add_i32 s52, 0, 0x1c000
	ds_read_b128 v[146:149], v155
	ds_read_b128 v[156:159], v155 offset:1024
	ds_read_b128 v[160:163], v155 offset:2048
	ds_read_b128 v[164:167], v155 offset:3072
	v_add_u32_e32 v155, s52, v150
	ds_read_b128 v[168:171], v155
	ds_read_b128 v[172:175], v155 offset:1024
	ds_read_b128 v[176:179], v155 offset:2048
	ds_read_b128 v[180:183], v155 offset:3072
	s_add_u32 s24, s24, 0x40000
	s_addc_u32 s25, s25, 0
	s_mov_b32 m0, s30
	v_lshl_add_u64 v[226:227], s[24:25], 0, v[136:137]
	ds_read_b128 v[188:191], v154 offset:32768
	ds_read_b128 v[192:195], v154 offset:33792
	ds_read_b128 v[196:199], v154 offset:34816
	ds_read_b128 v[200:203], v154 offset:35840
	ds_read_b128 v[204:207], v154 offset:36864
	ds_read_b128 v[208:211], v154 offset:37888
	ds_read_b128 v[212:215], v154 offset:38912
	ds_read_b128 v[216:219], v154 offset:39936
	global_load_lds_dwordx4 v[226:227], off
	v_lshl_add_u64 v[226:227], s[24:25], 0, v[132:133]
	s_mov_b32 m0, s31
	s_nop 0
	global_load_lds_dwordx4 v[226:227], off
	s_waitcnt vmcnt(8)
	s_waitcnt lgkmcnt(0)
	s_barrier
	s_setprio 1
	s_waitcnt lgkmcnt(0)
	v_mfma_f32_16x16x32_bf16 v[126:129], v[146:149], v[188:191], v[126:129]
	v_mfma_f32_16x16x32_bf16 v[122:125], v[160:163], v[188:191], v[122:125]
	v_mfma_f32_16x16x32_bf16 v[110:113], v[146:149], v[196:199], v[110:113]
	v_mfma_f32_16x16x32_bf16 v[106:109], v[160:163], v[196:199], v[106:109]
	v_mfma_f32_16x16x32_bf16 v[94:97], v[146:149], v[204:207], v[94:97]
	v_mfma_f32_16x16x32_bf16 v[90:93], v[160:163], v[204:207], v[90:93]
	v_mfma_f32_16x16x32_bf16 v[78:81], v[146:149], v[212:215], v[78:81]
	v_mfma_f32_16x16x32_bf16 v[74:77], v[160:163], v[212:215], v[74:77]
	v_mfma_f32_16x16x32_bf16 v[126:129], v[156:159], v[192:195], v[126:129]
	v_mfma_f32_16x16x32_bf16 v[122:125], v[164:167], v[192:195], v[122:125]
	v_mfma_f32_16x16x32_bf16 v[110:113], v[156:159], v[200:203], v[110:113]
	v_mfma_f32_16x16x32_bf16 v[106:109], v[164:167], v[200:203], v[106:109]
	v_mfma_f32_16x16x32_bf16 v[94:97], v[156:159], v[208:211], v[94:97]
	v_mfma_f32_16x16x32_bf16 v[90:93], v[164:167], v[208:211], v[90:93]
	v_mfma_f32_16x16x32_bf16 v[78:81], v[156:159], v[216:219], v[78:81]
	v_mfma_f32_16x16x32_bf16 v[74:77], v[164:167], v[216:219], v[74:77]
	s_setprio 0
	s_setprio 1
	v_mfma_f32_16x16x32_bf16 v[118:121], v[168:171], v[188:191], v[118:121]
	v_mfma_f32_16x16x32_bf16 v[114:117], v[176:179], v[188:191], v[114:117]
	v_mfma_f32_16x16x32_bf16 v[102:105], v[168:171], v[196:199], v[102:105]
	v_mfma_f32_16x16x32_bf16 v[98:101], v[176:179], v[196:199], v[98:101]
	v_mfma_f32_16x16x32_bf16 v[86:89], v[168:171], v[204:207], v[86:89]
	v_mfma_f32_16x16x32_bf16 v[82:85], v[176:179], v[204:207], v[82:85]
	v_mfma_f32_16x16x32_bf16 v[70:73], v[168:171], v[212:215], v[70:73]
	v_mfma_f32_16x16x32_bf16 v[66:69], v[176:179], v[212:215], v[66:69]
	v_mfma_f32_16x16x32_bf16 v[118:121], v[172:175], v[192:195], v[118:121]
	v_mfma_f32_16x16x32_bf16 v[114:117], v[180:183], v[192:195], v[114:117]
	v_mfma_f32_16x16x32_bf16 v[102:105], v[172:175], v[200:203], v[102:105]
	v_mfma_f32_16x16x32_bf16 v[98:101], v[180:183], v[200:203], v[98:101]
	v_mfma_f32_16x16x32_bf16 v[86:89], v[172:175], v[208:211], v[86:89]
	v_mfma_f32_16x16x32_bf16 v[82:85], v[180:183], v[208:211], v[82:85]
	v_mfma_f32_16x16x32_bf16 v[70:73], v[172:175], v[216:219], v[70:73]
	v_mfma_f32_16x16x32_bf16 v[66:69], v[180:183], v[216:219], v[66:69]
	s_setprio 0
	s_barrier
; #define PG8_STAGE(bufoff, gbase, voff) do { _Pragma("unroll") for (int _i = 0; _i < 2; ++_i) \
;         __builtin_amdgcn_global_load_lds((const unsigned*)((const char*)(gbase) + (voff)[_i]), (PG8_LAS unsigned*)(lds + (bufoff) + ldsw + _i * 8192), 16, 0, 0); } while (0)
; #define PG8_LDA(dst, b, h) do { _Pragma("unroll") for (int m = 0; m < 4; ++m) _Pragma("unroll") for (int k = 0; k < 2; ++k) dst[m][k] = *(const PG8_LAS bf16x8*)(lds + PG8_SA(b, h) + aoff + m * 2048 + k * 1024); } while (0)
; #define PG8_MMA(ai, bj, At, Bt) do { __builtin_amdgcn_s_setprio(1); _Pragma("unroll") for (int m = 0; m < 4; ++m) _Pragma("unroll") for (int n = 0; n < 2; ++n) _Pragma("unroll") for (int k = 0; k < 2; ++k) \
;         acc[ai][bj][m][n] = __builtin_amdgcn_mfma_f32_16x16x32_bf16(Bt[n][k], At[m][k], acc[ai][bj][m][n], 0, 0, 0); __builtin_amdgcn_s_setprio(0); } while (0)
; #define PG8_WAIT_V(n) asm volatile("s_waitcnt vmcnt(" #n ")" ::: "memory")
; #define PG8_WAIT_L(n) asm volatile("s_waitcnt lgkmcnt(" #n ")" ::: "memory")
; #define PG8_BAR __builtin_amdgcn_s_barrier()
; #define PG8_SCHED __builtin_amdgcn_sched_barrier(0)
; template <class Epi, class Sched, bool ALIGN_EPI = false, bool SP2 = false>
; __device__ __forceinline__ void gemm_phase(PG8_LAS unsigned char* lds, const Gemm g, const Sched& S, const Epi& E) {
;     ...
;         for (int t = 0; t < nt; t += 2) {
;             const bool last = (t == nt - 2);
;             const char* a1 = cA + (size_t)(t + 1) * kstep;
;             const char* a2 = last ? nA : cA + (size_t)(t + 2) * kstep; const char* b2 = last ? nB : cB + (size_t)(t + 2) * kstep;
;             const char* a3 = a2 + kstep; const char* b3 = b2 + kstep;
;     ...
;             PG8_LDA(At, 1, 1); PG8_STAGE(PG8_SB(1, 0), b3, voffB); PG8_STAGE(PG8_SB(1, 1), b3 + hstep, voffB); PG8_STAGE(PG8_SA(1, 0), a3, voffA);
;             PG8_WAIT_V(8); PG8_WAIT_L(0); PG8_BAR; PG8_MMA(1, 0, At, B0); PG8_MMA(1, 1, At, B1); PG8_BAR; PG8_SCHED;
	s_add_i32 s24, s51, s26
	v_lshl_add_u64 v[184:185], v[184:185], 0, s[6:7]
	s_mov_b32 m0, s24
	ds_read_b128 v[188:191], v154 offset:49152
	ds_read_b128 v[192:195], v154 offset:50176
	ds_read_b128 v[196:199], v154 offset:51200
	ds_read_b128 v[200:203], v154 offset:52224
	ds_read_b128 v[204:207], v154 offset:53248
	ds_read_b128 v[208:211], v154 offset:54272
	ds_read_b128 v[212:215], v154 offset:55296
	ds_read_b128 v[216:219], v154 offset:56320
	global_load_lds_dwordx4 v[184:185], off
	s_add_i32 m0, s24, 0x2000
	s_add_u32 s22, s22, 0x40080
	v_lshl_add_u64 v[184:185], v[220:221], 0, s[6:7]
	s_addc_u32 s23, s23, 0
	s_add_i32 s24, s52, s26
	global_load_lds_dwordx4 v[184:185], off
	v_lshl_add_u64 v[184:185], s[22:23], 0, v[134:135]
	s_mov_b32 m0, s24
	s_nop 0
	global_load_lds_dwordx4 v[184:185], off
	v_lshl_add_u64 v[184:185], s[22:23], 0, v[130:131]
	s_add_i32 m0, s24, 0x2000
	s_nop 0
	global_load_lds_dwordx4 v[184:185], off
	v_lshl_add_u64 v[184:185], v[222:223], 0, s[6:7]
	s_mov_b32 m0, s35
	s_nop 0
	global_load_lds_dwordx4 v[184:185], off
	v_lshl_add_u64 v[184:185], v[224:225], 0, s[6:7]
	s_mov_b32 m0, s36
	s_nop 0
	global_load_lds_dwordx4 v[184:185], off
	s_waitcnt vmcnt(8)
	s_waitcnt lgkmcnt(0)
	s_barrier
	s_setprio 1
	s_waitcnt lgkmcnt(0)
	v_mfma_f32_16x16x32_bf16 v[62:65], v[146:149], v[188:191], v[62:65]
	v_mfma_f32_16x16x32_bf16 v[58:61], v[160:163], v[188:191], v[58:61]
	v_mfma_f32_16x16x32_bf16 v[46:49], v[146:149], v[196:199], v[46:49]
	v_mfma_f32_16x16x32_bf16 v[42:45], v[160:163], v[196:199], v[42:45]
	v_mfma_f32_16x16x32_bf16 v[30:33], v[146:149], v[204:207], v[30:33]
	v_mfma_f32_16x16x32_bf16 v[26:29], v[160:163], v[204:207], v[26:29]
	v_mfma_f32_16x16x32_bf16 v[14:17], v[146:149], v[212:215], v[14:17]
	v_mfma_f32_16x16x32_bf16 v[10:13], v[160:163], v[212:215], v[10:13]
	v_mfma_f32_16x16x32_bf16 v[62:65], v[156:159], v[192:195], v[62:65]
	v_mfma_f32_16x16x32_bf16 v[58:61], v[164:167], v[192:195], v[58:61]
	v_mfma_f32_16x16x32_bf16 v[46:49], v[156:159], v[200:203], v[46:49]
	v_mfma_f32_16x16x32_bf16 v[42:45], v[164:167], v[200:203], v[42:45]
	v_mfma_f32_16x16x32_bf16 v[30:33], v[156:159], v[208:211], v[30:33]
	v_mfma_f32_16x16x32_bf16 v[26:29], v[164:167], v[208:211], v[26:29]
	v_mfma_f32_16x16x32_bf16 v[14:17], v[156:159], v[216:219], v[14:17]
	v_mfma_f32_16x16x32_bf16 v[10:13], v[164:167], v[216:219], v[10:13]
	s_setprio 0
	s_setprio 1
	v_mfma_f32_16x16x32_bf16 v[54:57], v[168:171], v[188:191], v[54:57]
	v_mfma_f32_16x16x32_bf16 v[50:53], v[176:179], v[188:191], v[50:53]
	v_mfma_f32_16x16x32_bf16 v[38:41], v[168:171], v[196:199], v[38:41]
	v_mfma_f32_16x16x32_bf16 v[34:37], v[176:179], v[196:199], v[34:37]
	v_mfma_f32_16x16x32_bf16 v[22:25], v[168:171], v[204:207], v[22:25]
	v_mfma_f32_16x16x32_bf16 v[18:21], v[176:179], v[204:207], v[18:21]
	v_mfma_f32_16x16x32_bf16 v[6:9], v[168:171], v[212:215], v[6:9]
	v_mfma_f32_16x16x32_bf16 v[2:5], v[176:179], v[212:215], v[2:5]
	v_mfma_f32_16x16x32_bf16 v[54:57], v[172:175], v[192:195], v[54:57]
	v_mfma_f32_16x16x32_bf16 v[50:53], v[180:183], v[192:195], v[50:53]
	v_mfma_f32_16x16x32_bf16 v[38:41], v[172:175], v[200:203], v[38:41]
	v_mfma_f32_16x16x32_bf16 v[34:37], v[180:183], v[200:203], v[34:37]
	v_mfma_f32_16x16x32_bf16 v[22:25], v[172:175], v[208:211], v[22:25]
	v_mfma_f32_16x16x32_bf16 v[18:21], v[180:183], v[208:211], v[18:21]
	v_mfma_f32_16x16x32_bf16 v[6:9], v[172:175], v[216:219], v[6:9]
	v_mfma_f32_16x16x32_bf16 v[2:5], v[180:183], v[216:219], v[2:5]
	s_setprio 0
	s_add_i32 s50, s50, 2
	s_add_u32 s20, s20, 0x100
	s_addc_u32 s21, s21, 0
	s_add_u32 s48, s48, 0x100
	s_addc_u32 s49, s49, 0
	s_cmp_gt_u32 s50, 13
	s_barrier
	s_cbranch_scc0 .LBB0_85
	s_and_b64 vcc, exec, s[8:9]
	s_cbranch_vccz .LBB0_88
	s_barrier

; #define PG8_STAGE(bufoff, gbase, voff) do { _Pragma("unroll") for (int _i = 0; _i < 2; ++_i) \
;         __builtin_amdgcn_global_load_lds((const unsigned*)((const char*)(gbase) + (voff)[_i]), (PG8_LAS unsigned*)(lds + (bufoff) + ldsw + _i * 8192), 16, 0, 0); } while (0)
; #define PG8_LDA(dst, b, h) do { _Pragma("unroll") for (int m = 0; m < 4; ++m) _Pragma("unroll") for (int k = 0; k < 2; ++k) dst[m][k] = *(const PG8_LAS bf16x8*)(lds + PG8_SA(b, h) + aoff + m * 2048 + k * 1024); } while (0)
; #define PG8_LDB(dst, b, h) do { _Pragma("unroll") for (int n = 0; n < 2; ++n) _Pragma("unroll") for (int k = 0; k < 2; ++k) dst[n][k] = *(const PG8_LAS bf16x8*)(lds + PG8_SB(b, h) + boff + n * 2048 + k * 1024); } while (0)
; #define PG8_MMA(ai, bj, At, Bt) do { __builtin_amdgcn_s_setprio(1); _Pragma("unroll") for (int m = 0; m < 4; ++m) _Pragma("unroll") for (int n = 0; n < 2; ++n) _Pragma("unroll") for (int k = 0; k < 2; ++k) \
;         acc[ai][bj][m][n] = __builtin_amdgcn_mfma_f32_16x16x32_bf16(Bt[n][k], At[m][k], acc[ai][bj][m][n], 0, 0, 0); __builtin_amdgcn_s_setprio(0); } while (0)
; #define PG8_WAIT_V(n) asm volatile("s_waitcnt vmcnt(" #n ")" ::: "memory")
; #define PG8_WAIT_L(n) asm volatile("s_waitcnt lgkmcnt(" #n ")" ::: "memory")
; #define PG8_BAR __builtin_amdgcn_s_barrier()
; #define PG8_SCHED __builtin_amdgcn_sched_barrier(0)
; template <class Epi, class Sched, bool ALIGN_EPI = false, bool SP2 = false>
; __device__ __forceinline__ void gemm_phase(PG8_LAS unsigned char* lds, const Gemm g, const Sched& S, const Epi& E) {
;     ...
;         for (int t = 0; t < nt; t += 2) {
;             const bool last = (t == nt - 2);
;             const char* a1 = cA + (size_t)(t + 1) * kstep;
;             const char* a2 = last ? nA : cA + (size_t)(t + 2) * kstep; const char* b2 = last ? nB : cB + (size_t)(t + 2) * kstep;
;             const char* a3 = a2 + kstep; const char* b3 = b2 + kstep;
;             if (last && has_next) S.a_ready(nxt);
;             if constexpr (SP2) {
;             PG8_LDB(B0, 0, 0); PG8_LDB(B1, 0, 1); PG8_SCHED; PG8_LDA(At, 0, 0); PG8_STAGE(PG8_SA(1, 1), a1 + hstep, voffA);
;             PG8_WAIT_V(8); PG8_WAIT_L(0); PG8_BAR; PG8_MMA(0, 0, At, B0); PG8_MMA(0, 1, At, B1); PG8_BAR; PG8_SCHED;
;             PG8_LDA(At, 0, 1); PG8_STAGE(PG8_SB(0, 0), b2, voffB); PG8_STAGE(PG8_SB(0, 1), b2 + hstep, voffB); PG8_STAGE(PG8_SA(0, 0), a2, voffA);
.LBB0_207:
	ds_read_b128 v[144:147], v140
	ds_read_b128 v[148:151], v140 offset:1024
	ds_read_b128 v[152:155], v140 offset:2048
	ds_read_b128 v[156:159], v140 offset:3072
	ds_read_b128 v[160:163], v141
	ds_read_b128 v[164:167], v141 offset:1024
	ds_read_b128 v[168:171], v141 offset:2048
	ds_read_b128 v[172:175], v141 offset:3072
	s_add_i32 s68, s36, 2
	s_add_u32 s34, s30, 0x100
	s_addc_u32 s35, s31, 0
	s_cmp_eq_u32 s53, s36
	s_cselect_b32 s36, s28, s66
	s_cselect_b32 s39, s27, s35
	s_cselect_b32 s38, s26, s34
	s_cselect_b32 s37, s29, s67
	s_mov_b32 m0, s60
	v_lshl_add_u64 v[184:185], s[30:31], 0, v[134:135]
	ds_read_b128 v[176:179], v142
	ds_read_b128 v[180:183], v142 offset:1024
	ds_read_b128 v[188:191], v142 offset:2048
	ds_read_b128 v[192:195], v142 offset:3072
	ds_read_b128 v[196:199], v142 offset:4096
	ds_read_b128 v[200:203], v142 offset:5120
	ds_read_b128 v[204:207], v142 offset:6144
	ds_read_b128 v[208:211], v142 offset:7168
	global_load_lds_dwordx4 v[184:185], off
	v_lshl_add_u64 v[184:185], s[30:31], 0, v[136:137]
	s_add_i32 m0, s41, 0xe000
	s_nop 0
	global_load_lds_dwordx4 v[184:185], off
	s_waitcnt vmcnt(8)
	s_waitcnt lgkmcnt(0)
	s_barrier
	s_setprio 1
	s_waitcnt lgkmcnt(0)
	v_mfma_f32_16x16x32_bf16 v[126:129], v[144:147], v[176:179], v[126:129]
	v_mfma_f32_16x16x32_bf16 v[122:125], v[152:155], v[176:179], v[122:125]
	v_mfma_f32_16x16x32_bf16 v[110:113], v[144:147], v[188:191], v[110:113]
	v_mfma_f32_16x16x32_bf16 v[106:109], v[152:155], v[188:191], v[106:109]
	v_mfma_f32_16x16x32_bf16 v[94:97], v[144:147], v[196:199], v[94:97]
	v_mfma_f32_16x16x32_bf16 v[90:93], v[152:155], v[196:199], v[90:93]
	v_mfma_f32_16x16x32_bf16 v[78:81], v[144:147], v[204:207], v[78:81]
	v_mfma_f32_16x16x32_bf16 v[74:77], v[152:155], v[204:207], v[74:77]
	v_mfma_f32_16x16x32_bf16 v[126:129], v[148:151], v[180:183], v[126:129]
	v_mfma_f32_16x16x32_bf16 v[122:125], v[156:159], v[180:183], v[122:125]
	v_mfma_f32_16x16x32_bf16 v[110:113], v[148:151], v[192:195], v[110:113]
	v_mfma_f32_16x16x32_bf16 v[106:109], v[156:159], v[192:195], v[106:109]
	v_mfma_f32_16x16x32_bf16 v[94:97], v[148:151], v[200:203], v[94:97]
	v_mfma_f32_16x16x32_bf16 v[90:93], v[156:159], v[200:203], v[90:93]
	v_mfma_f32_16x16x32_bf16 v[78:81], v[148:151], v[208:211], v[78:81]
	v_mfma_f32_16x16x32_bf16 v[74:77], v[156:159], v[208:211], v[74:77]
	s_setprio 0
	s_setprio 1
	v_mfma_f32_16x16x32_bf16 v[118:121], v[160:163], v[176:179], v[118:121]
	v_mfma_f32_16x16x32_bf16 v[114:117], v[168:171], v[176:179], v[114:117]
	v_mfma_f32_16x16x32_bf16 v[102:105], v[160:163], v[188:191], v[102:105]
	v_mfma_f32_16x16x32_bf16 v[98:101], v[168:171], v[188:191], v[98:101]
	v_mfma_f32_16x16x32_bf16 v[86:89], v[160:163], v[196:199], v[86:89]
	v_mfma_f32_16x16x32_bf16 v[82:85], v[168:171], v[196:199], v[82:85]
	v_mfma_f32_16x16x32_bf16 v[70:73], v[160:163], v[204:207], v[70:73]
	v_mfma_f32_16x16x32_bf16 v[66:69], v[168:171], v[204:207], v[66:69]
	v_mfma_f32_16x16x32_bf16 v[118:121], v[164:167], v[180:183], v[118:121]
	v_mfma_f32_16x16x32_bf16 v[114:117], v[172:175], v[180:183], v[114:117]
	v_mfma_f32_16x16x32_bf16 v[102:105], v[164:167], v[192:195], v[102:105]
	v_mfma_f32_16x16x32_bf16 v[98:101], v[172:175], v[192:195], v[98:101]
	v_mfma_f32_16x16x32_bf16 v[86:89], v[164:167], v[200:203], v[86:89]
	v_mfma_f32_16x16x32_bf16 v[82:85], v[172:175], v[200:203], v[82:85]
	v_mfma_f32_16x16x32_bf16 v[70:73], v[164:167], v[208:211], v[70:73]
	v_mfma_f32_16x16x32_bf16 v[66:69], v[172:175], v[208:211], v[66:69]
	s_setprio 0
	s_barrier
	s_add_i32 s30, s54, s40
	v_lshl_add_u64 v[184:185], s[36:37], 0, v[132:133]
	s_mov_b32 m0, s30
	ds_read_b128 v[176:179], v142 offset:16384
	ds_read_b128 v[180:183], v142 offset:17408
	ds_read_b128 v[188:191], v142 offset:18432
	ds_read_b128 v[192:195], v142 offset:19456
	ds_read_b128 v[196:199], v142 offset:20480
	ds_read_b128 v[200:203], v142 offset:21504
	ds_read_b128 v[204:207], v142 offset:22528
	ds_read_b128 v[208:211], v142 offset:23552
	global_load_lds_dwordx4 v[184:185], off
	s_add_i32 m0, s30, 0x2000
	s_add_u32 s30, s36, 0xb0000
	v_lshl_add_u64 v[212:213], s[36:37], 0, v[130:131]
	s_addc_u32 s31, s37, 0
	s_add_i32 s69, s55, s40
	global_load_lds_dwordx4 v[212:213], off
	v_lshl_add_u64 v[214:215], s[30:31], 0, v[132:133]
	s_mov_b32 m0, s69
	v_lshl_add_u64 v[216:217], s[38:39], 0, v[130:131]
	global_load_lds_dwordx4 v[214:215], off
	v_lshl_add_u64 v[214:215], s[30:31], 0, v[130:131]
	s_add_i32 m0, s69, 0x2000
	s_nop 0
	global_load_lds_dwordx4 v[214:215], off
	v_lshl_add_u64 v[214:215], s[38:39], 0, v[132:133]
	s_mov_b32 m0, s41
	s_nop 0
	global_load_lds_dwordx4 v[214:215], off
	s_mov_b32 m0, s42
	s_nop 0
	global_load_lds_dwordx4 v[216:217], off
	s_waitcnt vmcnt(8)
	s_waitcnt lgkmcnt(0)
	s_barrier
; #define PG8_STAGE(bufoff, gbase, voff) do { _Pragma("unroll") for (int _i = 0; _i < 2; ++_i) \
;         __builtin_amdgcn_global_load_lds((const unsigned*)((const char*)(gbase) + (voff)[_i]), (PG8_LAS unsigned*)(lds + (bufoff) + ldsw + _i * 8192), 16, 0, 0); } while (0)
; #define PG8_LDA(dst, b, h) do { _Pragma("unroll") for (int m = 0; m < 4; ++m) _Pragma("unroll") for (int k = 0; k < 2; ++k) dst[m][k] = *(const PG8_LAS bf16x8*)(lds + PG8_SA(b, h) + aoff + m * 2048 + k * 1024); } while (0)
; #define PG8_LDB(dst, b, h) do { _Pragma("unroll") for (int n = 0; n < 2; ++n) _Pragma("unroll") for (int k = 0; k < 2; ++k) dst[n][k] = *(const PG8_LAS bf16x8*)(lds + PG8_SB(b, h) + boff + n * 2048 + k * 1024); } while (0)
; #define PG8_MMA(ai, bj, At, Bt) do { __builtin_amdgcn_s_setprio(1); _Pragma("unroll") for (int m = 0; m < 4; ++m) _Pragma("unroll") for (int n = 0; n < 2; ++n) _Pragma("unroll") for (int k = 0; k < 2; ++k) \
;         acc[ai][bj][m][n] = __builtin_amdgcn_mfma_f32_16x16x32_bf16(Bt[n][k], At[m][k], acc[ai][bj][m][n], 0, 0, 0); __builtin_amdgcn_s_setprio(0); } while (0)
; #define PG8_WAIT_V(n) asm volatile("s_waitcnt vmcnt(" #n ")" ::: "memory")
; #define PG8_WAIT_L(n) asm volatile("s_waitcnt lgkmcnt(" #n ")" ::: "memory")
; #define PG8_BAR __builtin_amdgcn_s_barrier()
; #define PG8_SCHED __builtin_amdgcn_sched_barrier(0)
; template <class Epi, class Sched, bool ALIGN_EPI = false, bool SP2 = false>
; __device__ __forceinline__ void gemm_phase(PG8_LAS unsigned char* lds, const Gemm g, const Sched& S, const Epi& E) {
;     ...
;             PG8_WAIT_V(8); PG8_WAIT_L(0); PG8_BAR; PG8_MMA(1, 0, At, B0); PG8_MMA(1, 1, At, B1); PG8_BAR; PG8_SCHED;
;             PG8_LDB(B0, 1, 0); PG8_LDB(B1, 1, 1); PG8_SCHED; PG8_LDA(At, 1, 0); PG8_STAGE(PG8_SA(0, 1), a2 + hstep, voffA);
;             PG8_WAIT_V(8); PG8_WAIT_L(0); PG8_BAR; PG8_MMA(0, 0, At, B0); PG8_MMA(0, 1, At, B1); PG8_BAR; PG8_SCHED;
	s_setprio 1
	s_waitcnt lgkmcnt(0)
	v_mfma_f32_16x16x32_bf16 v[62:65], v[144:147], v[176:179], v[62:65]
	v_mfma_f32_16x16x32_bf16 v[58:61], v[152:155], v[176:179], v[58:61]
	v_mfma_f32_16x16x32_bf16 v[46:49], v[144:147], v[188:191], v[46:49]
	v_mfma_f32_16x16x32_bf16 v[42:45], v[152:155], v[188:191], v[42:45]
	v_mfma_f32_16x16x32_bf16 v[30:33], v[144:147], v[196:199], v[30:33]
	v_mfma_f32_16x16x32_bf16 v[26:29], v[152:155], v[196:199], v[26:29]
	v_mfma_f32_16x16x32_bf16 v[14:17], v[144:147], v[204:207], v[14:17]
	v_mfma_f32_16x16x32_bf16 v[10:13], v[152:155], v[204:207], v[10:13]
	v_mfma_f32_16x16x32_bf16 v[62:65], v[148:151], v[180:183], v[62:65]
	v_mfma_f32_16x16x32_bf16 v[58:61], v[156:159], v[180:183], v[58:61]
	v_mfma_f32_16x16x32_bf16 v[46:49], v[148:151], v[192:195], v[46:49]
	v_mfma_f32_16x16x32_bf16 v[42:45], v[156:159], v[192:195], v[42:45]
	v_mfma_f32_16x16x32_bf16 v[30:33], v[148:151], v[200:203], v[30:33]
	v_mfma_f32_16x16x32_bf16 v[26:29], v[156:159], v[200:203], v[26:29]
	v_mfma_f32_16x16x32_bf16 v[14:17], v[148:151], v[208:211], v[14:17]
	v_mfma_f32_16x16x32_bf16 v[10:13], v[156:159], v[208:211], v[10:13]
	s_setprio 0
	s_setprio 1
	v_mfma_f32_16x16x32_bf16 v[54:57], v[160:163], v[176:179], v[54:57]
	v_mfma_f32_16x16x32_bf16 v[50:53], v[168:171], v[176:179], v[50:53]
	v_mfma_f32_16x16x32_bf16 v[38:41], v[160:163], v[188:191], v[38:41]
	v_mfma_f32_16x16x32_bf16 v[34:37], v[168:171], v[188:191], v[34:37]
	v_mfma_f32_16x16x32_bf16 v[22:25], v[160:163], v[196:199], v[22:25]
	v_mfma_f32_16x16x32_bf16 v[18:21], v[168:171], v[196:199], v[18:21]
	v_mfma_f32_16x16x32_bf16 v[6:9], v[160:163], v[204:207], v[6:9]
	v_mfma_f32_16x16x32_bf16 v[2:5], v[168:171], v[204:207], v[2:5]
	v_mfma_f32_16x16x32_bf16 v[54:57], v[164:167], v[180:183], v[54:57]
	v_mfma_f32_16x16x32_bf16 v[50:53], v[172:175], v[180:183], v[50:53]
	v_mfma_f32_16x16x32_bf16 v[38:41], v[164:167], v[192:195], v[38:41]
	v_mfma_f32_16x16x32_bf16 v[34:37], v[172:175], v[192:195], v[34:37]
	v_mfma_f32_16x16x32_bf16 v[22:25], v[164:167], v[200:203], v[22:25]
	v_mfma_f32_16x16x32_bf16 v[18:21], v[172:175], v[200:203], v[18:21]
	v_mfma_f32_16x16x32_bf16 v[6:9], v[164:167], v[208:211], v[6:9]
	v_mfma_f32_16x16x32_bf16 v[2:5], v[172:175], v[208:211], v[2:5]
	s_setprio 0
	s_barrier
	s_add_i32 s69, 0, 0x18000
	v_add_u32_e32 v143, s69, v1
	s_add_i32 s70, 0, 0x1c000
	ds_read_b128 v[144:147], v143
	ds_read_b128 v[148:151], v143 offset:1024
	ds_read_b128 v[152:155], v143 offset:2048
	ds_read_b128 v[156:159], v143 offset:3072
	v_add_u32_e32 v143, s70, v1
	ds_read_b128 v[160:163], v143
	ds_read_b128 v[164:167], v143 offset:1024
	ds_read_b128 v[168:171], v143 offset:2048
	ds_read_b128 v[172:175], v143 offset:3072
	s_add_u32 s30, s38, 0xb0000
	s_addc_u32 s31, s39, 0
	s_mov_b32 m0, s43
	v_lshl_add_u64 v[218:219], s[30:31], 0, v[132:133]
	ds_read_b128 v[176:179], v142 offset:32768
	ds_read_b128 v[180:183], v142 offset:33792
	ds_read_b128 v[188:191], v142 offset:34816
	ds_read_b128 v[192:195], v142 offset:35840
	ds_read_b128 v[196:199], v142 offset:36864
	ds_read_b128 v[200:203], v142 offset:37888
	ds_read_b128 v[204:207], v142 offset:38912
	ds_read_b128 v[208:211], v142 offset:39936
	global_load_lds_dwordx4 v[218:219], off
	v_lshl_add_u64 v[218:219], s[30:31], 0, v[130:131]
	s_mov_b32 m0, s48
	s_nop 0
	global_load_lds_dwordx4 v[218:219], off
	s_waitcnt vmcnt(8)
	s_waitcnt lgkmcnt(0)
	s_barrier
	s_setprio 1
	s_waitcnt lgkmcnt(0)
	v_mfma_f32_16x16x32_bf16 v[126:129], v[144:147], v[176:179], v[126:129]
	v_mfma_f32_16x16x32_bf16 v[122:125], v[152:155], v[176:179], v[122:125]
	v_mfma_f32_16x16x32_bf16 v[110:113], v[144:147], v[188:191], v[110:113]
	v_mfma_f32_16x16x32_bf16 v[106:109], v[152:155], v[188:191], v[106:109]
	v_mfma_f32_16x16x32_bf16 v[94:97], v[144:147], v[196:199], v[94:97]
	v_mfma_f32_16x16x32_bf16 v[90:93], v[152:155], v[196:199], v[90:93]
	v_mfma_f32_16x16x32_bf16 v[78:81], v[144:147], v[204:207], v[78:81]
	v_mfma_f32_16x16x32_bf16 v[74:77], v[152:155], v[204:207], v[74:77]
	v_mfma_f32_16x16x32_bf16 v[126:129], v[148:151], v[180:183], v[126:129]
	v_mfma_f32_16x16x32_bf16 v[122:125], v[156:159], v[180:183], v[122:125]
	v_mfma_f32_16x16x32_bf16 v[110:113], v[148:151], v[192:195], v[110:113]
	v_mfma_f32_16x16x32_bf16 v[106:109], v[156:159], v[192:195], v[106:109]
	v_mfma_f32_16x16x32_bf16 v[94:97], v[148:151], v[200:203], v[94:97]
	v_mfma_f32_16x16x32_bf16 v[90:93], v[156:159], v[200:203], v[90:93]
	v_mfma_f32_16x16x32_bf16 v[78:81], v[148:151], v[208:211], v[78:81]
	v_mfma_f32_16x16x32_bf16 v[74:77], v[156:159], v[208:211], v[74:77]
	s_setprio 0
	s_setprio 1
	v_mfma_f32_16x16x32_bf16 v[118:121], v[160:163], v[176:179], v[118:121]
	v_mfma_f32_16x16x32_bf16 v[114:117], v[168:171], v[176:179], v[114:117]
	v_mfma_f32_16x16x32_bf16 v[102:105], v[160:163], v[188:191], v[102:105]
	v_mfma_f32_16x16x32_bf16 v[98:101], v[168:171], v[188:191], v[98:101]
	v_mfma_f32_16x16x32_bf16 v[86:89], v[160:163], v[196:199], v[86:89]
	v_mfma_f32_16x16x32_bf16 v[82:85], v[168:171], v[196:199], v[82:85]
	v_mfma_f32_16x16x32_bf16 v[70:73], v[160:163], v[204:207], v[70:73]
	v_mfma_f32_16x16x32_bf16 v[66:69], v[168:171], v[204:207], v[66:69]
	v_mfma_f32_16x16x32_bf16 v[118:121], v[164:167], v[180:183], v[118:121]
	v_mfma_f32_16x16x32_bf16 v[114:117], v[172:175], v[180:183], v[114:117]
	v_mfma_f32_16x16x32_bf16 v[102:105], v[164:167], v[192:195], v[102:105]
	v_mfma_f32_16x16x32_bf16 v[98:101], v[172:175], v[192:195], v[98:101]
	v_mfma_f32_16x16x32_bf16 v[86:89], v[164:167], v[200:203], v[86:89]
	v_mfma_f32_16x16x32_bf16 v[82:85], v[172:175], v[200:203], v[82:85]
	v_mfma_f32_16x16x32_bf16 v[70:73], v[164:167], v[208:211], v[70:73]
	v_mfma_f32_16x16x32_bf16 v[66:69], v[172:175], v[208:211], v[66:69]
	s_setprio 0
	s_barrier
; #define PG8_STAGE(bufoff, gbase, voff) do { _Pragma("unroll") for (int _i = 0; _i < 2; ++_i) \
;         __builtin_amdgcn_global_load_lds((const unsigned*)((const char*)(gbase) + (voff)[_i]), (PG8_LAS unsigned*)(lds + (bufoff) + ldsw + _i * 8192), 16, 0, 0); } while (0)
; #define PG8_LDA(dst, b, h) do { _Pragma("unroll") for (int m = 0; m < 4; ++m) _Pragma("unroll") for (int k = 0; k < 2; ++k) dst[m][k] = *(const PG8_LAS bf16x8*)(lds + PG8_SA(b, h) + aoff + m * 2048 + k * 1024); } while (0)
; #define PG8_MMA(ai, bj, At, Bt) do { __builtin_amdgcn_s_setprio(1); _Pragma("unroll") for (int m = 0; m < 4; ++m) _Pragma("unroll") for (int n = 0; n < 2; ++n) _Pragma("unroll") for (int k = 0; k < 2; ++k) \
;         acc[ai][bj][m][n] = __builtin_amdgcn_mfma_f32_16x16x32_bf16(Bt[n][k], At[m][k], acc[ai][bj][m][n], 0, 0, 0); __builtin_amdgcn_s_setprio(0); } while (0)
; #define PG8_WAIT_V(n) asm volatile("s_waitcnt vmcnt(" #n ")" ::: "memory")
; #define PG8_WAIT_L(n) asm volatile("s_waitcnt lgkmcnt(" #n ")" ::: "memory")
; #define PG8_BAR __builtin_amdgcn_s_barrier()
; #define PG8_SCHED __builtin_amdgcn_sched_barrier(0)
; template <class Epi, class Sched, bool ALIGN_EPI = false, bool SP2 = false>
; __device__ __forceinline__ void gemm_phase(PG8_LAS unsigned char* lds, const Gemm g, const Sched& S, const Epi& E) {
;     ...
;         for (int t = 0; t < nt; t += 2) {
;             const bool last = (t == nt - 2);
;             const char* a1 = cA + (size_t)(t + 1) * kstep;
;             const char* a2 = last ? nA : cA + (size_t)(t + 2) * kstep; const char* b2 = last ? nB : cB + (size_t)(t + 2) * kstep;
;             const char* a3 = a2 + kstep; const char* b3 = b2 + kstep;
;     ...
;             PG8_LDA(At, 1, 1); PG8_STAGE(PG8_SB(1, 0), b3, voffB); PG8_STAGE(PG8_SB(1, 1), b3 + hstep, voffB); PG8_STAGE(PG8_SA(1, 0), a3, voffA);
;             PG8_WAIT_V(8); PG8_WAIT_L(0); PG8_BAR; PG8_MMA(1, 0, At, B0); PG8_MMA(1, 1, At, B1); PG8_BAR; PG8_SCHED;
	s_add_i32 s30, s69, s40
	v_lshl_add_u64 v[184:185], v[184:185], 0, s[14:15]
	s_mov_b32 m0, s30
	ds_read_b128 v[176:179], v142 offset:49152
	ds_read_b128 v[180:183], v142 offset:50176
	ds_read_b128 v[188:191], v142 offset:51200
	ds_read_b128 v[192:195], v142 offset:52224
	ds_read_b128 v[196:199], v142 offset:53248
	ds_read_b128 v[200:203], v142 offset:54272
	ds_read_b128 v[204:207], v142 offset:55296
	ds_read_b128 v[208:211], v142 offset:56320
	global_load_lds_dwordx4 v[184:185], off
	s_add_i32 m0, s30, 0x2000
	s_add_u32 s30, s36, 0xb0080
	v_lshl_add_u64 v[184:185], v[212:213], 0, s[14:15]
	s_addc_u32 s31, s37, 0
	s_add_i32 s36, s70, s40
	global_load_lds_dwordx4 v[184:185], off
	v_lshl_add_u64 v[184:185], s[30:31], 0, v[132:133]
	s_mov_b32 m0, s36
	s_nop 0
	global_load_lds_dwordx4 v[184:185], off
	v_lshl_add_u64 v[184:185], s[30:31], 0, v[130:131]
	s_add_i32 m0, s36, 0x2000
	s_nop 0
	global_load_lds_dwordx4 v[184:185], off
	v_lshl_add_u64 v[184:185], v[214:215], 0, s[14:15]
	s_mov_b32 m0, s51
	s_nop 0
	global_load_lds_dwordx4 v[184:185], off
	v_lshl_add_u64 v[184:185], v[216:217], 0, s[14:15]
	s_mov_b32 m0, s52
	s_nop 0
	global_load_lds_dwordx4 v[184:185], off
	s_waitcnt vmcnt(8)
	s_waitcnt lgkmcnt(0)
	s_barrier
	s_setprio 1
	s_waitcnt lgkmcnt(0)
	v_mfma_f32_16x16x32_bf16 v[62:65], v[144:147], v[176:179], v[62:65]
	v_mfma_f32_16x16x32_bf16 v[58:61], v[152:155], v[176:179], v[58:61]
	v_mfma_f32_16x16x32_bf16 v[46:49], v[144:147], v[188:191], v[46:49]
	v_mfma_f32_16x16x32_bf16 v[42:45], v[152:155], v[188:191], v[42:45]
	v_mfma_f32_16x16x32_bf16 v[30:33], v[144:147], v[196:199], v[30:33]
	v_mfma_f32_16x16x32_bf16 v[26:29], v[152:155], v[196:199], v[26:29]
	v_mfma_f32_16x16x32_bf16 v[14:17], v[144:147], v[204:207], v[14:17]
	v_mfma_f32_16x16x32_bf16 v[10:13], v[152:155], v[204:207], v[10:13]
	v_mfma_f32_16x16x32_bf16 v[62:65], v[148:151], v[180:183], v[62:65]
	v_mfma_f32_16x16x32_bf16 v[58:61], v[156:159], v[180:183], v[58:61]
	v_mfma_f32_16x16x32_bf16 v[46:49], v[148:151], v[192:195], v[46:49]
	v_mfma_f32_16x16x32_bf16 v[42:45], v[156:159], v[192:195], v[42:45]
	v_mfma_f32_16x16x32_bf16 v[30:33], v[148:151], v[200:203], v[30:33]
	v_mfma_f32_16x16x32_bf16 v[26:29], v[156:159], v[200:203], v[26:29]
	v_mfma_f32_16x16x32_bf16 v[14:17], v[148:151], v[208:211], v[14:17]
	v_mfma_f32_16x16x32_bf16 v[10:13], v[156:159], v[208:211], v[10:13]
	s_setprio 0
	s_setprio 1
	v_mfma_f32_16x16x32_bf16 v[54:57], v[160:163], v[176:179], v[54:57]
	v_mfma_f32_16x16x32_bf16 v[50:53], v[168:171], v[176:179], v[50:53]
	v_mfma_f32_16x16x32_bf16 v[38:41], v[160:163], v[188:191], v[38:41]
	v_mfma_f32_16x16x32_bf16 v[34:37], v[168:171], v[188:191], v[34:37]
	v_mfma_f32_16x16x32_bf16 v[22:25], v[160:163], v[196:199], v[22:25]
	v_mfma_f32_16x16x32_bf16 v[18:21], v[168:171], v[196:199], v[18:21]
	v_mfma_f32_16x16x32_bf16 v[6:9], v[160:163], v[204:207], v[6:9]
	v_mfma_f32_16x16x32_bf16 v[2:5], v[168:171], v[204:207], v[2:5]
	v_mfma_f32_16x16x32_bf16 v[54:57], v[164:167], v[180:183], v[54:57]
	v_mfma_f32_16x16x32_bf16 v[50:53], v[172:175], v[180:183], v[50:53]
	v_mfma_f32_16x16x32_bf16 v[38:41], v[164:167], v[192:195], v[38:41]
	v_mfma_f32_16x16x32_bf16 v[34:37], v[172:175], v[192:195], v[34:37]
	v_mfma_f32_16x16x32_bf16 v[22:25], v[164:167], v[200:203], v[22:25]
	v_mfma_f32_16x16x32_bf16 v[18:21], v[172:175], v[200:203], v[18:21]
	v_mfma_f32_16x16x32_bf16 v[6:9], v[164:167], v[208:211], v[6:9]
	v_mfma_f32_16x16x32_bf16 v[2:5], v[172:175], v[208:211], v[2:5]
	s_setprio 0
	s_add_u32 s66, s66, 0x100
	s_addc_u32 s67, s67, 0
	s_cmp_ge_i32 s68, s50
	s_mov_b64 s[30:31], s[34:35]
	s_mov_b32 s36, s68
	s_barrier
	s_cbranch_scc0 .LBB0_207

; #define PG8_STAGE(bufoff, gbase, voff) do { _Pragma("unroll") for (int _i = 0; _i < 2; ++_i) \
;         __builtin_amdgcn_global_load_lds((const unsigned*)((const char*)(gbase) + (voff)[_i]), (PG8_LAS unsigned*)(lds + (bufoff) + ldsw + _i * 8192), 16, 0, 0); } while (0)
; #define PG8_LDA(dst, b, h) do { _Pragma("unroll") for (int m = 0; m < 4; ++m) _Pragma("unroll") for (int k = 0; k < 2; ++k) dst[m][k] = *(const PG8_LAS bf16x8*)(lds + PG8_SA(b, h) + aoff + m * 2048 + k * 1024); } while (0)
; #define PG8_LDB(dst, b, h) do { _Pragma("unroll") for (int n = 0; n < 2; ++n) _Pragma("unroll") for (int k = 0; k < 2; ++k) dst[n][k] = *(const PG8_LAS bf16x8*)(lds + PG8_SB(b, h) + boff + n * 2048 + k * 1024); } while (0)
; #define PG8_MMA(ai, bj, At, Bt) do { __builtin_amdgcn_s_setprio(1); _Pragma("unroll") for (int m = 0; m < 4; ++m) _Pragma("unroll") for (int n = 0; n < 2; ++n) _Pragma("unroll") for (int k = 0; k < 2; ++k) \
;         acc[ai][bj][m][n] = __builtin_amdgcn_mfma_f32_16x16x32_bf16(Bt[n][k], At[m][k], acc[ai][bj][m][n], 0, 0, 0); __builtin_amdgcn_s_setprio(0); } while (0)
; #define PG8_WAIT_V(n) asm volatile("s_waitcnt vmcnt(" #n ")" ::: "memory")
; #define PG8_WAIT_L(n) asm volatile("s_waitcnt lgkmcnt(" #n ")" ::: "memory")
; #define PG8_BAR __builtin_amdgcn_s_barrier()
; #define PG8_SCHED __builtin_amdgcn_sched_barrier(0)
; template <class Epi, class Sched, bool ALIGN_EPI = false, bool SP2 = false>
; __device__ __forceinline__ void gemm_phase(PG8_LAS unsigned char* lds, const Gemm g, const Sched& S, const Epi& E) {
;     ...
;         for (int t = 0; t < nt; t += 2) {
;             const bool last = (t == nt - 2);
;             const char* a1 = cA + (size_t)(t + 1) * kstep;
;             const char* a2 = last ? nA : cA + (size_t)(t + 2) * kstep; const char* b2 = last ? nB : cB + (size_t)(t + 2) * kstep;
;             const char* a3 = a2 + kstep; const char* b3 = b2 + kstep;
;             if (last && has_next) S.a_ready(nxt);
;             if constexpr (SP2) {
;             PG8_LDB(B0, 0, 0); PG8_LDB(B1, 0, 1); PG8_SCHED; PG8_LDA(At, 0, 0); PG8_STAGE(PG8_SA(1, 1), a1 + hstep, voffA);
;             PG8_WAIT_V(8); PG8_WAIT_L(0); PG8_BAR; PG8_MMA(0, 0, At, B0); PG8_MMA(0, 1, At, B1); PG8_BAR; PG8_SCHED;
;             PG8_LDA(At, 0, 1); PG8_STAGE(PG8_SB(0, 0), b2, voffB); PG8_STAGE(PG8_SB(0, 1), b2 + hstep, voffB); PG8_STAGE(PG8_SA(0, 0), a2, voffA);
.LBB0_252:
	v_add_u32_e32 v162, s52, v148
	v_add_u32_e32 v178, s53, v148
	s_add_u32 s28, s20, s26
	ds_read_b128 v[150:153], v162
	ds_read_b128 v[154:157], v162 offset:1024
	ds_read_b128 v[158:161], v162 offset:2048
	ds_read_b128 v[162:165], v162 offset:3072
	ds_read_b128 v[166:169], v178
	ds_read_b128 v[170:173], v178 offset:1024
	ds_read_b128 v[174:177], v178 offset:2048
	ds_read_b128 v[178:181], v178 offset:3072
	s_addc_u32 s29, s21, s27
	s_add_u32 s28, s28, 0x100
	s_addc_u32 s29, s29, 0
	s_add_u32 s60, s57, s26
	s_addc_u32 s61, s58, s27
	s_cmpk_eq_i32 s26, 0x1500
	s_cselect_b32 s31, s25, s29
	s_cselect_b32 s30, s24, s28
	s_cselect_b32 s29, s9, s61
	s_cselect_b32 s28, s8, s60
	v_lshl_add_u64 v[216:217], v[142:143], 0, s[26:27]
	s_add_i32 m0, s40, 0xc000
	ds_read_b128 v[182:185], v149
	ds_read_b128 v[188:191], v149 offset:1024
	ds_read_b128 v[192:195], v149 offset:2048
	ds_read_b128 v[196:199], v149 offset:3072
	ds_read_b128 v[200:203], v149 offset:4096
	ds_read_b128 v[204:207], v149 offset:5120
	ds_read_b128 v[208:211], v149 offset:6144
	ds_read_b128 v[212:215], v149 offset:7168
	global_load_lds_dwordx4 v[216:217], off
	v_lshl_add_u64 v[216:217], v[144:145], 0, s[26:27]
	s_add_i32 m0, s40, 0xe000
	s_nop 0
	global_load_lds_dwordx4 v[216:217], off
	s_waitcnt vmcnt(8)
	s_waitcnt lgkmcnt(0)
	s_barrier
	s_setprio 1
	s_waitcnt lgkmcnt(0)
	v_mfma_f32_16x16x32_bf16 v[106:109], v[150:153], v[182:185], v[106:109]
	v_mfma_f32_16x16x32_bf16 v[66:69], v[158:161], v[182:185], v[66:69]
	v_mfma_f32_16x16x32_bf16 v[114:117], v[150:153], v[192:195], v[114:117]
	v_mfma_f32_16x16x32_bf16 v[86:89], v[158:161], v[192:195], v[86:89]
	v_mfma_f32_16x16x32_bf16 v[126:129], v[150:153], v[200:203], v[126:129]
	v_mfma_f32_16x16x32_bf16 v[110:113], v[158:161], v[200:203], v[110:113]
	v_mfma_f32_16x16x32_bf16 v[122:125], v[150:153], v[208:211], v[122:125]
	v_mfma_f32_16x16x32_bf16 v[118:121], v[158:161], v[208:211], v[118:121]
	v_mfma_f32_16x16x32_bf16 v[106:109], v[154:157], v[188:191], v[106:109]
	v_mfma_f32_16x16x32_bf16 v[66:69], v[162:165], v[188:191], v[66:69]
	v_mfma_f32_16x16x32_bf16 v[114:117], v[154:157], v[196:199], v[114:117]
	v_mfma_f32_16x16x32_bf16 v[86:89], v[162:165], v[196:199], v[86:89]
	v_mfma_f32_16x16x32_bf16 v[126:129], v[154:157], v[204:207], v[126:129]
	v_mfma_f32_16x16x32_bf16 v[110:113], v[162:165], v[204:207], v[110:113]
	v_mfma_f32_16x16x32_bf16 v[122:125], v[154:157], v[212:215], v[122:125]
	v_mfma_f32_16x16x32_bf16 v[118:121], v[162:165], v[212:215], v[118:121]
	s_setprio 0
	s_setprio 1
	v_mfma_f32_16x16x32_bf16 v[42:45], v[166:169], v[182:185], v[42:45]
	v_mfma_f32_16x16x32_bf16 v[18:21], v[174:177], v[182:185], v[18:21]
	v_mfma_f32_16x16x32_bf16 v[50:53], v[166:169], v[192:195], v[50:53]
	v_mfma_f32_16x16x32_bf16 v[30:33], v[174:177], v[192:195], v[30:33]
	v_mfma_f32_16x16x32_bf16 v[74:77], v[166:169], v[200:203], v[74:77]
	v_mfma_f32_16x16x32_bf16 v[46:49], v[174:177], v[200:203], v[46:49]
	v_mfma_f32_16x16x32_bf16 v[94:97], v[166:169], v[208:211], v[94:97]
	v_mfma_f32_16x16x32_bf16 v[54:57], v[174:177], v[208:211], v[54:57]
	v_mfma_f32_16x16x32_bf16 v[42:45], v[170:173], v[188:191], v[42:45]
	v_mfma_f32_16x16x32_bf16 v[18:21], v[178:181], v[188:191], v[18:21]
	v_mfma_f32_16x16x32_bf16 v[50:53], v[170:173], v[196:199], v[50:53]
	v_mfma_f32_16x16x32_bf16 v[30:33], v[178:181], v[196:199], v[30:33]
	v_mfma_f32_16x16x32_bf16 v[74:77], v[170:173], v[204:207], v[74:77]
	v_mfma_f32_16x16x32_bf16 v[46:49], v[178:181], v[204:207], v[46:49]
	v_mfma_f32_16x16x32_bf16 v[94:97], v[170:173], v[212:215], v[94:97]
	v_mfma_f32_16x16x32_bf16 v[54:57], v[178:181], v[212:215], v[54:57]
	s_setprio 0
	s_barrier
	s_add_i32 s60, s52, s39
	v_lshl_add_u64 v[216:217], s[28:29], 0, v[130:131]
	s_mov_b32 m0, s60
	ds_read_b128 v[182:185], v149 offset:16384
	ds_read_b128 v[188:191], v149 offset:17408
	ds_read_b128 v[192:195], v149 offset:18432
	ds_read_b128 v[196:199], v149 offset:19456
	ds_read_b128 v[200:203], v149 offset:20480
	ds_read_b128 v[204:207], v149 offset:21504
	ds_read_b128 v[208:211], v149 offset:22528
	ds_read_b128 v[212:215], v149 offset:23552
	global_load_lds_dwordx4 v[216:217], off
	s_add_i32 m0, s60, 0x2000
	s_add_u32 s60, s28, 0xb0000
	v_lshl_add_u64 v[218:219], s[28:29], 0, v[132:133]
	s_addc_u32 s61, s29, 0
	s_add_i32 s62, s53, s39
	global_load_lds_dwordx4 v[218:219], off
	v_lshl_add_u64 v[220:221], s[60:61], 0, v[130:131]
	s_mov_b32 m0, s62
	v_lshl_add_u64 v[222:223], s[30:31], 0, v[132:133]
	global_load_lds_dwordx4 v[220:221], off
	v_lshl_add_u64 v[220:221], s[60:61], 0, v[132:133]
	s_add_i32 m0, s62, 0x2000
	s_nop 0
	global_load_lds_dwordx4 v[220:221], off
	v_lshl_add_u64 v[220:221], s[30:31], 0, v[130:131]
	s_mov_b32 m0, s40
	s_nop 0
	global_load_lds_dwordx4 v[220:221], off
	s_mov_b32 m0, s41
	s_nop 0
	global_load_lds_dwordx4 v[222:223], off
	s_waitcnt vmcnt(8)
	s_waitcnt lgkmcnt(0)
	s_barrier
; #define PG8_STAGE(bufoff, gbase, voff) do { _Pragma("unroll") for (int _i = 0; _i < 2; ++_i) \
;         __builtin_amdgcn_global_load_lds((const unsigned*)((const char*)(gbase) + (voff)[_i]), (PG8_LAS unsigned*)(lds + (bufoff) + ldsw + _i * 8192), 16, 0, 0); } while (0)
; #define PG8_LDA(dst, b, h) do { _Pragma("unroll") for (int m = 0; m < 4; ++m) _Pragma("unroll") for (int k = 0; k < 2; ++k) dst[m][k] = *(const PG8_LAS bf16x8*)(lds + PG8_SA(b, h) + aoff + m * 2048 + k * 1024); } while (0)
; #define PG8_LDB(dst, b, h) do { _Pragma("unroll") for (int n = 0; n < 2; ++n) _Pragma("unroll") for (int k = 0; k < 2; ++k) dst[n][k] = *(const PG8_LAS bf16x8*)(lds + PG8_SB(b, h) + boff + n * 2048 + k * 1024); } while (0)
; #define PG8_MMA(ai, bj, At, Bt) do { __builtin_amdgcn_s_setprio(1); _Pragma("unroll") for (int m = 0; m < 4; ++m) _Pragma("unroll") for (int n = 0; n < 2; ++n) _Pragma("unroll") for (int k = 0; k < 2; ++k) \
;         acc[ai][bj][m][n] = __builtin_amdgcn_mfma_f32_16x16x32_bf16(Bt[n][k], At[m][k], acc[ai][bj][m][n], 0, 0, 0); __builtin_amdgcn_s_setprio(0); } while (0)
; #define PG8_WAIT_V(n) asm volatile("s_waitcnt vmcnt(" #n ")" ::: "memory")
; #define PG8_WAIT_L(n) asm volatile("s_waitcnt lgkmcnt(" #n ")" ::: "memory")
; #define PG8_BAR __builtin_amdgcn_s_barrier()
; #define PG8_SCHED __builtin_amdgcn_sched_barrier(0)
; template <class Epi, class Sched, bool ALIGN_EPI = false, bool SP2 = false>
; __device__ __forceinline__ void gemm_phase(PG8_LAS unsigned char* lds, const Gemm g, const Sched& S, const Epi& E) {
;     ...
;             PG8_WAIT_V(8); PG8_WAIT_L(0); PG8_BAR; PG8_MMA(1, 0, At, B0); PG8_MMA(1, 1, At, B1); PG8_BAR; PG8_SCHED;
;             PG8_LDB(B0, 1, 0); PG8_LDB(B1, 1, 1); PG8_SCHED; PG8_LDA(At, 1, 0); PG8_STAGE(PG8_SA(0, 1), a2 + hstep, voffA);
;             PG8_WAIT_V(8); PG8_WAIT_L(0); PG8_BAR; PG8_MMA(0, 0, At, B0); PG8_MMA(0, 1, At, B1); PG8_BAR; PG8_SCHED;
	s_setprio 1
	s_waitcnt lgkmcnt(0)
	v_mfma_f32_16x16x32_bf16 v[102:105], v[150:153], v[182:185], v[102:105]
	v_mfma_f32_16x16x32_bf16 v[98:101], v[158:161], v[182:185], v[98:101]
	v_mfma_f32_16x16x32_bf16 v[78:81], v[150:153], v[192:195], v[78:81]
	v_mfma_f32_16x16x32_bf16 v[70:73], v[158:161], v[192:195], v[70:73]
	v_mfma_f32_16x16x32_bf16 v[38:41], v[150:153], v[200:203], v[38:41]
	v_mfma_f32_16x16x32_bf16 v[34:37], v[158:161], v[200:203], v[34:37]
	v_mfma_f32_16x16x32_bf16 v[14:17], v[150:153], v[208:211], v[14:17]
	v_mfma_f32_16x16x32_bf16 v[10:13], v[158:161], v[208:211], v[10:13]
	v_mfma_f32_16x16x32_bf16 v[102:105], v[154:157], v[188:191], v[102:105]
	v_mfma_f32_16x16x32_bf16 v[98:101], v[162:165], v[188:191], v[98:101]
	v_mfma_f32_16x16x32_bf16 v[78:81], v[154:157], v[196:199], v[78:81]
	v_mfma_f32_16x16x32_bf16 v[70:73], v[162:165], v[196:199], v[70:73]
	v_mfma_f32_16x16x32_bf16 v[38:41], v[154:157], v[204:207], v[38:41]
	v_mfma_f32_16x16x32_bf16 v[34:37], v[162:165], v[204:207], v[34:37]
	v_mfma_f32_16x16x32_bf16 v[14:17], v[154:157], v[212:215], v[14:17]
	v_mfma_f32_16x16x32_bf16 v[10:13], v[162:165], v[212:215], v[10:13]
	s_setprio 0
	s_setprio 1
	v_mfma_f32_16x16x32_bf16 v[90:93], v[166:169], v[182:185], v[90:93]
	v_mfma_f32_16x16x32_bf16 v[82:85], v[174:177], v[182:185], v[82:85]
	v_mfma_f32_16x16x32_bf16 v[62:65], v[166:169], v[192:195], v[62:65]
	v_mfma_f32_16x16x32_bf16 v[58:61], v[174:177], v[192:195], v[58:61]
	v_mfma_f32_16x16x32_bf16 v[26:29], v[166:169], v[200:203], v[26:29]
	v_mfma_f32_16x16x32_bf16 v[22:25], v[174:177], v[200:203], v[22:25]
	v_mfma_f32_16x16x32_bf16 v[6:9], v[166:169], v[208:211], v[6:9]
	v_mfma_f32_16x16x32_bf16 v[2:5], v[174:177], v[208:211], v[2:5]
	v_mfma_f32_16x16x32_bf16 v[90:93], v[170:173], v[188:191], v[90:93]
	v_mfma_f32_16x16x32_bf16 v[82:85], v[178:181], v[188:191], v[82:85]
	v_mfma_f32_16x16x32_bf16 v[62:65], v[170:173], v[196:199], v[62:65]
	v_mfma_f32_16x16x32_bf16 v[58:61], v[178:181], v[196:199], v[58:61]
	v_mfma_f32_16x16x32_bf16 v[26:29], v[170:173], v[204:207], v[26:29]
	v_mfma_f32_16x16x32_bf16 v[22:25], v[178:181], v[204:207], v[22:25]
	v_mfma_f32_16x16x32_bf16 v[6:9], v[170:173], v[212:215], v[6:9]
	v_mfma_f32_16x16x32_bf16 v[2:5], v[178:181], v[212:215], v[2:5]
	s_setprio 0
	s_barrier
	s_add_i32 s60, 0, 0x18000
	s_add_i32 s61, 0, 0x1c000
	v_add_u32_e32 v162, s60, v148
	v_add_u32_e32 v178, s61, v148
	ds_read_b128 v[150:153], v162
	ds_read_b128 v[154:157], v162 offset:1024
	ds_read_b128 v[158:161], v162 offset:2048
	ds_read_b128 v[162:165], v162 offset:3072
	ds_read_b128 v[166:169], v178
	ds_read_b128 v[170:173], v178 offset:1024
	ds_read_b128 v[174:177], v178 offset:2048
	ds_read_b128 v[178:181], v178 offset:3072
	s_add_u32 s30, s30, 0xb0000
	s_addc_u32 s31, s31, 0
	s_mov_b32 m0, s42
	v_lshl_add_u64 v[224:225], s[30:31], 0, v[130:131]
	ds_read_b128 v[182:185], v149 offset:32768
	ds_read_b128 v[188:191], v149 offset:33792
	ds_read_b128 v[192:195], v149 offset:34816
	ds_read_b128 v[196:199], v149 offset:35840
	ds_read_b128 v[200:203], v149 offset:36864
	ds_read_b128 v[204:207], v149 offset:37888
	ds_read_b128 v[208:211], v149 offset:38912
	ds_read_b128 v[212:215], v149 offset:39936
	global_load_lds_dwordx4 v[224:225], off
	v_lshl_add_u64 v[224:225], s[30:31], 0, v[132:133]
	s_mov_b32 m0, s43
	s_nop 0
	global_load_lds_dwordx4 v[224:225], off
	s_waitcnt vmcnt(8)
	s_waitcnt lgkmcnt(0)
	s_barrier
	s_setprio 1
	s_waitcnt lgkmcnt(0)
	v_mfma_f32_16x16x32_bf16 v[106:109], v[150:153], v[182:185], v[106:109]
	v_mfma_f32_16x16x32_bf16 v[66:69], v[158:161], v[182:185], v[66:69]
	v_mfma_f32_16x16x32_bf16 v[114:117], v[150:153], v[192:195], v[114:117]
	v_mfma_f32_16x16x32_bf16 v[86:89], v[158:161], v[192:195], v[86:89]
	v_mfma_f32_16x16x32_bf16 v[126:129], v[150:153], v[200:203], v[126:129]
	v_mfma_f32_16x16x32_bf16 v[110:113], v[158:161], v[200:203], v[110:113]
	v_mfma_f32_16x16x32_bf16 v[122:125], v[150:153], v[208:211], v[122:125]
	v_mfma_f32_16x16x32_bf16 v[118:121], v[158:161], v[208:211], v[118:121]
	v_mfma_f32_16x16x32_bf16 v[106:109], v[154:157], v[188:191], v[106:109]
	v_mfma_f32_16x16x32_bf16 v[66:69], v[162:165], v[188:191], v[66:69]
	v_mfma_f32_16x16x32_bf16 v[114:117], v[154:157], v[196:199], v[114:117]
	v_mfma_f32_16x16x32_bf16 v[86:89], v[162:165], v[196:199], v[86:89]
	v_mfma_f32_16x16x32_bf16 v[126:129], v[154:157], v[204:207], v[126:129]
	v_mfma_f32_16x16x32_bf16 v[110:113], v[162:165], v[204:207], v[110:113]
	v_mfma_f32_16x16x32_bf16 v[122:125], v[154:157], v[212:215], v[122:125]
	v_mfma_f32_16x16x32_bf16 v[118:121], v[162:165], v[212:215], v[118:121]
	s_setprio 0
	s_setprio 1
	v_mfma_f32_16x16x32_bf16 v[42:45], v[166:169], v[182:185], v[42:45]
	v_mfma_f32_16x16x32_bf16 v[18:21], v[174:177], v[182:185], v[18:21]
	v_mfma_f32_16x16x32_bf16 v[50:53], v[166:169], v[192:195], v[50:53]
	v_mfma_f32_16x16x32_bf16 v[30:33], v[174:177], v[192:195], v[30:33]
	v_mfma_f32_16x16x32_bf16 v[74:77], v[166:169], v[200:203], v[74:77]
	v_mfma_f32_16x16x32_bf16 v[46:49], v[174:177], v[200:203], v[46:49]
	v_mfma_f32_16x16x32_bf16 v[94:97], v[166:169], v[208:211], v[94:97]
	v_mfma_f32_16x16x32_bf16 v[54:57], v[174:177], v[208:211], v[54:57]
	v_mfma_f32_16x16x32_bf16 v[42:45], v[170:173], v[188:191], v[42:45]
	v_mfma_f32_16x16x32_bf16 v[18:21], v[178:181], v[188:191], v[18:21]
	v_mfma_f32_16x16x32_bf16 v[50:53], v[170:173], v[196:199], v[50:53]
	v_mfma_f32_16x16x32_bf16 v[30:33], v[178:181], v[196:199], v[30:33]
	v_mfma_f32_16x16x32_bf16 v[74:77], v[170:173], v[204:207], v[74:77]
	v_mfma_f32_16x16x32_bf16 v[46:49], v[178:181], v[204:207], v[46:49]
	v_mfma_f32_16x16x32_bf16 v[94:97], v[170:173], v[212:215], v[94:97]
	v_mfma_f32_16x16x32_bf16 v[54:57], v[178:181], v[212:215], v[54:57]
	s_setprio 0
	s_barrier
; #define PG8_STAGE(bufoff, gbase, voff) do { _Pragma("unroll") for (int _i = 0; _i < 2; ++_i) \
;         __builtin_amdgcn_global_load_lds((const unsigned*)((const char*)(gbase) + (voff)[_i]), (PG8_LAS unsigned*)(lds + (bufoff) + ldsw + _i * 8192), 16, 0, 0); } while (0)
; #define PG8_LDA(dst, b, h) do { _Pragma("unroll") for (int m = 0; m < 4; ++m) _Pragma("unroll") for (int k = 0; k < 2; ++k) dst[m][k] = *(const PG8_LAS bf16x8*)(lds + PG8_SA(b, h) + aoff + m * 2048 + k * 1024); } while (0)
; #define PG8_MMA(ai, bj, At, Bt) do { __builtin_amdgcn_s_setprio(1); _Pragma("unroll") for (int m = 0; m < 4; ++m) _Pragma("unroll") for (int n = 0; n < 2; ++n) _Pragma("unroll") for (int k = 0; k < 2; ++k) \
;         acc[ai][bj][m][n] = __builtin_amdgcn_mfma_f32_16x16x32_bf16(Bt[n][k], At[m][k], acc[ai][bj][m][n], 0, 0, 0); __builtin_amdgcn_s_setprio(0); } while (0)
; #define PG8_WAIT_V(n) asm volatile("s_waitcnt vmcnt(" #n ")" ::: "memory")
; #define PG8_WAIT_L(n) asm volatile("s_waitcnt lgkmcnt(" #n ")" ::: "memory")
; #define PG8_BAR __builtin_amdgcn_s_barrier()
; #define PG8_SCHED __builtin_amdgcn_sched_barrier(0)
; template <class Epi, class Sched, bool ALIGN_EPI = false, bool SP2 = false>
; __device__ __forceinline__ void gemm_phase(PG8_LAS unsigned char* lds, const Gemm g, const Sched& S, const Epi& E) {
;     ...
;             PG8_LDA(At, 1, 1); PG8_STAGE(PG8_SB(1, 0), b3, voffB); PG8_STAGE(PG8_SB(1, 1), b3 + hstep, voffB); PG8_STAGE(PG8_SA(1, 0), a3, voffA);
;             PG8_WAIT_V(8); PG8_WAIT_L(0); PG8_BAR; PG8_MMA(1, 0, At, B0); PG8_MMA(1, 1, At, B1); PG8_BAR; PG8_SCHED;
;     ...
; #pragma unroll
;         for (int a = 0; a < 2; ++a)
; #pragma unroll
;             for (int b = 0; b < 2; ++b)
; #pragma unroll
;                 for (int m = 0; m < 4; ++m)
; #pragma unroll
;                     for (int n = 0; n < 2; ++n) acc[a][b][m][n] = (f32x4){0.f, 0.f, 0.f, 0.f};
	s_add_i32 s30, s60, s39
	v_lshl_add_u64 v[216:217], v[216:217], 0, s[22:23]
	s_mov_b32 m0, s30
	ds_read_b128 v[182:185], v149 offset:49152
	ds_read_b128 v[188:191], v149 offset:50176
	ds_read_b128 v[192:195], v149 offset:51200
	ds_read_b128 v[196:199], v149 offset:52224
	ds_read_b128 v[200:203], v149 offset:53248
	ds_read_b128 v[204:207], v149 offset:54272
	ds_read_b128 v[208:211], v149 offset:55296
	ds_read_b128 v[212:215], v149 offset:56320
	global_load_lds_dwordx4 v[216:217], off
	s_add_i32 m0, s30, 0x2000
	s_add_u32 s28, s28, 0xb0080
	v_lshl_add_u64 v[216:217], v[218:219], 0, s[22:23]
	s_addc_u32 s29, s29, 0
	s_add_i32 s30, s61, s39
	global_load_lds_dwordx4 v[216:217], off
	v_lshl_add_u64 v[216:217], s[28:29], 0, v[130:131]
	s_mov_b32 m0, s30
	s_nop 0
	global_load_lds_dwordx4 v[216:217], off
	v_lshl_add_u64 v[216:217], s[28:29], 0, v[132:133]
	s_add_i32 m0, s30, 0x2000
	s_nop 0
	global_load_lds_dwordx4 v[216:217], off
	v_lshl_add_u64 v[216:217], v[220:221], 0, s[22:23]
	s_mov_b32 m0, s50
	s_nop 0
	global_load_lds_dwordx4 v[216:217], off
	v_lshl_add_u64 v[216:217], v[222:223], 0, s[22:23]
	s_mov_b32 m0, s51
	s_nop 0
	global_load_lds_dwordx4 v[216:217], off
	s_waitcnt vmcnt(8)
	s_waitcnt lgkmcnt(0)
	s_barrier
	s_setprio 1
	s_waitcnt lgkmcnt(0)
	v_mfma_f32_16x16x32_bf16 v[102:105], v[150:153], v[182:185], v[102:105]
	v_mfma_f32_16x16x32_bf16 v[98:101], v[158:161], v[182:185], v[98:101]
	v_mfma_f32_16x16x32_bf16 v[78:81], v[150:153], v[192:195], v[78:81]
	v_mfma_f32_16x16x32_bf16 v[70:73], v[158:161], v[192:195], v[70:73]
	v_mfma_f32_16x16x32_bf16 v[38:41], v[150:153], v[200:203], v[38:41]
	v_mfma_f32_16x16x32_bf16 v[34:37], v[158:161], v[200:203], v[34:37]
	v_mfma_f32_16x16x32_bf16 v[14:17], v[150:153], v[208:211], v[14:17]
	v_mfma_f32_16x16x32_bf16 v[10:13], v[158:161], v[208:211], v[10:13]
	v_mfma_f32_16x16x32_bf16 v[102:105], v[154:157], v[188:191], v[102:105]
	v_mfma_f32_16x16x32_bf16 v[98:101], v[162:165], v[188:191], v[98:101]
	v_mfma_f32_16x16x32_bf16 v[78:81], v[154:157], v[196:199], v[78:81]
	v_mfma_f32_16x16x32_bf16 v[70:73], v[162:165], v[196:199], v[70:73]
	v_mfma_f32_16x16x32_bf16 v[38:41], v[154:157], v[204:207], v[38:41]
	v_mfma_f32_16x16x32_bf16 v[34:37], v[162:165], v[204:207], v[34:37]
	v_mfma_f32_16x16x32_bf16 v[14:17], v[154:157], v[212:215], v[14:17]
	v_mfma_f32_16x16x32_bf16 v[10:13], v[162:165], v[212:215], v[10:13]
	s_setprio 0
	s_setprio 1
	v_mfma_f32_16x16x32_bf16 v[90:93], v[166:169], v[182:185], v[90:93]
	v_mfma_f32_16x16x32_bf16 v[82:85], v[174:177], v[182:185], v[82:85]
	v_mfma_f32_16x16x32_bf16 v[62:65], v[166:169], v[192:195], v[62:65]
	v_mfma_f32_16x16x32_bf16 v[58:61], v[174:177], v[192:195], v[58:61]
	v_mfma_f32_16x16x32_bf16 v[26:29], v[166:169], v[200:203], v[26:29]
	v_mfma_f32_16x16x32_bf16 v[22:25], v[174:177], v[200:203], v[22:25]
	v_mfma_f32_16x16x32_bf16 v[6:9], v[166:169], v[208:211], v[6:9]
	v_mfma_f32_16x16x32_bf16 v[2:5], v[174:177], v[208:211], v[2:5]
	v_mfma_f32_16x16x32_bf16 v[90:93], v[170:173], v[188:191], v[90:93]
	v_mfma_f32_16x16x32_bf16 v[82:85], v[178:181], v[188:191], v[82:85]
	v_mfma_f32_16x16x32_bf16 v[62:65], v[170:173], v[196:199], v[62:65]
	v_mfma_f32_16x16x32_bf16 v[58:61], v[178:181], v[196:199], v[58:61]
	v_mfma_f32_16x16x32_bf16 v[26:29], v[170:173], v[204:207], v[26:29]
	v_mfma_f32_16x16x32_bf16 v[22:25], v[178:181], v[204:207], v[22:25]
	v_mfma_f32_16x16x32_bf16 v[6:9], v[170:173], v[212:215], v[6:9]
	v_mfma_f32_16x16x32_bf16 v[2:5], v[178:181], v[212:215], v[2:5]
	s_setprio 0
	s_add_i32 s59, s59, 2
	s_add_u32 s26, s26, 0x100
	s_addc_u32 s27, s27, 0
	s_cmp_gt_u32 s59, 41
	s_barrier
	s_cbranch_scc0 .LBB0_252
	s_add_u32 s26, s57, 0xffffff00
	s_addc_u32 s27, s58, -1
	s_and_b64 vcc, exec, s[6:7]
	s_cbranch_vccnz .LBB0_255
	v_mov_b32_e32 v2, 0
	s_mov_b32 s18, s54
	s_mov_b32 s35, s55
	s_mov_b64 s[20:21], s[24:25]
	s_mov_b32 s49, s56
	v_mov_b32_e32 v3, v2
	v_mov_b32_e32 v4, v2
	v_mov_b32_e32 v5, v2
	v_mov_b32_e32 v6, v2
	v_mov_b32_e32 v7, v2
	v_mov_b32_e32 v8, v2
	v_mov_b32_e32 v9, v2
	v_mov_b32_e32 v22, v2
	v_mov_b32_e32 v23, v2
	v_mov_b32_e32 v24, v2
	v_mov_b32_e32 v25, v2
	v_mov_b32_e32 v26, v2
	v_mov_b32_e32 v27, v2
	v_mov_b32_e32 v28, v2
	v_mov_b32_e32 v29, v2
	v_mov_b32_e32 v58, v2
	v_mov_b32_e32 v59, v2
	v_mov_b32_e32 v60, v2
	v_mov_b32_e32 v61, v2
	v_mov_b32_e32 v62, v2
	v_mov_b32_e32 v63, v2
	v_mov_b32_e32 v64, v2
	v_mov_b32_e32 v65, v2
	v_mov_b32_e32 v82, v2
	v_mov_b32_e32 v83, v2
	v_mov_b32_e32 v84, v2
	v_mov_b32_e32 v85, v2
	v_mov_b32_e32 v90, v2
	v_mov_b32_e32 v91, v2
	v_mov_b32_e32 v92, v2
	v_mov_b32_e32 v93, v2
	v_mov_b32_e32 v10, v2
	v_mov_b32_e32 v11, v2
	v_mov_b32_e32 v12, v2
	v_mov_b32_e32 v13, v2
	v_mov_b32_e32 v14, v2
	v_mov_b32_e32 v15, v2
	v_mov_b32_e32 v16, v2
	v_mov_b32_e32 v17, v2
	v_mov_b32_e32 v34, v2
	v_mov_b32_e32 v35, v2
	v_mov_b32_e32 v36, v2
	v_mov_b32_e32 v37, v2
	v_mov_b32_e32 v38, v2
	v_mov_b32_e32 v39, v2
	v_mov_b32_e32 v40, v2
	v_mov_b32_e32 v41, v2
	v_mov_b32_e32 v70, v2
	v_mov_b32_e32 v71, v2
	v_mov_b32_e32 v72, v2
	v_mov_b32_e32 v73, v2
	v_mov_b32_e32 v78, v2
	v_mov_b32_e32 v79, v2
	v_mov_b32_e32 v80, v2
	v_mov_b32_e32 v81, v2
	v_mov_b32_e32 v98, v2
	v_mov_b32_e32 v99, v2
	v_mov_b32_e32 v100, v2
	v_mov_b32_e32 v101, v2
	v_mov_b32_e32 v102, v2
	v_mov_b32_e32 v103, v2
	v_mov_b32_e32 v104, v2
	v_mov_b32_e32 v105, v2
	v_mov_b32_e32 v54, v2
	v_mov_b32_e32 v55, v2
	v_mov_b32_e32 v56, v2
	v_mov_b32_e32 v57, v2
	v_mov_b32_e32 v94, v2
	v_mov_b32_e32 v95, v2
	v_mov_b32_e32 v96, v2
	v_mov_b32_e32 v97, v2
	v_mov_b32_e32 v46, v2
	v_mov_b32_e32 v47, v2
	v_mov_b32_e32 v48, v2
	v_mov_b32_e32 v49, v2
	v_mov_b32_e32 v74, v2
	v_mov_b32_e32 v75, v2
	v_mov_b32_e32 v76, v2
	v_mov_b32_e32 v77, v2
	v_mov_b32_e32 v30, v2
	v_mov_b32_e32 v31, v2
	v_mov_b32_e32 v32, v2
	v_mov_b32_e32 v33, v2
	v_mov_b32_e32 v50, v2
	v_mov_b32_e32 v51, v2
	v_mov_b32_e32 v52, v2
	v_mov_b32_e32 v53, v2
	v_mov_b32_e32 v18, v2
	v_mov_b32_e32 v19, v2
	v_mov_b32_e32 v20, v2
	v_mov_b32_e32 v21, v2
	v_mov_b32_e32 v42, v2
	v_mov_b32_e32 v43, v2
	v_mov_b32_e32 v44, v2
	v_mov_b32_e32 v45, v2
	v_mov_b32_e32 v118, v2
	v_mov_b32_e32 v119, v2
	v_mov_b32_e32 v120, v2
	v_mov_b32_e32 v121, v2
	v_mov_b32_e32 v122, v2
	v_mov_b32_e32 v123, v2
	v_mov_b32_e32 v124, v2
	v_mov_b32_e32 v125, v2
	v_mov_b32_e32 v110, v2
	v_mov_b32_e32 v111, v2
	v_mov_b32_e32 v112, v2
	v_mov_b32_e32 v113, v2
	v_mov_b32_e32 v126, v2
	v_mov_b32_e32 v127, v2
	v_mov_b32_e32 v128, v2
	v_mov_b32_e32 v129, v2
	v_mov_b32_e32 v86, v2
	v_mov_b32_e32 v87, v2
	v_mov_b32_e32 v88, v2
	v_mov_b32_e32 v89, v2
	v_mov_b32_e32 v114, v2
	v_mov_b32_e32 v115, v2
	v_mov_b32_e32 v116, v2
	v_mov_b32_e32 v117, v2
	v_mov_b32_e32 v66, v2
	v_mov_b32_e32 v67, v2
	v_mov_b32_e32 v68, v2
	v_mov_b32_e32 v69, v2
	v_mov_b32_e32 v106, v2
	v_mov_b32_e32 v107, v2
	v_mov_b32_e32 v108, v2
	v_mov_b32_e32 v109, v2
	s_andn2_b64 vcc, exec, s[4:5]
	s_cbranch_vccnz .LBB0_256
	s_branch .LBB0_257

; #define PG8_STAGE(bufoff, gbase, voff) do { _Pragma("unroll") for (int _i = 0; _i < 2; ++_i) \
;         __builtin_amdgcn_global_load_lds((const unsigned*)((const char*)(gbase) + (voff)[_i]), (PG8_LAS unsigned*)(lds + (bufoff) + ldsw + _i * 8192), 16, 0, 0); } while (0)
; #define PG8_LDA(dst, b, h) do { _Pragma("unroll") for (int m = 0; m < 4; ++m) _Pragma("unroll") for (int k = 0; k < 2; ++k) dst[m][k] = *(const PG8_LAS bf16x8*)(lds + PG8_SA(b, h) + aoff + m * 2048 + k * 1024); } while (0)
; #define PG8_LDB(dst, b, h) do { _Pragma("unroll") for (int n = 0; n < 2; ++n) _Pragma("unroll") for (int k = 0; k < 2; ++k) dst[n][k] = *(const PG8_LAS bf16x8*)(lds + PG8_SB(b, h) + boff + n * 2048 + k * 1024); } while (0)
; #define PG8_MMA(ai, bj, At, Bt) do { __builtin_amdgcn_s_setprio(1); _Pragma("unroll") for (int m = 0; m < 4; ++m) _Pragma("unroll") for (int n = 0; n < 2; ++n) _Pragma("unroll") for (int k = 0; k < 2; ++k) \
;         acc[ai][bj][m][n] = __builtin_amdgcn_mfma_f32_16x16x32_bf16(Bt[n][k], At[m][k], acc[ai][bj][m][n], 0, 0, 0); __builtin_amdgcn_s_setprio(0); } while (0)
; #define PG8_WAIT_V(n) asm volatile("s_waitcnt vmcnt(" #n ")" ::: "memory")
; #define PG8_WAIT_L(n) asm volatile("s_waitcnt lgkmcnt(" #n ")" ::: "memory")
; #define PG8_BAR __builtin_amdgcn_s_barrier()
; #define PG8_SCHED __builtin_amdgcn_sched_barrier(0)
; template <class Epi, class Sched, bool ALIGN_EPI = false, bool SP2 = false>
; __device__ __forceinline__ void gemm_phase(PG8_LAS unsigned char* lds, const Gemm g, const Sched& S, const Epi& E) {
;     ...
;         for (int t = 0; t < nt; t += 2) {
;             const bool last = (t == nt - 2);
;             const char* a1 = cA + (size_t)(t + 1) * kstep;
;             const char* a2 = last ? nA : cA + (size_t)(t + 2) * kstep; const char* b2 = last ? nB : cB + (size_t)(t + 2) * kstep;
;             const char* a3 = a2 + kstep; const char* b3 = b2 + kstep;
;             if (last && has_next) S.a_ready(nxt);
;             if constexpr (SP2) {
;             PG8_LDB(B0, 0, 0); PG8_LDB(B1, 0, 1); PG8_SCHED; PG8_LDA(At, 0, 0); PG8_STAGE(PG8_SA(1, 1), a1 + hstep, voffA);
;             PG8_WAIT_V(8); PG8_WAIT_L(0); PG8_BAR; PG8_MMA(0, 0, At, B0); PG8_MMA(0, 1, At, B1); PG8_BAR; PG8_SCHED;
;             PG8_LDA(At, 0, 1); PG8_STAGE(PG8_SB(0, 0), b2, voffB); PG8_STAGE(PG8_SB(0, 1), b2 + hstep, voffB); PG8_STAGE(PG8_SA(0, 0), a2, voffA);
.LBB0_319:
	v_add_u32_e32 v162, s52, v148
	v_add_u32_e32 v178, s53, v148
	s_add_u32 s26, s18, s24
	ds_read_b128 v[150:153], v162
	ds_read_b128 v[154:157], v162 offset:1024
	ds_read_b128 v[158:161], v162 offset:2048
	ds_read_b128 v[162:165], v162 offset:3072
	ds_read_b128 v[166:169], v178
	ds_read_b128 v[170:173], v178 offset:1024
	ds_read_b128 v[174:177], v178 offset:2048
	ds_read_b128 v[178:181], v178 offset:3072
	s_addc_u32 s27, s19, s25
	s_add_u32 s26, s26, 0x100
	s_addc_u32 s27, s27, 0
	s_add_u32 s60, s57, s24
	s_addc_u32 s61, s58, s25
	s_cmpk_eq_i32 s24, 0x1500
	s_cselect_b32 s29, s23, s27
	s_cselect_b32 s28, s22, s26
	s_cselect_b32 s27, s9, s61
	s_cselect_b32 s26, s8, s60
	v_lshl_add_u64 v[216:217], v[142:143], 0, s[24:25]
	s_add_i32 m0, s40, 0xc000
	ds_read_b128 v[182:185], v149
	ds_read_b128 v[188:191], v149 offset:1024
	ds_read_b128 v[192:195], v149 offset:2048
	ds_read_b128 v[196:199], v149 offset:3072
	ds_read_b128 v[200:203], v149 offset:4096
	ds_read_b128 v[204:207], v149 offset:5120
	ds_read_b128 v[208:211], v149 offset:6144
	ds_read_b128 v[212:215], v149 offset:7168
	global_load_lds_dwordx4 v[216:217], off
	v_lshl_add_u64 v[216:217], v[144:145], 0, s[24:25]
	s_add_i32 m0, s40, 0xe000
	s_nop 0
	global_load_lds_dwordx4 v[216:217], off
	s_waitcnt vmcnt(8)
	s_waitcnt lgkmcnt(0)
	s_barrier
	s_setprio 1
	s_waitcnt lgkmcnt(0)
	v_mfma_f32_16x16x32_bf16 v[106:109], v[150:153], v[182:185], v[106:109]
	v_mfma_f32_16x16x32_bf16 v[66:69], v[158:161], v[182:185], v[66:69]
	v_mfma_f32_16x16x32_bf16 v[114:117], v[150:153], v[192:195], v[114:117]
	v_mfma_f32_16x16x32_bf16 v[86:89], v[158:161], v[192:195], v[86:89]
	v_mfma_f32_16x16x32_bf16 v[126:129], v[150:153], v[200:203], v[126:129]
	v_mfma_f32_16x16x32_bf16 v[110:113], v[158:161], v[200:203], v[110:113]
	v_mfma_f32_16x16x32_bf16 v[122:125], v[150:153], v[208:211], v[122:125]
	v_mfma_f32_16x16x32_bf16 v[118:121], v[158:161], v[208:211], v[118:121]
	v_mfma_f32_16x16x32_bf16 v[106:109], v[154:157], v[188:191], v[106:109]
	v_mfma_f32_16x16x32_bf16 v[66:69], v[162:165], v[188:191], v[66:69]
	v_mfma_f32_16x16x32_bf16 v[114:117], v[154:157], v[196:199], v[114:117]
	v_mfma_f32_16x16x32_bf16 v[86:89], v[162:165], v[196:199], v[86:89]
	v_mfma_f32_16x16x32_bf16 v[126:129], v[154:157], v[204:207], v[126:129]
	v_mfma_f32_16x16x32_bf16 v[110:113], v[162:165], v[204:207], v[110:113]
	v_mfma_f32_16x16x32_bf16 v[122:125], v[154:157], v[212:215], v[122:125]
	v_mfma_f32_16x16x32_bf16 v[118:121], v[162:165], v[212:215], v[118:121]
	s_setprio 0
	s_setprio 1
	v_mfma_f32_16x16x32_bf16 v[42:45], v[166:169], v[182:185], v[42:45]
	v_mfma_f32_16x16x32_bf16 v[18:21], v[174:177], v[182:185], v[18:21]
	v_mfma_f32_16x16x32_bf16 v[50:53], v[166:169], v[192:195], v[50:53]
	v_mfma_f32_16x16x32_bf16 v[30:33], v[174:177], v[192:195], v[30:33]
	v_mfma_f32_16x16x32_bf16 v[70:73], v[166:169], v[200:203], v[70:73]
	v_mfma_f32_16x16x32_bf16 v[46:49], v[174:177], v[200:203], v[46:49]
	v_mfma_f32_16x16x32_bf16 v[94:97], v[166:169], v[208:211], v[94:97]
	v_mfma_f32_16x16x32_bf16 v[54:57], v[174:177], v[208:211], v[54:57]
	v_mfma_f32_16x16x32_bf16 v[42:45], v[170:173], v[188:191], v[42:45]
	v_mfma_f32_16x16x32_bf16 v[18:21], v[178:181], v[188:191], v[18:21]
	v_mfma_f32_16x16x32_bf16 v[50:53], v[170:173], v[196:199], v[50:53]
	v_mfma_f32_16x16x32_bf16 v[30:33], v[178:181], v[196:199], v[30:33]
	v_mfma_f32_16x16x32_bf16 v[70:73], v[170:173], v[204:207], v[70:73]
	v_mfma_f32_16x16x32_bf16 v[46:49], v[178:181], v[204:207], v[46:49]
	v_mfma_f32_16x16x32_bf16 v[94:97], v[170:173], v[212:215], v[94:97]
	v_mfma_f32_16x16x32_bf16 v[54:57], v[178:181], v[212:215], v[54:57]
	s_setprio 0
	s_barrier
	s_add_i32 s60, s52, s39
	v_lshl_add_u64 v[216:217], s[26:27], 0, v[130:131]
	s_mov_b32 m0, s60
	ds_read_b128 v[182:185], v149 offset:16384
	ds_read_b128 v[188:191], v149 offset:17408
	ds_read_b128 v[192:195], v149 offset:18432
	ds_read_b128 v[196:199], v149 offset:19456
	ds_read_b128 v[200:203], v149 offset:20480
	ds_read_b128 v[204:207], v149 offset:21504
	ds_read_b128 v[208:211], v149 offset:22528
	ds_read_b128 v[212:215], v149 offset:23552
	global_load_lds_dwordx4 v[216:217], off
	s_add_i32 m0, s60, 0x2000
	s_add_u32 s60, s26, 0xb0000
	v_lshl_add_u64 v[218:219], s[26:27], 0, v[132:133]
	s_addc_u32 s61, s27, 0
	s_add_i32 s62, s53, s39
	global_load_lds_dwordx4 v[218:219], off
	v_lshl_add_u64 v[220:221], s[60:61], 0, v[130:131]
	s_mov_b32 m0, s62
	v_lshl_add_u64 v[222:223], s[28:29], 0, v[132:133]
	global_load_lds_dwordx4 v[220:221], off
	v_lshl_add_u64 v[220:221], s[60:61], 0, v[132:133]
	s_add_i32 m0, s62, 0x2000
	s_nop 0
	global_load_lds_dwordx4 v[220:221], off
	v_lshl_add_u64 v[220:221], s[28:29], 0, v[130:131]
	s_mov_b32 m0, s40
	s_nop 0
	global_load_lds_dwordx4 v[220:221], off
	s_mov_b32 m0, s41
	s_nop 0
	global_load_lds_dwordx4 v[222:223], off
	s_waitcnt vmcnt(8)
	s_waitcnt lgkmcnt(0)
	s_barrier
; #define PG8_STAGE(bufoff, gbase, voff) do { _Pragma("unroll") for (int _i = 0; _i < 2; ++_i) \
;         __builtin_amdgcn_global_load_lds((const unsigned*)((const char*)(gbase) + (voff)[_i]), (PG8_LAS unsigned*)(lds + (bufoff) + ldsw + _i * 8192), 16, 0, 0); } while (0)
; #define PG8_LDA(dst, b, h) do { _Pragma("unroll") for (int m = 0; m < 4; ++m) _Pragma("unroll") for (int k = 0; k < 2; ++k) dst[m][k] = *(const PG8_LAS bf16x8*)(lds + PG8_SA(b, h) + aoff + m * 2048 + k * 1024); } while (0)
; #define PG8_LDB(dst, b, h) do { _Pragma("unroll") for (int n = 0; n < 2; ++n) _Pragma("unroll") for (int k = 0; k < 2; ++k) dst[n][k] = *(const PG8_LAS bf16x8*)(lds + PG8_SB(b, h) + boff + n * 2048 + k * 1024); } while (0)
; #define PG8_MMA(ai, bj, At, Bt) do { __builtin_amdgcn_s_setprio(1); _Pragma("unroll") for (int m = 0; m < 4; ++m) _Pragma("unroll") for (int n = 0; n < 2; ++n) _Pragma("unroll") for (int k = 0; k < 2; ++k) \
;         acc[ai][bj][m][n] = __builtin_amdgcn_mfma_f32_16x16x32_bf16(Bt[n][k], At[m][k], acc[ai][bj][m][n], 0, 0, 0); __builtin_amdgcn_s_setprio(0); } while (0)
; #define PG8_WAIT_V(n) asm volatile("s_waitcnt vmcnt(" #n ")" ::: "memory")
; #define PG8_WAIT_L(n) asm volatile("s_waitcnt lgkmcnt(" #n ")" ::: "memory")
; #define PG8_BAR __builtin_amdgcn_s_barrier()
; #define PG8_SCHED __builtin_amdgcn_sched_barrier(0)
; template <class Epi, class Sched, bool ALIGN_EPI = false, bool SP2 = false>
; __device__ __forceinline__ void gemm_phase(PG8_LAS unsigned char* lds, const Gemm g, const Sched& S, const Epi& E) {
;     ...
;             PG8_WAIT_V(8); PG8_WAIT_L(0); PG8_BAR; PG8_MMA(1, 0, At, B0); PG8_MMA(1, 1, At, B1); PG8_BAR; PG8_SCHED;
;             PG8_LDB(B0, 1, 0); PG8_LDB(B1, 1, 1); PG8_SCHED; PG8_LDA(At, 1, 0); PG8_STAGE(PG8_SA(0, 1), a2 + hstep, voffA);
;             PG8_WAIT_V(8); PG8_WAIT_L(0); PG8_BAR; PG8_MMA(0, 0, At, B0); PG8_MMA(0, 1, At, B1); PG8_BAR; PG8_SCHED;
	s_setprio 1
	s_waitcnt lgkmcnt(0)
	v_mfma_f32_16x16x32_bf16 v[102:105], v[150:153], v[182:185], v[102:105]
	v_mfma_f32_16x16x32_bf16 v[98:101], v[158:161], v[182:185], v[98:101]
	v_mfma_f32_16x16x32_bf16 v[78:81], v[150:153], v[192:195], v[78:81]
	v_mfma_f32_16x16x32_bf16 v[74:77], v[158:161], v[192:195], v[74:77]
	v_mfma_f32_16x16x32_bf16 v[38:41], v[150:153], v[200:203], v[38:41]
	v_mfma_f32_16x16x32_bf16 v[34:37], v[158:161], v[200:203], v[34:37]
	v_mfma_f32_16x16x32_bf16 v[14:17], v[150:153], v[208:211], v[14:17]
	v_mfma_f32_16x16x32_bf16 v[10:13], v[158:161], v[208:211], v[10:13]
	v_mfma_f32_16x16x32_bf16 v[102:105], v[154:157], v[188:191], v[102:105]
	v_mfma_f32_16x16x32_bf16 v[98:101], v[162:165], v[188:191], v[98:101]
	v_mfma_f32_16x16x32_bf16 v[78:81], v[154:157], v[196:199], v[78:81]
	v_mfma_f32_16x16x32_bf16 v[74:77], v[162:165], v[196:199], v[74:77]
	v_mfma_f32_16x16x32_bf16 v[38:41], v[154:157], v[204:207], v[38:41]
	v_mfma_f32_16x16x32_bf16 v[34:37], v[162:165], v[204:207], v[34:37]
	v_mfma_f32_16x16x32_bf16 v[14:17], v[154:157], v[212:215], v[14:17]
	v_mfma_f32_16x16x32_bf16 v[10:13], v[162:165], v[212:215], v[10:13]
	s_setprio 0
	s_setprio 1
	v_mfma_f32_16x16x32_bf16 v[90:93], v[166:169], v[182:185], v[90:93]
	v_mfma_f32_16x16x32_bf16 v[82:85], v[174:177], v[182:185], v[82:85]
	v_mfma_f32_16x16x32_bf16 v[62:65], v[166:169], v[192:195], v[62:65]
	v_mfma_f32_16x16x32_bf16 v[58:61], v[174:177], v[192:195], v[58:61]
	v_mfma_f32_16x16x32_bf16 v[26:29], v[166:169], v[200:203], v[26:29]
	v_mfma_f32_16x16x32_bf16 v[22:25], v[174:177], v[200:203], v[22:25]
	v_mfma_f32_16x16x32_bf16 v[6:9], v[166:169], v[208:211], v[6:9]
	v_mfma_f32_16x16x32_bf16 v[2:5], v[174:177], v[208:211], v[2:5]
	v_mfma_f32_16x16x32_bf16 v[90:93], v[170:173], v[188:191], v[90:93]
	v_mfma_f32_16x16x32_bf16 v[82:85], v[178:181], v[188:191], v[82:85]
	v_mfma_f32_16x16x32_bf16 v[62:65], v[170:173], v[196:199], v[62:65]
	v_mfma_f32_16x16x32_bf16 v[58:61], v[178:181], v[196:199], v[58:61]
	v_mfma_f32_16x16x32_bf16 v[26:29], v[170:173], v[204:207], v[26:29]
	v_mfma_f32_16x16x32_bf16 v[22:25], v[178:181], v[204:207], v[22:25]
	v_mfma_f32_16x16x32_bf16 v[6:9], v[170:173], v[212:215], v[6:9]
	v_mfma_f32_16x16x32_bf16 v[2:5], v[178:181], v[212:215], v[2:5]
	s_setprio 0
	s_barrier
	s_add_i32 s60, 0, 0x18000
	s_add_i32 s61, 0, 0x1c000
	v_add_u32_e32 v162, s60, v148
	v_add_u32_e32 v178, s61, v148
	ds_read_b128 v[150:153], v162
	ds_read_b128 v[154:157], v162 offset:1024
	ds_read_b128 v[158:161], v162 offset:2048
	ds_read_b128 v[162:165], v162 offset:3072
	ds_read_b128 v[166:169], v178
	ds_read_b128 v[170:173], v178 offset:1024
	ds_read_b128 v[174:177], v178 offset:2048
	ds_read_b128 v[178:181], v178 offset:3072
	s_add_u32 s28, s28, 0xb0000
	s_addc_u32 s29, s29, 0
	s_mov_b32 m0, s42
	v_lshl_add_u64 v[224:225], s[28:29], 0, v[130:131]
	ds_read_b128 v[182:185], v149 offset:32768
	ds_read_b128 v[188:191], v149 offset:33792
	ds_read_b128 v[192:195], v149 offset:34816
	ds_read_b128 v[196:199], v149 offset:35840
	ds_read_b128 v[200:203], v149 offset:36864
	ds_read_b128 v[204:207], v149 offset:37888
	ds_read_b128 v[208:211], v149 offset:38912
	ds_read_b128 v[212:215], v149 offset:39936
	global_load_lds_dwordx4 v[224:225], off
	v_lshl_add_u64 v[224:225], s[28:29], 0, v[132:133]
	s_mov_b32 m0, s43
	s_nop 0
	global_load_lds_dwordx4 v[224:225], off
	s_waitcnt vmcnt(8)
	s_waitcnt lgkmcnt(0)
	s_barrier
	s_setprio 1
	s_waitcnt lgkmcnt(0)
	v_mfma_f32_16x16x32_bf16 v[106:109], v[150:153], v[182:185], v[106:109]
	v_mfma_f32_16x16x32_bf16 v[66:69], v[158:161], v[182:185], v[66:69]
	v_mfma_f32_16x16x32_bf16 v[114:117], v[150:153], v[192:195], v[114:117]
	v_mfma_f32_16x16x32_bf16 v[86:89], v[158:161], v[192:195], v[86:89]
	v_mfma_f32_16x16x32_bf16 v[126:129], v[150:153], v[200:203], v[126:129]
	v_mfma_f32_16x16x32_bf16 v[110:113], v[158:161], v[200:203], v[110:113]
	v_mfma_f32_16x16x32_bf16 v[122:125], v[150:153], v[208:211], v[122:125]
	v_mfma_f32_16x16x32_bf16 v[118:121], v[158:161], v[208:211], v[118:121]
	v_mfma_f32_16x16x32_bf16 v[106:109], v[154:157], v[188:191], v[106:109]
	v_mfma_f32_16x16x32_bf16 v[66:69], v[162:165], v[188:191], v[66:69]
	v_mfma_f32_16x16x32_bf16 v[114:117], v[154:157], v[196:199], v[114:117]
	v_mfma_f32_16x16x32_bf16 v[86:89], v[162:165], v[196:199], v[86:89]
	v_mfma_f32_16x16x32_bf16 v[126:129], v[154:157], v[204:207], v[126:129]
	v_mfma_f32_16x16x32_bf16 v[110:113], v[162:165], v[204:207], v[110:113]
	v_mfma_f32_16x16x32_bf16 v[122:125], v[154:157], v[212:215], v[122:125]
	v_mfma_f32_16x16x32_bf16 v[118:121], v[162:165], v[212:215], v[118:121]
	s_setprio 0
	s_setprio 1
	v_mfma_f32_16x16x32_bf16 v[42:45], v[166:169], v[182:185], v[42:45]
	v_mfma_f32_16x16x32_bf16 v[18:21], v[174:177], v[182:185], v[18:21]
	v_mfma_f32_16x16x32_bf16 v[50:53], v[166:169], v[192:195], v[50:53]
	v_mfma_f32_16x16x32_bf16 v[30:33], v[174:177], v[192:195], v[30:33]
	v_mfma_f32_16x16x32_bf16 v[70:73], v[166:169], v[200:203], v[70:73]
	v_mfma_f32_16x16x32_bf16 v[46:49], v[174:177], v[200:203], v[46:49]
	v_mfma_f32_16x16x32_bf16 v[94:97], v[166:169], v[208:211], v[94:97]
	v_mfma_f32_16x16x32_bf16 v[54:57], v[174:177], v[208:211], v[54:57]
	v_mfma_f32_16x16x32_bf16 v[42:45], v[170:173], v[188:191], v[42:45]
	v_mfma_f32_16x16x32_bf16 v[18:21], v[178:181], v[188:191], v[18:21]
	v_mfma_f32_16x16x32_bf16 v[50:53], v[170:173], v[196:199], v[50:53]
	v_mfma_f32_16x16x32_bf16 v[30:33], v[178:181], v[196:199], v[30:33]
	v_mfma_f32_16x16x32_bf16 v[70:73], v[170:173], v[204:207], v[70:73]
	v_mfma_f32_16x16x32_bf16 v[46:49], v[178:181], v[204:207], v[46:49]
	v_mfma_f32_16x16x32_bf16 v[94:97], v[170:173], v[212:215], v[94:97]
	v_mfma_f32_16x16x32_bf16 v[54:57], v[178:181], v[212:215], v[54:57]
	s_setprio 0
	s_barrier
; #define PG8_STAGE(bufoff, gbase, voff) do { _Pragma("unroll") for (int _i = 0; _i < 2; ++_i) \
;         __builtin_amdgcn_global_load_lds((const unsigned*)((const char*)(gbase) + (voff)[_i]), (PG8_LAS unsigned*)(lds + (bufoff) + ldsw + _i * 8192), 16, 0, 0); } while (0)
; #define PG8_LDA(dst, b, h) do { _Pragma("unroll") for (int m = 0; m < 4; ++m) _Pragma("unroll") for (int k = 0; k < 2; ++k) dst[m][k] = *(const PG8_LAS bf16x8*)(lds + PG8_SA(b, h) + aoff + m * 2048 + k * 1024); } while (0)
; #define PG8_MMA(ai, bj, At, Bt) do { __builtin_amdgcn_s_setprio(1); _Pragma("unroll") for (int m = 0; m < 4; ++m) _Pragma("unroll") for (int n = 0; n < 2; ++n) _Pragma("unroll") for (int k = 0; k < 2; ++k) \
;         acc[ai][bj][m][n] = __builtin_amdgcn_mfma_f32_16x16x32_bf16(Bt[n][k], At[m][k], acc[ai][bj][m][n], 0, 0, 0); __builtin_amdgcn_s_setprio(0); } while (0)
; #define PG8_WAIT_V(n) asm volatile("s_waitcnt vmcnt(" #n ")" ::: "memory")
; #define PG8_WAIT_L(n) asm volatile("s_waitcnt lgkmcnt(" #n ")" ::: "memory")
; #define PG8_BAR __builtin_amdgcn_s_barrier()
; #define PG8_SCHED __builtin_amdgcn_sched_barrier(0)
; template <class Epi, class Sched, bool ALIGN_EPI = false, bool SP2 = false>
; __device__ __forceinline__ void gemm_phase(PG8_LAS unsigned char* lds, const Gemm g, const Sched& S, const Epi& E) {
;     ...
;             PG8_LDA(At, 1, 1); PG8_STAGE(PG8_SB(1, 0), b3, voffB); PG8_STAGE(PG8_SB(1, 1), b3 + hstep, voffB); PG8_STAGE(PG8_SA(1, 0), a3, voffA);
;             PG8_WAIT_V(8); PG8_WAIT_L(0); PG8_BAR; PG8_MMA(1, 0, At, B0); PG8_MMA(1, 1, At, B1); PG8_BAR; PG8_SCHED;
;     ...
; #pragma unroll
;         for (int a = 0; a < 2; ++a)
; #pragma unroll
;             for (int b = 0; b < 2; ++b)
; #pragma unroll
;                 for (int m = 0; m < 4; ++m)
; #pragma unroll
;                     for (int n = 0; n < 2; ++n) acc[a][b][m][n] = (f32x4){0.f, 0.f, 0.f, 0.f};
	s_add_i32 s28, s60, s39
	v_lshl_add_u64 v[216:217], v[216:217], 0, s[20:21]
	s_mov_b32 m0, s28
	ds_read_b128 v[182:185], v149 offset:49152
	ds_read_b128 v[188:191], v149 offset:50176
	ds_read_b128 v[192:195], v149 offset:51200
	ds_read_b128 v[196:199], v149 offset:52224
	ds_read_b128 v[200:203], v149 offset:53248
	ds_read_b128 v[204:207], v149 offset:54272
	ds_read_b128 v[208:211], v149 offset:55296
	ds_read_b128 v[212:215], v149 offset:56320
	global_load_lds_dwordx4 v[216:217], off
	s_add_i32 m0, s28, 0x2000
	s_add_u32 s26, s26, 0xb0080
	v_lshl_add_u64 v[216:217], v[218:219], 0, s[20:21]
	s_addc_u32 s27, s27, 0
	s_add_i32 s28, s61, s39
	global_load_lds_dwordx4 v[216:217], off
	v_lshl_add_u64 v[216:217], s[26:27], 0, v[130:131]
	s_mov_b32 m0, s28
	s_nop 0
	global_load_lds_dwordx4 v[216:217], off
	v_lshl_add_u64 v[216:217], s[26:27], 0, v[132:133]
	s_add_i32 m0, s28, 0x2000
	s_nop 0
	global_load_lds_dwordx4 v[216:217], off
	v_lshl_add_u64 v[216:217], v[220:221], 0, s[20:21]
	s_mov_b32 m0, s50
	s_nop 0
	global_load_lds_dwordx4 v[216:217], off
	v_lshl_add_u64 v[216:217], v[222:223], 0, s[20:21]
	s_mov_b32 m0, s51
	s_nop 0
	global_load_lds_dwordx4 v[216:217], off
	s_waitcnt vmcnt(8)
	s_waitcnt lgkmcnt(0)
	s_barrier
	s_setprio 1
	s_waitcnt lgkmcnt(0)
	v_mfma_f32_16x16x32_bf16 v[102:105], v[150:153], v[182:185], v[102:105]
	v_mfma_f32_16x16x32_bf16 v[98:101], v[158:161], v[182:185], v[98:101]
	v_mfma_f32_16x16x32_bf16 v[78:81], v[150:153], v[192:195], v[78:81]
	v_mfma_f32_16x16x32_bf16 v[74:77], v[158:161], v[192:195], v[74:77]
	v_mfma_f32_16x16x32_bf16 v[38:41], v[150:153], v[200:203], v[38:41]
	v_mfma_f32_16x16x32_bf16 v[34:37], v[158:161], v[200:203], v[34:37]
	v_mfma_f32_16x16x32_bf16 v[14:17], v[150:153], v[208:211], v[14:17]
	v_mfma_f32_16x16x32_bf16 v[10:13], v[158:161], v[208:211], v[10:13]
	v_mfma_f32_16x16x32_bf16 v[102:105], v[154:157], v[188:191], v[102:105]
	v_mfma_f32_16x16x32_bf16 v[98:101], v[162:165], v[188:191], v[98:101]
	v_mfma_f32_16x16x32_bf16 v[78:81], v[154:157], v[196:199], v[78:81]
	v_mfma_f32_16x16x32_bf16 v[74:77], v[162:165], v[196:199], v[74:77]
	v_mfma_f32_16x16x32_bf16 v[38:41], v[154:157], v[204:207], v[38:41]
	v_mfma_f32_16x16x32_bf16 v[34:37], v[162:165], v[204:207], v[34:37]
	v_mfma_f32_16x16x32_bf16 v[14:17], v[154:157], v[212:215], v[14:17]
	v_mfma_f32_16x16x32_bf16 v[10:13], v[162:165], v[212:215], v[10:13]
	s_setprio 0
	s_setprio 1
	v_mfma_f32_16x16x32_bf16 v[90:93], v[166:169], v[182:185], v[90:93]
	v_mfma_f32_16x16x32_bf16 v[82:85], v[174:177], v[182:185], v[82:85]
	v_mfma_f32_16x16x32_bf16 v[62:65], v[166:169], v[192:195], v[62:65]
	v_mfma_f32_16x16x32_bf16 v[58:61], v[174:177], v[192:195], v[58:61]
	v_mfma_f32_16x16x32_bf16 v[26:29], v[166:169], v[200:203], v[26:29]
	v_mfma_f32_16x16x32_bf16 v[22:25], v[174:177], v[200:203], v[22:25]
	v_mfma_f32_16x16x32_bf16 v[6:9], v[166:169], v[208:211], v[6:9]
	v_mfma_f32_16x16x32_bf16 v[2:5], v[174:177], v[208:211], v[2:5]
	v_mfma_f32_16x16x32_bf16 v[90:93], v[170:173], v[188:191], v[90:93]
	v_mfma_f32_16x16x32_bf16 v[82:85], v[178:181], v[188:191], v[82:85]
	v_mfma_f32_16x16x32_bf16 v[62:65], v[170:173], v[196:199], v[62:65]
	v_mfma_f32_16x16x32_bf16 v[58:61], v[178:181], v[196:199], v[58:61]
	v_mfma_f32_16x16x32_bf16 v[26:29], v[170:173], v[204:207], v[26:29]
	v_mfma_f32_16x16x32_bf16 v[22:25], v[178:181], v[204:207], v[22:25]
	v_mfma_f32_16x16x32_bf16 v[6:9], v[170:173], v[212:215], v[6:9]
	v_mfma_f32_16x16x32_bf16 v[2:5], v[178:181], v[212:215], v[2:5]
	s_setprio 0
	s_add_i32 s59, s59, 2
	s_add_u32 s24, s24, 0x100
	s_addc_u32 s25, s25, 0
	s_cmp_gt_u32 s59, 41
	s_barrier
	s_cbranch_scc0 .LBB0_319
	s_add_u32 s24, s57, 0xffffff00
	s_addc_u32 s25, s58, -1
	s_and_b64 vcc, exec, s[6:7]
	s_cbranch_vccnz .LBB0_322
	v_mov_b32_e32 v2, 0
	s_mov_b32 s16, s54
	s_mov_b32 s31, s55
	s_mov_b64 s[18:19], s[22:23]
	s_mov_b32 s49, s56
	v_mov_b32_e32 v3, v2
	v_mov_b32_e32 v4, v2
	v_mov_b32_e32 v5, v2
	v_mov_b32_e32 v6, v2
	v_mov_b32_e32 v7, v2
	v_mov_b32_e32 v8, v2
	v_mov_b32_e32 v9, v2
	v_mov_b32_e32 v22, v2
	v_mov_b32_e32 v23, v2
	v_mov_b32_e32 v24, v2
	v_mov_b32_e32 v25, v2
	v_mov_b32_e32 v26, v2
	v_mov_b32_e32 v27, v2
	v_mov_b32_e32 v28, v2
	v_mov_b32_e32 v29, v2
	v_mov_b32_e32 v58, v2
	v_mov_b32_e32 v59, v2
	v_mov_b32_e32 v60, v2
	v_mov_b32_e32 v61, v2
	v_mov_b32_e32 v62, v2
	v_mov_b32_e32 v63, v2
	v_mov_b32_e32 v64, v2
	v_mov_b32_e32 v65, v2
	v_mov_b32_e32 v82, v2
	v_mov_b32_e32 v83, v2
	v_mov_b32_e32 v84, v2
	v_mov_b32_e32 v85, v2
	v_mov_b32_e32 v90, v2
	v_mov_b32_e32 v91, v2
	v_mov_b32_e32 v92, v2
	v_mov_b32_e32 v93, v2
	v_mov_b32_e32 v10, v2
	v_mov_b32_e32 v11, v2
	v_mov_b32_e32 v12, v2
	v_mov_b32_e32 v13, v2
	v_mov_b32_e32 v14, v2
	v_mov_b32_e32 v15, v2
	v_mov_b32_e32 v16, v2
	v_mov_b32_e32 v17, v2
	v_mov_b32_e32 v34, v2
	v_mov_b32_e32 v35, v2
	v_mov_b32_e32 v36, v2
	v_mov_b32_e32 v37, v2
	v_mov_b32_e32 v38, v2
	v_mov_b32_e32 v39, v2
	v_mov_b32_e32 v40, v2
	v_mov_b32_e32 v41, v2
	v_mov_b32_e32 v74, v2
	v_mov_b32_e32 v75, v2
	v_mov_b32_e32 v76, v2
	v_mov_b32_e32 v77, v2
	v_mov_b32_e32 v78, v2
	v_mov_b32_e32 v79, v2
	v_mov_b32_e32 v80, v2
	v_mov_b32_e32 v81, v2
	v_mov_b32_e32 v98, v2
	v_mov_b32_e32 v99, v2
	v_mov_b32_e32 v100, v2
	v_mov_b32_e32 v101, v2
	v_mov_b32_e32 v102, v2
	v_mov_b32_e32 v103, v2
	v_mov_b32_e32 v104, v2
	v_mov_b32_e32 v105, v2
	v_mov_b32_e32 v54, v2
	v_mov_b32_e32 v55, v2
	v_mov_b32_e32 v56, v2
	v_mov_b32_e32 v57, v2
	v_mov_b32_e32 v94, v2
	v_mov_b32_e32 v95, v2
	v_mov_b32_e32 v96, v2
	v_mov_b32_e32 v97, v2
	v_mov_b32_e32 v46, v2
	v_mov_b32_e32 v47, v2
	v_mov_b32_e32 v48, v2
	v_mov_b32_e32 v49, v2
	v_mov_b32_e32 v70, v2
	v_mov_b32_e32 v71, v2
	v_mov_b32_e32 v72, v2
	v_mov_b32_e32 v73, v2
	v_mov_b32_e32 v30, v2
	v_mov_b32_e32 v31, v2
	v_mov_b32_e32 v32, v2
	v_mov_b32_e32 v33, v2
	v_mov_b32_e32 v50, v2
	v_mov_b32_e32 v51, v2
	v_mov_b32_e32 v52, v2
	v_mov_b32_e32 v53, v2
	v_mov_b32_e32 v18, v2
	v_mov_b32_e32 v19, v2
	v_mov_b32_e32 v20, v2
	v_mov_b32_e32 v21, v2
	v_mov_b32_e32 v42, v2
	v_mov_b32_e32 v43, v2
	v_mov_b32_e32 v44, v2
	v_mov_b32_e32 v45, v2
	v_mov_b32_e32 v118, v2
	v_mov_b32_e32 v119, v2
	v_mov_b32_e32 v120, v2
	v_mov_b32_e32 v121, v2
	v_mov_b32_e32 v122, v2
	v_mov_b32_e32 v123, v2
	v_mov_b32_e32 v124, v2
	v_mov_b32_e32 v125, v2
	v_mov_b32_e32 v110, v2
	v_mov_b32_e32 v111, v2
	v_mov_b32_e32 v112, v2
	v_mov_b32_e32 v113, v2
	v_mov_b32_e32 v126, v2
	v_mov_b32_e32 v127, v2
	v_mov_b32_e32 v128, v2
	v_mov_b32_e32 v129, v2
	v_mov_b32_e32 v86, v2
	v_mov_b32_e32 v87, v2
	v_mov_b32_e32 v88, v2
	v_mov_b32_e32 v89, v2
	v_mov_b32_e32 v114, v2
	v_mov_b32_e32 v115, v2
	v_mov_b32_e32 v116, v2
	v_mov_b32_e32 v117, v2
	v_mov_b32_e32 v66, v2
	v_mov_b32_e32 v67, v2
	v_mov_b32_e32 v68, v2
	v_mov_b32_e32 v69, v2
	v_mov_b32_e32 v106, v2
	v_mov_b32_e32 v107, v2
	v_mov_b32_e32 v108, v2
	v_mov_b32_e32 v109, v2
	s_andn2_b64 vcc, exec, s[4:5]
	s_cbranch_vccnz .LBB0_323
	s_branch .LBB0_324

; #define PG8_STAGE(bufoff, gbase, voff) do { _Pragma("unroll") for (int _i = 0; _i < 2; ++_i) \
;         __builtin_amdgcn_global_load_lds((const unsigned*)((const char*)(gbase) + (voff)[_i]), (PG8_LAS unsigned*)(lds + (bufoff) + ldsw + _i * 8192), 16, 0, 0); } while (0)
; #define PG8_LDA(dst, b, h) do { _Pragma("unroll") for (int m = 0; m < 4; ++m) _Pragma("unroll") for (int k = 0; k < 2; ++k) dst[m][k] = *(const PG8_LAS bf16x8*)(lds + PG8_SA(b, h) + aoff + m * 2048 + k * 1024); } while (0)
; #define PG8_LDB(dst, b, h) do { _Pragma("unroll") for (int n = 0; n < 2; ++n) _Pragma("unroll") for (int k = 0; k < 2; ++k) dst[n][k] = *(const PG8_LAS bf16x8*)(lds + PG8_SB(b, h) + boff + n * 2048 + k * 1024); } while (0)
; #define PG8_MMA(ai, bj, At, Bt) do { __builtin_amdgcn_s_setprio(1); _Pragma("unroll") for (int m = 0; m < 4; ++m) _Pragma("unroll") for (int n = 0; n < 2; ++n) _Pragma("unroll") for (int k = 0; k < 2; ++k) \
;         acc[ai][bj][m][n] = __builtin_amdgcn_mfma_f32_16x16x32_bf16(Bt[n][k], At[m][k], acc[ai][bj][m][n], 0, 0, 0); __builtin_amdgcn_s_setprio(0); } while (0)
; #define PG8_WAIT_V(n) asm volatile("s_waitcnt vmcnt(" #n ")" ::: "memory")
; #define PG8_WAIT_L(n) asm volatile("s_waitcnt lgkmcnt(" #n ")" ::: "memory")
; #define PG8_BAR __builtin_amdgcn_s_barrier()
; #define PG8_SCHED __builtin_amdgcn_sched_barrier(0)
; template <class Epi, class Sched, bool ALIGN_EPI = false, bool SP2 = false>
; __device__ __forceinline__ void gemm_phase(PG8_LAS unsigned char* lds, const Gemm g, const Sched& S, const Epi& E) {
;     ...
;         for (int t = 0; t < nt; t += 2) {
;             const bool last = (t == nt - 2);
;             const char* a1 = cA + (size_t)(t + 1) * kstep;
;             const char* a2 = last ? nA : cA + (size_t)(t + 2) * kstep; const char* b2 = last ? nB : cB + (size_t)(t + 2) * kstep;
;             const char* a3 = a2 + kstep; const char* b3 = b2 + kstep;
;             if (last && has_next) S.a_ready(nxt);
;             if constexpr (SP2) {
;             PG8_LDB(B0, 0, 0); PG8_LDB(B1, 0, 1); PG8_SCHED; PG8_LDA(At, 0, 0); PG8_STAGE(PG8_SA(1, 1), a1 + hstep, voffA);
;             PG8_WAIT_V(8); PG8_WAIT_L(0); PG8_BAR; PG8_MMA(0, 0, At, B0); PG8_MMA(0, 1, At, B1); PG8_BAR; PG8_SCHED;
;             PG8_LDA(At, 0, 1); PG8_STAGE(PG8_SB(0, 0), b2, voffB); PG8_STAGE(PG8_SB(0, 1), b2 + hstep, voffB); PG8_STAGE(PG8_SA(0, 0), a2, voffA);
.LBB0_457:
	ds_read_b128 v[148:151], v144
	ds_read_b128 v[152:155], v144 offset:1024
	ds_read_b128 v[156:159], v144 offset:2048
	ds_read_b128 v[160:163], v144 offset:3072
	ds_read_b128 v[164:167], v145
	ds_read_b128 v[168:171], v145 offset:1024
	ds_read_b128 v[172:175], v145 offset:2048
	ds_read_b128 v[176:179], v145 offset:3072
	s_add_u32 s24, s22, 0x100
	s_addc_u32 s25, s23, 0
	s_cmp_eq_u32 s53, 12
	s_cselect_b32 s29, s15, s25
	s_cselect_b32 s28, s49, s24
	s_cselect_b32 s27, s13, s52
	s_cselect_b32 s26, s50, s51
	v_lshl_add_u64 v[184:185], s[22:23], 0, v[134:135]
	s_add_i32 m0, s21, 0xc000
	ds_read_b128 v[180:183], v146
	ds_read_b128 v[188:191], v146 offset:1024
	ds_read_b128 v[192:195], v146 offset:2048
	ds_read_b128 v[196:199], v146 offset:3072
	ds_read_b128 v[200:203], v146 offset:4096
	ds_read_b128 v[204:207], v146 offset:5120
	ds_read_b128 v[208:211], v146 offset:6144
	ds_read_b128 v[212:215], v146 offset:7168
	global_load_lds_dwordx4 v[184:185], off
	v_lshl_add_u64 v[184:185], s[22:23], 0, v[136:137]
	s_add_i32 m0, s21, 0xe000
	s_nop 0
	global_load_lds_dwordx4 v[184:185], off
	s_waitcnt vmcnt(8)
	s_waitcnt lgkmcnt(0)
	s_barrier
	s_setprio 1
	s_waitcnt lgkmcnt(0)
	v_mfma_f32_16x16x32_bf16 v[126:129], v[148:151], v[180:183], v[126:129]
	v_mfma_f32_16x16x32_bf16 v[122:125], v[156:159], v[180:183], v[122:125]
	v_mfma_f32_16x16x32_bf16 v[118:121], v[148:151], v[192:195], v[118:121]
	v_mfma_f32_16x16x32_bf16 v[110:113], v[156:159], v[192:195], v[110:113]
	v_mfma_f32_16x16x32_bf16 v[102:105], v[148:151], v[200:203], v[102:105]
	v_mfma_f32_16x16x32_bf16 v[94:97], v[156:159], v[200:203], v[94:97]
	v_mfma_f32_16x16x32_bf16 v[86:89], v[148:151], v[208:211], v[86:89]
	v_mfma_f32_16x16x32_bf16 v[78:81], v[156:159], v[208:211], v[78:81]
	v_mfma_f32_16x16x32_bf16 v[126:129], v[152:155], v[188:191], v[126:129]
	v_mfma_f32_16x16x32_bf16 v[122:125], v[160:163], v[188:191], v[122:125]
	v_mfma_f32_16x16x32_bf16 v[118:121], v[152:155], v[196:199], v[118:121]
	v_mfma_f32_16x16x32_bf16 v[110:113], v[160:163], v[196:199], v[110:113]
	v_mfma_f32_16x16x32_bf16 v[102:105], v[152:155], v[204:207], v[102:105]
	v_mfma_f32_16x16x32_bf16 v[94:97], v[160:163], v[204:207], v[94:97]
	v_mfma_f32_16x16x32_bf16 v[86:89], v[152:155], v[212:215], v[86:89]
	v_mfma_f32_16x16x32_bf16 v[78:81], v[160:163], v[212:215], v[78:81]
	s_setprio 0
	s_setprio 1
	v_mfma_f32_16x16x32_bf16 v[114:117], v[164:167], v[180:183], v[114:117]
	v_mfma_f32_16x16x32_bf16 v[106:109], v[172:175], v[180:183], v[106:109]
	v_mfma_f32_16x16x32_bf16 v[98:101], v[164:167], v[192:195], v[98:101]
	v_mfma_f32_16x16x32_bf16 v[90:93], v[172:175], v[192:195], v[90:93]
	v_mfma_f32_16x16x32_bf16 v[82:85], v[164:167], v[200:203], v[82:85]
	v_mfma_f32_16x16x32_bf16 v[74:77], v[172:175], v[200:203], v[74:77]
	v_mfma_f32_16x16x32_bf16 v[70:73], v[164:167], v[208:211], v[70:73]
	v_mfma_f32_16x16x32_bf16 v[66:69], v[172:175], v[208:211], v[66:69]
	v_mfma_f32_16x16x32_bf16 v[114:117], v[168:171], v[188:191], v[114:117]
	v_mfma_f32_16x16x32_bf16 v[106:109], v[176:179], v[188:191], v[106:109]
	v_mfma_f32_16x16x32_bf16 v[98:101], v[168:171], v[196:199], v[98:101]
	v_mfma_f32_16x16x32_bf16 v[90:93], v[176:179], v[196:199], v[90:93]
	v_mfma_f32_16x16x32_bf16 v[82:85], v[168:171], v[204:207], v[82:85]
	v_mfma_f32_16x16x32_bf16 v[74:77], v[176:179], v[204:207], v[74:77]
	v_mfma_f32_16x16x32_bf16 v[70:73], v[168:171], v[212:215], v[70:73]
	v_mfma_f32_16x16x32_bf16 v[66:69], v[176:179], v[212:215], v[66:69]
	s_setprio 0
	s_barrier
	s_add_i32 s22, s41, s31
	v_lshl_add_u64 v[184:185], s[26:27], 0, v[130:131]
	s_mov_b32 m0, s22
	ds_read_b128 v[180:183], v146 offset:16384
	ds_read_b128 v[188:191], v146 offset:17408
	ds_read_b128 v[192:195], v146 offset:18432
	ds_read_b128 v[196:199], v146 offset:19456
	ds_read_b128 v[200:203], v146 offset:20480
	ds_read_b128 v[204:207], v146 offset:21504
	ds_read_b128 v[208:211], v146 offset:22528
	ds_read_b128 v[212:215], v146 offset:23552
	global_load_lds_dwordx4 v[184:185], off
	s_add_i32 m0, s22, 0x2000
	s_add_u32 s22, s26, 0x40000
	v_lshl_add_u64 v[216:217], s[26:27], 0, v[132:133]
	s_addc_u32 s23, s27, 0
	s_add_i32 s54, s42, s31
	global_load_lds_dwordx4 v[216:217], off
	v_lshl_add_u64 v[218:219], s[22:23], 0, v[130:131]
	s_mov_b32 m0, s54
	v_lshl_add_u64 v[220:221], s[28:29], 0, v[132:133]
	global_load_lds_dwordx4 v[218:219], off
	v_lshl_add_u64 v[218:219], s[22:23], 0, v[132:133]
	s_add_i32 m0, s54, 0x2000
	s_nop 0
	global_load_lds_dwordx4 v[218:219], off
	v_lshl_add_u64 v[218:219], s[28:29], 0, v[130:131]
	s_mov_b32 m0, s21
	s_nop 0
	global_load_lds_dwordx4 v[218:219], off
	s_mov_b32 m0, s34
	s_nop 0
	global_load_lds_dwordx4 v[220:221], off
	s_waitcnt vmcnt(8)
	s_waitcnt lgkmcnt(0)
	s_barrier
; #define PG8_STAGE(bufoff, gbase, voff) do { _Pragma("unroll") for (int _i = 0; _i < 2; ++_i) \
;         __builtin_amdgcn_global_load_lds((const unsigned*)((const char*)(gbase) + (voff)[_i]), (PG8_LAS unsigned*)(lds + (bufoff) + ldsw + _i * 8192), 16, 0, 0); } while (0)
; #define PG8_LDA(dst, b, h) do { _Pragma("unroll") for (int m = 0; m < 4; ++m) _Pragma("unroll") for (int k = 0; k < 2; ++k) dst[m][k] = *(const PG8_LAS bf16x8*)(lds + PG8_SA(b, h) + aoff + m * 2048 + k * 1024); } while (0)
; #define PG8_LDB(dst, b, h) do { _Pragma("unroll") for (int n = 0; n < 2; ++n) _Pragma("unroll") for (int k = 0; k < 2; ++k) dst[n][k] = *(const PG8_LAS bf16x8*)(lds + PG8_SB(b, h) + boff + n * 2048 + k * 1024); } while (0)
; #define PG8_MMA(ai, bj, At, Bt) do { __builtin_amdgcn_s_setprio(1); _Pragma("unroll") for (int m = 0; m < 4; ++m) _Pragma("unroll") for (int n = 0; n < 2; ++n) _Pragma("unroll") for (int k = 0; k < 2; ++k) \
;         acc[ai][bj][m][n] = __builtin_amdgcn_mfma_f32_16x16x32_bf16(Bt[n][k], At[m][k], acc[ai][bj][m][n], 0, 0, 0); __builtin_amdgcn_s_setprio(0); } while (0)
; #define PG8_WAIT_V(n) asm volatile("s_waitcnt vmcnt(" #n ")" ::: "memory")
; #define PG8_WAIT_L(n) asm volatile("s_waitcnt lgkmcnt(" #n ")" ::: "memory")
; #define PG8_BAR __builtin_amdgcn_s_barrier()
; #define PG8_SCHED __builtin_amdgcn_sched_barrier(0)
; template <class Epi, class Sched, bool ALIGN_EPI = false, bool SP2 = false>
; __device__ __forceinline__ void gemm_phase(PG8_LAS unsigned char* lds, const Gemm g, const Sched& S, const Epi& E) {
;     ...
;             PG8_WAIT_V(8); PG8_WAIT_L(0); PG8_BAR; PG8_MMA(1, 0, At, B0); PG8_MMA(1, 1, At, B1); PG8_BAR; PG8_SCHED;
;             PG8_LDB(B0, 1, 0); PG8_LDB(B1, 1, 1); PG8_SCHED; PG8_LDA(At, 1, 0); PG8_STAGE(PG8_SA(0, 1), a2 + hstep, voffA);
;             PG8_WAIT_V(8); PG8_WAIT_L(0); PG8_BAR; PG8_MMA(0, 0, At, B0); PG8_MMA(0, 1, At, B1); PG8_BAR; PG8_SCHED;
	s_setprio 1
	s_waitcnt lgkmcnt(0)
	v_mfma_f32_16x16x32_bf16 v[62:65], v[148:151], v[180:183], v[62:65]
	v_mfma_f32_16x16x32_bf16 v[58:61], v[156:159], v[180:183], v[58:61]
	v_mfma_f32_16x16x32_bf16 v[54:57], v[148:151], v[192:195], v[54:57]
	v_mfma_f32_16x16x32_bf16 v[46:49], v[156:159], v[192:195], v[46:49]
	v_mfma_f32_16x16x32_bf16 v[38:41], v[148:151], v[200:203], v[38:41]
	v_mfma_f32_16x16x32_bf16 v[30:33], v[156:159], v[200:203], v[30:33]
	v_mfma_f32_16x16x32_bf16 v[22:25], v[148:151], v[208:211], v[22:25]
	v_mfma_f32_16x16x32_bf16 v[14:17], v[156:159], v[208:211], v[14:17]
	v_mfma_f32_16x16x32_bf16 v[62:65], v[152:155], v[188:191], v[62:65]
	v_mfma_f32_16x16x32_bf16 v[58:61], v[160:163], v[188:191], v[58:61]
	v_mfma_f32_16x16x32_bf16 v[54:57], v[152:155], v[196:199], v[54:57]
	v_mfma_f32_16x16x32_bf16 v[46:49], v[160:163], v[196:199], v[46:49]
	v_mfma_f32_16x16x32_bf16 v[38:41], v[152:155], v[204:207], v[38:41]
	v_mfma_f32_16x16x32_bf16 v[30:33], v[160:163], v[204:207], v[30:33]
	v_mfma_f32_16x16x32_bf16 v[22:25], v[152:155], v[212:215], v[22:25]
	v_mfma_f32_16x16x32_bf16 v[14:17], v[160:163], v[212:215], v[14:17]
	s_setprio 0
	s_setprio 1
	v_mfma_f32_16x16x32_bf16 v[50:53], v[164:167], v[180:183], v[50:53]
	v_mfma_f32_16x16x32_bf16 v[42:45], v[172:175], v[180:183], v[42:45]
	v_mfma_f32_16x16x32_bf16 v[34:37], v[164:167], v[192:195], v[34:37]
	v_mfma_f32_16x16x32_bf16 v[26:29], v[172:175], v[192:195], v[26:29]
	v_mfma_f32_16x16x32_bf16 v[18:21], v[164:167], v[200:203], v[18:21]
	v_mfma_f32_16x16x32_bf16 v[10:13], v[172:175], v[200:203], v[10:13]
	v_mfma_f32_16x16x32_bf16 v[6:9], v[164:167], v[208:211], v[6:9]
	v_mfma_f32_16x16x32_bf16 v[2:5], v[172:175], v[208:211], v[2:5]
	v_mfma_f32_16x16x32_bf16 v[50:53], v[168:171], v[188:191], v[50:53]
	v_mfma_f32_16x16x32_bf16 v[42:45], v[176:179], v[188:191], v[42:45]
	v_mfma_f32_16x16x32_bf16 v[34:37], v[168:171], v[196:199], v[34:37]
	v_mfma_f32_16x16x32_bf16 v[26:29], v[176:179], v[196:199], v[26:29]
	v_mfma_f32_16x16x32_bf16 v[18:21], v[168:171], v[204:207], v[18:21]
	v_mfma_f32_16x16x32_bf16 v[10:13], v[176:179], v[204:207], v[10:13]
	v_mfma_f32_16x16x32_bf16 v[6:9], v[168:171], v[212:215], v[6:9]
	v_mfma_f32_16x16x32_bf16 v[2:5], v[176:179], v[212:215], v[2:5]
	s_setprio 0
	s_barrier
	s_add_i32 s54, 0, 0x18000
	v_add_u32_e32 v147, s54, v142
	s_add_i32 s55, 0, 0x1c000
	ds_read_b128 v[148:151], v147
	ds_read_b128 v[152:155], v147 offset:1024
	ds_read_b128 v[156:159], v147 offset:2048
	ds_read_b128 v[160:163], v147 offset:3072
	v_add_u32_e32 v147, s55, v142
	ds_read_b128 v[164:167], v147
	ds_read_b128 v[168:171], v147 offset:1024
	ds_read_b128 v[172:175], v147 offset:2048
	ds_read_b128 v[176:179], v147 offset:3072
	s_add_u32 s22, s28, 0x40000
	s_addc_u32 s23, s29, 0
	s_mov_b32 m0, s35
	v_lshl_add_u64 v[222:223], s[22:23], 0, v[130:131]
	ds_read_b128 v[180:183], v146 offset:32768
	ds_read_b128 v[188:191], v146 offset:33792
	ds_read_b128 v[192:195], v146 offset:34816
	ds_read_b128 v[196:199], v146 offset:35840
	ds_read_b128 v[200:203], v146 offset:36864
	ds_read_b128 v[204:207], v146 offset:37888
	ds_read_b128 v[208:211], v146 offset:38912
	ds_read_b128 v[212:215], v146 offset:39936
	global_load_lds_dwordx4 v[222:223], off
	v_lshl_add_u64 v[222:223], s[22:23], 0, v[132:133]
	s_mov_b32 m0, s36
	s_nop 0
	global_load_lds_dwordx4 v[222:223], off
	s_waitcnt vmcnt(8)
	s_waitcnt lgkmcnt(0)
	s_barrier
	s_setprio 1
	s_waitcnt lgkmcnt(0)
	v_mfma_f32_16x16x32_bf16 v[126:129], v[148:151], v[180:183], v[126:129]
	v_mfma_f32_16x16x32_bf16 v[122:125], v[156:159], v[180:183], v[122:125]
	v_mfma_f32_16x16x32_bf16 v[118:121], v[148:151], v[192:195], v[118:121]
	v_mfma_f32_16x16x32_bf16 v[110:113], v[156:159], v[192:195], v[110:113]
	v_mfma_f32_16x16x32_bf16 v[102:105], v[148:151], v[200:203], v[102:105]
	v_mfma_f32_16x16x32_bf16 v[94:97], v[156:159], v[200:203], v[94:97]
	v_mfma_f32_16x16x32_bf16 v[86:89], v[148:151], v[208:211], v[86:89]
	v_mfma_f32_16x16x32_bf16 v[78:81], v[156:159], v[208:211], v[78:81]
	v_mfma_f32_16x16x32_bf16 v[126:129], v[152:155], v[188:191], v[126:129]
	v_mfma_f32_16x16x32_bf16 v[122:125], v[160:163], v[188:191], v[122:125]
	v_mfma_f32_16x16x32_bf16 v[118:121], v[152:155], v[196:199], v[118:121]
	v_mfma_f32_16x16x32_bf16 v[110:113], v[160:163], v[196:199], v[110:113]
	v_mfma_f32_16x16x32_bf16 v[102:105], v[152:155], v[204:207], v[102:105]
	v_mfma_f32_16x16x32_bf16 v[94:97], v[160:163], v[204:207], v[94:97]
	v_mfma_f32_16x16x32_bf16 v[86:89], v[152:155], v[212:215], v[86:89]
	v_mfma_f32_16x16x32_bf16 v[78:81], v[160:163], v[212:215], v[78:81]
	s_setprio 0
	s_setprio 1
	v_mfma_f32_16x16x32_bf16 v[114:117], v[164:167], v[180:183], v[114:117]
	v_mfma_f32_16x16x32_bf16 v[106:109], v[172:175], v[180:183], v[106:109]
	v_mfma_f32_16x16x32_bf16 v[98:101], v[164:167], v[192:195], v[98:101]
	v_mfma_f32_16x16x32_bf16 v[90:93], v[172:175], v[192:195], v[90:93]
	v_mfma_f32_16x16x32_bf16 v[82:85], v[164:167], v[200:203], v[82:85]
	v_mfma_f32_16x16x32_bf16 v[74:77], v[172:175], v[200:203], v[74:77]
	v_mfma_f32_16x16x32_bf16 v[70:73], v[164:167], v[208:211], v[70:73]
	v_mfma_f32_16x16x32_bf16 v[66:69], v[172:175], v[208:211], v[66:69]
	v_mfma_f32_16x16x32_bf16 v[114:117], v[168:171], v[188:191], v[114:117]
	v_mfma_f32_16x16x32_bf16 v[106:109], v[176:179], v[188:191], v[106:109]
	v_mfma_f32_16x16x32_bf16 v[98:101], v[168:171], v[196:199], v[98:101]
	v_mfma_f32_16x16x32_bf16 v[90:93], v[176:179], v[196:199], v[90:93]
	v_mfma_f32_16x16x32_bf16 v[82:85], v[168:171], v[204:207], v[82:85]
	v_mfma_f32_16x16x32_bf16 v[74:77], v[176:179], v[204:207], v[74:77]
	v_mfma_f32_16x16x32_bf16 v[70:73], v[168:171], v[212:215], v[70:73]
	v_mfma_f32_16x16x32_bf16 v[66:69], v[176:179], v[212:215], v[66:69]
	s_setprio 0
	s_barrier
; #define PG8_STAGE(bufoff, gbase, voff) do { _Pragma("unroll") for (int _i = 0; _i < 2; ++_i) \
;         __builtin_amdgcn_global_load_lds((const unsigned*)((const char*)(gbase) + (voff)[_i]), (PG8_LAS unsigned*)(lds + (bufoff) + ldsw + _i * 8192), 16, 0, 0); } while (0)
; #define PG8_LDA(dst, b, h) do { _Pragma("unroll") for (int m = 0; m < 4; ++m) _Pragma("unroll") for (int k = 0; k < 2; ++k) dst[m][k] = *(const PG8_LAS bf16x8*)(lds + PG8_SA(b, h) + aoff + m * 2048 + k * 1024); } while (0)
; #define PG8_MMA(ai, bj, At, Bt) do { __builtin_amdgcn_s_setprio(1); _Pragma("unroll") for (int m = 0; m < 4; ++m) _Pragma("unroll") for (int n = 0; n < 2; ++n) _Pragma("unroll") for (int k = 0; k < 2; ++k) \
;         acc[ai][bj][m][n] = __builtin_amdgcn_mfma_f32_16x16x32_bf16(Bt[n][k], At[m][k], acc[ai][bj][m][n], 0, 0, 0); __builtin_amdgcn_s_setprio(0); } while (0)
; #define PG8_WAIT_V(n) asm volatile("s_waitcnt vmcnt(" #n ")" ::: "memory")
; #define PG8_WAIT_L(n) asm volatile("s_waitcnt lgkmcnt(" #n ")" ::: "memory")
; #define PG8_BAR __builtin_amdgcn_s_barrier()
; #define PG8_SCHED __builtin_amdgcn_sched_barrier(0)
; template <class Epi, class Sched, bool ALIGN_EPI = false, bool SP2 = false>
; __device__ __forceinline__ void gemm_phase(PG8_LAS unsigned char* lds, const Gemm g, const Sched& S, const Epi& E) {
;     ...
;         for (int t = 0; t < nt; t += 2) {
;             const bool last = (t == nt - 2);
;             const char* a1 = cA + (size_t)(t + 1) * kstep;
;             const char* a2 = last ? nA : cA + (size_t)(t + 2) * kstep; const char* b2 = last ? nB : cB + (size_t)(t + 2) * kstep;
;             const char* a3 = a2 + kstep; const char* b3 = b2 + kstep;
;     ...
;             PG8_LDA(At, 1, 1); PG8_STAGE(PG8_SB(1, 0), b3, voffB); PG8_STAGE(PG8_SB(1, 1), b3 + hstep, voffB); PG8_STAGE(PG8_SA(1, 0), a3, voffA);
;             PG8_WAIT_V(8); PG8_WAIT_L(0); PG8_BAR; PG8_MMA(1, 0, At, B0); PG8_MMA(1, 1, At, B1); PG8_BAR; PG8_SCHED;
	s_add_i32 s22, s54, s31
	v_lshl_add_u64 v[184:185], v[184:185], 0, s[8:9]
	s_mov_b32 m0, s22
	ds_read_b128 v[180:183], v146 offset:49152
	ds_read_b128 v[188:191], v146 offset:50176
	ds_read_b128 v[192:195], v146 offset:51200
	ds_read_b128 v[196:199], v146 offset:52224
	ds_read_b128 v[200:203], v146 offset:53248
	ds_read_b128 v[204:207], v146 offset:54272
	ds_read_b128 v[208:211], v146 offset:55296
	ds_read_b128 v[212:215], v146 offset:56320
	global_load_lds_dwordx4 v[184:185], off
	s_add_i32 m0, s22, 0x2000
	s_add_u32 s22, s26, 0x40080
	v_lshl_add_u64 v[184:185], v[216:217], 0, s[8:9]
	s_addc_u32 s23, s27, 0
	s_add_i32 s26, s55, s31
	global_load_lds_dwordx4 v[184:185], off
	v_lshl_add_u64 v[184:185], s[22:23], 0, v[130:131]
	s_mov_b32 m0, s26
	s_nop 0
	global_load_lds_dwordx4 v[184:185], off
	v_lshl_add_u64 v[184:185], s[22:23], 0, v[132:133]
	s_add_i32 m0, s26, 0x2000
	s_nop 0
	global_load_lds_dwordx4 v[184:185], off
	v_lshl_add_u64 v[184:185], v[218:219], 0, s[8:9]
	s_mov_b32 m0, s38
	s_nop 0
	global_load_lds_dwordx4 v[184:185], off
	v_lshl_add_u64 v[184:185], v[220:221], 0, s[8:9]
	s_mov_b32 m0, s39
	s_nop 0
	global_load_lds_dwordx4 v[184:185], off
	s_waitcnt vmcnt(8)
	s_waitcnt lgkmcnt(0)
	s_barrier
	s_setprio 1
	s_waitcnt lgkmcnt(0)
	v_mfma_f32_16x16x32_bf16 v[62:65], v[148:151], v[180:183], v[62:65]
	v_mfma_f32_16x16x32_bf16 v[58:61], v[156:159], v[180:183], v[58:61]
	v_mfma_f32_16x16x32_bf16 v[54:57], v[148:151], v[192:195], v[54:57]
	v_mfma_f32_16x16x32_bf16 v[46:49], v[156:159], v[192:195], v[46:49]
	v_mfma_f32_16x16x32_bf16 v[38:41], v[148:151], v[200:203], v[38:41]
	v_mfma_f32_16x16x32_bf16 v[30:33], v[156:159], v[200:203], v[30:33]
	v_mfma_f32_16x16x32_bf16 v[22:25], v[148:151], v[208:211], v[22:25]
	v_mfma_f32_16x16x32_bf16 v[14:17], v[156:159], v[208:211], v[14:17]
	v_mfma_f32_16x16x32_bf16 v[62:65], v[152:155], v[188:191], v[62:65]
	v_mfma_f32_16x16x32_bf16 v[58:61], v[160:163], v[188:191], v[58:61]
	v_mfma_f32_16x16x32_bf16 v[54:57], v[152:155], v[196:199], v[54:57]
	v_mfma_f32_16x16x32_bf16 v[46:49], v[160:163], v[196:199], v[46:49]
	v_mfma_f32_16x16x32_bf16 v[38:41], v[152:155], v[204:207], v[38:41]
	v_mfma_f32_16x16x32_bf16 v[30:33], v[160:163], v[204:207], v[30:33]
	v_mfma_f32_16x16x32_bf16 v[22:25], v[152:155], v[212:215], v[22:25]
	v_mfma_f32_16x16x32_bf16 v[14:17], v[160:163], v[212:215], v[14:17]
	s_setprio 0
	s_setprio 1
	v_mfma_f32_16x16x32_bf16 v[50:53], v[164:167], v[180:183], v[50:53]
	v_mfma_f32_16x16x32_bf16 v[42:45], v[172:175], v[180:183], v[42:45]
	v_mfma_f32_16x16x32_bf16 v[34:37], v[164:167], v[192:195], v[34:37]
	v_mfma_f32_16x16x32_bf16 v[26:29], v[172:175], v[192:195], v[26:29]
	v_mfma_f32_16x16x32_bf16 v[18:21], v[164:167], v[200:203], v[18:21]
	v_mfma_f32_16x16x32_bf16 v[10:13], v[172:175], v[200:203], v[10:13]
	v_mfma_f32_16x16x32_bf16 v[6:9], v[164:167], v[208:211], v[6:9]
	v_mfma_f32_16x16x32_bf16 v[2:5], v[172:175], v[208:211], v[2:5]
	v_mfma_f32_16x16x32_bf16 v[50:53], v[168:171], v[188:191], v[50:53]
	v_mfma_f32_16x16x32_bf16 v[42:45], v[176:179], v[188:191], v[42:45]
	v_mfma_f32_16x16x32_bf16 v[34:37], v[168:171], v[196:199], v[34:37]
	v_mfma_f32_16x16x32_bf16 v[26:29], v[176:179], v[196:199], v[26:29]
	v_mfma_f32_16x16x32_bf16 v[18:21], v[168:171], v[204:207], v[18:21]
	v_mfma_f32_16x16x32_bf16 v[10:13], v[176:179], v[204:207], v[10:13]
	v_mfma_f32_16x16x32_bf16 v[6:9], v[168:171], v[212:215], v[6:9]
	v_mfma_f32_16x16x32_bf16 v[2:5], v[176:179], v[212:215], v[2:5]
	s_setprio 0
	s_add_i32 s53, s53, 2
	s_add_u32 s51, s51, 0x100
	s_addc_u32 s52, s52, 0
	s_cmp_gt_u32 s53, 13
	s_mov_b64 s[22:23], s[24:25]
	s_barrier
	s_cbranch_scc0 .LBB0_457
	s_and_b64 vcc, exec, s[10:11]
	s_cbranch_vccz .LBB0_460
	s_barrier

; #define PG8_STAGE(bufoff, gbase, voff) do { _Pragma("unroll") for (int _i = 0; _i < 2; ++_i) \
;         __builtin_amdgcn_global_load_lds((const unsigned*)((const char*)(gbase) + (voff)[_i]), (PG8_LAS unsigned*)(lds + (bufoff) + ldsw + _i * 8192), 16, 0, 0); } while (0)
; #define PG8_LDA(dst, b, h) do { _Pragma("unroll") for (int m = 0; m < 4; ++m) _Pragma("unroll") for (int k = 0; k < 2; ++k) dst[m][k] = *(const PG8_LAS bf16x8*)(lds + PG8_SA(b, h) + aoff + m * 2048 + k * 1024); } while (0)
; #define PG8_LDB(dst, b, h) do { _Pragma("unroll") for (int n = 0; n < 2; ++n) _Pragma("unroll") for (int k = 0; k < 2; ++k) dst[n][k] = *(const PG8_LAS bf16x8*)(lds + PG8_SB(b, h) + boff + n * 2048 + k * 1024); } while (0)
; #define PG8_MMA(ai, bj, At, Bt) do { __builtin_amdgcn_s_setprio(1); _Pragma("unroll") for (int m = 0; m < 4; ++m) _Pragma("unroll") for (int n = 0; n < 2; ++n) _Pragma("unroll") for (int k = 0; k < 2; ++k) \
;         acc[ai][bj][m][n] = __builtin_amdgcn_mfma_f32_16x16x32_bf16(Bt[n][k], At[m][k], acc[ai][bj][m][n], 0, 0, 0); __builtin_amdgcn_s_setprio(0); } while (0)
; #define PG8_WAIT_V(n) asm volatile("s_waitcnt vmcnt(" #n ")" ::: "memory")
; #define PG8_WAIT_L(n) asm volatile("s_waitcnt lgkmcnt(" #n ")" ::: "memory")
; #define PG8_BAR __builtin_amdgcn_s_barrier()
; #define PG8_SCHED __builtin_amdgcn_sched_barrier(0)
; template <class Epi, class Sched, bool ALIGN_EPI = false, bool SP2 = false>
; __device__ __forceinline__ void gemm_phase(PG8_LAS unsigned char* lds, const Gemm g, const Sched& S, const Epi& E) {
;     ...
;         for (int t = 0; t < nt; t += 2) {
;             const bool last = (t == nt - 2);
;             const char* a1 = cA + (size_t)(t + 1) * kstep;
;             const char* a2 = last ? nA : cA + (size_t)(t + 2) * kstep; const char* b2 = last ? nB : cB + (size_t)(t + 2) * kstep;
;             const char* a3 = a2 + kstep; const char* b3 = b2 + kstep;
;             if (last && has_next) S.a_ready(nxt);
;             if constexpr (SP2) {
;             PG8_LDB(B0, 0, 0); PG8_LDB(B1, 0, 1); PG8_SCHED; PG8_LDA(At, 0, 0); PG8_STAGE(PG8_SA(1, 1), a1 + hstep, voffA);
;             PG8_WAIT_V(8); PG8_WAIT_L(0); PG8_BAR; PG8_MMA(0, 0, At, B0); PG8_MMA(0, 1, At, B1); PG8_BAR; PG8_SCHED;
;             PG8_LDA(At, 0, 1); PG8_STAGE(PG8_SB(0, 0), b2, voffB); PG8_STAGE(PG8_SB(0, 1), b2 + hstep, voffB); PG8_STAGE(PG8_SA(0, 0), a2, voffA);
.LBB0_713:
	ds_read_b128 v[162:165], v159
	ds_read_b128 v[166:169], v159 offset:1024
	ds_read_b128 v[170:173], v159 offset:2048
	ds_read_b128 v[174:177], v159 offset:3072
	ds_read_b128 v[178:181], v160
	ds_read_b128 v[182:185], v160 offset:1024
	ds_read_b128 v[188:191], v160 offset:2048
	ds_read_b128 v[192:195], v160 offset:3072
	s_add_i32 s66, s36, 2
	s_add_u32 s67, s34, 0x80
	s_addc_u32 s37, s35, 0
	s_cmp_eq_u32 s52, s36
	s_cselect_b32 s36, s4, s67
	s_cselect_b32 s37, s5, s37
	s_cselect_b32 s69, s31, s65
	s_cselect_b32 s68, s30, s63
	v_lshl_add_u64 v[156:157], s[34:35], 0, v[146:147]
	s_add_i32 m0, s42, 0xc000
	ds_read_b128 v[196:199], v161
	ds_read_b128 v[200:203], v161 offset:1024
	ds_read_b128 v[204:207], v161 offset:2048
	ds_read_b128 v[208:211], v161 offset:3072
	ds_read_b128 v[212:215], v161 offset:4096
	ds_read_b128 v[216:219], v161 offset:5120
	ds_read_b128 v[220:223], v161 offset:6144
	ds_read_b128 v[224:227], v161 offset:7168
	global_load_lds_dwordx4 v[156:157], off
	v_lshl_add_u64 v[156:157], s[34:35], 0, v[148:149]
	s_add_i32 m0, s42, 0xe000
	s_nop 0
	global_load_lds_dwordx4 v[156:157], off
	s_waitcnt vmcnt(8)
	s_waitcnt lgkmcnt(0)
	s_barrier
	s_setprio 1
	s_waitcnt lgkmcnt(0)
	v_mfma_f32_16x16x32_bf16 v[126:129], v[162:165], v[196:199], v[126:129]
	v_mfma_f32_16x16x32_bf16 v[122:125], v[170:173], v[196:199], v[122:125]
	v_mfma_f32_16x16x32_bf16 v[110:113], v[162:165], v[204:207], v[110:113]
	v_mfma_f32_16x16x32_bf16 v[106:109], v[170:173], v[204:207], v[106:109]
	v_mfma_f32_16x16x32_bf16 v[94:97], v[162:165], v[212:215], v[94:97]
	v_mfma_f32_16x16x32_bf16 v[90:93], v[170:173], v[212:215], v[90:93]
	v_mfma_f32_16x16x32_bf16 v[78:81], v[162:165], v[220:223], v[78:81]
	v_mfma_f32_16x16x32_bf16 v[74:77], v[170:173], v[220:223], v[74:77]
	v_mfma_f32_16x16x32_bf16 v[126:129], v[166:169], v[200:203], v[126:129]
	v_mfma_f32_16x16x32_bf16 v[122:125], v[174:177], v[200:203], v[122:125]
	v_mfma_f32_16x16x32_bf16 v[110:113], v[166:169], v[208:211], v[110:113]
	v_mfma_f32_16x16x32_bf16 v[106:109], v[174:177], v[208:211], v[106:109]
	v_mfma_f32_16x16x32_bf16 v[94:97], v[166:169], v[216:219], v[94:97]
	v_mfma_f32_16x16x32_bf16 v[90:93], v[174:177], v[216:219], v[90:93]
	v_mfma_f32_16x16x32_bf16 v[78:81], v[166:169], v[224:227], v[78:81]
	v_mfma_f32_16x16x32_bf16 v[74:77], v[174:177], v[224:227], v[74:77]
	s_setprio 0
	s_setprio 1
	v_mfma_f32_16x16x32_bf16 v[118:121], v[178:181], v[196:199], v[118:121]
	v_mfma_f32_16x16x32_bf16 v[114:117], v[188:191], v[196:199], v[114:117]
	v_mfma_f32_16x16x32_bf16 v[102:105], v[178:181], v[204:207], v[102:105]
	v_mfma_f32_16x16x32_bf16 v[98:101], v[188:191], v[204:207], v[98:101]
	v_mfma_f32_16x16x32_bf16 v[86:89], v[178:181], v[212:215], v[86:89]
	v_mfma_f32_16x16x32_bf16 v[82:85], v[188:191], v[212:215], v[82:85]
	v_mfma_f32_16x16x32_bf16 v[70:73], v[178:181], v[220:223], v[70:73]
	v_mfma_f32_16x16x32_bf16 v[66:69], v[188:191], v[220:223], v[66:69]
	v_mfma_f32_16x16x32_bf16 v[118:121], v[182:185], v[200:203], v[118:121]
	v_mfma_f32_16x16x32_bf16 v[114:117], v[192:195], v[200:203], v[114:117]
	v_mfma_f32_16x16x32_bf16 v[102:105], v[182:185], v[208:211], v[102:105]
	v_mfma_f32_16x16x32_bf16 v[98:101], v[192:195], v[208:211], v[98:101]
	v_mfma_f32_16x16x32_bf16 v[86:89], v[182:185], v[216:219], v[86:89]
	v_mfma_f32_16x16x32_bf16 v[82:85], v[192:195], v[216:219], v[82:85]
	v_mfma_f32_16x16x32_bf16 v[70:73], v[182:185], v[224:227], v[70:73]
	v_mfma_f32_16x16x32_bf16 v[66:69], v[192:195], v[224:227], v[66:69]
	s_setprio 0
	s_barrier
	s_add_i32 s67, s55, s40
	v_lshl_add_u64 v[156:157], s[68:69], 0, v[134:135]
	s_mov_b32 m0, s67
	ds_read_b128 v[196:199], v161 offset:16384
	ds_read_b128 v[200:203], v161 offset:17408
	ds_read_b128 v[204:207], v161 offset:18432
	ds_read_b128 v[208:211], v161 offset:19456
	ds_read_b128 v[212:215], v161 offset:20480
	ds_read_b128 v[216:219], v161 offset:21504
	ds_read_b128 v[220:223], v161 offset:22528
	ds_read_b128 v[224:227], v161 offset:23552
	global_load_lds_dwordx4 v[156:157], off
	s_add_i32 m0, s67, 0x2000
	v_lshl_add_u64 v[228:229], s[68:69], 0, v[130:131]
	s_add_u32 s68, s68, s6
	s_addc_u32 s69, s69, s7
	s_add_i32 s67, s56, s40
	global_load_lds_dwordx4 v[228:229], off
	v_lshl_add_u64 v[230:231], s[68:69], 0, v[134:135]
	s_mov_b32 m0, s67
	v_lshl_add_u64 v[232:233], s[68:69], 0, v[130:131]
	global_load_lds_dwordx4 v[230:231], off
	s_add_i32 m0, s67, 0x2000
	v_lshl_add_u64 v[234:235], s[36:37], 0, v[136:137]
	global_load_lds_dwordx4 v[232:233], off
	s_mov_b32 m0, s42
	v_lshl_add_u64 v[236:237], s[36:37], 0, v[132:133]
	global_load_lds_dwordx4 v[234:235], off
	s_mov_b32 m0, s43
	s_nop 0
	global_load_lds_dwordx4 v[236:237], off
	s_waitcnt vmcnt(8)
	s_waitcnt lgkmcnt(0)
	s_barrier
; #define PG8_STAGE(bufoff, gbase, voff) do { _Pragma("unroll") for (int _i = 0; _i < 2; ++_i) \
;         __builtin_amdgcn_global_load_lds((const unsigned*)((const char*)(gbase) + (voff)[_i]), (PG8_LAS unsigned*)(lds + (bufoff) + ldsw + _i * 8192), 16, 0, 0); } while (0)
; #define PG8_LDA(dst, b, h) do { _Pragma("unroll") for (int m = 0; m < 4; ++m) _Pragma("unroll") for (int k = 0; k < 2; ++k) dst[m][k] = *(const PG8_LAS bf16x8*)(lds + PG8_SA(b, h) + aoff + m * 2048 + k * 1024); } while (0)
; #define PG8_LDB(dst, b, h) do { _Pragma("unroll") for (int n = 0; n < 2; ++n) _Pragma("unroll") for (int k = 0; k < 2; ++k) dst[n][k] = *(const PG8_LAS bf16x8*)(lds + PG8_SB(b, h) + boff + n * 2048 + k * 1024); } while (0)
; #define PG8_MMA(ai, bj, At, Bt) do { __builtin_amdgcn_s_setprio(1); _Pragma("unroll") for (int m = 0; m < 4; ++m) _Pragma("unroll") for (int n = 0; n < 2; ++n) _Pragma("unroll") for (int k = 0; k < 2; ++k) \
;         acc[ai][bj][m][n] = __builtin_amdgcn_mfma_f32_16x16x32_bf16(Bt[n][k], At[m][k], acc[ai][bj][m][n], 0, 0, 0); __builtin_amdgcn_s_setprio(0); } while (0)
; #define PG8_WAIT_V(n) asm volatile("s_waitcnt vmcnt(" #n ")" ::: "memory")
; #define PG8_WAIT_L(n) asm volatile("s_waitcnt lgkmcnt(" #n ")" ::: "memory")
; #define PG8_BAR __builtin_amdgcn_s_barrier()
; #define PG8_SCHED __builtin_amdgcn_sched_barrier(0)
; template <class Epi, class Sched, bool ALIGN_EPI = false, bool SP2 = false>
; __device__ __forceinline__ void gemm_phase(PG8_LAS unsigned char* lds, const Gemm g, const Sched& S, const Epi& E) {
;     ...
;             PG8_WAIT_V(8); PG8_WAIT_L(0); PG8_BAR; PG8_MMA(1, 0, At, B0); PG8_MMA(1, 1, At, B1); PG8_BAR; PG8_SCHED;
;             PG8_LDB(B0, 1, 0); PG8_LDB(B1, 1, 1); PG8_SCHED; PG8_LDA(At, 1, 0); PG8_STAGE(PG8_SA(0, 1), a2 + hstep, voffA);
;             PG8_WAIT_V(8); PG8_WAIT_L(0); PG8_BAR; PG8_MMA(0, 0, At, B0); PG8_MMA(0, 1, At, B1); PG8_BAR; PG8_SCHED;
	s_setprio 1
	s_waitcnt lgkmcnt(0)
	v_mfma_f32_16x16x32_bf16 v[62:65], v[162:165], v[196:199], v[62:65]
	v_mfma_f32_16x16x32_bf16 v[58:61], v[170:173], v[196:199], v[58:61]
	v_mfma_f32_16x16x32_bf16 v[46:49], v[162:165], v[204:207], v[46:49]
	v_mfma_f32_16x16x32_bf16 v[42:45], v[170:173], v[204:207], v[42:45]
	v_mfma_f32_16x16x32_bf16 v[30:33], v[162:165], v[212:215], v[30:33]
	v_mfma_f32_16x16x32_bf16 v[26:29], v[170:173], v[212:215], v[26:29]
	v_mfma_f32_16x16x32_bf16 v[14:17], v[162:165], v[220:223], v[14:17]
	v_mfma_f32_16x16x32_bf16 v[10:13], v[170:173], v[220:223], v[10:13]
	v_mfma_f32_16x16x32_bf16 v[62:65], v[166:169], v[200:203], v[62:65]
	v_mfma_f32_16x16x32_bf16 v[58:61], v[174:177], v[200:203], v[58:61]
	v_mfma_f32_16x16x32_bf16 v[46:49], v[166:169], v[208:211], v[46:49]
	v_mfma_f32_16x16x32_bf16 v[42:45], v[174:177], v[208:211], v[42:45]
	v_mfma_f32_16x16x32_bf16 v[30:33], v[166:169], v[216:219], v[30:33]
	v_mfma_f32_16x16x32_bf16 v[26:29], v[174:177], v[216:219], v[26:29]
	v_mfma_f32_16x16x32_bf16 v[14:17], v[166:169], v[224:227], v[14:17]
	v_mfma_f32_16x16x32_bf16 v[10:13], v[174:177], v[224:227], v[10:13]
	s_setprio 0
	s_setprio 1
	v_mfma_f32_16x16x32_bf16 v[54:57], v[178:181], v[196:199], v[54:57]
	v_mfma_f32_16x16x32_bf16 v[50:53], v[188:191], v[196:199], v[50:53]
	v_mfma_f32_16x16x32_bf16 v[38:41], v[178:181], v[204:207], v[38:41]
	v_mfma_f32_16x16x32_bf16 v[34:37], v[188:191], v[204:207], v[34:37]
	v_mfma_f32_16x16x32_bf16 v[22:25], v[178:181], v[212:215], v[22:25]
	v_mfma_f32_16x16x32_bf16 v[18:21], v[188:191], v[212:215], v[18:21]
	v_mfma_f32_16x16x32_bf16 v[6:9], v[178:181], v[220:223], v[6:9]
	v_mfma_f32_16x16x32_bf16 v[2:5], v[188:191], v[220:223], v[2:5]
	v_mfma_f32_16x16x32_bf16 v[54:57], v[182:185], v[200:203], v[54:57]
	v_mfma_f32_16x16x32_bf16 v[50:53], v[192:195], v[200:203], v[50:53]
	v_mfma_f32_16x16x32_bf16 v[38:41], v[182:185], v[208:211], v[38:41]
	v_mfma_f32_16x16x32_bf16 v[34:37], v[192:195], v[208:211], v[34:37]
	v_mfma_f32_16x16x32_bf16 v[22:25], v[182:185], v[216:219], v[22:25]
	v_mfma_f32_16x16x32_bf16 v[18:21], v[192:195], v[216:219], v[18:21]
	v_mfma_f32_16x16x32_bf16 v[6:9], v[182:185], v[224:227], v[6:9]
	v_mfma_f32_16x16x32_bf16 v[2:5], v[192:195], v[224:227], v[2:5]
	s_setprio 0
	s_barrier
	s_add_i32 s67, 0, 0x18000
	v_add_u32_e32 v138, s67, v158
	s_add_i32 s68, 0, 0x1c000
	ds_read_b128 v[162:165], v138
	ds_read_b128 v[166:169], v138 offset:1024
	ds_read_b128 v[170:173], v138 offset:2048
	ds_read_b128 v[174:177], v138 offset:3072
	v_add_u32_e32 v138, s68, v158
	ds_read_b128 v[178:181], v138
	ds_read_b128 v[182:185], v138 offset:1024
	ds_read_b128 v[188:191], v138 offset:2048
	ds_read_b128 v[192:195], v138 offset:3072
	s_add_u32 s36, s36, s6
	s_addc_u32 s37, s37, s7
	s_mov_b32 m0, s48
	v_lshl_add_u64 v[238:239], s[36:37], 0, v[136:137]
	ds_read_b128 v[196:199], v161 offset:32768
	ds_read_b128 v[200:203], v161 offset:33792
	ds_read_b128 v[204:207], v161 offset:34816
	ds_read_b128 v[208:211], v161 offset:35840
	ds_read_b128 v[212:215], v161 offset:36864
	ds_read_b128 v[216:219], v161 offset:37888
	ds_read_b128 v[220:223], v161 offset:38912
	ds_read_b128 v[224:227], v161 offset:39936
	global_load_lds_dwordx4 v[238:239], off
	v_lshl_add_u64 v[238:239], s[36:37], 0, v[132:133]
	s_mov_b32 m0, s49
	s_nop 0
	global_load_lds_dwordx4 v[238:239], off
	s_waitcnt vmcnt(8)
	s_waitcnt lgkmcnt(0)
	s_barrier
	s_setprio 1
	s_waitcnt lgkmcnt(0)
	v_mfma_f32_16x16x32_bf16 v[126:129], v[162:165], v[196:199], v[126:129]
	v_mfma_f32_16x16x32_bf16 v[122:125], v[170:173], v[196:199], v[122:125]
	v_mfma_f32_16x16x32_bf16 v[110:113], v[162:165], v[204:207], v[110:113]
	v_mfma_f32_16x16x32_bf16 v[106:109], v[170:173], v[204:207], v[106:109]
	v_mfma_f32_16x16x32_bf16 v[94:97], v[162:165], v[212:215], v[94:97]
	v_mfma_f32_16x16x32_bf16 v[90:93], v[170:173], v[212:215], v[90:93]
	v_mfma_f32_16x16x32_bf16 v[78:81], v[162:165], v[220:223], v[78:81]
	v_mfma_f32_16x16x32_bf16 v[74:77], v[170:173], v[220:223], v[74:77]
	v_mfma_f32_16x16x32_bf16 v[126:129], v[166:169], v[200:203], v[126:129]
	v_mfma_f32_16x16x32_bf16 v[122:125], v[174:177], v[200:203], v[122:125]
	v_mfma_f32_16x16x32_bf16 v[110:113], v[166:169], v[208:211], v[110:113]
	v_mfma_f32_16x16x32_bf16 v[106:109], v[174:177], v[208:211], v[106:109]
	v_mfma_f32_16x16x32_bf16 v[94:97], v[166:169], v[216:219], v[94:97]
	v_mfma_f32_16x16x32_bf16 v[90:93], v[174:177], v[216:219], v[90:93]
	v_mfma_f32_16x16x32_bf16 v[78:81], v[166:169], v[224:227], v[78:81]
	v_mfma_f32_16x16x32_bf16 v[74:77], v[174:177], v[224:227], v[74:77]
	s_setprio 0
	s_setprio 1
	v_mfma_f32_16x16x32_bf16 v[118:121], v[178:181], v[196:199], v[118:121]
	v_mfma_f32_16x16x32_bf16 v[114:117], v[188:191], v[196:199], v[114:117]
	v_mfma_f32_16x16x32_bf16 v[102:105], v[178:181], v[204:207], v[102:105]
	v_mfma_f32_16x16x32_bf16 v[98:101], v[188:191], v[204:207], v[98:101]
	v_mfma_f32_16x16x32_bf16 v[86:89], v[178:181], v[212:215], v[86:89]
	v_mfma_f32_16x16x32_bf16 v[82:85], v[188:191], v[212:215], v[82:85]
	v_mfma_f32_16x16x32_bf16 v[70:73], v[178:181], v[220:223], v[70:73]
	v_mfma_f32_16x16x32_bf16 v[66:69], v[188:191], v[220:223], v[66:69]
	v_mfma_f32_16x16x32_bf16 v[118:121], v[182:185], v[200:203], v[118:121]
	v_mfma_f32_16x16x32_bf16 v[114:117], v[192:195], v[200:203], v[114:117]
	v_mfma_f32_16x16x32_bf16 v[102:105], v[182:185], v[208:211], v[102:105]
	v_mfma_f32_16x16x32_bf16 v[98:101], v[192:195], v[208:211], v[98:101]
	v_mfma_f32_16x16x32_bf16 v[86:89], v[182:185], v[216:219], v[86:89]
	v_mfma_f32_16x16x32_bf16 v[82:85], v[192:195], v[216:219], v[82:85]
	v_mfma_f32_16x16x32_bf16 v[70:73], v[182:185], v[224:227], v[70:73]
	v_mfma_f32_16x16x32_bf16 v[66:69], v[192:195], v[224:227], v[66:69]
	s_setprio 0
	s_barrier
; #define PG8_STAGE(bufoff, gbase, voff) do { _Pragma("unroll") for (int _i = 0; _i < 2; ++_i) \
;         __builtin_amdgcn_global_load_lds((const unsigned*)((const char*)(gbase) + (voff)[_i]), (PG8_LAS unsigned*)(lds + (bufoff) + ldsw + _i * 8192), 16, 0, 0); } while (0)
; #define PG8_LDA(dst, b, h) do { _Pragma("unroll") for (int m = 0; m < 4; ++m) _Pragma("unroll") for (int k = 0; k < 2; ++k) dst[m][k] = *(const PG8_LAS bf16x8*)(lds + PG8_SA(b, h) + aoff + m * 2048 + k * 1024); } while (0)
; #define PG8_MMA(ai, bj, At, Bt) do { __builtin_amdgcn_s_setprio(1); _Pragma("unroll") for (int m = 0; m < 4; ++m) _Pragma("unroll") for (int n = 0; n < 2; ++n) _Pragma("unroll") for (int k = 0; k < 2; ++k) \
;         acc[ai][bj][m][n] = __builtin_amdgcn_mfma_f32_16x16x32_bf16(Bt[n][k], At[m][k], acc[ai][bj][m][n], 0, 0, 0); __builtin_amdgcn_s_setprio(0); } while (0)
; #define PG8_WAIT_V(n) asm volatile("s_waitcnt vmcnt(" #n ")" ::: "memory")
; #define PG8_WAIT_L(n) asm volatile("s_waitcnt lgkmcnt(" #n ")" ::: "memory")
; #define PG8_BAR __builtin_amdgcn_s_barrier()
; #define PG8_SCHED __builtin_amdgcn_sched_barrier(0)
; template <class Epi, class Sched, bool ALIGN_EPI = false, bool SP2 = false>
; __device__ __forceinline__ void gemm_phase(PG8_LAS unsigned char* lds, const Gemm g, const Sched& S, const Epi& E) {
;     ...
;         for (int t = 0; t < nt; t += 2) {
;             const bool last = (t == nt - 2);
;             const char* a1 = cA + (size_t)(t + 1) * kstep;
;             const char* a2 = last ? nA : cA + (size_t)(t + 2) * kstep; const char* b2 = last ? nB : cB + (size_t)(t + 2) * kstep;
;             const char* a3 = a2 + kstep; const char* b3 = b2 + kstep;
;     ...
;             PG8_LDA(At, 1, 1); PG8_STAGE(PG8_SB(1, 0), b3, voffB); PG8_STAGE(PG8_SB(1, 1), b3 + hstep, voffB); PG8_STAGE(PG8_SA(1, 0), a3, voffA);
;             PG8_WAIT_V(8); PG8_WAIT_L(0); PG8_BAR; PG8_MMA(1, 0, At, B0); PG8_MMA(1, 1, At, B1); PG8_BAR; PG8_SCHED;
	s_add_i32 s36, s67, s40
	v_lshl_add_u64 v[156:157], v[156:157], 0, s[22:23]
	s_mov_b32 m0, s36
	ds_read_b128 v[196:199], v161 offset:49152
	ds_read_b128 v[200:203], v161 offset:50176
	ds_read_b128 v[204:207], v161 offset:51200
	ds_read_b128 v[208:211], v161 offset:52224
	ds_read_b128 v[212:215], v161 offset:53248
	ds_read_b128 v[216:219], v161 offset:54272
	ds_read_b128 v[220:223], v161 offset:55296
	ds_read_b128 v[224:227], v161 offset:56320
	global_load_lds_dwordx4 v[156:157], off
	v_lshl_add_u64 v[156:157], v[228:229], 0, s[22:23]
	s_add_i32 m0, s36, 0x2000
	s_add_i32 s36, s68, s40
	global_load_lds_dwordx4 v[156:157], off
	v_lshl_add_u64 v[156:157], v[230:231], 0, s[22:23]
	s_mov_b32 m0, s36
	s_nop 0
	global_load_lds_dwordx4 v[156:157], off
	v_lshl_add_u64 v[156:157], v[232:233], 0, s[22:23]
	s_add_i32 m0, s36, 0x2000
	s_nop 0
	global_load_lds_dwordx4 v[156:157], off
	v_lshl_add_u64 v[156:157], v[234:235], 0, s[22:23]
	s_mov_b32 m0, s50
	s_nop 0
	global_load_lds_dwordx4 v[156:157], off
	v_lshl_add_u64 v[156:157], v[236:237], 0, s[22:23]
	s_mov_b32 m0, s51
	s_nop 0
	global_load_lds_dwordx4 v[156:157], off
	s_waitcnt vmcnt(8)
	s_waitcnt lgkmcnt(0)
	s_barrier
	s_setprio 1
	s_waitcnt lgkmcnt(0)
	v_mfma_f32_16x16x32_bf16 v[62:65], v[162:165], v[196:199], v[62:65]
	v_mfma_f32_16x16x32_bf16 v[58:61], v[170:173], v[196:199], v[58:61]
	v_mfma_f32_16x16x32_bf16 v[46:49], v[162:165], v[204:207], v[46:49]
	v_mfma_f32_16x16x32_bf16 v[42:45], v[170:173], v[204:207], v[42:45]
	v_mfma_f32_16x16x32_bf16 v[30:33], v[162:165], v[212:215], v[30:33]
	v_mfma_f32_16x16x32_bf16 v[26:29], v[170:173], v[212:215], v[26:29]
	v_mfma_f32_16x16x32_bf16 v[14:17], v[162:165], v[220:223], v[14:17]
	v_mfma_f32_16x16x32_bf16 v[10:13], v[170:173], v[220:223], v[10:13]
	v_mfma_f32_16x16x32_bf16 v[62:65], v[166:169], v[200:203], v[62:65]
	v_mfma_f32_16x16x32_bf16 v[58:61], v[174:177], v[200:203], v[58:61]
	v_mfma_f32_16x16x32_bf16 v[46:49], v[166:169], v[208:211], v[46:49]
	v_mfma_f32_16x16x32_bf16 v[42:45], v[174:177], v[208:211], v[42:45]
	v_mfma_f32_16x16x32_bf16 v[30:33], v[166:169], v[216:219], v[30:33]
	v_mfma_f32_16x16x32_bf16 v[26:29], v[174:177], v[216:219], v[26:29]
	v_mfma_f32_16x16x32_bf16 v[14:17], v[166:169], v[224:227], v[14:17]
	v_mfma_f32_16x16x32_bf16 v[10:13], v[174:177], v[224:227], v[10:13]
	s_setprio 0
	s_setprio 1
	v_mfma_f32_16x16x32_bf16 v[54:57], v[178:181], v[196:199], v[54:57]
	v_mfma_f32_16x16x32_bf16 v[50:53], v[188:191], v[196:199], v[50:53]
	v_mfma_f32_16x16x32_bf16 v[38:41], v[178:181], v[204:207], v[38:41]
	v_mfma_f32_16x16x32_bf16 v[34:37], v[188:191], v[204:207], v[34:37]
	v_mfma_f32_16x16x32_bf16 v[22:25], v[178:181], v[212:215], v[22:25]
	v_mfma_f32_16x16x32_bf16 v[18:21], v[188:191], v[212:215], v[18:21]
	v_mfma_f32_16x16x32_bf16 v[6:9], v[178:181], v[220:223], v[6:9]
	v_mfma_f32_16x16x32_bf16 v[2:5], v[188:191], v[220:223], v[2:5]
	v_mfma_f32_16x16x32_bf16 v[54:57], v[182:185], v[200:203], v[54:57]
	v_mfma_f32_16x16x32_bf16 v[50:53], v[192:195], v[200:203], v[50:53]
	v_mfma_f32_16x16x32_bf16 v[38:41], v[182:185], v[208:211], v[38:41]
	v_mfma_f32_16x16x32_bf16 v[34:37], v[192:195], v[208:211], v[34:37]
	v_mfma_f32_16x16x32_bf16 v[22:25], v[182:185], v[216:219], v[22:25]
	v_mfma_f32_16x16x32_bf16 v[18:21], v[192:195], v[216:219], v[18:21]
	v_mfma_f32_16x16x32_bf16 v[6:9], v[182:185], v[224:227], v[6:9]
	v_mfma_f32_16x16x32_bf16 v[2:5], v[192:195], v[224:227], v[2:5]
	s_setprio 0
	s_add_u32 s34, s34, 0x100
	s_addc_u32 s35, s35, 0
	s_add_u32 s63, s63, 0x100
	s_addc_u32 s65, s65, 0
	s_cmp_ge_i32 s66, s0
	s_mov_b32 s36, s66
	s_barrier
	s_cbranch_scc0 .LBB0_713

; #define PG8_STAGE(bufoff, gbase, voff) do { _Pragma("unroll") for (int _i = 0; _i < 2; ++_i) \
;         __builtin_amdgcn_global_load_lds((const unsigned*)((const char*)(gbase) + (voff)[_i]), (PG8_LAS unsigned*)(lds + (bufoff) + ldsw + _i * 8192), 16, 0, 0); } while (0)
; #define PG8_LDA(dst, b, h) do { _Pragma("unroll") for (int m = 0; m < 4; ++m) _Pragma("unroll") for (int k = 0; k < 2; ++k) dst[m][k] = *(const PG8_LAS bf16x8*)(lds + PG8_SA(b, h) + aoff + m * 2048 + k * 1024); } while (0)
; #define PG8_LDB(dst, b, h) do { _Pragma("unroll") for (int n = 0; n < 2; ++n) _Pragma("unroll") for (int k = 0; k < 2; ++k) dst[n][k] = *(const PG8_LAS bf16x8*)(lds + PG8_SB(b, h) + boff + n * 2048 + k * 1024); } while (0)
; #define PG8_MMA(ai, bj, At, Bt) do { __builtin_amdgcn_s_setprio(1); _Pragma("unroll") for (int m = 0; m < 4; ++m) _Pragma("unroll") for (int n = 0; n < 2; ++n) _Pragma("unroll") for (int k = 0; k < 2; ++k) \
;         acc[ai][bj][m][n] = __builtin_amdgcn_mfma_f32_16x16x32_bf16(Bt[n][k], At[m][k], acc[ai][bj][m][n], 0, 0, 0); __builtin_amdgcn_s_setprio(0); } while (0)
; #define PG8_WAIT_V(n) asm volatile("s_waitcnt vmcnt(" #n ")" ::: "memory")
; #define PG8_WAIT_L(n) asm volatile("s_waitcnt lgkmcnt(" #n ")" ::: "memory")
; template <class Epi, class Sched, bool ALIGN_EPI = false, bool SP2 = false>
; __device__ __forceinline__ void gemm_phase(PG8_LAS unsigned char* lds, const Gemm g, const Sched& S, const Epi& E) {
;     ...
;             const bool last = (t == nt - 2);
;             const char* a1 = cA + (size_t)(t + 1) * kstep;
;             const char* a2 = last ? nA : cA + (size_t)(t + 2) * kstep; const char* b2 = last ? nB : cB + (size_t)(t + 2) * kstep;
;             const char* a3 = a2 + kstep; const char* b3 = b2 + kstep;
;             if (last && has_next) S.a_ready(nxt);
;             if constexpr (SP2) {
;             PG8_LDB(B0, 0, 0); PG8_LDB(B1, 0, 1); PG8_SCHED; PG8_LDA(At, 0, 0); PG8_STAGE(PG8_SA(1, 1), a1 + hstep, voffA);
;             PG8_WAIT_V(8); PG8_WAIT_L(0); PG8_BAR; PG8_MMA(0, 0, At, B0); PG8_MMA(0, 1, At, B1); PG8_BAR; PG8_SCHED;
;             PG8_LDA(At, 0, 1); PG8_STAGE(PG8_SB(0, 0), b2, voffB); PG8_STAGE(PG8_SB(0, 1), b2 + hstep, voffB); PG8_STAGE(PG8_SA(0, 0), a2, voffA);
;             PG8_WAIT_V(8); PG8_WAIT_L(0); PG8_BAR; PG8_MMA(1, 0, At, B0); PG8_MMA(1, 1, At, B1); PG8_BAR; PG8_SCHED;
.LBB0_738:
	ds_read_b128 v[160:163], v156
	ds_read_b128 v[164:167], v156 offset:1024
	ds_read_b128 v[168:171], v156 offset:2048
	ds_read_b128 v[172:175], v156 offset:3072
	ds_read_b128 v[176:179], v157
	ds_read_b128 v[180:183], v157 offset:1024
	ds_read_b128 v[188:191], v157 offset:2048
	ds_read_b128 v[192:195], v157 offset:3072
	s_add_i32 s71, s36, 2
	s_add_u32 s72, s34, 0x80
	s_addc_u32 s37, s35, 0
	s_cmp_eq_u32 s52, s36
	s_cselect_b32 s36, s14, s72
	s_cselect_b32 s37, s15, s37
	s_cselect_b32 s73, s31, s70
	s_cselect_b32 s72, s30, s69
	v_lshl_add_u64 v[152:153], s[34:35], 0, v[146:147]
	s_add_i32 m0, s42, 0xc000
	ds_read_b128 v[196:199], v158
	ds_read_b128 v[200:203], v158 offset:1024
	ds_read_b128 v[204:207], v158 offset:2048
	ds_read_b128 v[208:211], v158 offset:3072
	ds_read_b128 v[212:215], v158 offset:4096
	ds_read_b128 v[216:219], v158 offset:5120
	ds_read_b128 v[220:223], v158 offset:6144
	ds_read_b128 v[224:227], v158 offset:7168
	global_load_lds_dwordx4 v[152:153], off
	v_lshl_add_u64 v[152:153], s[34:35], 0, v[148:149]
	s_add_i32 m0, s42, 0xe000
	s_nop 0
	global_load_lds_dwordx4 v[152:153], off
	s_waitcnt vmcnt(8)
	s_waitcnt lgkmcnt(0)
	s_barrier
	s_setprio 1
	s_waitcnt lgkmcnt(0)
	v_mfma_f32_16x16x32_bf16 v[126:129], v[160:163], v[196:199], v[126:129]
	v_mfma_f32_16x16x32_bf16 v[122:125], v[168:171], v[196:199], v[122:125]
	v_mfma_f32_16x16x32_bf16 v[110:113], v[160:163], v[204:207], v[110:113]
	v_mfma_f32_16x16x32_bf16 v[106:109], v[168:171], v[204:207], v[106:109]
	v_mfma_f32_16x16x32_bf16 v[94:97], v[160:163], v[212:215], v[94:97]
	v_mfma_f32_16x16x32_bf16 v[90:93], v[168:171], v[212:215], v[90:93]
	v_mfma_f32_16x16x32_bf16 v[78:81], v[160:163], v[220:223], v[78:81]
	v_mfma_f32_16x16x32_bf16 v[74:77], v[168:171], v[220:223], v[74:77]
	v_mfma_f32_16x16x32_bf16 v[126:129], v[164:167], v[200:203], v[126:129]
	v_mfma_f32_16x16x32_bf16 v[122:125], v[172:175], v[200:203], v[122:125]
	v_mfma_f32_16x16x32_bf16 v[110:113], v[164:167], v[208:211], v[110:113]
	v_mfma_f32_16x16x32_bf16 v[106:109], v[172:175], v[208:211], v[106:109]
	v_mfma_f32_16x16x32_bf16 v[94:97], v[164:167], v[216:219], v[94:97]
	v_mfma_f32_16x16x32_bf16 v[90:93], v[172:175], v[216:219], v[90:93]
	v_mfma_f32_16x16x32_bf16 v[78:81], v[164:167], v[224:227], v[78:81]
	v_mfma_f32_16x16x32_bf16 v[74:77], v[172:175], v[224:227], v[74:77]
	s_setprio 0
	s_setprio 1
	v_mfma_f32_16x16x32_bf16 v[118:121], v[176:179], v[196:199], v[118:121]
	v_mfma_f32_16x16x32_bf16 v[114:117], v[188:191], v[196:199], v[114:117]
	v_mfma_f32_16x16x32_bf16 v[102:105], v[176:179], v[204:207], v[102:105]
	v_mfma_f32_16x16x32_bf16 v[98:101], v[188:191], v[204:207], v[98:101]
	v_mfma_f32_16x16x32_bf16 v[86:89], v[176:179], v[212:215], v[86:89]
	v_mfma_f32_16x16x32_bf16 v[82:85], v[188:191], v[212:215], v[82:85]
	v_mfma_f32_16x16x32_bf16 v[70:73], v[176:179], v[220:223], v[70:73]
	v_mfma_f32_16x16x32_bf16 v[66:69], v[188:191], v[220:223], v[66:69]
	v_mfma_f32_16x16x32_bf16 v[118:121], v[180:183], v[200:203], v[118:121]
	v_mfma_f32_16x16x32_bf16 v[114:117], v[192:195], v[200:203], v[114:117]
	v_mfma_f32_16x16x32_bf16 v[102:105], v[180:183], v[208:211], v[102:105]
	v_mfma_f32_16x16x32_bf16 v[98:101], v[192:195], v[208:211], v[98:101]
	v_mfma_f32_16x16x32_bf16 v[86:89], v[180:183], v[216:219], v[86:89]
	v_mfma_f32_16x16x32_bf16 v[82:85], v[192:195], v[216:219], v[82:85]
	v_mfma_f32_16x16x32_bf16 v[70:73], v[180:183], v[224:227], v[70:73]
	v_mfma_f32_16x16x32_bf16 v[66:69], v[192:195], v[224:227], v[66:69]
	s_setprio 0
	s_barrier
	s_add_i32 s74, s13, s41
	v_lshl_add_u64 v[152:153], s[72:73], 0, v[134:135]
	s_mov_b32 m0, s74
	ds_read_b128 v[196:199], v158 offset:16384
	ds_read_b128 v[200:203], v158 offset:17408
	ds_read_b128 v[204:207], v158 offset:18432
	ds_read_b128 v[208:211], v158 offset:19456
	ds_read_b128 v[212:215], v158 offset:20480
	ds_read_b128 v[216:219], v158 offset:21504
	ds_read_b128 v[220:223], v158 offset:22528
	ds_read_b128 v[224:227], v158 offset:23552
	global_load_lds_dwordx4 v[152:153], off
	s_add_i32 m0, s74, 0x2000
	v_lshl_add_u64 v[184:185], s[72:73], 0, v[130:131]
	s_add_u32 s72, s72, s6
	s_addc_u32 s73, s73, s7
	s_add_i32 s74, s53, s41
	global_load_lds_dwordx4 v[184:185], off
	v_lshl_add_u64 v[228:229], s[72:73], 0, v[134:135]
	s_mov_b32 m0, s74
	v_lshl_add_u64 v[230:231], s[72:73], 0, v[130:131]
	global_load_lds_dwordx4 v[228:229], off
	s_add_i32 m0, s74, 0x2000
	v_lshl_add_u64 v[232:233], s[36:37], 0, v[136:137]
	global_load_lds_dwordx4 v[230:231], off
	s_mov_b32 m0, s42
	v_lshl_add_u64 v[234:235], s[36:37], 0, v[132:133]
	global_load_lds_dwordx4 v[232:233], off
	s_mov_b32 m0, s43
	s_nop 0
	global_load_lds_dwordx4 v[234:235], off
	s_waitcnt vmcnt(8)
	s_waitcnt lgkmcnt(0)
	s_barrier
; #define PG8_STAGE(bufoff, gbase, voff) do { _Pragma("unroll") for (int _i = 0; _i < 2; ++_i) \
;         __builtin_amdgcn_global_load_lds((const unsigned*)((const char*)(gbase) + (voff)[_i]), (PG8_LAS unsigned*)(lds + (bufoff) + ldsw + _i * 8192), 16, 0, 0); } while (0)
; #define PG8_LDA(dst, b, h) do { _Pragma("unroll") for (int m = 0; m < 4; ++m) _Pragma("unroll") for (int k = 0; k < 2; ++k) dst[m][k] = *(const PG8_LAS bf16x8*)(lds + PG8_SA(b, h) + aoff + m * 2048 + k * 1024); } while (0)
; #define PG8_LDB(dst, b, h) do { _Pragma("unroll") for (int n = 0; n < 2; ++n) _Pragma("unroll") for (int k = 0; k < 2; ++k) dst[n][k] = *(const PG8_LAS bf16x8*)(lds + PG8_SB(b, h) + boff + n * 2048 + k * 1024); } while (0)
; #define PG8_MMA(ai, bj, At, Bt) do { __builtin_amdgcn_s_setprio(1); _Pragma("unroll") for (int m = 0; m < 4; ++m) _Pragma("unroll") for (int n = 0; n < 2; ++n) _Pragma("unroll") for (int k = 0; k < 2; ++k) \
;         acc[ai][bj][m][n] = __builtin_amdgcn_mfma_f32_16x16x32_bf16(Bt[n][k], At[m][k], acc[ai][bj][m][n], 0, 0, 0); __builtin_amdgcn_s_setprio(0); } while (0)
; #define PG8_WAIT_V(n) asm volatile("s_waitcnt vmcnt(" #n ")" ::: "memory")
; #define PG8_WAIT_L(n) asm volatile("s_waitcnt lgkmcnt(" #n ")" ::: "memory")
; #define PG8_BAR __builtin_amdgcn_s_barrier()
; #define PG8_SCHED __builtin_amdgcn_sched_barrier(0)
; template <class Epi, class Sched, bool ALIGN_EPI = false, bool SP2 = false>
; __device__ __forceinline__ void gemm_phase(PG8_LAS unsigned char* lds, const Gemm g, const Sched& S, const Epi& E) {
;     ...
;             PG8_WAIT_V(8); PG8_WAIT_L(0); PG8_BAR; PG8_MMA(1, 0, At, B0); PG8_MMA(1, 1, At, B1); PG8_BAR; PG8_SCHED;
;             PG8_LDB(B0, 1, 0); PG8_LDB(B1, 1, 1); PG8_SCHED; PG8_LDA(At, 1, 0); PG8_STAGE(PG8_SA(0, 1), a2 + hstep, voffA);
;             PG8_WAIT_V(8); PG8_WAIT_L(0); PG8_BAR; PG8_MMA(0, 0, At, B0); PG8_MMA(0, 1, At, B1); PG8_BAR; PG8_SCHED;
	s_setprio 1
	s_waitcnt lgkmcnt(0)
	v_mfma_f32_16x16x32_bf16 v[62:65], v[160:163], v[196:199], v[62:65]
	v_mfma_f32_16x16x32_bf16 v[58:61], v[168:171], v[196:199], v[58:61]
	v_mfma_f32_16x16x32_bf16 v[46:49], v[160:163], v[204:207], v[46:49]
	v_mfma_f32_16x16x32_bf16 v[42:45], v[168:171], v[204:207], v[42:45]
	v_mfma_f32_16x16x32_bf16 v[30:33], v[160:163], v[212:215], v[30:33]
	v_mfma_f32_16x16x32_bf16 v[26:29], v[168:171], v[212:215], v[26:29]
	v_mfma_f32_16x16x32_bf16 v[14:17], v[160:163], v[220:223], v[14:17]
	v_mfma_f32_16x16x32_bf16 v[10:13], v[168:171], v[220:223], v[10:13]
	v_mfma_f32_16x16x32_bf16 v[62:65], v[164:167], v[200:203], v[62:65]
	v_mfma_f32_16x16x32_bf16 v[58:61], v[172:175], v[200:203], v[58:61]
	v_mfma_f32_16x16x32_bf16 v[46:49], v[164:167], v[208:211], v[46:49]
	v_mfma_f32_16x16x32_bf16 v[42:45], v[172:175], v[208:211], v[42:45]
	v_mfma_f32_16x16x32_bf16 v[30:33], v[164:167], v[216:219], v[30:33]
	v_mfma_f32_16x16x32_bf16 v[26:29], v[172:175], v[216:219], v[26:29]
	v_mfma_f32_16x16x32_bf16 v[14:17], v[164:167], v[224:227], v[14:17]
	v_mfma_f32_16x16x32_bf16 v[10:13], v[172:175], v[224:227], v[10:13]
	s_setprio 0
	s_setprio 1
	v_mfma_f32_16x16x32_bf16 v[54:57], v[176:179], v[196:199], v[54:57]
	v_mfma_f32_16x16x32_bf16 v[50:53], v[188:191], v[196:199], v[50:53]
	v_mfma_f32_16x16x32_bf16 v[38:41], v[176:179], v[204:207], v[38:41]
	v_mfma_f32_16x16x32_bf16 v[34:37], v[188:191], v[204:207], v[34:37]
	v_mfma_f32_16x16x32_bf16 v[22:25], v[176:179], v[212:215], v[22:25]
	v_mfma_f32_16x16x32_bf16 v[18:21], v[188:191], v[212:215], v[18:21]
	v_mfma_f32_16x16x32_bf16 v[6:9], v[176:179], v[220:223], v[6:9]
	v_mfma_f32_16x16x32_bf16 v[2:5], v[188:191], v[220:223], v[2:5]
	v_mfma_f32_16x16x32_bf16 v[54:57], v[180:183], v[200:203], v[54:57]
	v_mfma_f32_16x16x32_bf16 v[50:53], v[192:195], v[200:203], v[50:53]
	v_mfma_f32_16x16x32_bf16 v[38:41], v[180:183], v[208:211], v[38:41]
	v_mfma_f32_16x16x32_bf16 v[34:37], v[192:195], v[208:211], v[34:37]
	v_mfma_f32_16x16x32_bf16 v[22:25], v[180:183], v[216:219], v[22:25]
	v_mfma_f32_16x16x32_bf16 v[18:21], v[192:195], v[216:219], v[18:21]
	v_mfma_f32_16x16x32_bf16 v[6:9], v[180:183], v[224:227], v[6:9]
	v_mfma_f32_16x16x32_bf16 v[2:5], v[192:195], v[224:227], v[2:5]
	s_setprio 0
	s_barrier
	s_add_i32 s72, 0, 0x18000
	v_add_u32_e32 v138, s72, v154
	s_add_i32 s73, 0, 0x1c000
	ds_read_b128 v[160:163], v138
	ds_read_b128 v[164:167], v138 offset:1024
	ds_read_b128 v[168:171], v138 offset:2048
	ds_read_b128 v[172:175], v138 offset:3072
	v_add_u32_e32 v138, s73, v154
	ds_read_b128 v[176:179], v138
	ds_read_b128 v[180:183], v138 offset:1024
	ds_read_b128 v[188:191], v138 offset:2048
	ds_read_b128 v[192:195], v138 offset:3072
	s_add_u32 s36, s36, s6
	s_addc_u32 s37, s37, s7
	s_mov_b32 m0, s48
	v_lshl_add_u64 v[236:237], s[36:37], 0, v[136:137]
	ds_read_b128 v[196:199], v158 offset:32768
	ds_read_b128 v[200:203], v158 offset:33792
	ds_read_b128 v[204:207], v158 offset:34816
	ds_read_b128 v[208:211], v158 offset:35840
	ds_read_b128 v[212:215], v158 offset:36864
	ds_read_b128 v[216:219], v158 offset:37888
	ds_read_b128 v[220:223], v158 offset:38912
	ds_read_b128 v[224:227], v158 offset:39936
	global_load_lds_dwordx4 v[236:237], off
	v_lshl_add_u64 v[236:237], s[36:37], 0, v[132:133]
	s_mov_b32 m0, s49
	s_nop 0
	global_load_lds_dwordx4 v[236:237], off
	s_waitcnt vmcnt(8)
	s_waitcnt lgkmcnt(0)
	s_barrier
	s_setprio 1
	s_waitcnt lgkmcnt(0)
	v_mfma_f32_16x16x32_bf16 v[126:129], v[160:163], v[196:199], v[126:129]
	v_mfma_f32_16x16x32_bf16 v[122:125], v[168:171], v[196:199], v[122:125]
	v_mfma_f32_16x16x32_bf16 v[110:113], v[160:163], v[204:207], v[110:113]
	v_mfma_f32_16x16x32_bf16 v[106:109], v[168:171], v[204:207], v[106:109]
	v_mfma_f32_16x16x32_bf16 v[94:97], v[160:163], v[212:215], v[94:97]
	v_mfma_f32_16x16x32_bf16 v[90:93], v[168:171], v[212:215], v[90:93]
	v_mfma_f32_16x16x32_bf16 v[78:81], v[160:163], v[220:223], v[78:81]
	v_mfma_f32_16x16x32_bf16 v[74:77], v[168:171], v[220:223], v[74:77]
	v_mfma_f32_16x16x32_bf16 v[126:129], v[164:167], v[200:203], v[126:129]
	v_mfma_f32_16x16x32_bf16 v[122:125], v[172:175], v[200:203], v[122:125]
	v_mfma_f32_16x16x32_bf16 v[110:113], v[164:167], v[208:211], v[110:113]
	v_mfma_f32_16x16x32_bf16 v[106:109], v[172:175], v[208:211], v[106:109]
	v_mfma_f32_16x16x32_bf16 v[94:97], v[164:167], v[216:219], v[94:97]
	v_mfma_f32_16x16x32_bf16 v[90:93], v[172:175], v[216:219], v[90:93]
	v_mfma_f32_16x16x32_bf16 v[78:81], v[164:167], v[224:227], v[78:81]
	v_mfma_f32_16x16x32_bf16 v[74:77], v[172:175], v[224:227], v[74:77]
	s_setprio 0
	s_setprio 1
	v_mfma_f32_16x16x32_bf16 v[118:121], v[176:179], v[196:199], v[118:121]
	v_mfma_f32_16x16x32_bf16 v[114:117], v[188:191], v[196:199], v[114:117]
	v_mfma_f32_16x16x32_bf16 v[102:105], v[176:179], v[204:207], v[102:105]
	v_mfma_f32_16x16x32_bf16 v[98:101], v[188:191], v[204:207], v[98:101]
	v_mfma_f32_16x16x32_bf16 v[86:89], v[176:179], v[212:215], v[86:89]
	v_mfma_f32_16x16x32_bf16 v[82:85], v[188:191], v[212:215], v[82:85]
	v_mfma_f32_16x16x32_bf16 v[70:73], v[176:179], v[220:223], v[70:73]
	v_mfma_f32_16x16x32_bf16 v[66:69], v[188:191], v[220:223], v[66:69]
	v_mfma_f32_16x16x32_bf16 v[118:121], v[180:183], v[200:203], v[118:121]
	v_mfma_f32_16x16x32_bf16 v[114:117], v[192:195], v[200:203], v[114:117]
	v_mfma_f32_16x16x32_bf16 v[102:105], v[180:183], v[208:211], v[102:105]
	v_mfma_f32_16x16x32_bf16 v[98:101], v[192:195], v[208:211], v[98:101]
	v_mfma_f32_16x16x32_bf16 v[86:89], v[180:183], v[216:219], v[86:89]
	v_mfma_f32_16x16x32_bf16 v[82:85], v[192:195], v[216:219], v[82:85]
	v_mfma_f32_16x16x32_bf16 v[70:73], v[180:183], v[224:227], v[70:73]
	v_mfma_f32_16x16x32_bf16 v[66:69], v[192:195], v[224:227], v[66:69]
	s_setprio 0
	s_barrier
; #define PG8_STAGE(bufoff, gbase, voff) do { _Pragma("unroll") for (int _i = 0; _i < 2; ++_i) \
;         __builtin_amdgcn_global_load_lds((const unsigned*)((const char*)(gbase) + (voff)[_i]), (PG8_LAS unsigned*)(lds + (bufoff) + ldsw + _i * 8192), 16, 0, 0); } while (0)
; #define PG8_LDA(dst, b, h) do { _Pragma("unroll") for (int m = 0; m < 4; ++m) _Pragma("unroll") for (int k = 0; k < 2; ++k) dst[m][k] = *(const PG8_LAS bf16x8*)(lds + PG8_SA(b, h) + aoff + m * 2048 + k * 1024); } while (0)
; #define PG8_MMA(ai, bj, At, Bt) do { __builtin_amdgcn_s_setprio(1); _Pragma("unroll") for (int m = 0; m < 4; ++m) _Pragma("unroll") for (int n = 0; n < 2; ++n) _Pragma("unroll") for (int k = 0; k < 2; ++k) \
;         acc[ai][bj][m][n] = __builtin_amdgcn_mfma_f32_16x16x32_bf16(Bt[n][k], At[m][k], acc[ai][bj][m][n], 0, 0, 0); __builtin_amdgcn_s_setprio(0); } while (0)
; #define PG8_WAIT_V(n) asm volatile("s_waitcnt vmcnt(" #n ")" ::: "memory")
; #define PG8_WAIT_L(n) asm volatile("s_waitcnt lgkmcnt(" #n ")" ::: "memory")
; #define PG8_BAR __builtin_amdgcn_s_barrier()
; #define PG8_SCHED __builtin_amdgcn_sched_barrier(0)
; template <class Epi, class Sched, bool ALIGN_EPI = false, bool SP2 = false>
; __device__ __forceinline__ void gemm_phase(PG8_LAS unsigned char* lds, const Gemm g, const Sched& S, const Epi& E) {
;     ...
;         for (int t = 0; t < nt; t += 2) {
;             const bool last = (t == nt - 2);
;             const char* a1 = cA + (size_t)(t + 1) * kstep;
;             const char* a2 = last ? nA : cA + (size_t)(t + 2) * kstep; const char* b2 = last ? nB : cB + (size_t)(t + 2) * kstep;
;             const char* a3 = a2 + kstep; const char* b3 = b2 + kstep;
;     ...
;             PG8_LDA(At, 1, 1); PG8_STAGE(PG8_SB(1, 0), b3, voffB); PG8_STAGE(PG8_SB(1, 1), b3 + hstep, voffB); PG8_STAGE(PG8_SA(1, 0), a3, voffA);
;             PG8_WAIT_V(8); PG8_WAIT_L(0); PG8_BAR; PG8_MMA(1, 0, At, B0); PG8_MMA(1, 1, At, B1); PG8_BAR; PG8_SCHED;
	s_add_i32 s36, s72, s41
	v_lshl_add_u64 v[152:153], v[152:153], 0, s[24:25]
	s_mov_b32 m0, s36
	ds_read_b128 v[196:199], v158 offset:49152
	ds_read_b128 v[200:203], v158 offset:50176
	ds_read_b128 v[204:207], v158 offset:51200
	ds_read_b128 v[208:211], v158 offset:52224
	ds_read_b128 v[212:215], v158 offset:53248
	ds_read_b128 v[216:219], v158 offset:54272
	ds_read_b128 v[220:223], v158 offset:55296
	ds_read_b128 v[224:227], v158 offset:56320
	global_load_lds_dwordx4 v[152:153], off
	v_lshl_add_u64 v[152:153], v[184:185], 0, s[24:25]
	s_add_i32 m0, s36, 0x2000
	s_add_i32 s36, s73, s41
	global_load_lds_dwordx4 v[152:153], off
	v_lshl_add_u64 v[152:153], v[228:229], 0, s[24:25]
	s_mov_b32 m0, s36
	s_nop 0
	global_load_lds_dwordx4 v[152:153], off
	v_lshl_add_u64 v[152:153], v[230:231], 0, s[24:25]
	s_add_i32 m0, s36, 0x2000
	s_nop 0
	global_load_lds_dwordx4 v[152:153], off
	v_lshl_add_u64 v[152:153], v[232:233], 0, s[24:25]
	s_mov_b32 m0, s11
	s_nop 0
	global_load_lds_dwordx4 v[152:153], off
	v_lshl_add_u64 v[152:153], v[234:235], 0, s[24:25]
	s_mov_b32 m0, s50
	s_nop 0
	global_load_lds_dwordx4 v[152:153], off
	s_waitcnt vmcnt(8)
	s_waitcnt lgkmcnt(0)
	s_barrier
	s_setprio 1
	s_waitcnt lgkmcnt(0)
	v_mfma_f32_16x16x32_bf16 v[62:65], v[160:163], v[196:199], v[62:65]
	v_mfma_f32_16x16x32_bf16 v[58:61], v[168:171], v[196:199], v[58:61]
	v_mfma_f32_16x16x32_bf16 v[46:49], v[160:163], v[204:207], v[46:49]
	v_mfma_f32_16x16x32_bf16 v[42:45], v[168:171], v[204:207], v[42:45]
	v_mfma_f32_16x16x32_bf16 v[30:33], v[160:163], v[212:215], v[30:33]
	v_mfma_f32_16x16x32_bf16 v[26:29], v[168:171], v[212:215], v[26:29]
	v_mfma_f32_16x16x32_bf16 v[14:17], v[160:163], v[220:223], v[14:17]
	v_mfma_f32_16x16x32_bf16 v[10:13], v[168:171], v[220:223], v[10:13]
	v_mfma_f32_16x16x32_bf16 v[62:65], v[164:167], v[200:203], v[62:65]
	v_mfma_f32_16x16x32_bf16 v[58:61], v[172:175], v[200:203], v[58:61]
	v_mfma_f32_16x16x32_bf16 v[46:49], v[164:167], v[208:211], v[46:49]
	v_mfma_f32_16x16x32_bf16 v[42:45], v[172:175], v[208:211], v[42:45]
	v_mfma_f32_16x16x32_bf16 v[30:33], v[164:167], v[216:219], v[30:33]
	v_mfma_f32_16x16x32_bf16 v[26:29], v[172:175], v[216:219], v[26:29]
	v_mfma_f32_16x16x32_bf16 v[14:17], v[164:167], v[224:227], v[14:17]
	v_mfma_f32_16x16x32_bf16 v[10:13], v[172:175], v[224:227], v[10:13]
	s_setprio 0
	s_setprio 1
	v_mfma_f32_16x16x32_bf16 v[54:57], v[176:179], v[196:199], v[54:57]
	v_mfma_f32_16x16x32_bf16 v[50:53], v[188:191], v[196:199], v[50:53]
	v_mfma_f32_16x16x32_bf16 v[38:41], v[176:179], v[204:207], v[38:41]
	v_mfma_f32_16x16x32_bf16 v[34:37], v[188:191], v[204:207], v[34:37]
	v_mfma_f32_16x16x32_bf16 v[22:25], v[176:179], v[212:215], v[22:25]
	v_mfma_f32_16x16x32_bf16 v[18:21], v[188:191], v[212:215], v[18:21]
	v_mfma_f32_16x16x32_bf16 v[6:9], v[176:179], v[220:223], v[6:9]
	v_mfma_f32_16x16x32_bf16 v[2:5], v[188:191], v[220:223], v[2:5]
	v_mfma_f32_16x16x32_bf16 v[54:57], v[180:183], v[200:203], v[54:57]
	v_mfma_f32_16x16x32_bf16 v[50:53], v[192:195], v[200:203], v[50:53]
	v_mfma_f32_16x16x32_bf16 v[38:41], v[180:183], v[208:211], v[38:41]
	v_mfma_f32_16x16x32_bf16 v[34:37], v[192:195], v[208:211], v[34:37]
	v_mfma_f32_16x16x32_bf16 v[22:25], v[180:183], v[216:219], v[22:25]
	v_mfma_f32_16x16x32_bf16 v[18:21], v[192:195], v[216:219], v[18:21]
	v_mfma_f32_16x16x32_bf16 v[6:9], v[180:183], v[224:227], v[6:9]
	v_mfma_f32_16x16x32_bf16 v[2:5], v[192:195], v[224:227], v[2:5]
	s_setprio 0
	s_add_u32 s34, s34, 0x100
	s_addc_u32 s35, s35, 0
	s_add_u32 s69, s69, 0x100
	s_addc_u32 s70, s70, 0
	s_cmp_ge_i32 s71, s0
	s_mov_b32 s36, s71
	s_barrier
	s_cbranch_scc0 .LBB0_738

; #define PG8_STAGE(bufoff, gbase, voff) do { _Pragma("unroll") for (int _i = 0; _i < 2; ++_i) \
;         __builtin_amdgcn_global_load_lds((const unsigned*)((const char*)(gbase) + (voff)[_i]), (PG8_LAS unsigned*)(lds + (bufoff) + ldsw + _i * 8192), 16, 0, 0); } while (0)
; #define PG8_LDA(dst, b, h) do { _Pragma("unroll") for (int m = 0; m < 4; ++m) _Pragma("unroll") for (int k = 0; k < 2; ++k) dst[m][k] = *(const PG8_LAS bf16x8*)(lds + PG8_SA(b, h) + aoff + m * 2048 + k * 1024); } while (0)
; #define PG8_LDB(dst, b, h) do { _Pragma("unroll") for (int n = 0; n < 2; ++n) _Pragma("unroll") for (int k = 0; k < 2; ++k) dst[n][k] = *(const PG8_LAS bf16x8*)(lds + PG8_SB(b, h) + boff + n * 2048 + k * 1024); } while (0)
; #define PG8_MMA(ai, bj, At, Bt) do { __builtin_amdgcn_s_setprio(1); _Pragma("unroll") for (int m = 0; m < 4; ++m) _Pragma("unroll") for (int n = 0; n < 2; ++n) _Pragma("unroll") for (int k = 0; k < 2; ++k) \
;         acc[ai][bj][m][n] = __builtin_amdgcn_mfma_f32_16x16x32_bf16(Bt[n][k], At[m][k], acc[ai][bj][m][n], 0, 0, 0); __builtin_amdgcn_s_setprio(0); } while (0)
; #define PG8_WAIT_V(n) asm volatile("s_waitcnt vmcnt(" #n ")" ::: "memory")
; #define PG8_WAIT_L(n) asm volatile("s_waitcnt lgkmcnt(" #n ")" ::: "memory")
; template <class Epi, class Sched, bool ALIGN_EPI = false, bool SP2 = false>
; __device__ __forceinline__ void gemm_phase(PG8_LAS unsigned char* lds, const Gemm g, const Sched& S, const Epi& E) {
;     ...
;             const bool last = (t == nt - 2);
;             const char* a1 = cA + (size_t)(t + 1) * kstep;
;             const char* a2 = last ? nA : cA + (size_t)(t + 2) * kstep; const char* b2 = last ? nB : cB + (size_t)(t + 2) * kstep;
;             const char* a3 = a2 + kstep; const char* b3 = b2 + kstep;
;             if (last && has_next) S.a_ready(nxt);
;             if constexpr (SP2) {
;             PG8_LDB(B0, 0, 0); PG8_LDB(B1, 0, 1); PG8_SCHED; PG8_LDA(At, 0, 0); PG8_STAGE(PG8_SA(1, 1), a1 + hstep, voffA);
;             PG8_WAIT_V(8); PG8_WAIT_L(0); PG8_BAR; PG8_MMA(0, 0, At, B0); PG8_MMA(0, 1, At, B1); PG8_BAR; PG8_SCHED;
;             PG8_LDA(At, 0, 1); PG8_STAGE(PG8_SB(0, 0), b2, voffB); PG8_STAGE(PG8_SB(0, 1), b2 + hstep, voffB); PG8_STAGE(PG8_SA(0, 0), a2, voffA);
;             PG8_WAIT_V(8); PG8_WAIT_L(0); PG8_BAR; PG8_MMA(1, 0, At, B0); PG8_MMA(1, 1, At, B1); PG8_BAR; PG8_SCHED;
.LBB0_771:
	ds_read_b128 v[156:159], v152
	ds_read_b128 v[160:163], v152 offset:1024
	ds_read_b128 v[164:167], v152 offset:2048
	ds_read_b128 v[168:171], v152 offset:3072
	ds_read_b128 v[172:175], v153
	ds_read_b128 v[176:179], v153 offset:1024
	ds_read_b128 v[180:183], v153 offset:2048
	ds_read_b128 v[188:191], v153 offset:3072
	s_add_i32 s65, s34, 2
	s_add_u32 s66, s30, 0x80
	s_addc_u32 s35, s31, 0
	s_cmp_eq_u32 s52, s34
	s_cselect_b32 s34, s4, s66
	s_cselect_b32 s35, s5, s35
	s_cselect_b32 s67, s29, s63
	s_cselect_b32 s66, s28, s62
	v_lshl_add_u64 v[184:185], s[30:31], 0, v[142:143]
	s_add_i32 m0, s40, 0xc000
	ds_read_b128 v[192:195], v154
	ds_read_b128 v[196:199], v154 offset:1024
	ds_read_b128 v[200:203], v154 offset:2048
	ds_read_b128 v[204:207], v154 offset:3072
	ds_read_b128 v[208:211], v154 offset:4096
	ds_read_b128 v[212:215], v154 offset:5120
	ds_read_b128 v[216:219], v154 offset:6144
	ds_read_b128 v[220:223], v154 offset:7168
	global_load_lds_dwordx4 v[184:185], off
	v_lshl_add_u64 v[184:185], s[30:31], 0, v[144:145]
	s_add_i32 m0, s40, 0xe000
	s_nop 0
	global_load_lds_dwordx4 v[184:185], off
	s_waitcnt vmcnt(8)
	s_waitcnt lgkmcnt(0)
	s_barrier
	s_setprio 1
	s_waitcnt lgkmcnt(0)
	v_mfma_f32_16x16x32_bf16 v[122:125], v[156:159], v[192:195], v[122:125]
	v_mfma_f32_16x16x32_bf16 v[126:129], v[164:167], v[192:195], v[126:129]
	v_mfma_f32_16x16x32_bf16 v[110:113], v[156:159], v[200:203], v[110:113]
	v_mfma_f32_16x16x32_bf16 v[106:109], v[164:167], v[200:203], v[106:109]
	v_mfma_f32_16x16x32_bf16 v[94:97], v[156:159], v[208:211], v[94:97]
	v_mfma_f32_16x16x32_bf16 v[90:93], v[164:167], v[208:211], v[90:93]
	v_mfma_f32_16x16x32_bf16 v[78:81], v[156:159], v[216:219], v[78:81]
	v_mfma_f32_16x16x32_bf16 v[74:77], v[164:167], v[216:219], v[74:77]
	v_mfma_f32_16x16x32_bf16 v[122:125], v[160:163], v[196:199], v[122:125]
	v_mfma_f32_16x16x32_bf16 v[126:129], v[168:171], v[196:199], v[126:129]
	v_mfma_f32_16x16x32_bf16 v[110:113], v[160:163], v[204:207], v[110:113]
	v_mfma_f32_16x16x32_bf16 v[106:109], v[168:171], v[204:207], v[106:109]
	v_mfma_f32_16x16x32_bf16 v[94:97], v[160:163], v[212:215], v[94:97]
	v_mfma_f32_16x16x32_bf16 v[90:93], v[168:171], v[212:215], v[90:93]
	v_mfma_f32_16x16x32_bf16 v[78:81], v[160:163], v[220:223], v[78:81]
	v_mfma_f32_16x16x32_bf16 v[74:77], v[168:171], v[220:223], v[74:77]
	s_setprio 0
	s_setprio 1
	v_mfma_f32_16x16x32_bf16 v[118:121], v[172:175], v[192:195], v[118:121]
	v_mfma_f32_16x16x32_bf16 v[114:117], v[180:183], v[192:195], v[114:117]
	v_mfma_f32_16x16x32_bf16 v[102:105], v[172:175], v[200:203], v[102:105]
	v_mfma_f32_16x16x32_bf16 v[98:101], v[180:183], v[200:203], v[98:101]
	v_mfma_f32_16x16x32_bf16 v[86:89], v[172:175], v[208:211], v[86:89]
	v_mfma_f32_16x16x32_bf16 v[82:85], v[180:183], v[208:211], v[82:85]
	v_mfma_f32_16x16x32_bf16 v[70:73], v[172:175], v[216:219], v[70:73]
	v_mfma_f32_16x16x32_bf16 v[66:69], v[180:183], v[216:219], v[66:69]
	v_mfma_f32_16x16x32_bf16 v[118:121], v[176:179], v[196:199], v[118:121]
	v_mfma_f32_16x16x32_bf16 v[114:117], v[188:191], v[196:199], v[114:117]
	v_mfma_f32_16x16x32_bf16 v[102:105], v[176:179], v[204:207], v[102:105]
	v_mfma_f32_16x16x32_bf16 v[98:101], v[188:191], v[204:207], v[98:101]
	v_mfma_f32_16x16x32_bf16 v[86:89], v[176:179], v[212:215], v[86:89]
	v_mfma_f32_16x16x32_bf16 v[82:85], v[188:191], v[212:215], v[82:85]
	v_mfma_f32_16x16x32_bf16 v[70:73], v[176:179], v[220:223], v[70:73]
	v_mfma_f32_16x16x32_bf16 v[66:69], v[188:191], v[220:223], v[66:69]
	s_setprio 0
	s_barrier
	s_add_i32 s68, s55, s39
	v_lshl_add_u64 v[184:185], s[66:67], 0, v[132:133]
	s_mov_b32 m0, s68
	ds_read_b128 v[192:195], v154 offset:16384
	ds_read_b128 v[196:199], v154 offset:17408
	ds_read_b128 v[200:203], v154 offset:18432
	ds_read_b128 v[204:207], v154 offset:19456
	ds_read_b128 v[208:211], v154 offset:20480
	ds_read_b128 v[212:215], v154 offset:21504
	ds_read_b128 v[216:219], v154 offset:22528
	ds_read_b128 v[220:223], v154 offset:23552
	global_load_lds_dwordx4 v[184:185], off
	s_add_i32 m0, s68, 0x2000
	v_lshl_add_u64 v[224:225], s[66:67], 0, v[136:137]
	s_add_u32 s66, s66, s12
	s_addc_u32 s67, s67, s13
	s_add_i32 s68, s56, s39
	global_load_lds_dwordx4 v[224:225], off
	v_lshl_add_u64 v[226:227], s[66:67], 0, v[132:133]
	s_mov_b32 m0, s68
	v_lshl_add_u64 v[228:229], s[66:67], 0, v[136:137]
	global_load_lds_dwordx4 v[226:227], off
	s_add_i32 m0, s68, 0x2000
	v_lshl_add_u64 v[230:231], s[34:35], 0, v[130:131]
	global_load_lds_dwordx4 v[228:229], off
	s_mov_b32 m0, s40
	v_lshl_add_u64 v[232:233], s[34:35], 0, v[134:135]
	global_load_lds_dwordx4 v[230:231], off
	s_mov_b32 m0, s41
	s_nop 0
	global_load_lds_dwordx4 v[232:233], off
	s_waitcnt vmcnt(8)
	s_waitcnt lgkmcnt(0)
	s_barrier
; #define PG8_STAGE(bufoff, gbase, voff) do { _Pragma("unroll") for (int _i = 0; _i < 2; ++_i) \
;         __builtin_amdgcn_global_load_lds((const unsigned*)((const char*)(gbase) + (voff)[_i]), (PG8_LAS unsigned*)(lds + (bufoff) + ldsw + _i * 8192), 16, 0, 0); } while (0)
; #define PG8_LDA(dst, b, h) do { _Pragma("unroll") for (int m = 0; m < 4; ++m) _Pragma("unroll") for (int k = 0; k < 2; ++k) dst[m][k] = *(const PG8_LAS bf16x8*)(lds + PG8_SA(b, h) + aoff + m * 2048 + k * 1024); } while (0)
; #define PG8_LDB(dst, b, h) do { _Pragma("unroll") for (int n = 0; n < 2; ++n) _Pragma("unroll") for (int k = 0; k < 2; ++k) dst[n][k] = *(const PG8_LAS bf16x8*)(lds + PG8_SB(b, h) + boff + n * 2048 + k * 1024); } while (0)
; #define PG8_MMA(ai, bj, At, Bt) do { __builtin_amdgcn_s_setprio(1); _Pragma("unroll") for (int m = 0; m < 4; ++m) _Pragma("unroll") for (int n = 0; n < 2; ++n) _Pragma("unroll") for (int k = 0; k < 2; ++k) \
;         acc[ai][bj][m][n] = __builtin_amdgcn_mfma_f32_16x16x32_bf16(Bt[n][k], At[m][k], acc[ai][bj][m][n], 0, 0, 0); __builtin_amdgcn_s_setprio(0); } while (0)
; #define PG8_WAIT_V(n) asm volatile("s_waitcnt vmcnt(" #n ")" ::: "memory")
; #define PG8_WAIT_L(n) asm volatile("s_waitcnt lgkmcnt(" #n ")" ::: "memory")
; #define PG8_BAR __builtin_amdgcn_s_barrier()
; #define PG8_SCHED __builtin_amdgcn_sched_barrier(0)
; template <class Epi, class Sched, bool ALIGN_EPI = false, bool SP2 = false>
; __device__ __forceinline__ void gemm_phase(PG8_LAS unsigned char* lds, const Gemm g, const Sched& S, const Epi& E) {
;     ...
;             PG8_WAIT_V(8); PG8_WAIT_L(0); PG8_BAR; PG8_MMA(1, 0, At, B0); PG8_MMA(1, 1, At, B1); PG8_BAR; PG8_SCHED;
;             PG8_LDB(B0, 1, 0); PG8_LDB(B1, 1, 1); PG8_SCHED; PG8_LDA(At, 1, 0); PG8_STAGE(PG8_SA(0, 1), a2 + hstep, voffA);
;             PG8_WAIT_V(8); PG8_WAIT_L(0); PG8_BAR; PG8_MMA(0, 0, At, B0); PG8_MMA(0, 1, At, B1); PG8_BAR; PG8_SCHED;
	s_setprio 1
	s_waitcnt lgkmcnt(0)
	v_mfma_f32_16x16x32_bf16 v[62:65], v[156:159], v[192:195], v[62:65]
	v_mfma_f32_16x16x32_bf16 v[58:61], v[164:167], v[192:195], v[58:61]
	v_mfma_f32_16x16x32_bf16 v[46:49], v[156:159], v[200:203], v[46:49]
	v_mfma_f32_16x16x32_bf16 v[42:45], v[164:167], v[200:203], v[42:45]
	v_mfma_f32_16x16x32_bf16 v[30:33], v[156:159], v[208:211], v[30:33]
	v_mfma_f32_16x16x32_bf16 v[26:29], v[164:167], v[208:211], v[26:29]
	v_mfma_f32_16x16x32_bf16 v[14:17], v[156:159], v[216:219], v[14:17]
	v_mfma_f32_16x16x32_bf16 v[10:13], v[164:167], v[216:219], v[10:13]
	v_mfma_f32_16x16x32_bf16 v[62:65], v[160:163], v[196:199], v[62:65]
	v_mfma_f32_16x16x32_bf16 v[58:61], v[168:171], v[196:199], v[58:61]
	v_mfma_f32_16x16x32_bf16 v[46:49], v[160:163], v[204:207], v[46:49]
	v_mfma_f32_16x16x32_bf16 v[42:45], v[168:171], v[204:207], v[42:45]
	v_mfma_f32_16x16x32_bf16 v[30:33], v[160:163], v[212:215], v[30:33]
	v_mfma_f32_16x16x32_bf16 v[26:29], v[168:171], v[212:215], v[26:29]
	v_mfma_f32_16x16x32_bf16 v[14:17], v[160:163], v[220:223], v[14:17]
	v_mfma_f32_16x16x32_bf16 v[10:13], v[168:171], v[220:223], v[10:13]
	s_setprio 0
	s_setprio 1
	v_mfma_f32_16x16x32_bf16 v[54:57], v[172:175], v[192:195], v[54:57]
	v_mfma_f32_16x16x32_bf16 v[50:53], v[180:183], v[192:195], v[50:53]
	v_mfma_f32_16x16x32_bf16 v[38:41], v[172:175], v[200:203], v[38:41]
	v_mfma_f32_16x16x32_bf16 v[34:37], v[180:183], v[200:203], v[34:37]
	v_mfma_f32_16x16x32_bf16 v[22:25], v[172:175], v[208:211], v[22:25]
	v_mfma_f32_16x16x32_bf16 v[18:21], v[180:183], v[208:211], v[18:21]
	v_mfma_f32_16x16x32_bf16 v[6:9], v[172:175], v[216:219], v[6:9]
	v_mfma_f32_16x16x32_bf16 v[2:5], v[180:183], v[216:219], v[2:5]
	v_mfma_f32_16x16x32_bf16 v[54:57], v[176:179], v[196:199], v[54:57]
	v_mfma_f32_16x16x32_bf16 v[50:53], v[188:191], v[196:199], v[50:53]
	v_mfma_f32_16x16x32_bf16 v[38:41], v[176:179], v[204:207], v[38:41]
	v_mfma_f32_16x16x32_bf16 v[34:37], v[188:191], v[204:207], v[34:37]
	v_mfma_f32_16x16x32_bf16 v[22:25], v[176:179], v[212:215], v[22:25]
	v_mfma_f32_16x16x32_bf16 v[18:21], v[188:191], v[212:215], v[18:21]
	v_mfma_f32_16x16x32_bf16 v[6:9], v[176:179], v[220:223], v[6:9]
	v_mfma_f32_16x16x32_bf16 v[2:5], v[188:191], v[220:223], v[2:5]
	s_setprio 0
	s_barrier
	s_add_i32 s66, 0, 0x18000
	v_add_u32_e32 v138, s66, v150
	s_add_i32 s67, 0, 0x1c000
	ds_read_b128 v[156:159], v138
	ds_read_b128 v[160:163], v138 offset:1024
	ds_read_b128 v[164:167], v138 offset:2048
	ds_read_b128 v[168:171], v138 offset:3072
	v_add_u32_e32 v138, s67, v150
	ds_read_b128 v[172:175], v138
	ds_read_b128 v[176:179], v138 offset:1024
	ds_read_b128 v[180:183], v138 offset:2048
	ds_read_b128 v[188:191], v138 offset:3072
	s_add_u32 s34, s34, s12
	s_addc_u32 s35, s35, s13
	s_mov_b32 m0, s42
	v_lshl_add_u64 v[234:235], s[34:35], 0, v[130:131]
	ds_read_b128 v[192:195], v154 offset:32768
	ds_read_b128 v[196:199], v154 offset:33792
	ds_read_b128 v[200:203], v154 offset:34816
	ds_read_b128 v[204:207], v154 offset:35840
	ds_read_b128 v[208:211], v154 offset:36864
	ds_read_b128 v[212:215], v154 offset:37888
	ds_read_b128 v[216:219], v154 offset:38912
	ds_read_b128 v[220:223], v154 offset:39936
	global_load_lds_dwordx4 v[234:235], off
	v_lshl_add_u64 v[234:235], s[34:35], 0, v[134:135]
	s_mov_b32 m0, s43
	s_nop 0
	global_load_lds_dwordx4 v[234:235], off
	s_waitcnt vmcnt(8)
	s_waitcnt lgkmcnt(0)
	s_barrier
	s_setprio 1
	s_waitcnt lgkmcnt(0)
	v_mfma_f32_16x16x32_bf16 v[122:125], v[156:159], v[192:195], v[122:125]
	v_mfma_f32_16x16x32_bf16 v[126:129], v[164:167], v[192:195], v[126:129]
	v_mfma_f32_16x16x32_bf16 v[110:113], v[156:159], v[200:203], v[110:113]
	v_mfma_f32_16x16x32_bf16 v[106:109], v[164:167], v[200:203], v[106:109]
	v_mfma_f32_16x16x32_bf16 v[94:97], v[156:159], v[208:211], v[94:97]
	v_mfma_f32_16x16x32_bf16 v[90:93], v[164:167], v[208:211], v[90:93]
	v_mfma_f32_16x16x32_bf16 v[78:81], v[156:159], v[216:219], v[78:81]
	v_mfma_f32_16x16x32_bf16 v[74:77], v[164:167], v[216:219], v[74:77]
	v_mfma_f32_16x16x32_bf16 v[122:125], v[160:163], v[196:199], v[122:125]
	v_mfma_f32_16x16x32_bf16 v[126:129], v[168:171], v[196:199], v[126:129]
	v_mfma_f32_16x16x32_bf16 v[110:113], v[160:163], v[204:207], v[110:113]
	v_mfma_f32_16x16x32_bf16 v[106:109], v[168:171], v[204:207], v[106:109]
	v_mfma_f32_16x16x32_bf16 v[94:97], v[160:163], v[212:215], v[94:97]
	v_mfma_f32_16x16x32_bf16 v[90:93], v[168:171], v[212:215], v[90:93]
	v_mfma_f32_16x16x32_bf16 v[78:81], v[160:163], v[220:223], v[78:81]
	v_mfma_f32_16x16x32_bf16 v[74:77], v[168:171], v[220:223], v[74:77]
	s_setprio 0
	s_setprio 1
	v_mfma_f32_16x16x32_bf16 v[118:121], v[172:175], v[192:195], v[118:121]
	v_mfma_f32_16x16x32_bf16 v[114:117], v[180:183], v[192:195], v[114:117]
	v_mfma_f32_16x16x32_bf16 v[102:105], v[172:175], v[200:203], v[102:105]
	v_mfma_f32_16x16x32_bf16 v[98:101], v[180:183], v[200:203], v[98:101]
	v_mfma_f32_16x16x32_bf16 v[86:89], v[172:175], v[208:211], v[86:89]
	v_mfma_f32_16x16x32_bf16 v[82:85], v[180:183], v[208:211], v[82:85]
	v_mfma_f32_16x16x32_bf16 v[70:73], v[172:175], v[216:219], v[70:73]
	v_mfma_f32_16x16x32_bf16 v[66:69], v[180:183], v[216:219], v[66:69]
	v_mfma_f32_16x16x32_bf16 v[118:121], v[176:179], v[196:199], v[118:121]
	v_mfma_f32_16x16x32_bf16 v[114:117], v[188:191], v[196:199], v[114:117]
	v_mfma_f32_16x16x32_bf16 v[102:105], v[176:179], v[204:207], v[102:105]
	v_mfma_f32_16x16x32_bf16 v[98:101], v[188:191], v[204:207], v[98:101]
	v_mfma_f32_16x16x32_bf16 v[86:89], v[176:179], v[212:215], v[86:89]
	v_mfma_f32_16x16x32_bf16 v[82:85], v[188:191], v[212:215], v[82:85]
	v_mfma_f32_16x16x32_bf16 v[70:73], v[176:179], v[220:223], v[70:73]
	v_mfma_f32_16x16x32_bf16 v[66:69], v[188:191], v[220:223], v[66:69]
	s_setprio 0
	s_barrier
; #define PG8_STAGE(bufoff, gbase, voff) do { _Pragma("unroll") for (int _i = 0; _i < 2; ++_i) \
;         __builtin_amdgcn_global_load_lds((const unsigned*)((const char*)(gbase) + (voff)[_i]), (PG8_LAS unsigned*)(lds + (bufoff) + ldsw + _i * 8192), 16, 0, 0); } while (0)
; #define PG8_LDA(dst, b, h) do { _Pragma("unroll") for (int m = 0; m < 4; ++m) _Pragma("unroll") for (int k = 0; k < 2; ++k) dst[m][k] = *(const PG8_LAS bf16x8*)(lds + PG8_SA(b, h) + aoff + m * 2048 + k * 1024); } while (0)
; #define PG8_MMA(ai, bj, At, Bt) do { __builtin_amdgcn_s_setprio(1); _Pragma("unroll") for (int m = 0; m < 4; ++m) _Pragma("unroll") for (int n = 0; n < 2; ++n) _Pragma("unroll") for (int k = 0; k < 2; ++k) \
;         acc[ai][bj][m][n] = __builtin_amdgcn_mfma_f32_16x16x32_bf16(Bt[n][k], At[m][k], acc[ai][bj][m][n], 0, 0, 0); __builtin_amdgcn_s_setprio(0); } while (0)
; #define PG8_WAIT_V(n) asm volatile("s_waitcnt vmcnt(" #n ")" ::: "memory")
; #define PG8_WAIT_L(n) asm volatile("s_waitcnt lgkmcnt(" #n ")" ::: "memory")
; #define PG8_BAR __builtin_amdgcn_s_barrier()
; #define PG8_SCHED __builtin_amdgcn_sched_barrier(0)
; template <class Epi, class Sched, bool ALIGN_EPI = false, bool SP2 = false>
; __device__ __forceinline__ void gemm_phase(PG8_LAS unsigned char* lds, const Gemm g, const Sched& S, const Epi& E) {
;     ...
;         for (int t = 0; t < nt; t += 2) {
;             const bool last = (t == nt - 2);
;             const char* a1 = cA + (size_t)(t + 1) * kstep;
;             const char* a2 = last ? nA : cA + (size_t)(t + 2) * kstep; const char* b2 = last ? nB : cB + (size_t)(t + 2) * kstep;
;             const char* a3 = a2 + kstep; const char* b3 = b2 + kstep;
;     ...
;             PG8_LDA(At, 1, 1); PG8_STAGE(PG8_SB(1, 0), b3, voffB); PG8_STAGE(PG8_SB(1, 1), b3 + hstep, voffB); PG8_STAGE(PG8_SA(1, 0), a3, voffA);
;             PG8_WAIT_V(8); PG8_WAIT_L(0); PG8_BAR; PG8_MMA(1, 0, At, B0); PG8_MMA(1, 1, At, B1); PG8_BAR; PG8_SCHED;
	s_add_i32 s34, s66, s39
	v_lshl_add_u64 v[184:185], v[184:185], 0, s[22:23]
	s_mov_b32 m0, s34
	ds_read_b128 v[192:195], v154 offset:49152
	ds_read_b128 v[196:199], v154 offset:50176
	ds_read_b128 v[200:203], v154 offset:51200
	ds_read_b128 v[204:207], v154 offset:52224
	ds_read_b128 v[208:211], v154 offset:53248
	ds_read_b128 v[212:215], v154 offset:54272
	ds_read_b128 v[216:219], v154 offset:55296
	ds_read_b128 v[220:223], v154 offset:56320
	global_load_lds_dwordx4 v[184:185], off
	v_lshl_add_u64 v[184:185], v[224:225], 0, s[22:23]
	s_add_i32 m0, s34, 0x2000
	s_add_i32 s34, s67, s39
	global_load_lds_dwordx4 v[184:185], off
	v_lshl_add_u64 v[184:185], v[226:227], 0, s[22:23]
	s_mov_b32 m0, s34
	s_nop 0
	global_load_lds_dwordx4 v[184:185], off
	v_lshl_add_u64 v[184:185], v[228:229], 0, s[22:23]
	s_add_i32 m0, s34, 0x2000
	s_nop 0
	global_load_lds_dwordx4 v[184:185], off
	v_lshl_add_u64 v[184:185], v[230:231], 0, s[22:23]
	s_mov_b32 m0, s48
	s_nop 0
	global_load_lds_dwordx4 v[184:185], off
	v_lshl_add_u64 v[184:185], v[232:233], 0, s[22:23]
	s_mov_b32 m0, s49
	s_nop 0
	global_load_lds_dwordx4 v[184:185], off
	s_waitcnt vmcnt(8)
	s_waitcnt lgkmcnt(0)
	s_barrier
	s_setprio 1
	s_waitcnt lgkmcnt(0)
	v_mfma_f32_16x16x32_bf16 v[62:65], v[156:159], v[192:195], v[62:65]
	v_mfma_f32_16x16x32_bf16 v[58:61], v[164:167], v[192:195], v[58:61]
	v_mfma_f32_16x16x32_bf16 v[46:49], v[156:159], v[200:203], v[46:49]
	v_mfma_f32_16x16x32_bf16 v[42:45], v[164:167], v[200:203], v[42:45]
	v_mfma_f32_16x16x32_bf16 v[30:33], v[156:159], v[208:211], v[30:33]
	v_mfma_f32_16x16x32_bf16 v[26:29], v[164:167], v[208:211], v[26:29]
	v_mfma_f32_16x16x32_bf16 v[14:17], v[156:159], v[216:219], v[14:17]
	v_mfma_f32_16x16x32_bf16 v[10:13], v[164:167], v[216:219], v[10:13]
	v_mfma_f32_16x16x32_bf16 v[62:65], v[160:163], v[196:199], v[62:65]
	v_mfma_f32_16x16x32_bf16 v[58:61], v[168:171], v[196:199], v[58:61]
	v_mfma_f32_16x16x32_bf16 v[46:49], v[160:163], v[204:207], v[46:49]
	v_mfma_f32_16x16x32_bf16 v[42:45], v[168:171], v[204:207], v[42:45]
	v_mfma_f32_16x16x32_bf16 v[30:33], v[160:163], v[212:215], v[30:33]
	v_mfma_f32_16x16x32_bf16 v[26:29], v[168:171], v[212:215], v[26:29]
	v_mfma_f32_16x16x32_bf16 v[14:17], v[160:163], v[220:223], v[14:17]
	v_mfma_f32_16x16x32_bf16 v[10:13], v[168:171], v[220:223], v[10:13]
	s_setprio 0
	s_setprio 1
	v_mfma_f32_16x16x32_bf16 v[54:57], v[172:175], v[192:195], v[54:57]
	v_mfma_f32_16x16x32_bf16 v[50:53], v[180:183], v[192:195], v[50:53]
	v_mfma_f32_16x16x32_bf16 v[38:41], v[172:175], v[200:203], v[38:41]
	v_mfma_f32_16x16x32_bf16 v[34:37], v[180:183], v[200:203], v[34:37]
	v_mfma_f32_16x16x32_bf16 v[22:25], v[172:175], v[208:211], v[22:25]
	v_mfma_f32_16x16x32_bf16 v[18:21], v[180:183], v[208:211], v[18:21]
	v_mfma_f32_16x16x32_bf16 v[6:9], v[172:175], v[216:219], v[6:9]
	v_mfma_f32_16x16x32_bf16 v[2:5], v[180:183], v[216:219], v[2:5]
	v_mfma_f32_16x16x32_bf16 v[54:57], v[176:179], v[196:199], v[54:57]
	v_mfma_f32_16x16x32_bf16 v[50:53], v[188:191], v[196:199], v[50:53]
	v_mfma_f32_16x16x32_bf16 v[38:41], v[176:179], v[204:207], v[38:41]
	v_mfma_f32_16x16x32_bf16 v[34:37], v[188:191], v[204:207], v[34:37]
	v_mfma_f32_16x16x32_bf16 v[22:25], v[176:179], v[212:215], v[22:25]
	v_mfma_f32_16x16x32_bf16 v[18:21], v[188:191], v[212:215], v[18:21]
	v_mfma_f32_16x16x32_bf16 v[6:9], v[176:179], v[220:223], v[6:9]
	v_mfma_f32_16x16x32_bf16 v[2:5], v[188:191], v[220:223], v[2:5]
	s_setprio 0
	s_add_u32 s30, s30, 0x100
	s_addc_u32 s31, s31, 0
	s_add_u32 s62, s62, 0x100
	s_addc_u32 s63, s63, 0
	s_cmp_ge_i32 s65, s50
	s_mov_b32 s34, s65
	s_barrier
	s_cbranch_scc0 .LBB0_771

; #define PG8_STAGE(bufoff, gbase, voff) do { _Pragma("unroll") for (int _i = 0; _i < 2; ++_i) \
;         __builtin_amdgcn_global_load_lds((const unsigned*)((const char*)(gbase) + (voff)[_i]), (PG8_LAS unsigned*)(lds + (bufoff) + ldsw + _i * 8192), 16, 0, 0); } while (0)
; #define PG8_LDA(dst, b, h) do { _Pragma("unroll") for (int m = 0; m < 4; ++m) _Pragma("unroll") for (int k = 0; k < 2; ++k) dst[m][k] = *(const PG8_LAS bf16x8*)(lds + PG8_SA(b, h) + aoff + m * 2048 + k * 1024); } while (0)
; #define PG8_LDB(dst, b, h) do { _Pragma("unroll") for (int n = 0; n < 2; ++n) _Pragma("unroll") for (int k = 0; k < 2; ++k) dst[n][k] = *(const PG8_LAS bf16x8*)(lds + PG8_SB(b, h) + boff + n * 2048 + k * 1024); } while (0)
; #define PG8_MMA(ai, bj, At, Bt) do { __builtin_amdgcn_s_setprio(1); _Pragma("unroll") for (int m = 0; m < 4; ++m) _Pragma("unroll") for (int n = 0; n < 2; ++n) _Pragma("unroll") for (int k = 0; k < 2; ++k) \
;         acc[ai][bj][m][n] = __builtin_amdgcn_mfma_f32_16x16x32_bf16(Bt[n][k], At[m][k], acc[ai][bj][m][n], 0, 0, 0); __builtin_amdgcn_s_setprio(0); } while (0)
; #define PG8_WAIT_V(n) asm volatile("s_waitcnt vmcnt(" #n ")" ::: "memory")
; #define PG8_WAIT_L(n) asm volatile("s_waitcnt lgkmcnt(" #n ")" ::: "memory")
; template <class Epi, class Sched, bool ALIGN_EPI = false, bool SP2 = false>
; __device__ __forceinline__ void gemm_phase(PG8_LAS unsigned char* lds, const Gemm g, const Sched& S, const Epi& E) {
;     ...
;             const bool last = (t == nt - 2);
;             const char* a1 = cA + (size_t)(t + 1) * kstep;
;             const char* a2 = last ? nA : cA + (size_t)(t + 2) * kstep; const char* b2 = last ? nB : cB + (size_t)(t + 2) * kstep;
;             const char* a3 = a2 + kstep; const char* b3 = b2 + kstep;
;             if (last && has_next) S.a_ready(nxt);
;             if constexpr (SP2) {
;             PG8_LDB(B0, 0, 0); PG8_LDB(B1, 0, 1); PG8_SCHED; PG8_LDA(At, 0, 0); PG8_STAGE(PG8_SA(1, 1), a1 + hstep, voffA);
;             PG8_WAIT_V(8); PG8_WAIT_L(0); PG8_BAR; PG8_MMA(0, 0, At, B0); PG8_MMA(0, 1, At, B1); PG8_BAR; PG8_SCHED;
;             PG8_LDA(At, 0, 1); PG8_STAGE(PG8_SB(0, 0), b2, voffB); PG8_STAGE(PG8_SB(0, 1), b2 + hstep, voffB); PG8_STAGE(PG8_SA(0, 0), a2, voffA);
;             PG8_WAIT_V(8); PG8_WAIT_L(0); PG8_BAR; PG8_MMA(1, 0, At, B0); PG8_MMA(1, 1, At, B1); PG8_BAR; PG8_SCHED;
.LBB0_791:
	ds_read_b128 v[148:151], v144
	ds_read_b128 v[152:155], v144 offset:1024
	ds_read_b128 v[156:159], v144 offset:2048
	ds_read_b128 v[160:163], v144 offset:3072
	ds_read_b128 v[164:167], v145
	ds_read_b128 v[168:171], v145 offset:1024
	ds_read_b128 v[172:175], v145 offset:2048
	ds_read_b128 v[176:179], v145 offset:3072
	s_add_i32 s56, s24, 2
	s_add_u32 s57, s22, 0x80
	s_addc_u32 s25, s23, 0
	s_cmp_eq_u32 s40, s24
	s_cselect_b32 s24, s4, s57
	s_cselect_b32 s25, s5, s25
	s_cselect_b32 s59, s21, s55
	s_cselect_b32 s58, s20, s54
	v_lshl_add_u64 v[184:185], s[22:23], 0, v[134:135]
	s_add_i32 m0, s30, 0xc000
	ds_read_b128 v[180:183], v146
	ds_read_b128 v[188:191], v146 offset:1024
	ds_read_b128 v[192:195], v146 offset:2048
	ds_read_b128 v[196:199], v146 offset:3072
	ds_read_b128 v[200:203], v146 offset:4096
	ds_read_b128 v[204:207], v146 offset:5120
	ds_read_b128 v[208:211], v146 offset:6144
	ds_read_b128 v[212:215], v146 offset:7168
	global_load_lds_dwordx4 v[184:185], off
	v_lshl_add_u64 v[184:185], s[22:23], 0, v[136:137]
	s_add_i32 m0, s30, 0xe000
	s_nop 0
	global_load_lds_dwordx4 v[184:185], off
	s_waitcnt vmcnt(8)
	s_waitcnt lgkmcnt(0)
	s_barrier
	s_setprio 1
	s_waitcnt lgkmcnt(0)
	v_mfma_f32_16x16x32_bf16 v[126:129], v[148:151], v[180:183], v[126:129]
	v_mfma_f32_16x16x32_bf16 v[122:125], v[156:159], v[180:183], v[122:125]
	v_mfma_f32_16x16x32_bf16 v[110:113], v[148:151], v[192:195], v[110:113]
	v_mfma_f32_16x16x32_bf16 v[106:109], v[156:159], v[192:195], v[106:109]
	v_mfma_f32_16x16x32_bf16 v[94:97], v[148:151], v[200:203], v[94:97]
	v_mfma_f32_16x16x32_bf16 v[90:93], v[156:159], v[200:203], v[90:93]
	v_mfma_f32_16x16x32_bf16 v[78:81], v[148:151], v[208:211], v[78:81]
	v_mfma_f32_16x16x32_bf16 v[74:77], v[156:159], v[208:211], v[74:77]
	v_mfma_f32_16x16x32_bf16 v[126:129], v[152:155], v[188:191], v[126:129]
	v_mfma_f32_16x16x32_bf16 v[122:125], v[160:163], v[188:191], v[122:125]
	v_mfma_f32_16x16x32_bf16 v[110:113], v[152:155], v[196:199], v[110:113]
	v_mfma_f32_16x16x32_bf16 v[106:109], v[160:163], v[196:199], v[106:109]
	v_mfma_f32_16x16x32_bf16 v[94:97], v[152:155], v[204:207], v[94:97]
	v_mfma_f32_16x16x32_bf16 v[90:93], v[160:163], v[204:207], v[90:93]
	v_mfma_f32_16x16x32_bf16 v[78:81], v[152:155], v[212:215], v[78:81]
	v_mfma_f32_16x16x32_bf16 v[74:77], v[160:163], v[212:215], v[74:77]
	s_setprio 0
	s_setprio 1
	v_mfma_f32_16x16x32_bf16 v[118:121], v[164:167], v[180:183], v[118:121]
	v_mfma_f32_16x16x32_bf16 v[114:117], v[172:175], v[180:183], v[114:117]
	v_mfma_f32_16x16x32_bf16 v[102:105], v[164:167], v[192:195], v[102:105]
	v_mfma_f32_16x16x32_bf16 v[98:101], v[172:175], v[192:195], v[98:101]
	v_mfma_f32_16x16x32_bf16 v[86:89], v[164:167], v[200:203], v[86:89]
	v_mfma_f32_16x16x32_bf16 v[82:85], v[172:175], v[200:203], v[82:85]
	v_mfma_f32_16x16x32_bf16 v[70:73], v[164:167], v[208:211], v[70:73]
	v_mfma_f32_16x16x32_bf16 v[66:69], v[172:175], v[208:211], v[66:69]
	v_mfma_f32_16x16x32_bf16 v[118:121], v[168:171], v[188:191], v[118:121]
	v_mfma_f32_16x16x32_bf16 v[114:117], v[176:179], v[188:191], v[114:117]
	v_mfma_f32_16x16x32_bf16 v[102:105], v[168:171], v[196:199], v[102:105]
	v_mfma_f32_16x16x32_bf16 v[98:101], v[176:179], v[196:199], v[98:101]
	v_mfma_f32_16x16x32_bf16 v[86:89], v[168:171], v[204:207], v[86:89]
	v_mfma_f32_16x16x32_bf16 v[82:85], v[176:179], v[204:207], v[82:85]
	v_mfma_f32_16x16x32_bf16 v[70:73], v[168:171], v[212:215], v[70:73]
	v_mfma_f32_16x16x32_bf16 v[66:69], v[176:179], v[212:215], v[66:69]
	s_setprio 0
	s_barrier
	s_add_i32 s57, s43, s29
	v_lshl_add_u64 v[184:185], s[58:59], 0, v[130:131]
	s_mov_b32 m0, s57
	ds_read_b128 v[180:183], v146 offset:16384
	ds_read_b128 v[188:191], v146 offset:17408
	ds_read_b128 v[192:195], v146 offset:18432
	ds_read_b128 v[196:199], v146 offset:19456
	ds_read_b128 v[200:203], v146 offset:20480
	ds_read_b128 v[204:207], v146 offset:21504
	ds_read_b128 v[208:211], v146 offset:22528
	ds_read_b128 v[212:215], v146 offset:23552
	global_load_lds_dwordx4 v[184:185], off
	s_add_i32 m0, s57, 0x2000
	v_lshl_add_u64 v[216:217], s[58:59], 0, v[132:133]
	s_add_u32 s58, s58, s6
	s_addc_u32 s59, s59, s7
	s_add_i32 s57, s48, s29
	global_load_lds_dwordx4 v[216:217], off
	v_lshl_add_u64 v[218:219], s[58:59], 0, v[130:131]
	s_mov_b32 m0, s57
	v_lshl_add_u64 v[220:221], s[58:59], 0, v[132:133]
	global_load_lds_dwordx4 v[218:219], off
	s_add_i32 m0, s57, 0x2000
	v_lshl_add_u64 v[222:223], s[24:25], 0, v[130:131]
	global_load_lds_dwordx4 v[220:221], off
	s_mov_b32 m0, s30
	v_lshl_add_u64 v[224:225], s[24:25], 0, v[132:133]
	global_load_lds_dwordx4 v[222:223], off
	s_mov_b32 m0, s31
	s_nop 0
	global_load_lds_dwordx4 v[224:225], off
	s_waitcnt vmcnt(8)
	s_waitcnt lgkmcnt(0)
	s_barrier
; #define PG8_STAGE(bufoff, gbase, voff) do { _Pragma("unroll") for (int _i = 0; _i < 2; ++_i) \
;         __builtin_amdgcn_global_load_lds((const unsigned*)((const char*)(gbase) + (voff)[_i]), (PG8_LAS unsigned*)(lds + (bufoff) + ldsw + _i * 8192), 16, 0, 0); } while (0)
; #define PG8_LDA(dst, b, h) do { _Pragma("unroll") for (int m = 0; m < 4; ++m) _Pragma("unroll") for (int k = 0; k < 2; ++k) dst[m][k] = *(const PG8_LAS bf16x8*)(lds + PG8_SA(b, h) + aoff + m * 2048 + k * 1024); } while (0)
; #define PG8_LDB(dst, b, h) do { _Pragma("unroll") for (int n = 0; n < 2; ++n) _Pragma("unroll") for (int k = 0; k < 2; ++k) dst[n][k] = *(const PG8_LAS bf16x8*)(lds + PG8_SB(b, h) + boff + n * 2048 + k * 1024); } while (0)
; #define PG8_MMA(ai, bj, At, Bt) do { __builtin_amdgcn_s_setprio(1); _Pragma("unroll") for (int m = 0; m < 4; ++m) _Pragma("unroll") for (int n = 0; n < 2; ++n) _Pragma("unroll") for (int k = 0; k < 2; ++k) \
;         acc[ai][bj][m][n] = __builtin_amdgcn_mfma_f32_16x16x32_bf16(Bt[n][k], At[m][k], acc[ai][bj][m][n], 0, 0, 0); __builtin_amdgcn_s_setprio(0); } while (0)
; #define PG8_WAIT_V(n) asm volatile("s_waitcnt vmcnt(" #n ")" ::: "memory")
; #define PG8_WAIT_L(n) asm volatile("s_waitcnt lgkmcnt(" #n ")" ::: "memory")
; #define PG8_BAR __builtin_amdgcn_s_barrier()
; #define PG8_SCHED __builtin_amdgcn_sched_barrier(0)
; template <class Epi, class Sched, bool ALIGN_EPI = false, bool SP2 = false>
; __device__ __forceinline__ void gemm_phase(PG8_LAS unsigned char* lds, const Gemm g, const Sched& S, const Epi& E) {
;     ...
;             PG8_WAIT_V(8); PG8_WAIT_L(0); PG8_BAR; PG8_MMA(1, 0, At, B0); PG8_MMA(1, 1, At, B1); PG8_BAR; PG8_SCHED;
;             PG8_LDB(B0, 1, 0); PG8_LDB(B1, 1, 1); PG8_SCHED; PG8_LDA(At, 1, 0); PG8_STAGE(PG8_SA(0, 1), a2 + hstep, voffA);
;             PG8_WAIT_V(8); PG8_WAIT_L(0); PG8_BAR; PG8_MMA(0, 0, At, B0); PG8_MMA(0, 1, At, B1); PG8_BAR; PG8_SCHED;
	s_setprio 1
	s_waitcnt lgkmcnt(0)
	v_mfma_f32_16x16x32_bf16 v[62:65], v[148:151], v[180:183], v[62:65]
	v_mfma_f32_16x16x32_bf16 v[58:61], v[156:159], v[180:183], v[58:61]
	v_mfma_f32_16x16x32_bf16 v[46:49], v[148:151], v[192:195], v[46:49]
	v_mfma_f32_16x16x32_bf16 v[42:45], v[156:159], v[192:195], v[42:45]
	v_mfma_f32_16x16x32_bf16 v[30:33], v[148:151], v[200:203], v[30:33]
	v_mfma_f32_16x16x32_bf16 v[26:29], v[156:159], v[200:203], v[26:29]
	v_mfma_f32_16x16x32_bf16 v[14:17], v[148:151], v[208:211], v[14:17]
	v_mfma_f32_16x16x32_bf16 v[10:13], v[156:159], v[208:211], v[10:13]
	v_mfma_f32_16x16x32_bf16 v[62:65], v[152:155], v[188:191], v[62:65]
	v_mfma_f32_16x16x32_bf16 v[58:61], v[160:163], v[188:191], v[58:61]
	v_mfma_f32_16x16x32_bf16 v[46:49], v[152:155], v[196:199], v[46:49]
	v_mfma_f32_16x16x32_bf16 v[42:45], v[160:163], v[196:199], v[42:45]
	v_mfma_f32_16x16x32_bf16 v[30:33], v[152:155], v[204:207], v[30:33]
	v_mfma_f32_16x16x32_bf16 v[26:29], v[160:163], v[204:207], v[26:29]
	v_mfma_f32_16x16x32_bf16 v[14:17], v[152:155], v[212:215], v[14:17]
	v_mfma_f32_16x16x32_bf16 v[10:13], v[160:163], v[212:215], v[10:13]
	s_setprio 0
	s_setprio 1
	v_mfma_f32_16x16x32_bf16 v[54:57], v[164:167], v[180:183], v[54:57]
	v_mfma_f32_16x16x32_bf16 v[50:53], v[172:175], v[180:183], v[50:53]
	v_mfma_f32_16x16x32_bf16 v[38:41], v[164:167], v[192:195], v[38:41]
	v_mfma_f32_16x16x32_bf16 v[34:37], v[172:175], v[192:195], v[34:37]
	v_mfma_f32_16x16x32_bf16 v[22:25], v[164:167], v[200:203], v[22:25]
	v_mfma_f32_16x16x32_bf16 v[18:21], v[172:175], v[200:203], v[18:21]
	v_mfma_f32_16x16x32_bf16 v[6:9], v[164:167], v[208:211], v[6:9]
	v_mfma_f32_16x16x32_bf16 v[2:5], v[172:175], v[208:211], v[2:5]
	v_mfma_f32_16x16x32_bf16 v[54:57], v[168:171], v[188:191], v[54:57]
	v_mfma_f32_16x16x32_bf16 v[50:53], v[176:179], v[188:191], v[50:53]
	v_mfma_f32_16x16x32_bf16 v[38:41], v[168:171], v[196:199], v[38:41]
	v_mfma_f32_16x16x32_bf16 v[34:37], v[176:179], v[196:199], v[34:37]
	v_mfma_f32_16x16x32_bf16 v[22:25], v[168:171], v[204:207], v[22:25]
	v_mfma_f32_16x16x32_bf16 v[18:21], v[176:179], v[204:207], v[18:21]
	v_mfma_f32_16x16x32_bf16 v[6:9], v[168:171], v[212:215], v[6:9]
	v_mfma_f32_16x16x32_bf16 v[2:5], v[176:179], v[212:215], v[2:5]
	s_setprio 0
	s_barrier
	s_add_i32 s57, 0, 0x18000
	v_add_u32_e32 v147, s57, v142
	s_add_i32 s58, 0, 0x1c000
	ds_read_b128 v[148:151], v147
	ds_read_b128 v[152:155], v147 offset:1024
	ds_read_b128 v[156:159], v147 offset:2048
	ds_read_b128 v[160:163], v147 offset:3072
	v_add_u32_e32 v147, s58, v142
	ds_read_b128 v[164:167], v147
	ds_read_b128 v[168:171], v147 offset:1024
	ds_read_b128 v[172:175], v147 offset:2048
	ds_read_b128 v[176:179], v147 offset:3072
	s_add_u32 s24, s24, s6
	s_addc_u32 s25, s25, s7
	s_mov_b32 m0, s34
	v_lshl_add_u64 v[226:227], s[24:25], 0, v[130:131]
	ds_read_b128 v[180:183], v146 offset:32768
	ds_read_b128 v[188:191], v146 offset:33792
	ds_read_b128 v[192:195], v146 offset:34816
	ds_read_b128 v[196:199], v146 offset:35840
	ds_read_b128 v[200:203], v146 offset:36864
	ds_read_b128 v[204:207], v146 offset:37888
	ds_read_b128 v[208:211], v146 offset:38912
	ds_read_b128 v[212:215], v146 offset:39936
	global_load_lds_dwordx4 v[226:227], off
	v_lshl_add_u64 v[226:227], s[24:25], 0, v[132:133]
	s_mov_b32 m0, s35
	s_nop 0
	global_load_lds_dwordx4 v[226:227], off
	s_waitcnt vmcnt(8)
	s_waitcnt lgkmcnt(0)
	s_barrier
	s_setprio 1
	s_waitcnt lgkmcnt(0)
	v_mfma_f32_16x16x32_bf16 v[126:129], v[148:151], v[180:183], v[126:129]
	v_mfma_f32_16x16x32_bf16 v[122:125], v[156:159], v[180:183], v[122:125]
	v_mfma_f32_16x16x32_bf16 v[110:113], v[148:151], v[192:195], v[110:113]
	v_mfma_f32_16x16x32_bf16 v[106:109], v[156:159], v[192:195], v[106:109]
	v_mfma_f32_16x16x32_bf16 v[94:97], v[148:151], v[200:203], v[94:97]
	v_mfma_f32_16x16x32_bf16 v[90:93], v[156:159], v[200:203], v[90:93]
	v_mfma_f32_16x16x32_bf16 v[78:81], v[148:151], v[208:211], v[78:81]
	v_mfma_f32_16x16x32_bf16 v[74:77], v[156:159], v[208:211], v[74:77]
	v_mfma_f32_16x16x32_bf16 v[126:129], v[152:155], v[188:191], v[126:129]
	v_mfma_f32_16x16x32_bf16 v[122:125], v[160:163], v[188:191], v[122:125]
	v_mfma_f32_16x16x32_bf16 v[110:113], v[152:155], v[196:199], v[110:113]
	v_mfma_f32_16x16x32_bf16 v[106:109], v[160:163], v[196:199], v[106:109]
	v_mfma_f32_16x16x32_bf16 v[94:97], v[152:155], v[204:207], v[94:97]
	v_mfma_f32_16x16x32_bf16 v[90:93], v[160:163], v[204:207], v[90:93]
	v_mfma_f32_16x16x32_bf16 v[78:81], v[152:155], v[212:215], v[78:81]
	v_mfma_f32_16x16x32_bf16 v[74:77], v[160:163], v[212:215], v[74:77]
	s_setprio 0
	s_setprio 1
	v_mfma_f32_16x16x32_bf16 v[118:121], v[164:167], v[180:183], v[118:121]
	v_mfma_f32_16x16x32_bf16 v[114:117], v[172:175], v[180:183], v[114:117]
	v_mfma_f32_16x16x32_bf16 v[102:105], v[164:167], v[192:195], v[102:105]
	v_mfma_f32_16x16x32_bf16 v[98:101], v[172:175], v[192:195], v[98:101]
	v_mfma_f32_16x16x32_bf16 v[86:89], v[164:167], v[200:203], v[86:89]
	v_mfma_f32_16x16x32_bf16 v[82:85], v[172:175], v[200:203], v[82:85]
	v_mfma_f32_16x16x32_bf16 v[70:73], v[164:167], v[208:211], v[70:73]
	v_mfma_f32_16x16x32_bf16 v[66:69], v[172:175], v[208:211], v[66:69]
	v_mfma_f32_16x16x32_bf16 v[118:121], v[168:171], v[188:191], v[118:121]
	v_mfma_f32_16x16x32_bf16 v[114:117], v[176:179], v[188:191], v[114:117]
	v_mfma_f32_16x16x32_bf16 v[102:105], v[168:171], v[196:199], v[102:105]
	v_mfma_f32_16x16x32_bf16 v[98:101], v[176:179], v[196:199], v[98:101]
	v_mfma_f32_16x16x32_bf16 v[86:89], v[168:171], v[204:207], v[86:89]
	v_mfma_f32_16x16x32_bf16 v[82:85], v[176:179], v[204:207], v[82:85]
	v_mfma_f32_16x16x32_bf16 v[70:73], v[168:171], v[212:215], v[70:73]
	v_mfma_f32_16x16x32_bf16 v[66:69], v[176:179], v[212:215], v[66:69]
	s_setprio 0
	s_barrier
; #define PG8_STAGE(bufoff, gbase, voff) do { _Pragma("unroll") for (int _i = 0; _i < 2; ++_i) \
;         __builtin_amdgcn_global_load_lds((const unsigned*)((const char*)(gbase) + (voff)[_i]), (PG8_LAS unsigned*)(lds + (bufoff) + ldsw + _i * 8192), 16, 0, 0); } while (0)
; #define PG8_LDA(dst, b, h) do { _Pragma("unroll") for (int m = 0; m < 4; ++m) _Pragma("unroll") for (int k = 0; k < 2; ++k) dst[m][k] = *(const PG8_LAS bf16x8*)(lds + PG8_SA(b, h) + aoff + m * 2048 + k * 1024); } while (0)
; #define PG8_MMA(ai, bj, At, Bt) do { __builtin_amdgcn_s_setprio(1); _Pragma("unroll") for (int m = 0; m < 4; ++m) _Pragma("unroll") for (int n = 0; n < 2; ++n) _Pragma("unroll") for (int k = 0; k < 2; ++k) \
;         acc[ai][bj][m][n] = __builtin_amdgcn_mfma_f32_16x16x32_bf16(Bt[n][k], At[m][k], acc[ai][bj][m][n], 0, 0, 0); __builtin_amdgcn_s_setprio(0); } while (0)
; #define PG8_WAIT_V(n) asm volatile("s_waitcnt vmcnt(" #n ")" ::: "memory")
; #define PG8_WAIT_L(n) asm volatile("s_waitcnt lgkmcnt(" #n ")" ::: "memory")
; #define PG8_BAR __builtin_amdgcn_s_barrier()
; #define PG8_SCHED __builtin_amdgcn_sched_barrier(0)
; template <class Epi, class Sched, bool ALIGN_EPI = false, bool SP2 = false>
; __device__ __forceinline__ void gemm_phase(PG8_LAS unsigned char* lds, const Gemm g, const Sched& S, const Epi& E) {
;     ...
;         for (int t = 0; t < nt; t += 2) {
;             const bool last = (t == nt - 2);
;             const char* a1 = cA + (size_t)(t + 1) * kstep;
;             const char* a2 = last ? nA : cA + (size_t)(t + 2) * kstep; const char* b2 = last ? nB : cB + (size_t)(t + 2) * kstep;
;             const char* a3 = a2 + kstep; const char* b3 = b2 + kstep;
;     ...
;             PG8_LDA(At, 1, 1); PG8_STAGE(PG8_SB(1, 0), b3, voffB); PG8_STAGE(PG8_SB(1, 1), b3 + hstep, voffB); PG8_STAGE(PG8_SA(1, 0), a3, voffA);
;             PG8_WAIT_V(8); PG8_WAIT_L(0); PG8_BAR; PG8_MMA(1, 0, At, B0); PG8_MMA(1, 1, At, B1); PG8_BAR; PG8_SCHED;
	s_add_i32 s24, s57, s29
	v_lshl_add_u64 v[184:185], v[184:185], 0, s[16:17]
	s_mov_b32 m0, s24
	ds_read_b128 v[180:183], v146 offset:49152
	ds_read_b128 v[188:191], v146 offset:50176
	ds_read_b128 v[192:195], v146 offset:51200
	ds_read_b128 v[196:199], v146 offset:52224
	ds_read_b128 v[200:203], v146 offset:53248
	ds_read_b128 v[204:207], v146 offset:54272
	ds_read_b128 v[208:211], v146 offset:55296
	ds_read_b128 v[212:215], v146 offset:56320
	global_load_lds_dwordx4 v[184:185], off
	v_lshl_add_u64 v[184:185], v[216:217], 0, s[16:17]
	s_add_i32 m0, s24, 0x2000
	s_add_i32 s24, s58, s29
	global_load_lds_dwordx4 v[184:185], off
	v_lshl_add_u64 v[184:185], v[218:219], 0, s[16:17]
	s_mov_b32 m0, s24
	s_nop 0
	global_load_lds_dwordx4 v[184:185], off
	v_lshl_add_u64 v[184:185], v[220:221], 0, s[16:17]
	s_add_i32 m0, s24, 0x2000
	s_nop 0
	global_load_lds_dwordx4 v[184:185], off
	v_lshl_add_u64 v[184:185], v[222:223], 0, s[16:17]
	s_mov_b32 m0, s38
	s_nop 0
	global_load_lds_dwordx4 v[184:185], off
	v_lshl_add_u64 v[184:185], v[224:225], 0, s[16:17]
	s_mov_b32 m0, s39
	s_nop 0
	global_load_lds_dwordx4 v[184:185], off
	s_waitcnt vmcnt(8)
	s_waitcnt lgkmcnt(0)
	s_barrier
	s_setprio 1
	s_waitcnt lgkmcnt(0)
	v_mfma_f32_16x16x32_bf16 v[62:65], v[148:151], v[180:183], v[62:65]
	v_mfma_f32_16x16x32_bf16 v[58:61], v[156:159], v[180:183], v[58:61]
	v_mfma_f32_16x16x32_bf16 v[46:49], v[148:151], v[192:195], v[46:49]
	v_mfma_f32_16x16x32_bf16 v[42:45], v[156:159], v[192:195], v[42:45]
	v_mfma_f32_16x16x32_bf16 v[30:33], v[148:151], v[200:203], v[30:33]
	v_mfma_f32_16x16x32_bf16 v[26:29], v[156:159], v[200:203], v[26:29]
	v_mfma_f32_16x16x32_bf16 v[14:17], v[148:151], v[208:211], v[14:17]
	v_mfma_f32_16x16x32_bf16 v[10:13], v[156:159], v[208:211], v[10:13]
	v_mfma_f32_16x16x32_bf16 v[62:65], v[152:155], v[188:191], v[62:65]
	v_mfma_f32_16x16x32_bf16 v[58:61], v[160:163], v[188:191], v[58:61]
	v_mfma_f32_16x16x32_bf16 v[46:49], v[152:155], v[196:199], v[46:49]
	v_mfma_f32_16x16x32_bf16 v[42:45], v[160:163], v[196:199], v[42:45]
	v_mfma_f32_16x16x32_bf16 v[30:33], v[152:155], v[204:207], v[30:33]
	v_mfma_f32_16x16x32_bf16 v[26:29], v[160:163], v[204:207], v[26:29]
	v_mfma_f32_16x16x32_bf16 v[14:17], v[152:155], v[212:215], v[14:17]
	v_mfma_f32_16x16x32_bf16 v[10:13], v[160:163], v[212:215], v[10:13]
	s_setprio 0
	s_setprio 1
	v_mfma_f32_16x16x32_bf16 v[54:57], v[164:167], v[180:183], v[54:57]
	v_mfma_f32_16x16x32_bf16 v[50:53], v[172:175], v[180:183], v[50:53]
	v_mfma_f32_16x16x32_bf16 v[38:41], v[164:167], v[192:195], v[38:41]
	v_mfma_f32_16x16x32_bf16 v[34:37], v[172:175], v[192:195], v[34:37]
	v_mfma_f32_16x16x32_bf16 v[22:25], v[164:167], v[200:203], v[22:25]
	v_mfma_f32_16x16x32_bf16 v[18:21], v[172:175], v[200:203], v[18:21]
	v_mfma_f32_16x16x32_bf16 v[6:9], v[164:167], v[208:211], v[6:9]
	v_mfma_f32_16x16x32_bf16 v[2:5], v[172:175], v[208:211], v[2:5]
	v_mfma_f32_16x16x32_bf16 v[54:57], v[168:171], v[188:191], v[54:57]
	v_mfma_f32_16x16x32_bf16 v[50:53], v[176:179], v[188:191], v[50:53]
	v_mfma_f32_16x16x32_bf16 v[38:41], v[168:171], v[196:199], v[38:41]
	v_mfma_f32_16x16x32_bf16 v[34:37], v[176:179], v[196:199], v[34:37]
	v_mfma_f32_16x16x32_bf16 v[22:25], v[168:171], v[204:207], v[22:25]
	v_mfma_f32_16x16x32_bf16 v[18:21], v[176:179], v[204:207], v[18:21]
	v_mfma_f32_16x16x32_bf16 v[6:9], v[168:171], v[212:215], v[6:9]
	v_mfma_f32_16x16x32_bf16 v[2:5], v[176:179], v[212:215], v[2:5]
	s_setprio 0
	s_add_u32 s22, s22, 0x100
	s_addc_u32 s23, s23, 0
	s_add_u32 s54, s54, 0x100
	s_addc_u32 s55, s55, 0
	s_cmp_ge_i32 s56, 2
	s_mov_b32 s24, s56
	s_barrier
	s_cbranch_scc0 .LBB0_791

; #define PG8_STAGE(bufoff, gbase, voff) do { _Pragma("unroll") for (int _i = 0; _i < 2; ++_i) \
;         __builtin_amdgcn_global_load_lds((const unsigned*)((const char*)(gbase) + (voff)[_i]), (PG8_LAS unsigned*)(lds + (bufoff) + ldsw + _i * 8192), 16, 0, 0); } while (0)
; #define PG8_LDA(dst, b, h) do { _Pragma("unroll") for (int m = 0; m < 4; ++m) _Pragma("unroll") for (int k = 0; k < 2; ++k) dst[m][k] = *(const PG8_LAS bf16x8*)(lds + PG8_SA(b, h) + aoff + m * 2048 + k * 1024); } while (0)
; #define PG8_LDB(dst, b, h) do { _Pragma("unroll") for (int n = 0; n < 2; ++n) _Pragma("unroll") for (int k = 0; k < 2; ++k) dst[n][k] = *(const PG8_LAS bf16x8*)(lds + PG8_SB(b, h) + boff + n * 2048 + k * 1024); } while (0)
; #define PG8_MMA(ai, bj, At, Bt) do { __builtin_amdgcn_s_setprio(1); _Pragma("unroll") for (int m = 0; m < 4; ++m) _Pragma("unroll") for (int n = 0; n < 2; ++n) _Pragma("unroll") for (int k = 0; k < 2; ++k) \
;         acc[ai][bj][m][n] = __builtin_amdgcn_mfma_f32_16x16x32_bf16(Bt[n][k], At[m][k], acc[ai][bj][m][n], 0, 0, 0); __builtin_amdgcn_s_setprio(0); } while (0)
; #define PG8_WAIT_V(n) asm volatile("s_waitcnt vmcnt(" #n ")" ::: "memory")
; #define PG8_WAIT_L(n) asm volatile("s_waitcnt lgkmcnt(" #n ")" ::: "memory")
; template <class Epi, class Sched, bool ALIGN_EPI = false, bool SP2 = false>
; __device__ __forceinline__ void gemm_phase(PG8_LAS unsigned char* lds, const Gemm g, const Sched& S, const Epi& E) {
;     ...
;             const bool last = (t == nt - 2);
;             const char* a1 = cA + (size_t)(t + 1) * kstep;
;             const char* a2 = last ? nA : cA + (size_t)(t + 2) * kstep; const char* b2 = last ? nB : cB + (size_t)(t + 2) * kstep;
;             const char* a3 = a2 + kstep; const char* b3 = b2 + kstep;
;             if (last && has_next) S.a_ready(nxt);
;             if constexpr (SP2) {
;             PG8_LDB(B0, 0, 0); PG8_LDB(B1, 0, 1); PG8_SCHED; PG8_LDA(At, 0, 0); PG8_STAGE(PG8_SA(1, 1), a1 + hstep, voffA);
;             PG8_WAIT_V(8); PG8_WAIT_L(0); PG8_BAR; PG8_MMA(0, 0, At, B0); PG8_MMA(0, 1, At, B1); PG8_BAR; PG8_SCHED;
;             PG8_LDA(At, 0, 1); PG8_STAGE(PG8_SB(0, 0), b2, voffB); PG8_STAGE(PG8_SB(0, 1), b2 + hstep, voffB); PG8_STAGE(PG8_SA(0, 0), a2, voffA);
;             PG8_WAIT_V(8); PG8_WAIT_L(0); PG8_BAR; PG8_MMA(1, 0, At, B0); PG8_MMA(1, 1, At, B1); PG8_BAR; PG8_SCHED;
.LBB0_1405:
	v_add_u32_e32 v162, s56, v148
	v_add_u32_e32 v178, s57, v148
	s_add_u32 s34, s18, s30
	ds_read_b128 v[150:153], v162
	ds_read_b128 v[154:157], v162 offset:1024
	ds_read_b128 v[158:161], v162 offset:2048
	ds_read_b128 v[162:165], v162 offset:3072
	ds_read_b128 v[166:169], v178
	ds_read_b128 v[170:173], v178 offset:1024
	ds_read_b128 v[174:177], v178 offset:2048
	ds_read_b128 v[178:181], v178 offset:3072
	s_addc_u32 s35, s19, s31
	s_add_u32 s34, s34, 0x100
	s_addc_u32 s35, s35, 0
	s_add_u32 s65, s59, s30
	s_addc_u32 s66, s60, s31
	s_cmpk_eq_i32 s30, 0x700
	s_cselect_b32 s37, s25, s35
	s_cselect_b32 s36, s61, s34
	s_cselect_b32 s35, s23, s66
	s_cselect_b32 s34, s62, s65
	v_lshl_add_u64 v[216:217], v[142:143], 0, s[30:31]
	s_add_i32 m0, s42, 0xc000
	ds_read_b128 v[182:185], v149
	ds_read_b128 v[188:191], v149 offset:1024
	ds_read_b128 v[192:195], v149 offset:2048
	ds_read_b128 v[196:199], v149 offset:3072
	ds_read_b128 v[200:203], v149 offset:4096
	ds_read_b128 v[204:207], v149 offset:5120
	ds_read_b128 v[208:211], v149 offset:6144
	ds_read_b128 v[212:215], v149 offset:7168
	global_load_lds_dwordx4 v[216:217], off
	v_lshl_add_u64 v[216:217], v[144:145], 0, s[30:31]
	s_add_i32 m0, s42, 0xe000
	s_nop 0
	global_load_lds_dwordx4 v[216:217], off
	s_waitcnt vmcnt(8)
	s_waitcnt lgkmcnt(0)
	s_barrier
	s_setprio 1
	s_waitcnt lgkmcnt(0)
	v_mfma_f32_16x16x32_bf16 v[110:113], v[150:153], v[182:185], v[110:113]
	v_mfma_f32_16x16x32_bf16 v[74:77], v[158:161], v[182:185], v[74:77]
	v_mfma_f32_16x16x32_bf16 v[118:121], v[150:153], v[192:195], v[118:121]
	v_mfma_f32_16x16x32_bf16 v[94:97], v[158:161], v[192:195], v[94:97]
	v_mfma_f32_16x16x32_bf16 v[126:129], v[150:153], v[200:203], v[126:129]
	v_mfma_f32_16x16x32_bf16 v[106:109], v[158:161], v[200:203], v[106:109]
	v_mfma_f32_16x16x32_bf16 v[122:125], v[150:153], v[208:211], v[122:125]
	v_mfma_f32_16x16x32_bf16 v[114:117], v[158:161], v[208:211], v[114:117]
	v_mfma_f32_16x16x32_bf16 v[110:113], v[154:157], v[188:191], v[110:113]
	v_mfma_f32_16x16x32_bf16 v[74:77], v[162:165], v[188:191], v[74:77]
	v_mfma_f32_16x16x32_bf16 v[118:121], v[154:157], v[196:199], v[118:121]
	v_mfma_f32_16x16x32_bf16 v[94:97], v[162:165], v[196:199], v[94:97]
	v_mfma_f32_16x16x32_bf16 v[126:129], v[154:157], v[204:207], v[126:129]
	v_mfma_f32_16x16x32_bf16 v[106:109], v[162:165], v[204:207], v[106:109]
	v_mfma_f32_16x16x32_bf16 v[122:125], v[154:157], v[212:215], v[122:125]
	v_mfma_f32_16x16x32_bf16 v[114:117], v[162:165], v[212:215], v[114:117]
	s_setprio 0
	s_setprio 1
	v_mfma_f32_16x16x32_bf16 v[46:49], v[166:169], v[182:185], v[46:49]
	v_mfma_f32_16x16x32_bf16 v[14:17], v[174:177], v[182:185], v[14:17]
	v_mfma_f32_16x16x32_bf16 v[54:57], v[166:169], v[192:195], v[54:57]
	v_mfma_f32_16x16x32_bf16 v[30:33], v[174:177], v[192:195], v[30:33]
	v_mfma_f32_16x16x32_bf16 v[70:73], v[166:169], v[200:203], v[70:73]
	v_mfma_f32_16x16x32_bf16 v[42:45], v[174:177], v[200:203], v[42:45]
	v_mfma_f32_16x16x32_bf16 v[86:89], v[166:169], v[208:211], v[86:89]
	v_mfma_f32_16x16x32_bf16 v[50:53], v[174:177], v[208:211], v[50:53]
	v_mfma_f32_16x16x32_bf16 v[46:49], v[170:173], v[188:191], v[46:49]
	v_mfma_f32_16x16x32_bf16 v[14:17], v[178:181], v[188:191], v[14:17]
	v_mfma_f32_16x16x32_bf16 v[54:57], v[170:173], v[196:199], v[54:57]
	v_mfma_f32_16x16x32_bf16 v[30:33], v[178:181], v[196:199], v[30:33]
	v_mfma_f32_16x16x32_bf16 v[70:73], v[170:173], v[204:207], v[70:73]
	v_mfma_f32_16x16x32_bf16 v[42:45], v[178:181], v[204:207], v[42:45]
	v_mfma_f32_16x16x32_bf16 v[86:89], v[170:173], v[212:215], v[86:89]
	v_mfma_f32_16x16x32_bf16 v[50:53], v[178:181], v[212:215], v[50:53]
	s_setprio 0
	s_barrier
	s_add_i32 s65, s56, s41
	v_lshl_add_u64 v[216:217], s[34:35], 0, v[130:131]
	s_mov_b32 m0, s65
	ds_read_b128 v[182:185], v149 offset:16384
	ds_read_b128 v[188:191], v149 offset:17408
	ds_read_b128 v[192:195], v149 offset:18432
	ds_read_b128 v[196:199], v149 offset:19456
	ds_read_b128 v[200:203], v149 offset:20480
	ds_read_b128 v[204:207], v149 offset:21504
	ds_read_b128 v[208:211], v149 offset:22528
	ds_read_b128 v[212:215], v149 offset:23552
	global_load_lds_dwordx4 v[216:217], off
	s_add_i32 m0, s65, 0x2000
	s_add_u32 s66, s34, 0x40000
	v_lshl_add_u64 v[218:219], s[34:35], 0, v[132:133]
	s_addc_u32 s67, s35, 0
	s_add_i32 s65, s57, s41
	global_load_lds_dwordx4 v[218:219], off
	v_lshl_add_u64 v[220:221], s[66:67], 0, v[130:131]
	s_mov_b32 m0, s65
	v_lshl_add_u64 v[222:223], s[36:37], 0, v[132:133]
	global_load_lds_dwordx4 v[220:221], off
	v_lshl_add_u64 v[220:221], s[66:67], 0, v[132:133]
	s_add_i32 m0, s65, 0x2000
	s_nop 0
	global_load_lds_dwordx4 v[220:221], off
	v_lshl_add_u64 v[220:221], s[36:37], 0, v[130:131]
	s_mov_b32 m0, s42
	s_nop 0
	global_load_lds_dwordx4 v[220:221], off
	s_mov_b32 m0, s48
	s_nop 0
	global_load_lds_dwordx4 v[222:223], off
	s_waitcnt vmcnt(8)
	s_waitcnt lgkmcnt(0)
	s_barrier
; #define PG8_STAGE(bufoff, gbase, voff) do { _Pragma("unroll") for (int _i = 0; _i < 2; ++_i) \
;         __builtin_amdgcn_global_load_lds((const unsigned*)((const char*)(gbase) + (voff)[_i]), (PG8_LAS unsigned*)(lds + (bufoff) + ldsw + _i * 8192), 16, 0, 0); } while (0)
; #define PG8_LDA(dst, b, h) do { _Pragma("unroll") for (int m = 0; m < 4; ++m) _Pragma("unroll") for (int k = 0; k < 2; ++k) dst[m][k] = *(const PG8_LAS bf16x8*)(lds + PG8_SA(b, h) + aoff + m * 2048 + k * 1024); } while (0)
; #define PG8_LDB(dst, b, h) do { _Pragma("unroll") for (int n = 0; n < 2; ++n) _Pragma("unroll") for (int k = 0; k < 2; ++k) dst[n][k] = *(const PG8_LAS bf16x8*)(lds + PG8_SB(b, h) + boff + n * 2048 + k * 1024); } while (0)
; #define PG8_MMA(ai, bj, At, Bt) do { __builtin_amdgcn_s_setprio(1); _Pragma("unroll") for (int m = 0; m < 4; ++m) _Pragma("unroll") for (int n = 0; n < 2; ++n) _Pragma("unroll") for (int k = 0; k < 2; ++k) \
;         acc[ai][bj][m][n] = __builtin_amdgcn_mfma_f32_16x16x32_bf16(Bt[n][k], At[m][k], acc[ai][bj][m][n], 0, 0, 0); __builtin_amdgcn_s_setprio(0); } while (0)
; #define PG8_WAIT_V(n) asm volatile("s_waitcnt vmcnt(" #n ")" ::: "memory")
; #define PG8_WAIT_L(n) asm volatile("s_waitcnt lgkmcnt(" #n ")" ::: "memory")
; #define PG8_BAR __builtin_amdgcn_s_barrier()
; #define PG8_SCHED __builtin_amdgcn_sched_barrier(0)
; template <class Epi, class Sched, bool ALIGN_EPI = false, bool SP2 = false>
; __device__ __forceinline__ void gemm_phase(PG8_LAS unsigned char* lds, const Gemm g, const Sched& S, const Epi& E) {
;     ...
;             PG8_WAIT_V(8); PG8_WAIT_L(0); PG8_BAR; PG8_MMA(1, 0, At, B0); PG8_MMA(1, 1, At, B1); PG8_BAR; PG8_SCHED;
;             PG8_LDB(B0, 1, 0); PG8_LDB(B1, 1, 1); PG8_SCHED; PG8_LDA(At, 1, 0); PG8_STAGE(PG8_SA(0, 1), a2 + hstep, voffA);
;             PG8_WAIT_V(8); PG8_WAIT_L(0); PG8_BAR; PG8_MMA(0, 0, At, B0); PG8_MMA(0, 1, At, B1); PG8_BAR; PG8_SCHED;
	s_setprio 1
	s_waitcnt lgkmcnt(0)
	v_mfma_f32_16x16x32_bf16 v[102:105], v[150:153], v[182:185], v[102:105]
	v_mfma_f32_16x16x32_bf16 v[98:101], v[158:161], v[182:185], v[98:101]
	v_mfma_f32_16x16x32_bf16 v[82:85], v[150:153], v[192:195], v[82:85]
	v_mfma_f32_16x16x32_bf16 v[78:81], v[158:161], v[192:195], v[78:81]
	v_mfma_f32_16x16x32_bf16 v[38:41], v[150:153], v[200:203], v[38:41]
	v_mfma_f32_16x16x32_bf16 v[34:37], v[158:161], v[200:203], v[34:37]
	v_mfma_f32_16x16x32_bf16 v[18:21], v[150:153], v[208:211], v[18:21]
	v_mfma_f32_16x16x32_bf16 v[10:13], v[158:161], v[208:211], v[10:13]
	v_mfma_f32_16x16x32_bf16 v[102:105], v[154:157], v[188:191], v[102:105]
	v_mfma_f32_16x16x32_bf16 v[98:101], v[162:165], v[188:191], v[98:101]
	v_mfma_f32_16x16x32_bf16 v[82:85], v[154:157], v[196:199], v[82:85]
	v_mfma_f32_16x16x32_bf16 v[78:81], v[162:165], v[196:199], v[78:81]
	v_mfma_f32_16x16x32_bf16 v[38:41], v[154:157], v[204:207], v[38:41]
	v_mfma_f32_16x16x32_bf16 v[34:37], v[162:165], v[204:207], v[34:37]
	v_mfma_f32_16x16x32_bf16 v[18:21], v[154:157], v[212:215], v[18:21]
	v_mfma_f32_16x16x32_bf16 v[10:13], v[162:165], v[212:215], v[10:13]
	s_setprio 0
	s_setprio 1
	v_mfma_f32_16x16x32_bf16 v[90:93], v[166:169], v[182:185], v[90:93]
	v_mfma_f32_16x16x32_bf16 v[66:69], v[174:177], v[182:185], v[66:69]
	v_mfma_f32_16x16x32_bf16 v[62:65], v[166:169], v[192:195], v[62:65]
	v_mfma_f32_16x16x32_bf16 v[58:61], v[174:177], v[192:195], v[58:61]
	v_mfma_f32_16x16x32_bf16 v[26:29], v[166:169], v[200:203], v[26:29]
	v_mfma_f32_16x16x32_bf16 v[22:25], v[174:177], v[200:203], v[22:25]
	v_mfma_f32_16x16x32_bf16 v[6:9], v[166:169], v[208:211], v[6:9]
	v_mfma_f32_16x16x32_bf16 v[2:5], v[174:177], v[208:211], v[2:5]
	v_mfma_f32_16x16x32_bf16 v[90:93], v[170:173], v[188:191], v[90:93]
	v_mfma_f32_16x16x32_bf16 v[66:69], v[178:181], v[188:191], v[66:69]
	v_mfma_f32_16x16x32_bf16 v[62:65], v[170:173], v[196:199], v[62:65]
	v_mfma_f32_16x16x32_bf16 v[58:61], v[178:181], v[196:199], v[58:61]
	v_mfma_f32_16x16x32_bf16 v[26:29], v[170:173], v[204:207], v[26:29]
	v_mfma_f32_16x16x32_bf16 v[22:25], v[178:181], v[204:207], v[22:25]
	v_mfma_f32_16x16x32_bf16 v[6:9], v[170:173], v[212:215], v[6:9]
	v_mfma_f32_16x16x32_bf16 v[2:5], v[178:181], v[212:215], v[2:5]
	s_setprio 0
	s_barrier
	s_add_i32 s65, 0, 0x18000
	s_add_i32 s66, 0, 0x1c000
	v_add_u32_e32 v162, s65, v148
	v_add_u32_e32 v178, s66, v148
	ds_read_b128 v[150:153], v162
	ds_read_b128 v[154:157], v162 offset:1024
	ds_read_b128 v[158:161], v162 offset:2048
	ds_read_b128 v[162:165], v162 offset:3072
	ds_read_b128 v[166:169], v178
	ds_read_b128 v[170:173], v178 offset:1024
	ds_read_b128 v[174:177], v178 offset:2048
	ds_read_b128 v[178:181], v178 offset:3072
	s_add_u32 s36, s36, 0x40000
	s_addc_u32 s37, s37, 0
	s_mov_b32 m0, s49
	v_lshl_add_u64 v[224:225], s[36:37], 0, v[130:131]
	ds_read_b128 v[182:185], v149 offset:32768
	ds_read_b128 v[188:191], v149 offset:33792
	ds_read_b128 v[192:195], v149 offset:34816
	ds_read_b128 v[196:199], v149 offset:35840
	ds_read_b128 v[200:203], v149 offset:36864
	ds_read_b128 v[204:207], v149 offset:37888
	ds_read_b128 v[208:211], v149 offset:38912
	ds_read_b128 v[212:215], v149 offset:39936
	global_load_lds_dwordx4 v[224:225], off
	v_lshl_add_u64 v[224:225], s[36:37], 0, v[132:133]
	s_mov_b32 m0, s51
	s_nop 0
	global_load_lds_dwordx4 v[224:225], off
	s_waitcnt vmcnt(8)
	s_waitcnt lgkmcnt(0)
	s_barrier
	s_setprio 1
	s_waitcnt lgkmcnt(0)
	v_mfma_f32_16x16x32_bf16 v[110:113], v[150:153], v[182:185], v[110:113]
	v_mfma_f32_16x16x32_bf16 v[74:77], v[158:161], v[182:185], v[74:77]
	v_mfma_f32_16x16x32_bf16 v[118:121], v[150:153], v[192:195], v[118:121]
	v_mfma_f32_16x16x32_bf16 v[94:97], v[158:161], v[192:195], v[94:97]
	v_mfma_f32_16x16x32_bf16 v[126:129], v[150:153], v[200:203], v[126:129]
	v_mfma_f32_16x16x32_bf16 v[106:109], v[158:161], v[200:203], v[106:109]
	v_mfma_f32_16x16x32_bf16 v[122:125], v[150:153], v[208:211], v[122:125]
	v_mfma_f32_16x16x32_bf16 v[114:117], v[158:161], v[208:211], v[114:117]
	v_mfma_f32_16x16x32_bf16 v[110:113], v[154:157], v[188:191], v[110:113]
	v_mfma_f32_16x16x32_bf16 v[74:77], v[162:165], v[188:191], v[74:77]
	v_mfma_f32_16x16x32_bf16 v[118:121], v[154:157], v[196:199], v[118:121]
	v_mfma_f32_16x16x32_bf16 v[94:97], v[162:165], v[196:199], v[94:97]
	v_mfma_f32_16x16x32_bf16 v[126:129], v[154:157], v[204:207], v[126:129]
	v_mfma_f32_16x16x32_bf16 v[106:109], v[162:165], v[204:207], v[106:109]
	v_mfma_f32_16x16x32_bf16 v[122:125], v[154:157], v[212:215], v[122:125]
	v_mfma_f32_16x16x32_bf16 v[114:117], v[162:165], v[212:215], v[114:117]
	s_setprio 0
	s_setprio 1
	v_mfma_f32_16x16x32_bf16 v[46:49], v[166:169], v[182:185], v[46:49]
	v_mfma_f32_16x16x32_bf16 v[14:17], v[174:177], v[182:185], v[14:17]
	v_mfma_f32_16x16x32_bf16 v[54:57], v[166:169], v[192:195], v[54:57]
	v_mfma_f32_16x16x32_bf16 v[30:33], v[174:177], v[192:195], v[30:33]
	v_mfma_f32_16x16x32_bf16 v[70:73], v[166:169], v[200:203], v[70:73]
	v_mfma_f32_16x16x32_bf16 v[42:45], v[174:177], v[200:203], v[42:45]
	v_mfma_f32_16x16x32_bf16 v[86:89], v[166:169], v[208:211], v[86:89]
	v_mfma_f32_16x16x32_bf16 v[50:53], v[174:177], v[208:211], v[50:53]
	v_mfma_f32_16x16x32_bf16 v[46:49], v[170:173], v[188:191], v[46:49]
	v_mfma_f32_16x16x32_bf16 v[14:17], v[178:181], v[188:191], v[14:17]
	v_mfma_f32_16x16x32_bf16 v[54:57], v[170:173], v[196:199], v[54:57]
	v_mfma_f32_16x16x32_bf16 v[30:33], v[178:181], v[196:199], v[30:33]
	v_mfma_f32_16x16x32_bf16 v[70:73], v[170:173], v[204:207], v[70:73]
	v_mfma_f32_16x16x32_bf16 v[42:45], v[178:181], v[204:207], v[42:45]
	v_mfma_f32_16x16x32_bf16 v[86:89], v[170:173], v[212:215], v[86:89]
	v_mfma_f32_16x16x32_bf16 v[50:53], v[178:181], v[212:215], v[50:53]
	s_setprio 0
	s_barrier
; #define PG8_STAGE(bufoff, gbase, voff) do { _Pragma("unroll") for (int _i = 0; _i < 2; ++_i) \
;         __builtin_amdgcn_global_load_lds((const unsigned*)((const char*)(gbase) + (voff)[_i]), (PG8_LAS unsigned*)(lds + (bufoff) + ldsw + _i * 8192), 16, 0, 0); } while (0)
; #define PG8_LDA(dst, b, h) do { _Pragma("unroll") for (int m = 0; m < 4; ++m) _Pragma("unroll") for (int k = 0; k < 2; ++k) dst[m][k] = *(const PG8_LAS bf16x8*)(lds + PG8_SA(b, h) + aoff + m * 2048 + k * 1024); } while (0)
; #define PG8_MMA(ai, bj, At, Bt) do { __builtin_amdgcn_s_setprio(1); _Pragma("unroll") for (int m = 0; m < 4; ++m) _Pragma("unroll") for (int n = 0; n < 2; ++n) _Pragma("unroll") for (int k = 0; k < 2; ++k) \
;         acc[ai][bj][m][n] = __builtin_amdgcn_mfma_f32_16x16x32_bf16(Bt[n][k], At[m][k], acc[ai][bj][m][n], 0, 0, 0); __builtin_amdgcn_s_setprio(0); } while (0)
; #define PG8_WAIT_V(n) asm volatile("s_waitcnt vmcnt(" #n ")" ::: "memory")
; #define PG8_WAIT_L(n) asm volatile("s_waitcnt lgkmcnt(" #n ")" ::: "memory")
; #define PG8_BAR __builtin_amdgcn_s_barrier()
; #define PG8_SCHED __builtin_amdgcn_sched_barrier(0)
; template <class Epi, class Sched, bool ALIGN_EPI = false, bool SP2 = false>
; __device__ __forceinline__ void gemm_phase(PG8_LAS unsigned char* lds, const Gemm g, const Sched& S, const Epi& E) {
;     ...
;             PG8_LDA(At, 1, 1); PG8_STAGE(PG8_SB(1, 0), b3, voffB); PG8_STAGE(PG8_SB(1, 1), b3 + hstep, voffB); PG8_STAGE(PG8_SA(1, 0), a3, voffA);
;             PG8_WAIT_V(8); PG8_WAIT_L(0); PG8_BAR; PG8_MMA(1, 0, At, B0); PG8_MMA(1, 1, At, B1); PG8_BAR; PG8_SCHED;
;     ...
;         if (!has_next) break;
; #pragma unroll
;         for (int a = 0; a < 2; ++a)
; #pragma unroll
;             for (int b = 0; b < 2; ++b)
; #pragma unroll
;                 for (int m = 0; m < 4; ++m)
; #pragma unroll
;                     for (int n = 0; n < 2; ++n) acc[a][b][m][n] = (f32x4){0.f, 0.f, 0.f, 0.f};
;         cur = nxt; cA = nA; cB = nB; ++ui;
	s_add_i32 s36, s65, s41
	v_lshl_add_u64 v[216:217], v[216:217], 0, s[20:21]
	s_mov_b32 m0, s36
	ds_read_b128 v[182:185], v149 offset:49152
	ds_read_b128 v[188:191], v149 offset:50176
	ds_read_b128 v[192:195], v149 offset:51200
	ds_read_b128 v[196:199], v149 offset:52224
	ds_read_b128 v[200:203], v149 offset:53248
	ds_read_b128 v[204:207], v149 offset:54272
	ds_read_b128 v[208:211], v149 offset:55296
	ds_read_b128 v[212:215], v149 offset:56320
	global_load_lds_dwordx4 v[216:217], off
	s_add_i32 m0, s36, 0x2000
	s_add_u32 s34, s34, 0x40080
	v_lshl_add_u64 v[216:217], v[218:219], 0, s[20:21]
	s_addc_u32 s35, s35, 0
	s_add_i32 s36, s66, s41
	global_load_lds_dwordx4 v[216:217], off
	v_lshl_add_u64 v[216:217], s[34:35], 0, v[130:131]
	s_mov_b32 m0, s36
	s_nop 0
	global_load_lds_dwordx4 v[216:217], off
	v_lshl_add_u64 v[216:217], s[34:35], 0, v[132:133]
	s_add_i32 m0, s36, 0x2000
	s_nop 0
	global_load_lds_dwordx4 v[216:217], off
	v_lshl_add_u64 v[216:217], v[220:221], 0, s[20:21]
	s_mov_b32 m0, s54
	s_nop 0
	global_load_lds_dwordx4 v[216:217], off
	v_lshl_add_u64 v[216:217], v[222:223], 0, s[20:21]
	s_mov_b32 m0, s55
	s_nop 0
	global_load_lds_dwordx4 v[216:217], off
	s_waitcnt vmcnt(8)
	s_waitcnt lgkmcnt(0)
	s_barrier
	s_setprio 1
	s_waitcnt lgkmcnt(0)
	v_mfma_f32_16x16x32_bf16 v[102:105], v[150:153], v[182:185], v[102:105]
	v_mfma_f32_16x16x32_bf16 v[98:101], v[158:161], v[182:185], v[98:101]
	v_mfma_f32_16x16x32_bf16 v[82:85], v[150:153], v[192:195], v[82:85]
	v_mfma_f32_16x16x32_bf16 v[78:81], v[158:161], v[192:195], v[78:81]
	v_mfma_f32_16x16x32_bf16 v[38:41], v[150:153], v[200:203], v[38:41]
	v_mfma_f32_16x16x32_bf16 v[34:37], v[158:161], v[200:203], v[34:37]
	v_mfma_f32_16x16x32_bf16 v[18:21], v[150:153], v[208:211], v[18:21]
	v_mfma_f32_16x16x32_bf16 v[10:13], v[158:161], v[208:211], v[10:13]
	v_mfma_f32_16x16x32_bf16 v[102:105], v[154:157], v[188:191], v[102:105]
	v_mfma_f32_16x16x32_bf16 v[98:101], v[162:165], v[188:191], v[98:101]
	v_mfma_f32_16x16x32_bf16 v[82:85], v[154:157], v[196:199], v[82:85]
	v_mfma_f32_16x16x32_bf16 v[78:81], v[162:165], v[196:199], v[78:81]
	v_mfma_f32_16x16x32_bf16 v[38:41], v[154:157], v[204:207], v[38:41]
	v_mfma_f32_16x16x32_bf16 v[34:37], v[162:165], v[204:207], v[34:37]
	v_mfma_f32_16x16x32_bf16 v[18:21], v[154:157], v[212:215], v[18:21]
	v_mfma_f32_16x16x32_bf16 v[10:13], v[162:165], v[212:215], v[10:13]
	s_setprio 0
	s_setprio 1
	v_mfma_f32_16x16x32_bf16 v[90:93], v[166:169], v[182:185], v[90:93]
	v_mfma_f32_16x16x32_bf16 v[66:69], v[174:177], v[182:185], v[66:69]
	v_mfma_f32_16x16x32_bf16 v[62:65], v[166:169], v[192:195], v[62:65]
	v_mfma_f32_16x16x32_bf16 v[58:61], v[174:177], v[192:195], v[58:61]
	v_mfma_f32_16x16x32_bf16 v[26:29], v[166:169], v[200:203], v[26:29]
	v_mfma_f32_16x16x32_bf16 v[22:25], v[174:177], v[200:203], v[22:25]
	v_mfma_f32_16x16x32_bf16 v[6:9], v[166:169], v[208:211], v[6:9]
	v_mfma_f32_16x16x32_bf16 v[2:5], v[174:177], v[208:211], v[2:5]
	v_mfma_f32_16x16x32_bf16 v[90:93], v[170:173], v[188:191], v[90:93]
	v_mfma_f32_16x16x32_bf16 v[66:69], v[178:181], v[188:191], v[66:69]
	v_mfma_f32_16x16x32_bf16 v[62:65], v[170:173], v[196:199], v[62:65]
	v_mfma_f32_16x16x32_bf16 v[58:61], v[178:181], v[196:199], v[58:61]
	v_mfma_f32_16x16x32_bf16 v[26:29], v[170:173], v[204:207], v[26:29]
	v_mfma_f32_16x16x32_bf16 v[22:25], v[178:181], v[204:207], v[22:25]
	v_mfma_f32_16x16x32_bf16 v[6:9], v[170:173], v[212:215], v[6:9]
	v_mfma_f32_16x16x32_bf16 v[2:5], v[178:181], v[212:215], v[2:5]
	s_setprio 0
	s_add_i32 s63, s63, 2
	s_add_u32 s30, s30, 0x100
	s_addc_u32 s31, s31, 0
	s_cmp_gt_u32 s63, 13
	s_barrier
	s_cbranch_scc0 .LBB0_1405
	s_add_u32 s30, s59, 0xffffff00
	s_addc_u32 s31, s60, -1
	s_andn2_b64 vcc, exec, s[6:7]
	s_cbranch_vccnz .LBB0_1408
	v_mov_b32_e32 v2, 0
	s_mov_b32 s8, s22
	s_mov_b32 s16, s24
	s_mov_b64 s[18:19], s[28:29]
	s_mov_b32 s53, s58
	v_mov_b32_e32 v3, v2
	v_mov_b32_e32 v4, v2
	v_mov_b32_e32 v5, v2
	v_mov_b32_e32 v6, v2
	v_mov_b32_e32 v7, v2
	v_mov_b32_e32 v8, v2
	v_mov_b32_e32 v9, v2
	v_mov_b32_e32 v22, v2
	v_mov_b32_e32 v23, v2
	v_mov_b32_e32 v24, v2
	v_mov_b32_e32 v25, v2
	v_mov_b32_e32 v26, v2
	v_mov_b32_e32 v27, v2
	v_mov_b32_e32 v28, v2
	v_mov_b32_e32 v29, v2
	v_mov_b32_e32 v58, v2
	v_mov_b32_e32 v59, v2
	v_mov_b32_e32 v60, v2
	v_mov_b32_e32 v61, v2
	v_mov_b32_e32 v62, v2
	v_mov_b32_e32 v63, v2
	v_mov_b32_e32 v64, v2
	v_mov_b32_e32 v65, v2
	v_mov_b32_e32 v66, v2
	v_mov_b32_e32 v67, v2
	v_mov_b32_e32 v68, v2
	v_mov_b32_e32 v69, v2
	v_mov_b32_e32 v90, v2
	v_mov_b32_e32 v91, v2
	v_mov_b32_e32 v92, v2
	v_mov_b32_e32 v93, v2
	v_mov_b32_e32 v10, v2
	v_mov_b32_e32 v11, v2
	v_mov_b32_e32 v12, v2
	v_mov_b32_e32 v13, v2
	v_mov_b32_e32 v18, v2
	v_mov_b32_e32 v19, v2
	v_mov_b32_e32 v20, v2
	v_mov_b32_e32 v21, v2
	v_mov_b32_e32 v34, v2
	v_mov_b32_e32 v35, v2
	v_mov_b32_e32 v36, v2
	v_mov_b32_e32 v37, v2
	v_mov_b32_e32 v38, v2
	v_mov_b32_e32 v39, v2
	v_mov_b32_e32 v40, v2
	v_mov_b32_e32 v41, v2
	v_mov_b32_e32 v78, v2
	v_mov_b32_e32 v79, v2
	v_mov_b32_e32 v80, v2
	v_mov_b32_e32 v81, v2
	v_mov_b32_e32 v82, v2
	v_mov_b32_e32 v83, v2
	v_mov_b32_e32 v84, v2
	v_mov_b32_e32 v85, v2
	v_mov_b32_e32 v98, v2
	v_mov_b32_e32 v99, v2
	v_mov_b32_e32 v100, v2
	v_mov_b32_e32 v101, v2
	v_mov_b32_e32 v102, v2
	v_mov_b32_e32 v103, v2
	v_mov_b32_e32 v104, v2
	v_mov_b32_e32 v105, v2
	v_mov_b32_e32 v50, v2
	v_mov_b32_e32 v51, v2
	v_mov_b32_e32 v52, v2
	v_mov_b32_e32 v53, v2
	v_mov_b32_e32 v86, v2
	v_mov_b32_e32 v87, v2
	v_mov_b32_e32 v88, v2
	v_mov_b32_e32 v89, v2
	v_mov_b32_e32 v42, v2
	v_mov_b32_e32 v43, v2
	v_mov_b32_e32 v44, v2
	v_mov_b32_e32 v45, v2
	v_mov_b32_e32 v70, v2
	v_mov_b32_e32 v71, v2
	v_mov_b32_e32 v72, v2
	v_mov_b32_e32 v73, v2
	v_mov_b32_e32 v30, v2
	v_mov_b32_e32 v31, v2
	v_mov_b32_e32 v32, v2
	v_mov_b32_e32 v33, v2
	v_mov_b32_e32 v54, v2
	v_mov_b32_e32 v55, v2
	v_mov_b32_e32 v56, v2
	v_mov_b32_e32 v57, v2
	v_mov_b32_e32 v14, v2
	v_mov_b32_e32 v15, v2
	v_mov_b32_e32 v16, v2
	v_mov_b32_e32 v17, v2
	v_mov_b32_e32 v46, v2
	v_mov_b32_e32 v47, v2
	v_mov_b32_e32 v48, v2
	v_mov_b32_e32 v49, v2
	v_mov_b32_e32 v114, v2
	v_mov_b32_e32 v115, v2
	v_mov_b32_e32 v116, v2
	v_mov_b32_e32 v117, v2
	v_mov_b32_e32 v122, v2
	v_mov_b32_e32 v123, v2
	v_mov_b32_e32 v124, v2
	v_mov_b32_e32 v125, v2
	v_mov_b32_e32 v106, v2
	v_mov_b32_e32 v107, v2
	v_mov_b32_e32 v108, v2
	v_mov_b32_e32 v109, v2
	v_mov_b32_e32 v126, v2
	v_mov_b32_e32 v127, v2
	v_mov_b32_e32 v128, v2
	v_mov_b32_e32 v129, v2
	v_mov_b32_e32 v94, v2
	v_mov_b32_e32 v95, v2
	v_mov_b32_e32 v96, v2
	v_mov_b32_e32 v97, v2
	v_mov_b32_e32 v118, v2
	v_mov_b32_e32 v119, v2
	v_mov_b32_e32 v120, v2
	v_mov_b32_e32 v121, v2
	v_mov_b32_e32 v74, v2
	v_mov_b32_e32 v75, v2
	v_mov_b32_e32 v76, v2
	v_mov_b32_e32 v77, v2
	v_mov_b32_e32 v110, v2
	v_mov_b32_e32 v111, v2
	v_mov_b32_e32 v112, v2
	v_mov_b32_e32 v113, v2
	s_andn2_b64 vcc, exec, s[4:5]
	s_cbranch_vccnz .LBB0_1409
	s_branch .LBB0_1410

; #define PG8_STAGE(bufoff, gbase, voff) do { _Pragma("unroll") for (int _i = 0; _i < 2; ++_i) \
;         __builtin_amdgcn_global_load_lds((const unsigned*)((const char*)(gbase) + (voff)[_i]), (PG8_LAS unsigned*)(lds + (bufoff) + ldsw + _i * 8192), 16, 0, 0); } while (0)
; #define PG8_LDA(dst, b, h) do { _Pragma("unroll") for (int m = 0; m < 4; ++m) _Pragma("unroll") for (int k = 0; k < 2; ++k) dst[m][k] = *(const PG8_LAS bf16x8*)(lds + PG8_SA(b, h) + aoff + m * 2048 + k * 1024); } while (0)
; #define PG8_LDB(dst, b, h) do { _Pragma("unroll") for (int n = 0; n < 2; ++n) _Pragma("unroll") for (int k = 0; k < 2; ++k) dst[n][k] = *(const PG8_LAS bf16x8*)(lds + PG8_SB(b, h) + boff + n * 2048 + k * 1024); } while (0)
; #define PG8_MMA(ai, bj, At, Bt) do { __builtin_amdgcn_s_setprio(1); _Pragma("unroll") for (int m = 0; m < 4; ++m) _Pragma("unroll") for (int n = 0; n < 2; ++n) _Pragma("unroll") for (int k = 0; k < 2; ++k) \
;         acc[ai][bj][m][n] = __builtin_amdgcn_mfma_f32_16x16x32_bf16(Bt[n][k], At[m][k], acc[ai][bj][m][n], 0, 0, 0); __builtin_amdgcn_s_setprio(0); } while (0)
; #define PG8_WAIT_V(n) asm volatile("s_waitcnt vmcnt(" #n ")" ::: "memory")
; #define PG8_WAIT_L(n) asm volatile("s_waitcnt lgkmcnt(" #n ")" ::: "memory")
; template <class Epi, class Sched, bool ALIGN_EPI = false, bool SP2 = false>
; __device__ __forceinline__ void gemm_phase(PG8_LAS unsigned char* lds, const Gemm g, const Sched& S, const Epi& E) {
;     ...
;             const bool last = (t == nt - 2);
;             const char* a1 = cA + (size_t)(t + 1) * kstep;
;             const char* a2 = last ? nA : cA + (size_t)(t + 2) * kstep; const char* b2 = last ? nB : cB + (size_t)(t + 2) * kstep;
;             const char* a3 = a2 + kstep; const char* b3 = b2 + kstep;
;             if (last && has_next) S.a_ready(nxt);
;             if constexpr (SP2) {
;             PG8_LDB(B0, 0, 0); PG8_LDB(B1, 0, 1); PG8_SCHED; PG8_LDA(At, 0, 0); PG8_STAGE(PG8_SA(1, 1), a1 + hstep, voffA);
;             PG8_WAIT_V(8); PG8_WAIT_L(0); PG8_BAR; PG8_MMA(0, 0, At, B0); PG8_MMA(0, 1, At, B1); PG8_BAR; PG8_SCHED;
;             PG8_LDA(At, 0, 1); PG8_STAGE(PG8_SB(0, 0), b2, voffB); PG8_STAGE(PG8_SB(0, 1), b2 + hstep, voffB); PG8_STAGE(PG8_SA(0, 0), a2, voffA);
;             PG8_WAIT_V(8); PG8_WAIT_L(0); PG8_BAR; PG8_MMA(1, 0, At, B0); PG8_MMA(1, 1, At, B1); PG8_BAR; PG8_SCHED;
.LBB0_1482:
	ds_read_b128 v[144:147], v140
	ds_read_b128 v[148:151], v140 offset:1024
	ds_read_b128 v[152:155], v140 offset:2048
	ds_read_b128 v[156:159], v140 offset:3072
	ds_read_b128 v[160:163], v141
	ds_read_b128 v[164:167], v141 offset:1024
	ds_read_b128 v[168:171], v141 offset:2048
	ds_read_b128 v[172:175], v141 offset:3072
	s_add_i32 s75, s40, 2
	s_add_u32 s38, s36, 0x100
	s_addc_u32 s39, s37, 0
	s_cmp_eq_u32 s61, s40
	s_cselect_b32 s40, s34, s73
	s_cselect_b32 s49, s31, s39
	s_cselect_b32 s48, s30, s38
	s_cselect_b32 s41, s35, s74
	v_lshl_add_u64 v[184:185], s[36:37], 0, v[134:135]
	s_add_i32 m0, s53, 0xc000
	ds_read_b128 v[176:179], v142
	ds_read_b128 v[180:183], v142 offset:1024
	ds_read_b128 v[188:191], v142 offset:2048
	ds_read_b128 v[192:195], v142 offset:3072
	ds_read_b128 v[196:199], v142 offset:4096
	ds_read_b128 v[200:203], v142 offset:5120
	ds_read_b128 v[204:207], v142 offset:6144
	ds_read_b128 v[208:211], v142 offset:7168
	global_load_lds_dwordx4 v[184:185], off
	v_lshl_add_u64 v[184:185], s[36:37], 0, v[136:137]
	s_add_i32 m0, s53, 0xe000
	s_nop 0
	global_load_lds_dwordx4 v[184:185], off
	s_waitcnt vmcnt(8)
	s_waitcnt lgkmcnt(0)
	s_barrier
	s_setprio 1
	s_waitcnt lgkmcnt(0)
	v_mfma_f32_16x16x32_bf16 v[126:129], v[144:147], v[176:179], v[126:129]
	v_mfma_f32_16x16x32_bf16 v[122:125], v[152:155], v[176:179], v[122:125]
	v_mfma_f32_16x16x32_bf16 v[110:113], v[144:147], v[188:191], v[110:113]
	v_mfma_f32_16x16x32_bf16 v[106:109], v[152:155], v[188:191], v[106:109]
	v_mfma_f32_16x16x32_bf16 v[94:97], v[144:147], v[196:199], v[94:97]
	v_mfma_f32_16x16x32_bf16 v[90:93], v[152:155], v[196:199], v[90:93]
	v_mfma_f32_16x16x32_bf16 v[78:81], v[144:147], v[204:207], v[78:81]
	v_mfma_f32_16x16x32_bf16 v[74:77], v[152:155], v[204:207], v[74:77]
	v_mfma_f32_16x16x32_bf16 v[126:129], v[148:151], v[180:183], v[126:129]
	v_mfma_f32_16x16x32_bf16 v[122:125], v[156:159], v[180:183], v[122:125]
	v_mfma_f32_16x16x32_bf16 v[110:113], v[148:151], v[192:195], v[110:113]
	v_mfma_f32_16x16x32_bf16 v[106:109], v[156:159], v[192:195], v[106:109]
	v_mfma_f32_16x16x32_bf16 v[94:97], v[148:151], v[200:203], v[94:97]
	v_mfma_f32_16x16x32_bf16 v[90:93], v[156:159], v[200:203], v[90:93]
	v_mfma_f32_16x16x32_bf16 v[78:81], v[148:151], v[208:211], v[78:81]
	v_mfma_f32_16x16x32_bf16 v[74:77], v[156:159], v[208:211], v[74:77]
	s_setprio 0
	s_setprio 1
	v_mfma_f32_16x16x32_bf16 v[118:121], v[160:163], v[176:179], v[118:121]
	v_mfma_f32_16x16x32_bf16 v[114:117], v[168:171], v[176:179], v[114:117]
	v_mfma_f32_16x16x32_bf16 v[102:105], v[160:163], v[188:191], v[102:105]
	v_mfma_f32_16x16x32_bf16 v[98:101], v[168:171], v[188:191], v[98:101]
	v_mfma_f32_16x16x32_bf16 v[86:89], v[160:163], v[196:199], v[86:89]
	v_mfma_f32_16x16x32_bf16 v[82:85], v[168:171], v[196:199], v[82:85]
	v_mfma_f32_16x16x32_bf16 v[70:73], v[160:163], v[204:207], v[70:73]
	v_mfma_f32_16x16x32_bf16 v[66:69], v[168:171], v[204:207], v[66:69]
	v_mfma_f32_16x16x32_bf16 v[118:121], v[164:167], v[180:183], v[118:121]
	v_mfma_f32_16x16x32_bf16 v[114:117], v[172:175], v[180:183], v[114:117]
	v_mfma_f32_16x16x32_bf16 v[102:105], v[164:167], v[192:195], v[102:105]
	v_mfma_f32_16x16x32_bf16 v[98:101], v[172:175], v[192:195], v[98:101]
	v_mfma_f32_16x16x32_bf16 v[86:89], v[164:167], v[200:203], v[86:89]
	v_mfma_f32_16x16x32_bf16 v[82:85], v[172:175], v[200:203], v[82:85]
	v_mfma_f32_16x16x32_bf16 v[70:73], v[164:167], v[208:211], v[70:73]
	v_mfma_f32_16x16x32_bf16 v[66:69], v[172:175], v[208:211], v[66:69]
	s_setprio 0
	s_barrier
	s_add_i32 s36, s62, s52
	v_lshl_add_u64 v[184:185], s[40:41], 0, v[132:133]
	s_mov_b32 m0, s36
	ds_read_b128 v[176:179], v142 offset:16384
	ds_read_b128 v[180:183], v142 offset:17408
	ds_read_b128 v[188:191], v142 offset:18432
	ds_read_b128 v[192:195], v142 offset:19456
	ds_read_b128 v[196:199], v142 offset:20480
	ds_read_b128 v[200:203], v142 offset:21504
	ds_read_b128 v[204:207], v142 offset:22528
	ds_read_b128 v[208:211], v142 offset:23552
	global_load_lds_dwordx4 v[184:185], off
	s_add_i32 m0, s36, 0x2000
	s_add_u32 s36, s40, 0x60000
	v_lshl_add_u64 v[212:213], s[40:41], 0, v[130:131]
	s_addc_u32 s37, s41, 0
	s_add_i32 s76, s63, s52
	global_load_lds_dwordx4 v[212:213], off
	v_lshl_add_u64 v[214:215], s[36:37], 0, v[132:133]
	s_mov_b32 m0, s76
	v_lshl_add_u64 v[216:217], s[48:49], 0, v[130:131]
	global_load_lds_dwordx4 v[214:215], off
	v_lshl_add_u64 v[214:215], s[36:37], 0, v[130:131]
	s_add_i32 m0, s76, 0x2000
	s_nop 0
	global_load_lds_dwordx4 v[214:215], off
	v_lshl_add_u64 v[214:215], s[48:49], 0, v[132:133]
	s_mov_b32 m0, s53
	s_nop 0
	global_load_lds_dwordx4 v[214:215], off
	s_mov_b32 m0, s54
	s_nop 0
	global_load_lds_dwordx4 v[216:217], off
	s_waitcnt vmcnt(8)
	s_waitcnt lgkmcnt(0)
	s_barrier
; #define PG8_STAGE(bufoff, gbase, voff) do { _Pragma("unroll") for (int _i = 0; _i < 2; ++_i) \
;         __builtin_amdgcn_global_load_lds((const unsigned*)((const char*)(gbase) + (voff)[_i]), (PG8_LAS unsigned*)(lds + (bufoff) + ldsw + _i * 8192), 16, 0, 0); } while (0)
; #define PG8_LDA(dst, b, h) do { _Pragma("unroll") for (int m = 0; m < 4; ++m) _Pragma("unroll") for (int k = 0; k < 2; ++k) dst[m][k] = *(const PG8_LAS bf16x8*)(lds + PG8_SA(b, h) + aoff + m * 2048 + k * 1024); } while (0)
; #define PG8_LDB(dst, b, h) do { _Pragma("unroll") for (int n = 0; n < 2; ++n) _Pragma("unroll") for (int k = 0; k < 2; ++k) dst[n][k] = *(const PG8_LAS bf16x8*)(lds + PG8_SB(b, h) + boff + n * 2048 + k * 1024); } while (0)
; #define PG8_MMA(ai, bj, At, Bt) do { __builtin_amdgcn_s_setprio(1); _Pragma("unroll") for (int m = 0; m < 4; ++m) _Pragma("unroll") for (int n = 0; n < 2; ++n) _Pragma("unroll") for (int k = 0; k < 2; ++k) \
;         acc[ai][bj][m][n] = __builtin_amdgcn_mfma_f32_16x16x32_bf16(Bt[n][k], At[m][k], acc[ai][bj][m][n], 0, 0, 0); __builtin_amdgcn_s_setprio(0); } while (0)
; #define PG8_WAIT_V(n) asm volatile("s_waitcnt vmcnt(" #n ")" ::: "memory")
; #define PG8_WAIT_L(n) asm volatile("s_waitcnt lgkmcnt(" #n ")" ::: "memory")
; #define PG8_BAR __builtin_amdgcn_s_barrier()
; #define PG8_SCHED __builtin_amdgcn_sched_barrier(0)
; template <class Epi, class Sched, bool ALIGN_EPI = false, bool SP2 = false>
; __device__ __forceinline__ void gemm_phase(PG8_LAS unsigned char* lds, const Gemm g, const Sched& S, const Epi& E) {
;     ...
;             PG8_WAIT_V(8); PG8_WAIT_L(0); PG8_BAR; PG8_MMA(1, 0, At, B0); PG8_MMA(1, 1, At, B1); PG8_BAR; PG8_SCHED;
;             PG8_LDB(B0, 1, 0); PG8_LDB(B1, 1, 1); PG8_SCHED; PG8_LDA(At, 1, 0); PG8_STAGE(PG8_SA(0, 1), a2 + hstep, voffA);
;             PG8_WAIT_V(8); PG8_WAIT_L(0); PG8_BAR; PG8_MMA(0, 0, At, B0); PG8_MMA(0, 1, At, B1); PG8_BAR; PG8_SCHED;
	s_setprio 1
	s_waitcnt lgkmcnt(0)
	v_mfma_f32_16x16x32_bf16 v[62:65], v[144:147], v[176:179], v[62:65]
	v_mfma_f32_16x16x32_bf16 v[58:61], v[152:155], v[176:179], v[58:61]
	v_mfma_f32_16x16x32_bf16 v[46:49], v[144:147], v[188:191], v[46:49]
	v_mfma_f32_16x16x32_bf16 v[42:45], v[152:155], v[188:191], v[42:45]
	v_mfma_f32_16x16x32_bf16 v[30:33], v[144:147], v[196:199], v[30:33]
	v_mfma_f32_16x16x32_bf16 v[26:29], v[152:155], v[196:199], v[26:29]
	v_mfma_f32_16x16x32_bf16 v[14:17], v[144:147], v[204:207], v[14:17]
	v_mfma_f32_16x16x32_bf16 v[10:13], v[152:155], v[204:207], v[10:13]
	v_mfma_f32_16x16x32_bf16 v[62:65], v[148:151], v[180:183], v[62:65]
	v_mfma_f32_16x16x32_bf16 v[58:61], v[156:159], v[180:183], v[58:61]
	v_mfma_f32_16x16x32_bf16 v[46:49], v[148:151], v[192:195], v[46:49]
	v_mfma_f32_16x16x32_bf16 v[42:45], v[156:159], v[192:195], v[42:45]
	v_mfma_f32_16x16x32_bf16 v[30:33], v[148:151], v[200:203], v[30:33]
	v_mfma_f32_16x16x32_bf16 v[26:29], v[156:159], v[200:203], v[26:29]
	v_mfma_f32_16x16x32_bf16 v[14:17], v[148:151], v[208:211], v[14:17]
	v_mfma_f32_16x16x32_bf16 v[10:13], v[156:159], v[208:211], v[10:13]
	s_setprio 0
	s_setprio 1
	v_mfma_f32_16x16x32_bf16 v[54:57], v[160:163], v[176:179], v[54:57]
	v_mfma_f32_16x16x32_bf16 v[50:53], v[168:171], v[176:179], v[50:53]
	v_mfma_f32_16x16x32_bf16 v[38:41], v[160:163], v[188:191], v[38:41]
	v_mfma_f32_16x16x32_bf16 v[34:37], v[168:171], v[188:191], v[34:37]
	v_mfma_f32_16x16x32_bf16 v[22:25], v[160:163], v[196:199], v[22:25]
	v_mfma_f32_16x16x32_bf16 v[18:21], v[168:171], v[196:199], v[18:21]
	v_mfma_f32_16x16x32_bf16 v[6:9], v[160:163], v[204:207], v[6:9]
	v_mfma_f32_16x16x32_bf16 v[2:5], v[168:171], v[204:207], v[2:5]
	v_mfma_f32_16x16x32_bf16 v[54:57], v[164:167], v[180:183], v[54:57]
	v_mfma_f32_16x16x32_bf16 v[50:53], v[172:175], v[180:183], v[50:53]
	v_mfma_f32_16x16x32_bf16 v[38:41], v[164:167], v[192:195], v[38:41]
	v_mfma_f32_16x16x32_bf16 v[34:37], v[172:175], v[192:195], v[34:37]
	v_mfma_f32_16x16x32_bf16 v[22:25], v[164:167], v[200:203], v[22:25]
	v_mfma_f32_16x16x32_bf16 v[18:21], v[172:175], v[200:203], v[18:21]
	v_mfma_f32_16x16x32_bf16 v[6:9], v[164:167], v[208:211], v[6:9]
	v_mfma_f32_16x16x32_bf16 v[2:5], v[172:175], v[208:211], v[2:5]
	s_setprio 0
	s_barrier
	s_add_i32 s76, 0, 0x18000
	v_add_u32_e32 v143, s76, v1
	s_add_i32 s77, 0, 0x1c000
	ds_read_b128 v[144:147], v143
	ds_read_b128 v[148:151], v143 offset:1024
	ds_read_b128 v[152:155], v143 offset:2048
	ds_read_b128 v[156:159], v143 offset:3072
	v_add_u32_e32 v143, s77, v1
	ds_read_b128 v[160:163], v143
	ds_read_b128 v[164:167], v143 offset:1024
	ds_read_b128 v[168:171], v143 offset:2048
	ds_read_b128 v[172:175], v143 offset:3072
	s_add_u32 s36, s48, 0x60000
	s_addc_u32 s37, s49, 0
	s_mov_b32 m0, s55
	v_lshl_add_u64 v[218:219], s[36:37], 0, v[132:133]
	ds_read_b128 v[176:179], v142 offset:32768
	ds_read_b128 v[180:183], v142 offset:33792
	ds_read_b128 v[188:191], v142 offset:34816
	ds_read_b128 v[192:195], v142 offset:35840
	ds_read_b128 v[196:199], v142 offset:36864
	ds_read_b128 v[200:203], v142 offset:37888
	ds_read_b128 v[204:207], v142 offset:38912
	ds_read_b128 v[208:211], v142 offset:39936
	global_load_lds_dwordx4 v[218:219], off
	v_lshl_add_u64 v[218:219], s[36:37], 0, v[130:131]
	s_mov_b32 m0, s56
	s_nop 0
	global_load_lds_dwordx4 v[218:219], off
	s_waitcnt vmcnt(8)
	s_waitcnt lgkmcnt(0)
	s_barrier
	s_setprio 1
	s_waitcnt lgkmcnt(0)
	v_mfma_f32_16x16x32_bf16 v[126:129], v[144:147], v[176:179], v[126:129]
	v_mfma_f32_16x16x32_bf16 v[122:125], v[152:155], v[176:179], v[122:125]
	v_mfma_f32_16x16x32_bf16 v[110:113], v[144:147], v[188:191], v[110:113]
	v_mfma_f32_16x16x32_bf16 v[106:109], v[152:155], v[188:191], v[106:109]
	v_mfma_f32_16x16x32_bf16 v[94:97], v[144:147], v[196:199], v[94:97]
	v_mfma_f32_16x16x32_bf16 v[90:93], v[152:155], v[196:199], v[90:93]
	v_mfma_f32_16x16x32_bf16 v[78:81], v[144:147], v[204:207], v[78:81]
	v_mfma_f32_16x16x32_bf16 v[74:77], v[152:155], v[204:207], v[74:77]
	v_mfma_f32_16x16x32_bf16 v[126:129], v[148:151], v[180:183], v[126:129]
	v_mfma_f32_16x16x32_bf16 v[122:125], v[156:159], v[180:183], v[122:125]
	v_mfma_f32_16x16x32_bf16 v[110:113], v[148:151], v[192:195], v[110:113]
	v_mfma_f32_16x16x32_bf16 v[106:109], v[156:159], v[192:195], v[106:109]
	v_mfma_f32_16x16x32_bf16 v[94:97], v[148:151], v[200:203], v[94:97]
	v_mfma_f32_16x16x32_bf16 v[90:93], v[156:159], v[200:203], v[90:93]
	v_mfma_f32_16x16x32_bf16 v[78:81], v[148:151], v[208:211], v[78:81]
	v_mfma_f32_16x16x32_bf16 v[74:77], v[156:159], v[208:211], v[74:77]
	s_setprio 0
	s_setprio 1
	v_mfma_f32_16x16x32_bf16 v[118:121], v[160:163], v[176:179], v[118:121]
	v_mfma_f32_16x16x32_bf16 v[114:117], v[168:171], v[176:179], v[114:117]
	v_mfma_f32_16x16x32_bf16 v[102:105], v[160:163], v[188:191], v[102:105]
	v_mfma_f32_16x16x32_bf16 v[98:101], v[168:171], v[188:191], v[98:101]
	v_mfma_f32_16x16x32_bf16 v[86:89], v[160:163], v[196:199], v[86:89]
	v_mfma_f32_16x16x32_bf16 v[82:85], v[168:171], v[196:199], v[82:85]
	v_mfma_f32_16x16x32_bf16 v[70:73], v[160:163], v[204:207], v[70:73]
	v_mfma_f32_16x16x32_bf16 v[66:69], v[168:171], v[204:207], v[66:69]
	v_mfma_f32_16x16x32_bf16 v[118:121], v[164:167], v[180:183], v[118:121]
	v_mfma_f32_16x16x32_bf16 v[114:117], v[172:175], v[180:183], v[114:117]
	v_mfma_f32_16x16x32_bf16 v[102:105], v[164:167], v[192:195], v[102:105]
	v_mfma_f32_16x16x32_bf16 v[98:101], v[172:175], v[192:195], v[98:101]
	v_mfma_f32_16x16x32_bf16 v[86:89], v[164:167], v[200:203], v[86:89]
	v_mfma_f32_16x16x32_bf16 v[82:85], v[172:175], v[200:203], v[82:85]
	v_mfma_f32_16x16x32_bf16 v[70:73], v[164:167], v[208:211], v[70:73]
	v_mfma_f32_16x16x32_bf16 v[66:69], v[172:175], v[208:211], v[66:69]
	s_setprio 0
	s_barrier
; #define PG8_STAGE(bufoff, gbase, voff) do { _Pragma("unroll") for (int _i = 0; _i < 2; ++_i) \
;         __builtin_amdgcn_global_load_lds((const unsigned*)((const char*)(gbase) + (voff)[_i]), (PG8_LAS unsigned*)(lds + (bufoff) + ldsw + _i * 8192), 16, 0, 0); } while (0)
; #define PG8_LDA(dst, b, h) do { _Pragma("unroll") for (int m = 0; m < 4; ++m) _Pragma("unroll") for (int k = 0; k < 2; ++k) dst[m][k] = *(const PG8_LAS bf16x8*)(lds + PG8_SA(b, h) + aoff + m * 2048 + k * 1024); } while (0)
; #define PG8_MMA(ai, bj, At, Bt) do { __builtin_amdgcn_s_setprio(1); _Pragma("unroll") for (int m = 0; m < 4; ++m) _Pragma("unroll") for (int n = 0; n < 2; ++n) _Pragma("unroll") for (int k = 0; k < 2; ++k) \
;         acc[ai][bj][m][n] = __builtin_amdgcn_mfma_f32_16x16x32_bf16(Bt[n][k], At[m][k], acc[ai][bj][m][n], 0, 0, 0); __builtin_amdgcn_s_setprio(0); } while (0)
; #define PG8_WAIT_V(n) asm volatile("s_waitcnt vmcnt(" #n ")" ::: "memory")
; #define PG8_WAIT_L(n) asm volatile("s_waitcnt lgkmcnt(" #n ")" ::: "memory")
; #define PG8_BAR __builtin_amdgcn_s_barrier()
; #define PG8_SCHED __builtin_amdgcn_sched_barrier(0)
; template <class Epi, class Sched, bool ALIGN_EPI = false, bool SP2 = false>
; __device__ __forceinline__ void gemm_phase(PG8_LAS unsigned char* lds, const Gemm g, const Sched& S, const Epi& E) {
;     ...
;         for (int t = 0; t < nt; t += 2) {
;             const bool last = (t == nt - 2);
;             const char* a1 = cA + (size_t)(t + 1) * kstep;
;             const char* a2 = last ? nA : cA + (size_t)(t + 2) * kstep; const char* b2 = last ? nB : cB + (size_t)(t + 2) * kstep;
;             const char* a3 = a2 + kstep; const char* b3 = b2 + kstep;
;     ...
;             PG8_LDA(At, 1, 1); PG8_STAGE(PG8_SB(1, 0), b3, voffB); PG8_STAGE(PG8_SB(1, 1), b3 + hstep, voffB); PG8_STAGE(PG8_SA(1, 0), a3, voffA);
;             PG8_WAIT_V(8); PG8_WAIT_L(0); PG8_BAR; PG8_MMA(1, 0, At, B0); PG8_MMA(1, 1, At, B1); PG8_BAR; PG8_SCHED;
	s_add_i32 s36, s76, s52
	v_lshl_add_u64 v[184:185], v[184:185], 0, s[16:17]
	s_mov_b32 m0, s36
	ds_read_b128 v[176:179], v142 offset:49152
	ds_read_b128 v[180:183], v142 offset:50176
	ds_read_b128 v[188:191], v142 offset:51200
	ds_read_b128 v[192:195], v142 offset:52224
	ds_read_b128 v[196:199], v142 offset:53248
	ds_read_b128 v[200:203], v142 offset:54272
	ds_read_b128 v[204:207], v142 offset:55296
	ds_read_b128 v[208:211], v142 offset:56320
	global_load_lds_dwordx4 v[184:185], off
	s_add_i32 m0, s36, 0x2000
	s_add_u32 s36, s40, 0x60080
	v_lshl_add_u64 v[184:185], v[212:213], 0, s[16:17]
	s_addc_u32 s37, s41, 0
	s_add_i32 s40, s77, s52
	global_load_lds_dwordx4 v[184:185], off
	v_lshl_add_u64 v[184:185], s[36:37], 0, v[132:133]
	s_mov_b32 m0, s40
	s_nop 0
	global_load_lds_dwordx4 v[184:185], off
	v_lshl_add_u64 v[184:185], s[36:37], 0, v[130:131]
	s_add_i32 m0, s40, 0x2000
	s_nop 0
	global_load_lds_dwordx4 v[184:185], off
	v_lshl_add_u64 v[184:185], v[214:215], 0, s[16:17]
	s_mov_b32 m0, s59
	s_nop 0
	global_load_lds_dwordx4 v[184:185], off
	v_lshl_add_u64 v[184:185], v[216:217], 0, s[16:17]
	s_mov_b32 m0, s60
	s_nop 0
	global_load_lds_dwordx4 v[184:185], off
	s_waitcnt vmcnt(8)
	s_waitcnt lgkmcnt(0)
	s_barrier
	s_setprio 1
	s_waitcnt lgkmcnt(0)
	v_mfma_f32_16x16x32_bf16 v[62:65], v[144:147], v[176:179], v[62:65]
	v_mfma_f32_16x16x32_bf16 v[58:61], v[152:155], v[176:179], v[58:61]
	v_mfma_f32_16x16x32_bf16 v[46:49], v[144:147], v[188:191], v[46:49]
	v_mfma_f32_16x16x32_bf16 v[42:45], v[152:155], v[188:191], v[42:45]
	v_mfma_f32_16x16x32_bf16 v[30:33], v[144:147], v[196:199], v[30:33]
	v_mfma_f32_16x16x32_bf16 v[26:29], v[152:155], v[196:199], v[26:29]
	v_mfma_f32_16x16x32_bf16 v[14:17], v[144:147], v[204:207], v[14:17]
	v_mfma_f32_16x16x32_bf16 v[10:13], v[152:155], v[204:207], v[10:13]
	v_mfma_f32_16x16x32_bf16 v[62:65], v[148:151], v[180:183], v[62:65]
	v_mfma_f32_16x16x32_bf16 v[58:61], v[156:159], v[180:183], v[58:61]
	v_mfma_f32_16x16x32_bf16 v[46:49], v[148:151], v[192:195], v[46:49]
	v_mfma_f32_16x16x32_bf16 v[42:45], v[156:159], v[192:195], v[42:45]
	v_mfma_f32_16x16x32_bf16 v[30:33], v[148:151], v[200:203], v[30:33]
	v_mfma_f32_16x16x32_bf16 v[26:29], v[156:159], v[200:203], v[26:29]
	v_mfma_f32_16x16x32_bf16 v[14:17], v[148:151], v[208:211], v[14:17]
	v_mfma_f32_16x16x32_bf16 v[10:13], v[156:159], v[208:211], v[10:13]
	s_setprio 0
	s_setprio 1
	v_mfma_f32_16x16x32_bf16 v[54:57], v[160:163], v[176:179], v[54:57]
	v_mfma_f32_16x16x32_bf16 v[50:53], v[168:171], v[176:179], v[50:53]
	v_mfma_f32_16x16x32_bf16 v[38:41], v[160:163], v[188:191], v[38:41]
	v_mfma_f32_16x16x32_bf16 v[34:37], v[168:171], v[188:191], v[34:37]
	v_mfma_f32_16x16x32_bf16 v[22:25], v[160:163], v[196:199], v[22:25]
	v_mfma_f32_16x16x32_bf16 v[18:21], v[168:171], v[196:199], v[18:21]
	v_mfma_f32_16x16x32_bf16 v[6:9], v[160:163], v[204:207], v[6:9]
	v_mfma_f32_16x16x32_bf16 v[2:5], v[168:171], v[204:207], v[2:5]
	v_mfma_f32_16x16x32_bf16 v[54:57], v[164:167], v[180:183], v[54:57]
	v_mfma_f32_16x16x32_bf16 v[50:53], v[172:175], v[180:183], v[50:53]
	v_mfma_f32_16x16x32_bf16 v[38:41], v[164:167], v[192:195], v[38:41]
	v_mfma_f32_16x16x32_bf16 v[34:37], v[172:175], v[192:195], v[34:37]
	v_mfma_f32_16x16x32_bf16 v[22:25], v[164:167], v[200:203], v[22:25]
	v_mfma_f32_16x16x32_bf16 v[18:21], v[172:175], v[200:203], v[18:21]
	v_mfma_f32_16x16x32_bf16 v[6:9], v[164:167], v[208:211], v[6:9]
	v_mfma_f32_16x16x32_bf16 v[2:5], v[172:175], v[208:211], v[2:5]
	s_setprio 0
	s_add_u32 s73, s73, 0x100
	s_addc_u32 s74, s74, 0
	s_cmp_ge_i32 s75, s58
	s_mov_b64 s[36:37], s[38:39]
	s_mov_b32 s40, s75
	s_barrier
	s_cbranch_scc0 .LBB0_1482

; #define PG8_STAGE(bufoff, gbase, voff) do { _Pragma("unroll") for (int _i = 0; _i < 2; ++_i) \
;         __builtin_amdgcn_global_load_lds((const unsigned*)((const char*)(gbase) + (voff)[_i]), (PG8_LAS unsigned*)(lds + (bufoff) + ldsw + _i * 8192), 16, 0, 0); } while (0)
; #define PG8_LDA(dst, b, h) do { _Pragma("unroll") for (int m = 0; m < 4; ++m) _Pragma("unroll") for (int k = 0; k < 2; ++k) dst[m][k] = *(const PG8_LAS bf16x8*)(lds + PG8_SA(b, h) + aoff + m * 2048 + k * 1024); } while (0)
; #define PG8_LDB(dst, b, h) do { _Pragma("unroll") for (int n = 0; n < 2; ++n) _Pragma("unroll") for (int k = 0; k < 2; ++k) dst[n][k] = *(const PG8_LAS bf16x8*)(lds + PG8_SB(b, h) + boff + n * 2048 + k * 1024); } while (0)
; #define PG8_MMA(ai, bj, At, Bt) do { __builtin_amdgcn_s_setprio(1); _Pragma("unroll") for (int m = 0; m < 4; ++m) _Pragma("unroll") for (int n = 0; n < 2; ++n) _Pragma("unroll") for (int k = 0; k < 2; ++k) \
;         acc[ai][bj][m][n] = __builtin_amdgcn_mfma_f32_16x16x32_bf16(Bt[n][k], At[m][k], acc[ai][bj][m][n], 0, 0, 0); __builtin_amdgcn_s_setprio(0); } while (0)
; #define PG8_WAIT_V(n) asm volatile("s_waitcnt vmcnt(" #n ")" ::: "memory")
; #define PG8_WAIT_L(n) asm volatile("s_waitcnt lgkmcnt(" #n ")" ::: "memory")
; template <class Epi, class Sched, bool ALIGN_EPI = false, bool SP2 = false>
; __device__ __forceinline__ void gemm_phase(PG8_LAS unsigned char* lds, const Gemm g, const Sched& S, const Epi& E) {
;     ...
;             const bool last = (t == nt - 2);
;             const char* a1 = cA + (size_t)(t + 1) * kstep;
;             const char* a2 = last ? nA : cA + (size_t)(t + 2) * kstep; const char* b2 = last ? nB : cB + (size_t)(t + 2) * kstep;
;             const char* a3 = a2 + kstep; const char* b3 = b2 + kstep;
;             if (last && has_next) S.a_ready(nxt);
;             if constexpr (SP2) {
;             PG8_LDB(B0, 0, 0); PG8_LDB(B1, 0, 1); PG8_SCHED; PG8_LDA(At, 0, 0); PG8_STAGE(PG8_SA(1, 1), a1 + hstep, voffA);
;             PG8_WAIT_V(8); PG8_WAIT_L(0); PG8_BAR; PG8_MMA(0, 0, At, B0); PG8_MMA(0, 1, At, B1); PG8_BAR; PG8_SCHED;
;             PG8_LDA(At, 0, 1); PG8_STAGE(PG8_SB(0, 0), b2, voffB); PG8_STAGE(PG8_SB(0, 1), b2 + hstep, voffB); PG8_STAGE(PG8_SA(0, 0), a2, voffA);
;             PG8_WAIT_V(8); PG8_WAIT_L(0); PG8_BAR; PG8_MMA(1, 0, At, B0); PG8_MMA(1, 1, At, B1); PG8_BAR; PG8_SCHED;
.LBB0_1523:
	v_add_u32_e32 v162, s56, v148
	v_add_u32_e32 v178, s57, v148
	s_add_u32 s34, s18, s30
	ds_read_b128 v[150:153], v162
	ds_read_b128 v[154:157], v162 offset:1024
	ds_read_b128 v[158:161], v162 offset:2048
	ds_read_b128 v[162:165], v162 offset:3072
	ds_read_b128 v[166:169], v178
	ds_read_b128 v[170:173], v178 offset:1024
	ds_read_b128 v[174:177], v178 offset:2048
	ds_read_b128 v[178:181], v178 offset:3072
	s_addc_u32 s35, s19, s31
	s_add_u32 s34, s34, 0x100
	s_addc_u32 s35, s35, 0
	s_add_u32 s65, s59, s30
	s_addc_u32 s66, s60, s31
	s_cmpk_eq_i32 s30, 0x700
	s_cselect_b32 s37, s25, s35
	s_cselect_b32 s36, s61, s34
	s_cselect_b32 s35, s23, s66
	s_cselect_b32 s34, s62, s65
	v_lshl_add_u64 v[216:217], v[142:143], 0, s[30:31]
	s_add_i32 m0, s48, 0xc000
	ds_read_b128 v[182:185], v149
	ds_read_b128 v[188:191], v149 offset:1024
	ds_read_b128 v[192:195], v149 offset:2048
	ds_read_b128 v[196:199], v149 offset:3072
	ds_read_b128 v[200:203], v149 offset:4096
	ds_read_b128 v[204:207], v149 offset:5120
	ds_read_b128 v[208:211], v149 offset:6144
	ds_read_b128 v[212:215], v149 offset:7168
	global_load_lds_dwordx4 v[216:217], off
	v_lshl_add_u64 v[216:217], v[144:145], 0, s[30:31]
	s_add_i32 m0, s48, 0xe000
	s_nop 0
	global_load_lds_dwordx4 v[216:217], off
	s_waitcnt vmcnt(8)
	s_waitcnt lgkmcnt(0)
	s_barrier
	s_setprio 1
	s_waitcnt lgkmcnt(0)
	v_mfma_f32_16x16x32_bf16 v[110:113], v[150:153], v[182:185], v[110:113]
	v_mfma_f32_16x16x32_bf16 v[74:77], v[158:161], v[182:185], v[74:77]
	v_mfma_f32_16x16x32_bf16 v[118:121], v[150:153], v[192:195], v[118:121]
	v_mfma_f32_16x16x32_bf16 v[94:97], v[158:161], v[192:195], v[94:97]
	v_mfma_f32_16x16x32_bf16 v[126:129], v[150:153], v[200:203], v[126:129]
	v_mfma_f32_16x16x32_bf16 v[106:109], v[158:161], v[200:203], v[106:109]
	v_mfma_f32_16x16x32_bf16 v[122:125], v[150:153], v[208:211], v[122:125]
	v_mfma_f32_16x16x32_bf16 v[114:117], v[158:161], v[208:211], v[114:117]
	v_mfma_f32_16x16x32_bf16 v[110:113], v[154:157], v[188:191], v[110:113]
	v_mfma_f32_16x16x32_bf16 v[74:77], v[162:165], v[188:191], v[74:77]
	v_mfma_f32_16x16x32_bf16 v[118:121], v[154:157], v[196:199], v[118:121]
	v_mfma_f32_16x16x32_bf16 v[94:97], v[162:165], v[196:199], v[94:97]
	v_mfma_f32_16x16x32_bf16 v[126:129], v[154:157], v[204:207], v[126:129]
	v_mfma_f32_16x16x32_bf16 v[106:109], v[162:165], v[204:207], v[106:109]
	v_mfma_f32_16x16x32_bf16 v[122:125], v[154:157], v[212:215], v[122:125]
	v_mfma_f32_16x16x32_bf16 v[114:117], v[162:165], v[212:215], v[114:117]
	s_setprio 0
	s_setprio 1
	v_mfma_f32_16x16x32_bf16 v[46:49], v[166:169], v[182:185], v[46:49]
	v_mfma_f32_16x16x32_bf16 v[14:17], v[174:177], v[182:185], v[14:17]
	v_mfma_f32_16x16x32_bf16 v[54:57], v[166:169], v[192:195], v[54:57]
	v_mfma_f32_16x16x32_bf16 v[30:33], v[174:177], v[192:195], v[30:33]
	v_mfma_f32_16x16x32_bf16 v[70:73], v[166:169], v[200:203], v[70:73]
	v_mfma_f32_16x16x32_bf16 v[42:45], v[174:177], v[200:203], v[42:45]
	v_mfma_f32_16x16x32_bf16 v[86:89], v[166:169], v[208:211], v[86:89]
	v_mfma_f32_16x16x32_bf16 v[50:53], v[174:177], v[208:211], v[50:53]
	v_mfma_f32_16x16x32_bf16 v[46:49], v[170:173], v[188:191], v[46:49]
	v_mfma_f32_16x16x32_bf16 v[14:17], v[178:181], v[188:191], v[14:17]
	v_mfma_f32_16x16x32_bf16 v[54:57], v[170:173], v[196:199], v[54:57]
	v_mfma_f32_16x16x32_bf16 v[30:33], v[178:181], v[196:199], v[30:33]
	v_mfma_f32_16x16x32_bf16 v[70:73], v[170:173], v[204:207], v[70:73]
	v_mfma_f32_16x16x32_bf16 v[42:45], v[178:181], v[204:207], v[42:45]
	v_mfma_f32_16x16x32_bf16 v[86:89], v[170:173], v[212:215], v[86:89]
	v_mfma_f32_16x16x32_bf16 v[50:53], v[178:181], v[212:215], v[50:53]
	s_setprio 0
	s_barrier
	s_add_i32 s65, s56, s43
	v_lshl_add_u64 v[216:217], s[34:35], 0, v[130:131]
	s_mov_b32 m0, s65
	ds_read_b128 v[182:185], v149 offset:16384
	ds_read_b128 v[188:191], v149 offset:17408
	ds_read_b128 v[192:195], v149 offset:18432
	ds_read_b128 v[196:199], v149 offset:19456
	ds_read_b128 v[200:203], v149 offset:20480
	ds_read_b128 v[204:207], v149 offset:21504
	ds_read_b128 v[208:211], v149 offset:22528
	ds_read_b128 v[212:215], v149 offset:23552
	global_load_lds_dwordx4 v[216:217], off
	s_add_i32 m0, s65, 0x2000
	s_add_u32 s66, s34, 0x40000
	v_lshl_add_u64 v[218:219], s[34:35], 0, v[132:133]
	s_addc_u32 s67, s35, 0
	s_add_i32 s65, s57, s43
	global_load_lds_dwordx4 v[218:219], off
	v_lshl_add_u64 v[220:221], s[66:67], 0, v[130:131]
	s_mov_b32 m0, s65
	v_lshl_add_u64 v[222:223], s[36:37], 0, v[132:133]
	global_load_lds_dwordx4 v[220:221], off
	v_lshl_add_u64 v[220:221], s[66:67], 0, v[132:133]
	s_add_i32 m0, s65, 0x2000
	s_nop 0
	global_load_lds_dwordx4 v[220:221], off
	v_lshl_add_u64 v[220:221], s[36:37], 0, v[130:131]
	s_mov_b32 m0, s48
	s_nop 0
	global_load_lds_dwordx4 v[220:221], off
	s_mov_b32 m0, s49
	s_nop 0
	global_load_lds_dwordx4 v[222:223], off
	s_waitcnt vmcnt(8)
	s_waitcnt lgkmcnt(0)
	s_barrier
; #define PG8_STAGE(bufoff, gbase, voff) do { _Pragma("unroll") for (int _i = 0; _i < 2; ++_i) \
;         __builtin_amdgcn_global_load_lds((const unsigned*)((const char*)(gbase) + (voff)[_i]), (PG8_LAS unsigned*)(lds + (bufoff) + ldsw + _i * 8192), 16, 0, 0); } while (0)
; #define PG8_LDA(dst, b, h) do { _Pragma("unroll") for (int m = 0; m < 4; ++m) _Pragma("unroll") for (int k = 0; k < 2; ++k) dst[m][k] = *(const PG8_LAS bf16x8*)(lds + PG8_SA(b, h) + aoff + m * 2048 + k * 1024); } while (0)
; #define PG8_LDB(dst, b, h) do { _Pragma("unroll") for (int n = 0; n < 2; ++n) _Pragma("unroll") for (int k = 0; k < 2; ++k) dst[n][k] = *(const PG8_LAS bf16x8*)(lds + PG8_SB(b, h) + boff + n * 2048 + k * 1024); } while (0)
; #define PG8_MMA(ai, bj, At, Bt) do { __builtin_amdgcn_s_setprio(1); _Pragma("unroll") for (int m = 0; m < 4; ++m) _Pragma("unroll") for (int n = 0; n < 2; ++n) _Pragma("unroll") for (int k = 0; k < 2; ++k) \
;         acc[ai][bj][m][n] = __builtin_amdgcn_mfma_f32_16x16x32_bf16(Bt[n][k], At[m][k], acc[ai][bj][m][n], 0, 0, 0); __builtin_amdgcn_s_setprio(0); } while (0)
; #define PG8_WAIT_V(n) asm volatile("s_waitcnt vmcnt(" #n ")" ::: "memory")
; #define PG8_WAIT_L(n) asm volatile("s_waitcnt lgkmcnt(" #n ")" ::: "memory")
; #define PG8_BAR __builtin_amdgcn_s_barrier()
; #define PG8_SCHED __builtin_amdgcn_sched_barrier(0)
; template <class Epi, class Sched, bool ALIGN_EPI = false, bool SP2 = false>
; __device__ __forceinline__ void gemm_phase(PG8_LAS unsigned char* lds, const Gemm g, const Sched& S, const Epi& E) {
;     ...
;             PG8_WAIT_V(8); PG8_WAIT_L(0); PG8_BAR; PG8_MMA(1, 0, At, B0); PG8_MMA(1, 1, At, B1); PG8_BAR; PG8_SCHED;
;             PG8_LDB(B0, 1, 0); PG8_LDB(B1, 1, 1); PG8_SCHED; PG8_LDA(At, 1, 0); PG8_STAGE(PG8_SA(0, 1), a2 + hstep, voffA);
;             PG8_WAIT_V(8); PG8_WAIT_L(0); PG8_BAR; PG8_MMA(0, 0, At, B0); PG8_MMA(0, 1, At, B1); PG8_BAR; PG8_SCHED;
	s_setprio 1
	s_waitcnt lgkmcnt(0)
	v_mfma_f32_16x16x32_bf16 v[102:105], v[150:153], v[182:185], v[102:105]
	v_mfma_f32_16x16x32_bf16 v[98:101], v[158:161], v[182:185], v[98:101]
	v_mfma_f32_16x16x32_bf16 v[82:85], v[150:153], v[192:195], v[82:85]
	v_mfma_f32_16x16x32_bf16 v[78:81], v[158:161], v[192:195], v[78:81]
	v_mfma_f32_16x16x32_bf16 v[38:41], v[150:153], v[200:203], v[38:41]
	v_mfma_f32_16x16x32_bf16 v[34:37], v[158:161], v[200:203], v[34:37]
	v_mfma_f32_16x16x32_bf16 v[18:21], v[150:153], v[208:211], v[18:21]
	v_mfma_f32_16x16x32_bf16 v[10:13], v[158:161], v[208:211], v[10:13]
	v_mfma_f32_16x16x32_bf16 v[102:105], v[154:157], v[188:191], v[102:105]
	v_mfma_f32_16x16x32_bf16 v[98:101], v[162:165], v[188:191], v[98:101]
	v_mfma_f32_16x16x32_bf16 v[82:85], v[154:157], v[196:199], v[82:85]
	v_mfma_f32_16x16x32_bf16 v[78:81], v[162:165], v[196:199], v[78:81]
	v_mfma_f32_16x16x32_bf16 v[38:41], v[154:157], v[204:207], v[38:41]
	v_mfma_f32_16x16x32_bf16 v[34:37], v[162:165], v[204:207], v[34:37]
	v_mfma_f32_16x16x32_bf16 v[18:21], v[154:157], v[212:215], v[18:21]
	v_mfma_f32_16x16x32_bf16 v[10:13], v[162:165], v[212:215], v[10:13]
	s_setprio 0
	s_setprio 1
	v_mfma_f32_16x16x32_bf16 v[90:93], v[166:169], v[182:185], v[90:93]
	v_mfma_f32_16x16x32_bf16 v[66:69], v[174:177], v[182:185], v[66:69]
	v_mfma_f32_16x16x32_bf16 v[62:65], v[166:169], v[192:195], v[62:65]
	v_mfma_f32_16x16x32_bf16 v[58:61], v[174:177], v[192:195], v[58:61]
	v_mfma_f32_16x16x32_bf16 v[26:29], v[166:169], v[200:203], v[26:29]
	v_mfma_f32_16x16x32_bf16 v[22:25], v[174:177], v[200:203], v[22:25]
	v_mfma_f32_16x16x32_bf16 v[6:9], v[166:169], v[208:211], v[6:9]
	v_mfma_f32_16x16x32_bf16 v[2:5], v[174:177], v[208:211], v[2:5]
	v_mfma_f32_16x16x32_bf16 v[90:93], v[170:173], v[188:191], v[90:93]
	v_mfma_f32_16x16x32_bf16 v[66:69], v[178:181], v[188:191], v[66:69]
	v_mfma_f32_16x16x32_bf16 v[62:65], v[170:173], v[196:199], v[62:65]
	v_mfma_f32_16x16x32_bf16 v[58:61], v[178:181], v[196:199], v[58:61]
	v_mfma_f32_16x16x32_bf16 v[26:29], v[170:173], v[204:207], v[26:29]
	v_mfma_f32_16x16x32_bf16 v[22:25], v[178:181], v[204:207], v[22:25]
	v_mfma_f32_16x16x32_bf16 v[6:9], v[170:173], v[212:215], v[6:9]
	v_mfma_f32_16x16x32_bf16 v[2:5], v[178:181], v[212:215], v[2:5]
	s_setprio 0
	s_barrier
	s_add_i32 s65, 0, 0x18000
	s_add_i32 s66, 0, 0x1c000
	v_add_u32_e32 v162, s65, v148
	v_add_u32_e32 v178, s66, v148
	ds_read_b128 v[150:153], v162
	ds_read_b128 v[154:157], v162 offset:1024
	ds_read_b128 v[158:161], v162 offset:2048
	ds_read_b128 v[162:165], v162 offset:3072
	ds_read_b128 v[166:169], v178
	ds_read_b128 v[170:173], v178 offset:1024
	ds_read_b128 v[174:177], v178 offset:2048
	ds_read_b128 v[178:181], v178 offset:3072
	s_add_u32 s36, s36, 0x40000
	s_addc_u32 s37, s37, 0
	s_mov_b32 m0, s50
	v_lshl_add_u64 v[224:225], s[36:37], 0, v[130:131]
	ds_read_b128 v[182:185], v149 offset:32768
	ds_read_b128 v[188:191], v149 offset:33792
	ds_read_b128 v[192:195], v149 offset:34816
	ds_read_b128 v[196:199], v149 offset:35840
	ds_read_b128 v[200:203], v149 offset:36864
	ds_read_b128 v[204:207], v149 offset:37888
	ds_read_b128 v[208:211], v149 offset:38912
	ds_read_b128 v[212:215], v149 offset:39936
	global_load_lds_dwordx4 v[224:225], off
	v_lshl_add_u64 v[224:225], s[36:37], 0, v[132:133]
	s_mov_b32 m0, s51
	s_nop 0
	global_load_lds_dwordx4 v[224:225], off
	s_waitcnt vmcnt(8)
	s_waitcnt lgkmcnt(0)
	s_barrier
	s_setprio 1
	s_waitcnt lgkmcnt(0)
	v_mfma_f32_16x16x32_bf16 v[110:113], v[150:153], v[182:185], v[110:113]
	v_mfma_f32_16x16x32_bf16 v[74:77], v[158:161], v[182:185], v[74:77]
	v_mfma_f32_16x16x32_bf16 v[118:121], v[150:153], v[192:195], v[118:121]
	v_mfma_f32_16x16x32_bf16 v[94:97], v[158:161], v[192:195], v[94:97]
	v_mfma_f32_16x16x32_bf16 v[126:129], v[150:153], v[200:203], v[126:129]
	v_mfma_f32_16x16x32_bf16 v[106:109], v[158:161], v[200:203], v[106:109]
	v_mfma_f32_16x16x32_bf16 v[122:125], v[150:153], v[208:211], v[122:125]
	v_mfma_f32_16x16x32_bf16 v[114:117], v[158:161], v[208:211], v[114:117]
	v_mfma_f32_16x16x32_bf16 v[110:113], v[154:157], v[188:191], v[110:113]
	v_mfma_f32_16x16x32_bf16 v[74:77], v[162:165], v[188:191], v[74:77]
	v_mfma_f32_16x16x32_bf16 v[118:121], v[154:157], v[196:199], v[118:121]
	v_mfma_f32_16x16x32_bf16 v[94:97], v[162:165], v[196:199], v[94:97]
	v_mfma_f32_16x16x32_bf16 v[126:129], v[154:157], v[204:207], v[126:129]
	v_mfma_f32_16x16x32_bf16 v[106:109], v[162:165], v[204:207], v[106:109]
	v_mfma_f32_16x16x32_bf16 v[122:125], v[154:157], v[212:215], v[122:125]
	v_mfma_f32_16x16x32_bf16 v[114:117], v[162:165], v[212:215], v[114:117]
	s_setprio 0
	s_setprio 1
	v_mfma_f32_16x16x32_bf16 v[46:49], v[166:169], v[182:185], v[46:49]
	v_mfma_f32_16x16x32_bf16 v[14:17], v[174:177], v[182:185], v[14:17]
	v_mfma_f32_16x16x32_bf16 v[54:57], v[166:169], v[192:195], v[54:57]
	v_mfma_f32_16x16x32_bf16 v[30:33], v[174:177], v[192:195], v[30:33]
	v_mfma_f32_16x16x32_bf16 v[70:73], v[166:169], v[200:203], v[70:73]
	v_mfma_f32_16x16x32_bf16 v[42:45], v[174:177], v[200:203], v[42:45]
	v_mfma_f32_16x16x32_bf16 v[86:89], v[166:169], v[208:211], v[86:89]
	v_mfma_f32_16x16x32_bf16 v[50:53], v[174:177], v[208:211], v[50:53]
	v_mfma_f32_16x16x32_bf16 v[46:49], v[170:173], v[188:191], v[46:49]
	v_mfma_f32_16x16x32_bf16 v[14:17], v[178:181], v[188:191], v[14:17]
	v_mfma_f32_16x16x32_bf16 v[54:57], v[170:173], v[196:199], v[54:57]
	v_mfma_f32_16x16x32_bf16 v[30:33], v[178:181], v[196:199], v[30:33]
	v_mfma_f32_16x16x32_bf16 v[70:73], v[170:173], v[204:207], v[70:73]
	v_mfma_f32_16x16x32_bf16 v[42:45], v[178:181], v[204:207], v[42:45]
	v_mfma_f32_16x16x32_bf16 v[86:89], v[170:173], v[212:215], v[86:89]
	v_mfma_f32_16x16x32_bf16 v[50:53], v[178:181], v[212:215], v[50:53]
	s_setprio 0
	s_barrier
; #define PG8_STAGE(bufoff, gbase, voff) do { _Pragma("unroll") for (int _i = 0; _i < 2; ++_i) \
;         __builtin_amdgcn_global_load_lds((const unsigned*)((const char*)(gbase) + (voff)[_i]), (PG8_LAS unsigned*)(lds + (bufoff) + ldsw + _i * 8192), 16, 0, 0); } while (0)
; #define PG8_LDA(dst, b, h) do { _Pragma("unroll") for (int m = 0; m < 4; ++m) _Pragma("unroll") for (int k = 0; k < 2; ++k) dst[m][k] = *(const PG8_LAS bf16x8*)(lds + PG8_SA(b, h) + aoff + m * 2048 + k * 1024); } while (0)
; #define PG8_MMA(ai, bj, At, Bt) do { __builtin_amdgcn_s_setprio(1); _Pragma("unroll") for (int m = 0; m < 4; ++m) _Pragma("unroll") for (int n = 0; n < 2; ++n) _Pragma("unroll") for (int k = 0; k < 2; ++k) \
;         acc[ai][bj][m][n] = __builtin_amdgcn_mfma_f32_16x16x32_bf16(Bt[n][k], At[m][k], acc[ai][bj][m][n], 0, 0, 0); __builtin_amdgcn_s_setprio(0); } while (0)
; #define PG8_WAIT_V(n) asm volatile("s_waitcnt vmcnt(" #n ")" ::: "memory")
; #define PG8_WAIT_L(n) asm volatile("s_waitcnt lgkmcnt(" #n ")" ::: "memory")
; #define PG8_BAR __builtin_amdgcn_s_barrier()
; #define PG8_SCHED __builtin_amdgcn_sched_barrier(0)
; template <class Epi, class Sched, bool ALIGN_EPI = false, bool SP2 = false>
; __device__ __forceinline__ void gemm_phase(PG8_LAS unsigned char* lds, const Gemm g, const Sched& S, const Epi& E) {
;     ...
;             PG8_LDA(At, 1, 1); PG8_STAGE(PG8_SB(1, 0), b3, voffB); PG8_STAGE(PG8_SB(1, 1), b3 + hstep, voffB); PG8_STAGE(PG8_SA(1, 0), a3, voffA);
;             PG8_WAIT_V(8); PG8_WAIT_L(0); PG8_BAR; PG8_MMA(1, 0, At, B0); PG8_MMA(1, 1, At, B1); PG8_BAR; PG8_SCHED;
;     ...
;         if (!has_next) break;
; #pragma unroll
;         for (int a = 0; a < 2; ++a)
; #pragma unroll
;             for (int b = 0; b < 2; ++b)
; #pragma unroll
;                 for (int m = 0; m < 4; ++m)
; #pragma unroll
;                     for (int n = 0; n < 2; ++n) acc[a][b][m][n] = (f32x4){0.f, 0.f, 0.f, 0.f};
;         cur = nxt; cA = nA; cB = nB; ++ui;
	s_add_i32 s36, s65, s43
	v_lshl_add_u64 v[216:217], v[216:217], 0, s[20:21]
	s_mov_b32 m0, s36
	ds_read_b128 v[182:185], v149 offset:49152
	ds_read_b128 v[188:191], v149 offset:50176
	ds_read_b128 v[192:195], v149 offset:51200
	ds_read_b128 v[196:199], v149 offset:52224
	ds_read_b128 v[200:203], v149 offset:53248
	ds_read_b128 v[204:207], v149 offset:54272
	ds_read_b128 v[208:211], v149 offset:55296
	ds_read_b128 v[212:215], v149 offset:56320
	global_load_lds_dwordx4 v[216:217], off
	s_add_i32 m0, s36, 0x2000
	s_add_u32 s34, s34, 0x40080
	v_lshl_add_u64 v[216:217], v[218:219], 0, s[20:21]
	s_addc_u32 s35, s35, 0
	s_add_i32 s36, s66, s43
	global_load_lds_dwordx4 v[216:217], off
	v_lshl_add_u64 v[216:217], s[34:35], 0, v[130:131]
	s_mov_b32 m0, s36
	s_nop 0
	global_load_lds_dwordx4 v[216:217], off
	v_lshl_add_u64 v[216:217], s[34:35], 0, v[132:133]
	s_add_i32 m0, s36, 0x2000
	s_nop 0
	global_load_lds_dwordx4 v[216:217], off
	v_lshl_add_u64 v[216:217], v[220:221], 0, s[20:21]
	s_mov_b32 m0, s54
	s_nop 0
	global_load_lds_dwordx4 v[216:217], off
	v_lshl_add_u64 v[216:217], v[222:223], 0, s[20:21]
	s_mov_b32 m0, s55
	s_nop 0
	global_load_lds_dwordx4 v[216:217], off
	s_waitcnt vmcnt(8)
	s_waitcnt lgkmcnt(0)
	s_barrier
	s_setprio 1
	s_waitcnt lgkmcnt(0)
	v_mfma_f32_16x16x32_bf16 v[102:105], v[150:153], v[182:185], v[102:105]
	v_mfma_f32_16x16x32_bf16 v[98:101], v[158:161], v[182:185], v[98:101]
	v_mfma_f32_16x16x32_bf16 v[82:85], v[150:153], v[192:195], v[82:85]
	v_mfma_f32_16x16x32_bf16 v[78:81], v[158:161], v[192:195], v[78:81]
	v_mfma_f32_16x16x32_bf16 v[38:41], v[150:153], v[200:203], v[38:41]
	v_mfma_f32_16x16x32_bf16 v[34:37], v[158:161], v[200:203], v[34:37]
	v_mfma_f32_16x16x32_bf16 v[18:21], v[150:153], v[208:211], v[18:21]
	v_mfma_f32_16x16x32_bf16 v[10:13], v[158:161], v[208:211], v[10:13]
	v_mfma_f32_16x16x32_bf16 v[102:105], v[154:157], v[188:191], v[102:105]
	v_mfma_f32_16x16x32_bf16 v[98:101], v[162:165], v[188:191], v[98:101]
	v_mfma_f32_16x16x32_bf16 v[82:85], v[154:157], v[196:199], v[82:85]
	v_mfma_f32_16x16x32_bf16 v[78:81], v[162:165], v[196:199], v[78:81]
	v_mfma_f32_16x16x32_bf16 v[38:41], v[154:157], v[204:207], v[38:41]
	v_mfma_f32_16x16x32_bf16 v[34:37], v[162:165], v[204:207], v[34:37]
	v_mfma_f32_16x16x32_bf16 v[18:21], v[154:157], v[212:215], v[18:21]
	v_mfma_f32_16x16x32_bf16 v[10:13], v[162:165], v[212:215], v[10:13]
	s_setprio 0
	s_setprio 1
	v_mfma_f32_16x16x32_bf16 v[90:93], v[166:169], v[182:185], v[90:93]
	v_mfma_f32_16x16x32_bf16 v[66:69], v[174:177], v[182:185], v[66:69]
	v_mfma_f32_16x16x32_bf16 v[62:65], v[166:169], v[192:195], v[62:65]
	v_mfma_f32_16x16x32_bf16 v[58:61], v[174:177], v[192:195], v[58:61]
	v_mfma_f32_16x16x32_bf16 v[26:29], v[166:169], v[200:203], v[26:29]
	v_mfma_f32_16x16x32_bf16 v[22:25], v[174:177], v[200:203], v[22:25]
	v_mfma_f32_16x16x32_bf16 v[6:9], v[166:169], v[208:211], v[6:9]
	v_mfma_f32_16x16x32_bf16 v[2:5], v[174:177], v[208:211], v[2:5]
	v_mfma_f32_16x16x32_bf16 v[90:93], v[170:173], v[188:191], v[90:93]
	v_mfma_f32_16x16x32_bf16 v[66:69], v[178:181], v[188:191], v[66:69]
	v_mfma_f32_16x16x32_bf16 v[62:65], v[170:173], v[196:199], v[62:65]
	v_mfma_f32_16x16x32_bf16 v[58:61], v[178:181], v[196:199], v[58:61]
	v_mfma_f32_16x16x32_bf16 v[26:29], v[170:173], v[204:207], v[26:29]
	v_mfma_f32_16x16x32_bf16 v[22:25], v[178:181], v[204:207], v[22:25]
	v_mfma_f32_16x16x32_bf16 v[6:9], v[170:173], v[212:215], v[6:9]
	v_mfma_f32_16x16x32_bf16 v[2:5], v[178:181], v[212:215], v[2:5]
	s_setprio 0
	s_add_i32 s63, s63, 2
	s_add_u32 s30, s30, 0x100
	s_addc_u32 s31, s31, 0
	s_cmp_gt_u32 s63, 13
	s_barrier
	s_cbranch_scc0 .LBB0_1523
	s_add_u32 s30, s59, 0xffffff00
	s_addc_u32 s31, s60, -1
	s_andn2_b64 vcc, exec, s[6:7]
	s_cbranch_vccnz .LBB0_1526
	v_mov_b32_e32 v2, 0
	s_mov_b32 s8, s22
	s_mov_b32 s16, s24
	s_mov_b64 s[18:19], s[28:29]
	s_mov_b32 s53, s58
	v_mov_b32_e32 v3, v2
	v_mov_b32_e32 v4, v2
	v_mov_b32_e32 v5, v2
	v_mov_b32_e32 v6, v2
	v_mov_b32_e32 v7, v2
	v_mov_b32_e32 v8, v2
	v_mov_b32_e32 v9, v2
	v_mov_b32_e32 v22, v2
	v_mov_b32_e32 v23, v2
	v_mov_b32_e32 v24, v2
	v_mov_b32_e32 v25, v2
	v_mov_b32_e32 v26, v2
	v_mov_b32_e32 v27, v2
	v_mov_b32_e32 v28, v2
	v_mov_b32_e32 v29, v2
	v_mov_b32_e32 v58, v2
	v_mov_b32_e32 v59, v2
	v_mov_b32_e32 v60, v2
	v_mov_b32_e32 v61, v2
	v_mov_b32_e32 v62, v2
	v_mov_b32_e32 v63, v2
	v_mov_b32_e32 v64, v2
	v_mov_b32_e32 v65, v2
	v_mov_b32_e32 v66, v2
	v_mov_b32_e32 v67, v2
	v_mov_b32_e32 v68, v2
	v_mov_b32_e32 v69, v2
	v_mov_b32_e32 v90, v2
	v_mov_b32_e32 v91, v2
	v_mov_b32_e32 v92, v2
	v_mov_b32_e32 v93, v2
	v_mov_b32_e32 v10, v2
	v_mov_b32_e32 v11, v2
	v_mov_b32_e32 v12, v2
	v_mov_b32_e32 v13, v2
	v_mov_b32_e32 v18, v2
	v_mov_b32_e32 v19, v2
	v_mov_b32_e32 v20, v2
	v_mov_b32_e32 v21, v2
	v_mov_b32_e32 v34, v2
	v_mov_b32_e32 v35, v2
	v_mov_b32_e32 v36, v2
	v_mov_b32_e32 v37, v2
	v_mov_b32_e32 v38, v2
	v_mov_b32_e32 v39, v2
	v_mov_b32_e32 v40, v2
	v_mov_b32_e32 v41, v2
	v_mov_b32_e32 v78, v2
	v_mov_b32_e32 v79, v2
	v_mov_b32_e32 v80, v2
	v_mov_b32_e32 v81, v2
	v_mov_b32_e32 v82, v2
	v_mov_b32_e32 v83, v2
	v_mov_b32_e32 v84, v2
	v_mov_b32_e32 v85, v2
	v_mov_b32_e32 v98, v2
	v_mov_b32_e32 v99, v2
	v_mov_b32_e32 v100, v2
	v_mov_b32_e32 v101, v2
	v_mov_b32_e32 v102, v2
	v_mov_b32_e32 v103, v2
	v_mov_b32_e32 v104, v2
	v_mov_b32_e32 v105, v2
	v_mov_b32_e32 v50, v2
	v_mov_b32_e32 v51, v2
	v_mov_b32_e32 v52, v2
	v_mov_b32_e32 v53, v2
	v_mov_b32_e32 v86, v2
	v_mov_b32_e32 v87, v2
	v_mov_b32_e32 v88, v2
	v_mov_b32_e32 v89, v2
	v_mov_b32_e32 v42, v2
	v_mov_b32_e32 v43, v2
	v_mov_b32_e32 v44, v2
	v_mov_b32_e32 v45, v2
	v_mov_b32_e32 v70, v2
	v_mov_b32_e32 v71, v2
	v_mov_b32_e32 v72, v2
	v_mov_b32_e32 v73, v2
	v_mov_b32_e32 v30, v2
	v_mov_b32_e32 v31, v2
	v_mov_b32_e32 v32, v2
	v_mov_b32_e32 v33, v2
	v_mov_b32_e32 v54, v2
	v_mov_b32_e32 v55, v2
	v_mov_b32_e32 v56, v2
	v_mov_b32_e32 v57, v2
	v_mov_b32_e32 v14, v2
	v_mov_b32_e32 v15, v2
	v_mov_b32_e32 v16, v2
	v_mov_b32_e32 v17, v2
	v_mov_b32_e32 v46, v2
	v_mov_b32_e32 v47, v2
	v_mov_b32_e32 v48, v2
	v_mov_b32_e32 v49, v2
	v_mov_b32_e32 v114, v2
	v_mov_b32_e32 v115, v2
	v_mov_b32_e32 v116, v2
	v_mov_b32_e32 v117, v2
	v_mov_b32_e32 v122, v2
	v_mov_b32_e32 v123, v2
	v_mov_b32_e32 v124, v2
	v_mov_b32_e32 v125, v2
	v_mov_b32_e32 v106, v2
	v_mov_b32_e32 v107, v2
	v_mov_b32_e32 v108, v2
	v_mov_b32_e32 v109, v2
	v_mov_b32_e32 v126, v2
	v_mov_b32_e32 v127, v2
	v_mov_b32_e32 v128, v2
	v_mov_b32_e32 v129, v2
	v_mov_b32_e32 v94, v2
	v_mov_b32_e32 v95, v2
	v_mov_b32_e32 v96, v2
	v_mov_b32_e32 v97, v2
	v_mov_b32_e32 v118, v2
	v_mov_b32_e32 v119, v2
	v_mov_b32_e32 v120, v2
	v_mov_b32_e32 v121, v2
	v_mov_b32_e32 v74, v2
	v_mov_b32_e32 v75, v2
	v_mov_b32_e32 v76, v2
	v_mov_b32_e32 v77, v2
	v_mov_b32_e32 v110, v2
	v_mov_b32_e32 v111, v2
	v_mov_b32_e32 v112, v2
	v_mov_b32_e32 v113, v2
	s_andn2_b64 vcc, exec, s[4:5]
	s_cbranch_vccnz .LBB0_1527
	s_branch .LBB0_1528

; #define PG8_STAGE(bufoff, gbase, voff) do { _Pragma("unroll") for (int _i = 0; _i < 2; ++_i) \
;         __builtin_amdgcn_global_load_lds((const unsigned*)((const char*)(gbase) + (voff)[_i]), (PG8_LAS unsigned*)(lds + (bufoff) + ldsw + _i * 8192), 16, 0, 0); } while (0)
; #define PG8_LDA(dst, b, h) do { _Pragma("unroll") for (int m = 0; m < 4; ++m) _Pragma("unroll") for (int k = 0; k < 2; ++k) dst[m][k] = *(const PG8_LAS bf16x8*)(lds + PG8_SA(b, h) + aoff + m * 2048 + k * 1024); } while (0)
; #define PG8_LDB(dst, b, h) do { _Pragma("unroll") for (int n = 0; n < 2; ++n) _Pragma("unroll") for (int k = 0; k < 2; ++k) dst[n][k] = *(const PG8_LAS bf16x8*)(lds + PG8_SB(b, h) + boff + n * 2048 + k * 1024); } while (0)
; #define PG8_MMA(ai, bj, At, Bt) do { __builtin_amdgcn_s_setprio(1); _Pragma("unroll") for (int m = 0; m < 4; ++m) _Pragma("unroll") for (int n = 0; n < 2; ++n) _Pragma("unroll") for (int k = 0; k < 2; ++k) \
;         acc[ai][bj][m][n] = __builtin_amdgcn_mfma_f32_16x16x32_bf16(Bt[n][k], At[m][k], acc[ai][bj][m][n], 0, 0, 0); __builtin_amdgcn_s_setprio(0); } while (0)
; #define PG8_WAIT_V(n) asm volatile("s_waitcnt vmcnt(" #n ")" ::: "memory")
; #define PG8_WAIT_L(n) asm volatile("s_waitcnt lgkmcnt(" #n ")" ::: "memory")
; template <class Epi, class Sched, bool ALIGN_EPI = false, bool SP2 = false>
; __device__ __forceinline__ void gemm_phase(PG8_LAS unsigned char* lds, const Gemm g, const Sched& S, const Epi& E) {
;     ...
;             const bool last = (t == nt - 2);
;             const char* a1 = cA + (size_t)(t + 1) * kstep;
;             const char* a2 = last ? nA : cA + (size_t)(t + 2) * kstep; const char* b2 = last ? nB : cB + (size_t)(t + 2) * kstep;
;             const char* a3 = a2 + kstep; const char* b3 = b2 + kstep;
;             if (last && has_next) S.a_ready(nxt);
;             if constexpr (SP2) {
;             PG8_LDB(B0, 0, 0); PG8_LDB(B1, 0, 1); PG8_SCHED; PG8_LDA(At, 0, 0); PG8_STAGE(PG8_SA(1, 1), a1 + hstep, voffA);
;             PG8_WAIT_V(8); PG8_WAIT_L(0); PG8_BAR; PG8_MMA(0, 0, At, B0); PG8_MMA(0, 1, At, B1); PG8_BAR; PG8_SCHED;
;             PG8_LDA(At, 0, 1); PG8_STAGE(PG8_SB(0, 0), b2, voffB); PG8_STAGE(PG8_SB(0, 1), b2 + hstep, voffB); PG8_STAGE(PG8_SA(0, 0), a2, voffA);
;             PG8_WAIT_V(8); PG8_WAIT_L(0); PG8_BAR; PG8_MMA(1, 0, At, B0); PG8_MMA(1, 1, At, B1); PG8_BAR; PG8_SCHED;
.LBB0_1733:
	ds_read_b128 v[144:147], v140
	ds_read_b128 v[148:151], v140 offset:1024
	ds_read_b128 v[152:155], v140 offset:2048
	ds_read_b128 v[156:159], v140 offset:3072
	ds_read_b128 v[160:163], v141
	ds_read_b128 v[164:167], v141 offset:1024
	ds_read_b128 v[168:171], v141 offset:2048
	ds_read_b128 v[172:175], v141 offset:3072
	s_add_i32 s66, s36, 2
	s_add_u32 s34, s30, 0x100
	s_addc_u32 s35, s31, 0
	s_cmp_eq_u32 s50, s36
	s_cselect_b32 s36, s28, s63
	s_cselect_b32 s39, s27, s35
	s_cselect_b32 s38, s26, s34
	s_cselect_b32 s37, s29, s65
	s_mov_b32 m0, s58
	v_lshl_add_u64 v[184:185], s[30:31], 0, v[134:135]
	ds_read_b128 v[176:179], v142
	ds_read_b128 v[180:183], v142 offset:1024
	ds_read_b128 v[188:191], v142 offset:2048
	ds_read_b128 v[192:195], v142 offset:3072
	ds_read_b128 v[196:199], v142 offset:4096
	ds_read_b128 v[200:203], v142 offset:5120
	ds_read_b128 v[204:207], v142 offset:6144
	ds_read_b128 v[208:211], v142 offset:7168
	global_load_lds_dwordx4 v[184:185], off
	v_lshl_add_u64 v[184:185], s[30:31], 0, v[136:137]
	s_add_i32 m0, s1, 0xe000
	s_nop 0
	global_load_lds_dwordx4 v[184:185], off
	s_waitcnt vmcnt(8)
	s_waitcnt lgkmcnt(0)
	s_barrier
	s_setprio 1
	s_waitcnt lgkmcnt(0)
	v_mfma_f32_16x16x32_bf16 v[126:129], v[144:147], v[176:179], v[126:129]
	v_mfma_f32_16x16x32_bf16 v[122:125], v[152:155], v[176:179], v[122:125]
	v_mfma_f32_16x16x32_bf16 v[110:113], v[144:147], v[188:191], v[110:113]
	v_mfma_f32_16x16x32_bf16 v[106:109], v[152:155], v[188:191], v[106:109]
	v_mfma_f32_16x16x32_bf16 v[94:97], v[144:147], v[196:199], v[94:97]
	v_mfma_f32_16x16x32_bf16 v[90:93], v[152:155], v[196:199], v[90:93]
	v_mfma_f32_16x16x32_bf16 v[78:81], v[144:147], v[204:207], v[78:81]
	v_mfma_f32_16x16x32_bf16 v[74:77], v[152:155], v[204:207], v[74:77]
	v_mfma_f32_16x16x32_bf16 v[126:129], v[148:151], v[180:183], v[126:129]
	v_mfma_f32_16x16x32_bf16 v[122:125], v[156:159], v[180:183], v[122:125]
	v_mfma_f32_16x16x32_bf16 v[110:113], v[148:151], v[192:195], v[110:113]
	v_mfma_f32_16x16x32_bf16 v[106:109], v[156:159], v[192:195], v[106:109]
	v_mfma_f32_16x16x32_bf16 v[94:97], v[148:151], v[200:203], v[94:97]
	v_mfma_f32_16x16x32_bf16 v[90:93], v[156:159], v[200:203], v[90:93]
	v_mfma_f32_16x16x32_bf16 v[78:81], v[148:151], v[208:211], v[78:81]
	v_mfma_f32_16x16x32_bf16 v[74:77], v[156:159], v[208:211], v[74:77]
	s_setprio 0
	s_setprio 1
	v_mfma_f32_16x16x32_bf16 v[118:121], v[160:163], v[176:179], v[118:121]
	v_mfma_f32_16x16x32_bf16 v[114:117], v[168:171], v[176:179], v[114:117]
	v_mfma_f32_16x16x32_bf16 v[102:105], v[160:163], v[188:191], v[102:105]
	v_mfma_f32_16x16x32_bf16 v[98:101], v[168:171], v[188:191], v[98:101]
	v_mfma_f32_16x16x32_bf16 v[86:89], v[160:163], v[196:199], v[86:89]
	v_mfma_f32_16x16x32_bf16 v[82:85], v[168:171], v[196:199], v[82:85]
	v_mfma_f32_16x16x32_bf16 v[70:73], v[160:163], v[204:207], v[70:73]
	v_mfma_f32_16x16x32_bf16 v[66:69], v[168:171], v[204:207], v[66:69]
	v_mfma_f32_16x16x32_bf16 v[118:121], v[164:167], v[180:183], v[118:121]
	v_mfma_f32_16x16x32_bf16 v[114:117], v[172:175], v[180:183], v[114:117]
	v_mfma_f32_16x16x32_bf16 v[102:105], v[164:167], v[192:195], v[102:105]
	v_mfma_f32_16x16x32_bf16 v[98:101], v[172:175], v[192:195], v[98:101]
	v_mfma_f32_16x16x32_bf16 v[86:89], v[164:167], v[200:203], v[86:89]
	v_mfma_f32_16x16x32_bf16 v[82:85], v[172:175], v[200:203], v[82:85]
	v_mfma_f32_16x16x32_bf16 v[70:73], v[164:167], v[208:211], v[70:73]
	v_mfma_f32_16x16x32_bf16 v[66:69], v[172:175], v[208:211], v[66:69]
	s_setprio 0
	s_barrier
	s_add_i32 s30, s51, s0
	v_lshl_add_u64 v[184:185], s[36:37], 0, v[132:133]
	s_mov_b32 m0, s30
	ds_read_b128 v[176:179], v142 offset:16384
	ds_read_b128 v[180:183], v142 offset:17408
	ds_read_b128 v[188:191], v142 offset:18432
	ds_read_b128 v[192:195], v142 offset:19456
	ds_read_b128 v[196:199], v142 offset:20480
	ds_read_b128 v[200:203], v142 offset:21504
	ds_read_b128 v[204:207], v142 offset:22528
	ds_read_b128 v[208:211], v142 offset:23552
	global_load_lds_dwordx4 v[184:185], off
	s_add_i32 m0, s30, 0x2000
	s_add_u32 s30, s36, 0xb0000
	v_lshl_add_u64 v[212:213], s[36:37], 0, v[130:131]
	s_addc_u32 s31, s37, 0
	s_add_i32 s67, s52, s0
	global_load_lds_dwordx4 v[212:213], off
	v_lshl_add_u64 v[214:215], s[30:31], 0, v[132:133]
	s_mov_b32 m0, s67
	v_lshl_add_u64 v[216:217], s[38:39], 0, v[130:131]
	global_load_lds_dwordx4 v[214:215], off
	v_lshl_add_u64 v[214:215], s[30:31], 0, v[130:131]
	s_add_i32 m0, s67, 0x2000
	s_nop 0
	global_load_lds_dwordx4 v[214:215], off
	v_lshl_add_u64 v[214:215], s[38:39], 0, v[132:133]
	s_mov_b32 m0, s1
	s_nop 0
	global_load_lds_dwordx4 v[214:215], off
	s_mov_b32 m0, s40
	s_nop 0
	global_load_lds_dwordx4 v[216:217], off
	s_waitcnt vmcnt(8)
	s_waitcnt lgkmcnt(0)
	s_barrier
; #define PG8_STAGE(bufoff, gbase, voff) do { _Pragma("unroll") for (int _i = 0; _i < 2; ++_i) \
;         __builtin_amdgcn_global_load_lds((const unsigned*)((const char*)(gbase) + (voff)[_i]), (PG8_LAS unsigned*)(lds + (bufoff) + ldsw + _i * 8192), 16, 0, 0); } while (0)
; #define PG8_LDA(dst, b, h) do { _Pragma("unroll") for (int m = 0; m < 4; ++m) _Pragma("unroll") for (int k = 0; k < 2; ++k) dst[m][k] = *(const PG8_LAS bf16x8*)(lds + PG8_SA(b, h) + aoff + m * 2048 + k * 1024); } while (0)
; #define PG8_LDB(dst, b, h) do { _Pragma("unroll") for (int n = 0; n < 2; ++n) _Pragma("unroll") for (int k = 0; k < 2; ++k) dst[n][k] = *(const PG8_LAS bf16x8*)(lds + PG8_SB(b, h) + boff + n * 2048 + k * 1024); } while (0)
; #define PG8_MMA(ai, bj, At, Bt) do { __builtin_amdgcn_s_setprio(1); _Pragma("unroll") for (int m = 0; m < 4; ++m) _Pragma("unroll") for (int n = 0; n < 2; ++n) _Pragma("unroll") for (int k = 0; k < 2; ++k) \
;         acc[ai][bj][m][n] = __builtin_amdgcn_mfma_f32_16x16x32_bf16(Bt[n][k], At[m][k], acc[ai][bj][m][n], 0, 0, 0); __builtin_amdgcn_s_setprio(0); } while (0)
; #define PG8_WAIT_V(n) asm volatile("s_waitcnt vmcnt(" #n ")" ::: "memory")
; #define PG8_WAIT_L(n) asm volatile("s_waitcnt lgkmcnt(" #n ")" ::: "memory")
; #define PG8_BAR __builtin_amdgcn_s_barrier()
; #define PG8_SCHED __builtin_amdgcn_sched_barrier(0)
; template <class Epi, class Sched, bool ALIGN_EPI = false, bool SP2 = false>
; __device__ __forceinline__ void gemm_phase(PG8_LAS unsigned char* lds, const Gemm g, const Sched& S, const Epi& E) {
;     ...
;             PG8_WAIT_V(8); PG8_WAIT_L(0); PG8_BAR; PG8_MMA(1, 0, At, B0); PG8_MMA(1, 1, At, B1); PG8_BAR; PG8_SCHED;
;             PG8_LDB(B0, 1, 0); PG8_LDB(B1, 1, 1); PG8_SCHED; PG8_LDA(At, 1, 0); PG8_STAGE(PG8_SA(0, 1), a2 + hstep, voffA);
;             PG8_WAIT_V(8); PG8_WAIT_L(0); PG8_BAR; PG8_MMA(0, 0, At, B0); PG8_MMA(0, 1, At, B1); PG8_BAR; PG8_SCHED;
	s_setprio 1
	s_waitcnt lgkmcnt(0)
	v_mfma_f32_16x16x32_bf16 v[62:65], v[144:147], v[176:179], v[62:65]
	v_mfma_f32_16x16x32_bf16 v[58:61], v[152:155], v[176:179], v[58:61]
	v_mfma_f32_16x16x32_bf16 v[46:49], v[144:147], v[188:191], v[46:49]
	v_mfma_f32_16x16x32_bf16 v[42:45], v[152:155], v[188:191], v[42:45]
	v_mfma_f32_16x16x32_bf16 v[30:33], v[144:147], v[196:199], v[30:33]
	v_mfma_f32_16x16x32_bf16 v[26:29], v[152:155], v[196:199], v[26:29]
	v_mfma_f32_16x16x32_bf16 v[14:17], v[144:147], v[204:207], v[14:17]
	v_mfma_f32_16x16x32_bf16 v[10:13], v[152:155], v[204:207], v[10:13]
	v_mfma_f32_16x16x32_bf16 v[62:65], v[148:151], v[180:183], v[62:65]
	v_mfma_f32_16x16x32_bf16 v[58:61], v[156:159], v[180:183], v[58:61]
	v_mfma_f32_16x16x32_bf16 v[46:49], v[148:151], v[192:195], v[46:49]
	v_mfma_f32_16x16x32_bf16 v[42:45], v[156:159], v[192:195], v[42:45]
	v_mfma_f32_16x16x32_bf16 v[30:33], v[148:151], v[200:203], v[30:33]
	v_mfma_f32_16x16x32_bf16 v[26:29], v[156:159], v[200:203], v[26:29]
	v_mfma_f32_16x16x32_bf16 v[14:17], v[148:151], v[208:211], v[14:17]
	v_mfma_f32_16x16x32_bf16 v[10:13], v[156:159], v[208:211], v[10:13]
	s_setprio 0
	s_setprio 1
	v_mfma_f32_16x16x32_bf16 v[54:57], v[160:163], v[176:179], v[54:57]
	v_mfma_f32_16x16x32_bf16 v[50:53], v[168:171], v[176:179], v[50:53]
	v_mfma_f32_16x16x32_bf16 v[38:41], v[160:163], v[188:191], v[38:41]
	v_mfma_f32_16x16x32_bf16 v[34:37], v[168:171], v[188:191], v[34:37]
	v_mfma_f32_16x16x32_bf16 v[22:25], v[160:163], v[196:199], v[22:25]
	v_mfma_f32_16x16x32_bf16 v[18:21], v[168:171], v[196:199], v[18:21]
	v_mfma_f32_16x16x32_bf16 v[6:9], v[160:163], v[204:207], v[6:9]
	v_mfma_f32_16x16x32_bf16 v[2:5], v[168:171], v[204:207], v[2:5]
	v_mfma_f32_16x16x32_bf16 v[54:57], v[164:167], v[180:183], v[54:57]
	v_mfma_f32_16x16x32_bf16 v[50:53], v[172:175], v[180:183], v[50:53]
	v_mfma_f32_16x16x32_bf16 v[38:41], v[164:167], v[192:195], v[38:41]
	v_mfma_f32_16x16x32_bf16 v[34:37], v[172:175], v[192:195], v[34:37]
	v_mfma_f32_16x16x32_bf16 v[22:25], v[164:167], v[200:203], v[22:25]
	v_mfma_f32_16x16x32_bf16 v[18:21], v[172:175], v[200:203], v[18:21]
	v_mfma_f32_16x16x32_bf16 v[6:9], v[164:167], v[208:211], v[6:9]
	v_mfma_f32_16x16x32_bf16 v[2:5], v[172:175], v[208:211], v[2:5]
	s_setprio 0
	s_barrier
	s_add_i32 s67, 0, 0x18000
	v_add_u32_e32 v143, s67, v1
	s_add_i32 s68, 0, 0x1c000
	ds_read_b128 v[144:147], v143
	ds_read_b128 v[148:151], v143 offset:1024
	ds_read_b128 v[152:155], v143 offset:2048
	ds_read_b128 v[156:159], v143 offset:3072
	v_add_u32_e32 v143, s68, v1
	ds_read_b128 v[160:163], v143
	ds_read_b128 v[164:167], v143 offset:1024
	ds_read_b128 v[168:171], v143 offset:2048
	ds_read_b128 v[172:175], v143 offset:3072
	s_add_u32 s30, s38, 0xb0000
	s_addc_u32 s31, s39, 0
	s_mov_b32 m0, s41
	v_lshl_add_u64 v[218:219], s[30:31], 0, v[132:133]
	ds_read_b128 v[176:179], v142 offset:32768
	ds_read_b128 v[180:183], v142 offset:33792
	ds_read_b128 v[188:191], v142 offset:34816
	ds_read_b128 v[192:195], v142 offset:35840
	ds_read_b128 v[196:199], v142 offset:36864
	ds_read_b128 v[200:203], v142 offset:37888
	ds_read_b128 v[204:207], v142 offset:38912
	ds_read_b128 v[208:211], v142 offset:39936
	global_load_lds_dwordx4 v[218:219], off
	v_lshl_add_u64 v[218:219], s[30:31], 0, v[130:131]
	s_mov_b32 m0, s42
	s_nop 0
	global_load_lds_dwordx4 v[218:219], off
	s_waitcnt vmcnt(8)
	s_waitcnt lgkmcnt(0)
	s_barrier
	s_setprio 1
	s_waitcnt lgkmcnt(0)
	v_mfma_f32_16x16x32_bf16 v[126:129], v[144:147], v[176:179], v[126:129]
	v_mfma_f32_16x16x32_bf16 v[122:125], v[152:155], v[176:179], v[122:125]
	v_mfma_f32_16x16x32_bf16 v[110:113], v[144:147], v[188:191], v[110:113]
	v_mfma_f32_16x16x32_bf16 v[106:109], v[152:155], v[188:191], v[106:109]
	v_mfma_f32_16x16x32_bf16 v[94:97], v[144:147], v[196:199], v[94:97]
	v_mfma_f32_16x16x32_bf16 v[90:93], v[152:155], v[196:199], v[90:93]
	v_mfma_f32_16x16x32_bf16 v[78:81], v[144:147], v[204:207], v[78:81]
	v_mfma_f32_16x16x32_bf16 v[74:77], v[152:155], v[204:207], v[74:77]
	v_mfma_f32_16x16x32_bf16 v[126:129], v[148:151], v[180:183], v[126:129]
	v_mfma_f32_16x16x32_bf16 v[122:125], v[156:159], v[180:183], v[122:125]
	v_mfma_f32_16x16x32_bf16 v[110:113], v[148:151], v[192:195], v[110:113]
	v_mfma_f32_16x16x32_bf16 v[106:109], v[156:159], v[192:195], v[106:109]
	v_mfma_f32_16x16x32_bf16 v[94:97], v[148:151], v[200:203], v[94:97]
	v_mfma_f32_16x16x32_bf16 v[90:93], v[156:159], v[200:203], v[90:93]
	v_mfma_f32_16x16x32_bf16 v[78:81], v[148:151], v[208:211], v[78:81]
	v_mfma_f32_16x16x32_bf16 v[74:77], v[156:159], v[208:211], v[74:77]
	s_setprio 0
	s_setprio 1
	v_mfma_f32_16x16x32_bf16 v[118:121], v[160:163], v[176:179], v[118:121]
	v_mfma_f32_16x16x32_bf16 v[114:117], v[168:171], v[176:179], v[114:117]
	v_mfma_f32_16x16x32_bf16 v[102:105], v[160:163], v[188:191], v[102:105]
	v_mfma_f32_16x16x32_bf16 v[98:101], v[168:171], v[188:191], v[98:101]
	v_mfma_f32_16x16x32_bf16 v[86:89], v[160:163], v[196:199], v[86:89]
	v_mfma_f32_16x16x32_bf16 v[82:85], v[168:171], v[196:199], v[82:85]
	v_mfma_f32_16x16x32_bf16 v[70:73], v[160:163], v[204:207], v[70:73]
	v_mfma_f32_16x16x32_bf16 v[66:69], v[168:171], v[204:207], v[66:69]
	v_mfma_f32_16x16x32_bf16 v[118:121], v[164:167], v[180:183], v[118:121]
	v_mfma_f32_16x16x32_bf16 v[114:117], v[172:175], v[180:183], v[114:117]
	v_mfma_f32_16x16x32_bf16 v[102:105], v[164:167], v[192:195], v[102:105]
	v_mfma_f32_16x16x32_bf16 v[98:101], v[172:175], v[192:195], v[98:101]
	v_mfma_f32_16x16x32_bf16 v[86:89], v[164:167], v[200:203], v[86:89]
	v_mfma_f32_16x16x32_bf16 v[82:85], v[172:175], v[200:203], v[82:85]
	v_mfma_f32_16x16x32_bf16 v[70:73], v[164:167], v[208:211], v[70:73]
	v_mfma_f32_16x16x32_bf16 v[66:69], v[172:175], v[208:211], v[66:69]
	s_setprio 0
	s_barrier
; #define PG8_STAGE(bufoff, gbase, voff) do { _Pragma("unroll") for (int _i = 0; _i < 2; ++_i) \
;         __builtin_amdgcn_global_load_lds((const unsigned*)((const char*)(gbase) + (voff)[_i]), (PG8_LAS unsigned*)(lds + (bufoff) + ldsw + _i * 8192), 16, 0, 0); } while (0)
; #define PG8_LDA(dst, b, h) do { _Pragma("unroll") for (int m = 0; m < 4; ++m) _Pragma("unroll") for (int k = 0; k < 2; ++k) dst[m][k] = *(const PG8_LAS bf16x8*)(lds + PG8_SA(b, h) + aoff + m * 2048 + k * 1024); } while (0)
; #define PG8_MMA(ai, bj, At, Bt) do { __builtin_amdgcn_s_setprio(1); _Pragma("unroll") for (int m = 0; m < 4; ++m) _Pragma("unroll") for (int n = 0; n < 2; ++n) _Pragma("unroll") for (int k = 0; k < 2; ++k) \
;         acc[ai][bj][m][n] = __builtin_amdgcn_mfma_f32_16x16x32_bf16(Bt[n][k], At[m][k], acc[ai][bj][m][n], 0, 0, 0); __builtin_amdgcn_s_setprio(0); } while (0)
; #define PG8_WAIT_V(n) asm volatile("s_waitcnt vmcnt(" #n ")" ::: "memory")
; #define PG8_WAIT_L(n) asm volatile("s_waitcnt lgkmcnt(" #n ")" ::: "memory")
; #define PG8_BAR __builtin_amdgcn_s_barrier()
; #define PG8_SCHED __builtin_amdgcn_sched_barrier(0)
; template <class Epi, class Sched, bool ALIGN_EPI = false, bool SP2 = false>
; __device__ __forceinline__ void gemm_phase(PG8_LAS unsigned char* lds, const Gemm g, const Sched& S, const Epi& E) {
;     ...
;         for (int t = 0; t < nt; t += 2) {
;             const bool last = (t == nt - 2);
;             const char* a1 = cA + (size_t)(t + 1) * kstep;
;             const char* a2 = last ? nA : cA + (size_t)(t + 2) * kstep; const char* b2 = last ? nB : cB + (size_t)(t + 2) * kstep;
;             const char* a3 = a2 + kstep; const char* b3 = b2 + kstep;
;     ...
;             PG8_LDA(At, 1, 1); PG8_STAGE(PG8_SB(1, 0), b3, voffB); PG8_STAGE(PG8_SB(1, 1), b3 + hstep, voffB); PG8_STAGE(PG8_SA(1, 0), a3, voffA);
;             PG8_WAIT_V(8); PG8_WAIT_L(0); PG8_BAR; PG8_MMA(1, 0, At, B0); PG8_MMA(1, 1, At, B1); PG8_BAR; PG8_SCHED;
	s_add_i32 s30, s67, s0
	v_lshl_add_u64 v[184:185], v[184:185], 0, s[14:15]
	s_mov_b32 m0, s30
	ds_read_b128 v[176:179], v142 offset:49152
	ds_read_b128 v[180:183], v142 offset:50176
	ds_read_b128 v[188:191], v142 offset:51200
	ds_read_b128 v[192:195], v142 offset:52224
	ds_read_b128 v[196:199], v142 offset:53248
	ds_read_b128 v[200:203], v142 offset:54272
	ds_read_b128 v[204:207], v142 offset:55296
	ds_read_b128 v[208:211], v142 offset:56320
	global_load_lds_dwordx4 v[184:185], off
	s_add_i32 m0, s30, 0x2000
	s_add_u32 s30, s36, 0xb0080
	v_lshl_add_u64 v[184:185], v[212:213], 0, s[14:15]
	s_addc_u32 s31, s37, 0
	s_add_i32 s36, s68, s0
	global_load_lds_dwordx4 v[184:185], off
	v_lshl_add_u64 v[184:185], s[30:31], 0, v[132:133]
	s_mov_b32 m0, s36
	s_nop 0
	global_load_lds_dwordx4 v[184:185], off
	v_lshl_add_u64 v[184:185], s[30:31], 0, v[130:131]
	s_add_i32 m0, s36, 0x2000
	s_nop 0
	global_load_lds_dwordx4 v[184:185], off
	v_lshl_add_u64 v[184:185], v[214:215], 0, s[14:15]
	s_mov_b32 m0, s48
	s_nop 0
	global_load_lds_dwordx4 v[184:185], off
	v_lshl_add_u64 v[184:185], v[216:217], 0, s[14:15]
	s_mov_b32 m0, s49
	s_nop 0
	global_load_lds_dwordx4 v[184:185], off
	s_waitcnt vmcnt(8)
	s_waitcnt lgkmcnt(0)
	s_barrier
	s_setprio 1
	s_waitcnt lgkmcnt(0)
	v_mfma_f32_16x16x32_bf16 v[62:65], v[144:147], v[176:179], v[62:65]
	v_mfma_f32_16x16x32_bf16 v[58:61], v[152:155], v[176:179], v[58:61]
	v_mfma_f32_16x16x32_bf16 v[46:49], v[144:147], v[188:191], v[46:49]
	v_mfma_f32_16x16x32_bf16 v[42:45], v[152:155], v[188:191], v[42:45]
	v_mfma_f32_16x16x32_bf16 v[30:33], v[144:147], v[196:199], v[30:33]
	v_mfma_f32_16x16x32_bf16 v[26:29], v[152:155], v[196:199], v[26:29]
	v_mfma_f32_16x16x32_bf16 v[14:17], v[144:147], v[204:207], v[14:17]
	v_mfma_f32_16x16x32_bf16 v[10:13], v[152:155], v[204:207], v[10:13]
	v_mfma_f32_16x16x32_bf16 v[62:65], v[148:151], v[180:183], v[62:65]
	v_mfma_f32_16x16x32_bf16 v[58:61], v[156:159], v[180:183], v[58:61]
	v_mfma_f32_16x16x32_bf16 v[46:49], v[148:151], v[192:195], v[46:49]
	v_mfma_f32_16x16x32_bf16 v[42:45], v[156:159], v[192:195], v[42:45]
	v_mfma_f32_16x16x32_bf16 v[30:33], v[148:151], v[200:203], v[30:33]
	v_mfma_f32_16x16x32_bf16 v[26:29], v[156:159], v[200:203], v[26:29]
	v_mfma_f32_16x16x32_bf16 v[14:17], v[148:151], v[208:211], v[14:17]
	v_mfma_f32_16x16x32_bf16 v[10:13], v[156:159], v[208:211], v[10:13]
	s_setprio 0
	s_setprio 1
	v_mfma_f32_16x16x32_bf16 v[54:57], v[160:163], v[176:179], v[54:57]
	v_mfma_f32_16x16x32_bf16 v[50:53], v[168:171], v[176:179], v[50:53]
	v_mfma_f32_16x16x32_bf16 v[38:41], v[160:163], v[188:191], v[38:41]
	v_mfma_f32_16x16x32_bf16 v[34:37], v[168:171], v[188:191], v[34:37]
	v_mfma_f32_16x16x32_bf16 v[22:25], v[160:163], v[196:199], v[22:25]
	v_mfma_f32_16x16x32_bf16 v[18:21], v[168:171], v[196:199], v[18:21]
	v_mfma_f32_16x16x32_bf16 v[6:9], v[160:163], v[204:207], v[6:9]
	v_mfma_f32_16x16x32_bf16 v[2:5], v[168:171], v[204:207], v[2:5]
	v_mfma_f32_16x16x32_bf16 v[54:57], v[164:167], v[180:183], v[54:57]
	v_mfma_f32_16x16x32_bf16 v[50:53], v[172:175], v[180:183], v[50:53]
	v_mfma_f32_16x16x32_bf16 v[38:41], v[164:167], v[192:195], v[38:41]
	v_mfma_f32_16x16x32_bf16 v[34:37], v[172:175], v[192:195], v[34:37]
	v_mfma_f32_16x16x32_bf16 v[22:25], v[164:167], v[200:203], v[22:25]
	v_mfma_f32_16x16x32_bf16 v[18:21], v[172:175], v[200:203], v[18:21]
	v_mfma_f32_16x16x32_bf16 v[6:9], v[164:167], v[208:211], v[6:9]
	v_mfma_f32_16x16x32_bf16 v[2:5], v[172:175], v[208:211], v[2:5]
	s_setprio 0
	s_add_u32 s63, s63, 0x100
	s_addc_u32 s65, s65, 0
	s_cmp_ge_i32 s66, s47
	s_mov_b64 s[30:31], s[34:35]
	s_mov_b32 s36, s66
	s_barrier
	s_cbranch_scc0 .LBB0_1733

; #define PG8_STAGE(bufoff, gbase, voff) do { _Pragma("unroll") for (int _i = 0; _i < 2; ++_i) \
;         __builtin_amdgcn_global_load_lds((const unsigned*)((const char*)(gbase) + (voff)[_i]), (PG8_LAS unsigned*)(lds + (bufoff) + ldsw + _i * 8192), 16, 0, 0); } while (0)
; #define PG8_LDA(dst, b, h) do { _Pragma("unroll") for (int m = 0; m < 4; ++m) _Pragma("unroll") for (int k = 0; k < 2; ++k) dst[m][k] = *(const PG8_LAS bf16x8*)(lds + PG8_SA(b, h) + aoff + m * 2048 + k * 1024); } while (0)
; #define PG8_LDB(dst, b, h) do { _Pragma("unroll") for (int n = 0; n < 2; ++n) _Pragma("unroll") for (int k = 0; k < 2; ++k) dst[n][k] = *(const PG8_LAS bf16x8*)(lds + PG8_SB(b, h) + boff + n * 2048 + k * 1024); } while (0)
; #define PG8_MMA(ai, bj, At, Bt) do { __builtin_amdgcn_s_setprio(1); _Pragma("unroll") for (int m = 0; m < 4; ++m) _Pragma("unroll") for (int n = 0; n < 2; ++n) _Pragma("unroll") for (int k = 0; k < 2; ++k) \
;         acc[ai][bj][m][n] = __builtin_amdgcn_mfma_f32_16x16x32_bf16(Bt[n][k], At[m][k], acc[ai][bj][m][n], 0, 0, 0); __builtin_amdgcn_s_setprio(0); } while (0)
; #define PG8_WAIT_V(n) asm volatile("s_waitcnt vmcnt(" #n ")" ::: "memory")
; #define PG8_WAIT_L(n) asm volatile("s_waitcnt lgkmcnt(" #n ")" ::: "memory")
; template <class Epi, class Sched, bool ALIGN_EPI = false, bool SP2 = false>
; __device__ __forceinline__ void gemm_phase(PG8_LAS unsigned char* lds, const Gemm g, const Sched& S, const Epi& E) {
;     ...
;             const bool last = (t == nt - 2);
;             const char* a1 = cA + (size_t)(t + 1) * kstep;
;             const char* a2 = last ? nA : cA + (size_t)(t + 2) * kstep; const char* b2 = last ? nB : cB + (size_t)(t + 2) * kstep;
;             const char* a3 = a2 + kstep; const char* b3 = b2 + kstep;
;             if (last && has_next) S.a_ready(nxt);
;             if constexpr (SP2) {
;             PG8_LDB(B0, 0, 0); PG8_LDB(B1, 0, 1); PG8_SCHED; PG8_LDA(At, 0, 0); PG8_STAGE(PG8_SA(1, 1), a1 + hstep, voffA);
;             PG8_WAIT_V(8); PG8_WAIT_L(0); PG8_BAR; PG8_MMA(0, 0, At, B0); PG8_MMA(0, 1, At, B1); PG8_BAR; PG8_SCHED;
;             PG8_LDA(At, 0, 1); PG8_STAGE(PG8_SB(0, 0), b2, voffB); PG8_STAGE(PG8_SB(0, 1), b2 + hstep, voffB); PG8_STAGE(PG8_SA(0, 0), a2, voffA);
;             PG8_WAIT_V(8); PG8_WAIT_L(0); PG8_BAR; PG8_MMA(1, 0, At, B0); PG8_MMA(1, 1, At, B1); PG8_BAR; PG8_SCHED;
.LBB0_1778:
	v_add_u32_e32 v162, s51, v148
	v_add_u32_e32 v178, s52, v148
	s_add_u32 s30, s22, s28
	ds_read_b128 v[150:153], v162
	ds_read_b128 v[154:157], v162 offset:1024
	ds_read_b128 v[158:161], v162 offset:2048
	ds_read_b128 v[162:165], v162 offset:3072
	ds_read_b128 v[166:169], v178
	ds_read_b128 v[170:173], v178 offset:1024
	ds_read_b128 v[174:177], v178 offset:2048
	ds_read_b128 v[178:181], v178 offset:3072
	s_addc_u32 s31, s23, s29
	s_add_u32 s30, s30, 0x100
	s_addc_u32 s31, s31, 0
	s_add_u32 s60, s57, s28
	s_addc_u32 s61, s58, s29
	s_cmpk_eq_i32 s28, 0x1500
	s_cselect_b32 s35, s27, s31
	s_cselect_b32 s34, s26, s30
	s_cselect_b32 s31, s9, s61
	s_cselect_b32 s30, s8, s60
	v_lshl_add_u64 v[216:217], v[142:143], 0, s[28:29]
	s_add_i32 m0, s40, 0xc000
	ds_read_b128 v[182:185], v149
	ds_read_b128 v[188:191], v149 offset:1024
	ds_read_b128 v[192:195], v149 offset:2048
	ds_read_b128 v[196:199], v149 offset:3072
	ds_read_b128 v[200:203], v149 offset:4096
	ds_read_b128 v[204:207], v149 offset:5120
	ds_read_b128 v[208:211], v149 offset:6144
	ds_read_b128 v[212:215], v149 offset:7168
	global_load_lds_dwordx4 v[216:217], off
	v_lshl_add_u64 v[216:217], v[144:145], 0, s[28:29]
	s_add_i32 m0, s40, 0xe000
	s_nop 0
	global_load_lds_dwordx4 v[216:217], off
	s_waitcnt vmcnt(8)
	s_waitcnt lgkmcnt(0)
	s_barrier
	s_setprio 1
	s_waitcnt lgkmcnt(0)
	v_mfma_f32_16x16x32_bf16 v[114:117], v[150:153], v[182:185], v[114:117]
	v_mfma_f32_16x16x32_bf16 v[82:85], v[158:161], v[182:185], v[82:85]
	v_mfma_f32_16x16x32_bf16 v[122:125], v[150:153], v[192:195], v[122:125]
	v_mfma_f32_16x16x32_bf16 v[86:89], v[158:161], v[192:195], v[86:89]
	v_mfma_f32_16x16x32_bf16 v[126:129], v[150:153], v[200:203], v[126:129]
	v_mfma_f32_16x16x32_bf16 v[90:93], v[158:161], v[200:203], v[90:93]
	v_mfma_f32_16x16x32_bf16 v[118:121], v[150:153], v[208:211], v[118:121]
	v_mfma_f32_16x16x32_bf16 v[102:105], v[158:161], v[208:211], v[102:105]
	v_mfma_f32_16x16x32_bf16 v[114:117], v[154:157], v[188:191], v[114:117]
	v_mfma_f32_16x16x32_bf16 v[82:85], v[162:165], v[188:191], v[82:85]
	v_mfma_f32_16x16x32_bf16 v[122:125], v[154:157], v[196:199], v[122:125]
	v_mfma_f32_16x16x32_bf16 v[86:89], v[162:165], v[196:199], v[86:89]
	v_mfma_f32_16x16x32_bf16 v[126:129], v[154:157], v[204:207], v[126:129]
	v_mfma_f32_16x16x32_bf16 v[90:93], v[162:165], v[204:207], v[90:93]
	v_mfma_f32_16x16x32_bf16 v[118:121], v[154:157], v[212:215], v[118:121]
	v_mfma_f32_16x16x32_bf16 v[102:105], v[162:165], v[212:215], v[102:105]
	s_setprio 0
	s_setprio 1
	v_mfma_f32_16x16x32_bf16 v[26:29], v[166:169], v[182:185], v[26:29]
	v_mfma_f32_16x16x32_bf16 v[2:5], v[174:177], v[182:185], v[2:5]
	v_mfma_f32_16x16x32_bf16 v[30:33], v[166:169], v[192:195], v[30:33]
	v_mfma_f32_16x16x32_bf16 v[6:9], v[174:177], v[192:195], v[6:9]
	v_mfma_f32_16x16x32_bf16 v[42:45], v[166:169], v[200:203], v[42:45]
	v_mfma_f32_16x16x32_bf16 v[10:13], v[174:177], v[200:203], v[10:13]
	v_mfma_f32_16x16x32_bf16 v[58:61], v[166:169], v[208:211], v[58:61]
	v_mfma_f32_16x16x32_bf16 v[14:17], v[174:177], v[208:211], v[14:17]
	v_mfma_f32_16x16x32_bf16 v[26:29], v[170:173], v[188:191], v[26:29]
	v_mfma_f32_16x16x32_bf16 v[2:5], v[178:181], v[188:191], v[2:5]
	v_mfma_f32_16x16x32_bf16 v[30:33], v[170:173], v[196:199], v[30:33]
	v_mfma_f32_16x16x32_bf16 v[6:9], v[178:181], v[196:199], v[6:9]
	v_mfma_f32_16x16x32_bf16 v[42:45], v[170:173], v[204:207], v[42:45]
	v_mfma_f32_16x16x32_bf16 v[10:13], v[178:181], v[204:207], v[10:13]
	v_mfma_f32_16x16x32_bf16 v[58:61], v[170:173], v[212:215], v[58:61]
	v_mfma_f32_16x16x32_bf16 v[14:17], v[178:181], v[212:215], v[14:17]
	s_setprio 0
	s_barrier
	s_add_i32 s60, s51, s39
	v_lshl_add_u64 v[216:217], s[30:31], 0, v[130:131]
	s_mov_b32 m0, s60
	ds_read_b128 v[182:185], v149 offset:16384
	ds_read_b128 v[188:191], v149 offset:17408
	ds_read_b128 v[192:195], v149 offset:18432
	ds_read_b128 v[196:199], v149 offset:19456
	ds_read_b128 v[200:203], v149 offset:20480
	ds_read_b128 v[204:207], v149 offset:21504
	ds_read_b128 v[208:211], v149 offset:22528
	ds_read_b128 v[212:215], v149 offset:23552
	global_load_lds_dwordx4 v[216:217], off
	s_add_i32 m0, s60, 0x2000
	s_add_u32 s60, s30, 0xb0000
	v_lshl_add_u64 v[218:219], s[30:31], 0, v[132:133]
	s_addc_u32 s61, s31, 0
	s_add_i32 s62, s52, s39
	global_load_lds_dwordx4 v[218:219], off
	v_lshl_add_u64 v[220:221], s[60:61], 0, v[130:131]
	s_mov_b32 m0, s62
	v_lshl_add_u64 v[222:223], s[34:35], 0, v[132:133]
	global_load_lds_dwordx4 v[220:221], off
	v_lshl_add_u64 v[220:221], s[60:61], 0, v[132:133]
	s_add_i32 m0, s62, 0x2000
	s_nop 0
	global_load_lds_dwordx4 v[220:221], off
	v_lshl_add_u64 v[220:221], s[34:35], 0, v[130:131]
	s_mov_b32 m0, s40
	s_nop 0
	global_load_lds_dwordx4 v[220:221], off
	s_mov_b32 m0, s41
	s_nop 0
	global_load_lds_dwordx4 v[222:223], off
	s_waitcnt vmcnt(8)
	s_waitcnt lgkmcnt(0)
	s_barrier
; #define PG8_STAGE(bufoff, gbase, voff) do { _Pragma("unroll") for (int _i = 0; _i < 2; ++_i) \
;         __builtin_amdgcn_global_load_lds((const unsigned*)((const char*)(gbase) + (voff)[_i]), (PG8_LAS unsigned*)(lds + (bufoff) + ldsw + _i * 8192), 16, 0, 0); } while (0)
; #define PG8_LDA(dst, b, h) do { _Pragma("unroll") for (int m = 0; m < 4; ++m) _Pragma("unroll") for (int k = 0; k < 2; ++k) dst[m][k] = *(const PG8_LAS bf16x8*)(lds + PG8_SA(b, h) + aoff + m * 2048 + k * 1024); } while (0)
; #define PG8_LDB(dst, b, h) do { _Pragma("unroll") for (int n = 0; n < 2; ++n) _Pragma("unroll") for (int k = 0; k < 2; ++k) dst[n][k] = *(const PG8_LAS bf16x8*)(lds + PG8_SB(b, h) + boff + n * 2048 + k * 1024); } while (0)
; #define PG8_MMA(ai, bj, At, Bt) do { __builtin_amdgcn_s_setprio(1); _Pragma("unroll") for (int m = 0; m < 4; ++m) _Pragma("unroll") for (int n = 0; n < 2; ++n) _Pragma("unroll") for (int k = 0; k < 2; ++k) \
;         acc[ai][bj][m][n] = __builtin_amdgcn_mfma_f32_16x16x32_bf16(Bt[n][k], At[m][k], acc[ai][bj][m][n], 0, 0, 0); __builtin_amdgcn_s_setprio(0); } while (0)
; #define PG8_WAIT_V(n) asm volatile("s_waitcnt vmcnt(" #n ")" ::: "memory")
; #define PG8_WAIT_L(n) asm volatile("s_waitcnt lgkmcnt(" #n ")" ::: "memory")
; #define PG8_BAR __builtin_amdgcn_s_barrier()
; #define PG8_SCHED __builtin_amdgcn_sched_barrier(0)
; template <class Epi, class Sched, bool ALIGN_EPI = false, bool SP2 = false>
; __device__ __forceinline__ void gemm_phase(PG8_LAS unsigned char* lds, const Gemm g, const Sched& S, const Epi& E) {
;     ...
;             PG8_WAIT_V(8); PG8_WAIT_L(0); PG8_BAR; PG8_MMA(1, 0, At, B0); PG8_MMA(1, 1, At, B1); PG8_BAR; PG8_SCHED;
;             PG8_LDB(B0, 1, 0); PG8_LDB(B1, 1, 1); PG8_SCHED; PG8_LDA(At, 1, 0); PG8_STAGE(PG8_SA(0, 1), a2 + hstep, voffA);
;             PG8_WAIT_V(8); PG8_WAIT_L(0); PG8_BAR; PG8_MMA(0, 0, At, B0); PG8_MMA(0, 1, At, B1); PG8_BAR; PG8_SCHED;
	s_setprio 1
	s_waitcnt lgkmcnt(0)
	v_mfma_f32_16x16x32_bf16 v[110:113], v[150:153], v[182:185], v[110:113]
	v_mfma_f32_16x16x32_bf16 v[106:109], v[158:161], v[182:185], v[106:109]
	v_mfma_f32_16x16x32_bf16 v[98:101], v[150:153], v[192:195], v[98:101]
	v_mfma_f32_16x16x32_bf16 v[94:97], v[158:161], v[192:195], v[94:97]
	v_mfma_f32_16x16x32_bf16 v[74:77], v[150:153], v[200:203], v[74:77]
	v_mfma_f32_16x16x32_bf16 v[70:73], v[158:161], v[200:203], v[70:73]
	v_mfma_f32_16x16x32_bf16 v[54:57], v[150:153], v[208:211], v[54:57]
	v_mfma_f32_16x16x32_bf16 v[50:53], v[158:161], v[208:211], v[50:53]
	v_mfma_f32_16x16x32_bf16 v[110:113], v[154:157], v[188:191], v[110:113]
	v_mfma_f32_16x16x32_bf16 v[106:109], v[162:165], v[188:191], v[106:109]
	v_mfma_f32_16x16x32_bf16 v[98:101], v[154:157], v[196:199], v[98:101]
	v_mfma_f32_16x16x32_bf16 v[94:97], v[162:165], v[196:199], v[94:97]
	v_mfma_f32_16x16x32_bf16 v[74:77], v[154:157], v[204:207], v[74:77]
	v_mfma_f32_16x16x32_bf16 v[70:73], v[162:165], v[204:207], v[70:73]
	v_mfma_f32_16x16x32_bf16 v[54:57], v[154:157], v[212:215], v[54:57]
	v_mfma_f32_16x16x32_bf16 v[50:53], v[162:165], v[212:215], v[50:53]
	s_setprio 0
	s_setprio 1
	v_mfma_f32_16x16x32_bf16 v[66:69], v[166:169], v[182:185], v[66:69]
	v_mfma_f32_16x16x32_bf16 v[18:21], v[174:177], v[182:185], v[18:21]
	v_mfma_f32_16x16x32_bf16 v[78:81], v[166:169], v[192:195], v[78:81]
	v_mfma_f32_16x16x32_bf16 v[22:25], v[174:177], v[192:195], v[22:25]
	v_mfma_f32_16x16x32_bf16 v[62:65], v[166:169], v[200:203], v[62:65]
	v_mfma_f32_16x16x32_bf16 v[46:49], v[174:177], v[200:203], v[46:49]
	v_mfma_f32_16x16x32_bf16 v[38:41], v[166:169], v[208:211], v[38:41]
	v_mfma_f32_16x16x32_bf16 v[34:37], v[174:177], v[208:211], v[34:37]
	v_mfma_f32_16x16x32_bf16 v[66:69], v[170:173], v[188:191], v[66:69]
	v_mfma_f32_16x16x32_bf16 v[18:21], v[178:181], v[188:191], v[18:21]
	v_mfma_f32_16x16x32_bf16 v[78:81], v[170:173], v[196:199], v[78:81]
	v_mfma_f32_16x16x32_bf16 v[22:25], v[178:181], v[196:199], v[22:25]
	v_mfma_f32_16x16x32_bf16 v[62:65], v[170:173], v[204:207], v[62:65]
	v_mfma_f32_16x16x32_bf16 v[46:49], v[178:181], v[204:207], v[46:49]
	v_mfma_f32_16x16x32_bf16 v[38:41], v[170:173], v[212:215], v[38:41]
	v_mfma_f32_16x16x32_bf16 v[34:37], v[178:181], v[212:215], v[34:37]
	s_setprio 0
	s_barrier
	s_add_i32 s60, 0, 0x18000
	s_add_i32 s61, 0, 0x1c000
	v_add_u32_e32 v162, s60, v148
	v_add_u32_e32 v178, s61, v148
	ds_read_b128 v[150:153], v162
	ds_read_b128 v[154:157], v162 offset:1024
	ds_read_b128 v[158:161], v162 offset:2048
	ds_read_b128 v[162:165], v162 offset:3072
	ds_read_b128 v[166:169], v178
	ds_read_b128 v[170:173], v178 offset:1024
	ds_read_b128 v[174:177], v178 offset:2048
	ds_read_b128 v[178:181], v178 offset:3072
	s_add_u32 s34, s34, 0xb0000
	s_addc_u32 s35, s35, 0
	s_mov_b32 m0, s42
	v_lshl_add_u64 v[224:225], s[34:35], 0, v[130:131]
	ds_read_b128 v[182:185], v149 offset:32768
	ds_read_b128 v[188:191], v149 offset:33792
	ds_read_b128 v[192:195], v149 offset:34816
	ds_read_b128 v[196:199], v149 offset:35840
	ds_read_b128 v[200:203], v149 offset:36864
	ds_read_b128 v[204:207], v149 offset:37888
	ds_read_b128 v[208:211], v149 offset:38912
	ds_read_b128 v[212:215], v149 offset:39936
	global_load_lds_dwordx4 v[224:225], off
	v_lshl_add_u64 v[224:225], s[34:35], 0, v[132:133]
	s_mov_b32 m0, s46
	s_nop 0
	global_load_lds_dwordx4 v[224:225], off
	s_waitcnt vmcnt(8)
	s_waitcnt lgkmcnt(0)
	s_barrier
	s_setprio 1
	s_waitcnt lgkmcnt(0)
	v_mfma_f32_16x16x32_bf16 v[114:117], v[150:153], v[182:185], v[114:117]
	v_mfma_f32_16x16x32_bf16 v[82:85], v[158:161], v[182:185], v[82:85]
	v_mfma_f32_16x16x32_bf16 v[122:125], v[150:153], v[192:195], v[122:125]
	v_mfma_f32_16x16x32_bf16 v[86:89], v[158:161], v[192:195], v[86:89]
	v_mfma_f32_16x16x32_bf16 v[126:129], v[150:153], v[200:203], v[126:129]
	v_mfma_f32_16x16x32_bf16 v[90:93], v[158:161], v[200:203], v[90:93]
	v_mfma_f32_16x16x32_bf16 v[118:121], v[150:153], v[208:211], v[118:121]
	v_mfma_f32_16x16x32_bf16 v[102:105], v[158:161], v[208:211], v[102:105]
	v_mfma_f32_16x16x32_bf16 v[114:117], v[154:157], v[188:191], v[114:117]
	v_mfma_f32_16x16x32_bf16 v[82:85], v[162:165], v[188:191], v[82:85]
	v_mfma_f32_16x16x32_bf16 v[122:125], v[154:157], v[196:199], v[122:125]
	v_mfma_f32_16x16x32_bf16 v[86:89], v[162:165], v[196:199], v[86:89]
	v_mfma_f32_16x16x32_bf16 v[126:129], v[154:157], v[204:207], v[126:129]
	v_mfma_f32_16x16x32_bf16 v[90:93], v[162:165], v[204:207], v[90:93]
	v_mfma_f32_16x16x32_bf16 v[118:121], v[154:157], v[212:215], v[118:121]
	v_mfma_f32_16x16x32_bf16 v[102:105], v[162:165], v[212:215], v[102:105]
	s_setprio 0
	s_setprio 1
	v_mfma_f32_16x16x32_bf16 v[26:29], v[166:169], v[182:185], v[26:29]
	v_mfma_f32_16x16x32_bf16 v[2:5], v[174:177], v[182:185], v[2:5]
	v_mfma_f32_16x16x32_bf16 v[30:33], v[166:169], v[192:195], v[30:33]
	v_mfma_f32_16x16x32_bf16 v[6:9], v[174:177], v[192:195], v[6:9]
	v_mfma_f32_16x16x32_bf16 v[42:45], v[166:169], v[200:203], v[42:45]
	v_mfma_f32_16x16x32_bf16 v[10:13], v[174:177], v[200:203], v[10:13]
	v_mfma_f32_16x16x32_bf16 v[58:61], v[166:169], v[208:211], v[58:61]
	v_mfma_f32_16x16x32_bf16 v[14:17], v[174:177], v[208:211], v[14:17]
	v_mfma_f32_16x16x32_bf16 v[26:29], v[170:173], v[188:191], v[26:29]
	v_mfma_f32_16x16x32_bf16 v[2:5], v[178:181], v[188:191], v[2:5]
	v_mfma_f32_16x16x32_bf16 v[30:33], v[170:173], v[196:199], v[30:33]
	v_mfma_f32_16x16x32_bf16 v[6:9], v[178:181], v[196:199], v[6:9]
	v_mfma_f32_16x16x32_bf16 v[42:45], v[170:173], v[204:207], v[42:45]
	v_mfma_f32_16x16x32_bf16 v[10:13], v[178:181], v[204:207], v[10:13]
	v_mfma_f32_16x16x32_bf16 v[58:61], v[170:173], v[212:215], v[58:61]
	v_mfma_f32_16x16x32_bf16 v[14:17], v[178:181], v[212:215], v[14:17]
	s_setprio 0
	s_barrier
; #define PG8_STAGE(bufoff, gbase, voff) do { _Pragma("unroll") for (int _i = 0; _i < 2; ++_i) \
;         __builtin_amdgcn_global_load_lds((const unsigned*)((const char*)(gbase) + (voff)[_i]), (PG8_LAS unsigned*)(lds + (bufoff) + ldsw + _i * 8192), 16, 0, 0); } while (0)
; #define PG8_LDA(dst, b, h) do { _Pragma("unroll") for (int m = 0; m < 4; ++m) _Pragma("unroll") for (int k = 0; k < 2; ++k) dst[m][k] = *(const PG8_LAS bf16x8*)(lds + PG8_SA(b, h) + aoff + m * 2048 + k * 1024); } while (0)
; #define PG8_MMA(ai, bj, At, Bt) do { __builtin_amdgcn_s_setprio(1); _Pragma("unroll") for (int m = 0; m < 4; ++m) _Pragma("unroll") for (int n = 0; n < 2; ++n) _Pragma("unroll") for (int k = 0; k < 2; ++k) \
;         acc[ai][bj][m][n] = __builtin_amdgcn_mfma_f32_16x16x32_bf16(Bt[n][k], At[m][k], acc[ai][bj][m][n], 0, 0, 0); __builtin_amdgcn_s_setprio(0); } while (0)
; #define PG8_WAIT_V(n) asm volatile("s_waitcnt vmcnt(" #n ")" ::: "memory")
; #define PG8_WAIT_L(n) asm volatile("s_waitcnt lgkmcnt(" #n ")" ::: "memory")
; #define PG8_BAR __builtin_amdgcn_s_barrier()
; #define PG8_SCHED __builtin_amdgcn_sched_barrier(0)
; template <class Epi, class Sched, bool ALIGN_EPI = false, bool SP2 = false>
; __device__ __forceinline__ void gemm_phase(PG8_LAS unsigned char* lds, const Gemm g, const Sched& S, const Epi& E) {
;     ...
;             PG8_LDA(At, 1, 1); PG8_STAGE(PG8_SB(1, 0), b3, voffB); PG8_STAGE(PG8_SB(1, 1), b3 + hstep, voffB); PG8_STAGE(PG8_SA(1, 0), a3, voffA);
;             PG8_WAIT_V(8); PG8_WAIT_L(0); PG8_BAR; PG8_MMA(1, 0, At, B0); PG8_MMA(1, 1, At, B1); PG8_BAR; PG8_SCHED;
;     ...
; #pragma unroll
;         for (int a = 0; a < 2; ++a)
; #pragma unroll
;             for (int b = 0; b < 2; ++b)
; #pragma unroll
;                 for (int m = 0; m < 4; ++m)
; #pragma unroll
;                     for (int n = 0; n < 2; ++n) acc[a][b][m][n] = (f32x4){0.f, 0.f, 0.f, 0.f};
;         cur = nxt; cA = nA; cB = nB; ++ui;
	s_add_i32 s34, s60, s39
	v_lshl_add_u64 v[216:217], v[216:217], 0, s[24:25]
	s_mov_b32 m0, s34
	ds_read_b128 v[182:185], v149 offset:49152
	ds_read_b128 v[188:191], v149 offset:50176
	ds_read_b128 v[192:195], v149 offset:51200
	ds_read_b128 v[196:199], v149 offset:52224
	ds_read_b128 v[200:203], v149 offset:53248
	ds_read_b128 v[204:207], v149 offset:54272
	ds_read_b128 v[208:211], v149 offset:55296
	ds_read_b128 v[212:215], v149 offset:56320
	global_load_lds_dwordx4 v[216:217], off
	s_add_i32 m0, s34, 0x2000
	s_add_u32 s30, s30, 0xb0080
	v_lshl_add_u64 v[216:217], v[218:219], 0, s[24:25]
	s_addc_u32 s31, s31, 0
	s_add_i32 s34, s61, s39
	global_load_lds_dwordx4 v[216:217], off
	v_lshl_add_u64 v[216:217], s[30:31], 0, v[130:131]
	s_mov_b32 m0, s34
	s_nop 0
	global_load_lds_dwordx4 v[216:217], off
	v_lshl_add_u64 v[216:217], s[30:31], 0, v[132:133]
	s_add_i32 m0, s34, 0x2000
	s_nop 0
	global_load_lds_dwordx4 v[216:217], off
	v_lshl_add_u64 v[216:217], v[220:221], 0, s[24:25]
	s_mov_b32 m0, s49
	s_nop 0
	global_load_lds_dwordx4 v[216:217], off
	v_lshl_add_u64 v[216:217], v[222:223], 0, s[24:25]
	s_mov_b32 m0, s50
	s_nop 0
	global_load_lds_dwordx4 v[216:217], off
	s_waitcnt vmcnt(8)
	s_waitcnt lgkmcnt(0)
	s_barrier
	s_setprio 1
	s_waitcnt lgkmcnt(0)
	v_mfma_f32_16x16x32_bf16 v[110:113], v[150:153], v[182:185], v[110:113]
	v_mfma_f32_16x16x32_bf16 v[106:109], v[158:161], v[182:185], v[106:109]
	v_mfma_f32_16x16x32_bf16 v[98:101], v[150:153], v[192:195], v[98:101]
	v_mfma_f32_16x16x32_bf16 v[94:97], v[158:161], v[192:195], v[94:97]
	v_mfma_f32_16x16x32_bf16 v[74:77], v[150:153], v[200:203], v[74:77]
	v_mfma_f32_16x16x32_bf16 v[70:73], v[158:161], v[200:203], v[70:73]
	v_mfma_f32_16x16x32_bf16 v[54:57], v[150:153], v[208:211], v[54:57]
	v_mfma_f32_16x16x32_bf16 v[50:53], v[158:161], v[208:211], v[50:53]
	v_mfma_f32_16x16x32_bf16 v[110:113], v[154:157], v[188:191], v[110:113]
	v_mfma_f32_16x16x32_bf16 v[106:109], v[162:165], v[188:191], v[106:109]
	v_mfma_f32_16x16x32_bf16 v[98:101], v[154:157], v[196:199], v[98:101]
	v_mfma_f32_16x16x32_bf16 v[94:97], v[162:165], v[196:199], v[94:97]
	v_mfma_f32_16x16x32_bf16 v[74:77], v[154:157], v[204:207], v[74:77]
	v_mfma_f32_16x16x32_bf16 v[70:73], v[162:165], v[204:207], v[70:73]
	v_mfma_f32_16x16x32_bf16 v[54:57], v[154:157], v[212:215], v[54:57]
	v_mfma_f32_16x16x32_bf16 v[50:53], v[162:165], v[212:215], v[50:53]
	s_setprio 0
	s_setprio 1
	v_mfma_f32_16x16x32_bf16 v[66:69], v[166:169], v[182:185], v[66:69]
	v_mfma_f32_16x16x32_bf16 v[18:21], v[174:177], v[182:185], v[18:21]
	v_mfma_f32_16x16x32_bf16 v[78:81], v[166:169], v[192:195], v[78:81]
	v_mfma_f32_16x16x32_bf16 v[22:25], v[174:177], v[192:195], v[22:25]
	v_mfma_f32_16x16x32_bf16 v[62:65], v[166:169], v[200:203], v[62:65]
	v_mfma_f32_16x16x32_bf16 v[46:49], v[174:177], v[200:203], v[46:49]
	v_mfma_f32_16x16x32_bf16 v[38:41], v[166:169], v[208:211], v[38:41]
	v_mfma_f32_16x16x32_bf16 v[34:37], v[174:177], v[208:211], v[34:37]
	v_mfma_f32_16x16x32_bf16 v[66:69], v[170:173], v[188:191], v[66:69]
	v_mfma_f32_16x16x32_bf16 v[18:21], v[178:181], v[188:191], v[18:21]
	v_mfma_f32_16x16x32_bf16 v[78:81], v[170:173], v[196:199], v[78:81]
	v_mfma_f32_16x16x32_bf16 v[22:25], v[178:181], v[196:199], v[22:25]
	v_mfma_f32_16x16x32_bf16 v[62:65], v[170:173], v[204:207], v[62:65]
	v_mfma_f32_16x16x32_bf16 v[46:49], v[178:181], v[204:207], v[46:49]
	v_mfma_f32_16x16x32_bf16 v[38:41], v[170:173], v[212:215], v[38:41]
	v_mfma_f32_16x16x32_bf16 v[34:37], v[178:181], v[212:215], v[34:37]
	s_setprio 0
	s_add_i32 s59, s59, 2
	s_add_u32 s28, s28, 0x100
	s_addc_u32 s29, s29, 0
	s_cmp_gt_u32 s59, 41
	s_barrier
	s_cbranch_scc0 .LBB0_1778
	s_add_u32 s28, s57, 0xffffff00
	s_addc_u32 s29, s58, -1
	s_and_b64 vcc, exec, s[6:7]
	s_cbranch_vccnz .LBB0_1781
	v_mov_b32_e32 v34, 0
	s_mov_b32 s20, s54
	s_mov_b32 s37, s55
	s_mov_b64 s[22:23], s[26:27]
	s_mov_b32 s48, s56
	v_mov_b32_e32 v35, v34
	v_mov_b32_e32 v36, v34
	v_mov_b32_e32 v37, v34
	v_mov_b32_e32 v38, v34
	v_mov_b32_e32 v39, v34
	v_mov_b32_e32 v40, v34
	v_mov_b32_e32 v41, v34
	v_mov_b32_e32 v46, v34
	v_mov_b32_e32 v47, v34
	v_mov_b32_e32 v48, v34
	v_mov_b32_e32 v49, v34
	v_mov_b32_e32 v62, v34
	v_mov_b32_e32 v63, v34
	v_mov_b32_e32 v64, v34
	v_mov_b32_e32 v65, v34
	v_mov_b32_e32 v22, v34
	v_mov_b32_e32 v23, v34
	v_mov_b32_e32 v24, v34
	v_mov_b32_e32 v25, v34
	v_mov_b32_e32 v78, v34
	v_mov_b32_e32 v79, v34
	v_mov_b32_e32 v80, v34
	v_mov_b32_e32 v81, v34
	v_mov_b32_e32 v18, v34
	v_mov_b32_e32 v19, v34
	v_mov_b32_e32 v20, v34
	v_mov_b32_e32 v21, v34
	v_mov_b32_e32 v66, v34
	v_mov_b32_e32 v67, v34
	v_mov_b32_e32 v68, v34
	v_mov_b32_e32 v69, v34
	v_mov_b32_e32 v50, v34
	v_mov_b32_e32 v51, v34
	v_mov_b32_e32 v52, v34
	v_mov_b32_e32 v53, v34
	v_mov_b32_e32 v54, v34
	v_mov_b32_e32 v55, v34
	v_mov_b32_e32 v56, v34
	v_mov_b32_e32 v57, v34
	v_mov_b32_e32 v70, v34
	v_mov_b32_e32 v71, v34
	v_mov_b32_e32 v72, v34
	v_mov_b32_e32 v73, v34
	v_mov_b32_e32 v74, v34
	v_mov_b32_e32 v75, v34
	v_mov_b32_e32 v76, v34
	v_mov_b32_e32 v77, v34
	v_mov_b32_e32 v94, v34
	v_mov_b32_e32 v95, v34
	v_mov_b32_e32 v96, v34
	v_mov_b32_e32 v97, v34
	v_mov_b32_e32 v98, v34
	v_mov_b32_e32 v99, v34
	v_mov_b32_e32 v100, v34
	v_mov_b32_e32 v101, v34
	v_mov_b32_e32 v106, v34
	v_mov_b32_e32 v107, v34
	v_mov_b32_e32 v108, v34
	v_mov_b32_e32 v109, v34
	v_mov_b32_e32 v110, v34
	v_mov_b32_e32 v111, v34
	v_mov_b32_e32 v112, v34
	v_mov_b32_e32 v113, v34
	v_mov_b32_e32 v14, v34
	v_mov_b32_e32 v15, v34
	v_mov_b32_e32 v16, v34
	v_mov_b32_e32 v17, v34
	v_mov_b32_e32 v58, v34
	v_mov_b32_e32 v59, v34
	v_mov_b32_e32 v60, v34
	v_mov_b32_e32 v61, v34
	v_mov_b32_e32 v10, v34
	v_mov_b32_e32 v11, v34
	v_mov_b32_e32 v12, v34
	v_mov_b32_e32 v13, v34
	v_mov_b32_e32 v42, v34
	v_mov_b32_e32 v43, v34
	v_mov_b32_e32 v44, v34
	v_mov_b32_e32 v45, v34
	v_mov_b32_e32 v6, v34
	v_mov_b32_e32 v7, v34
	v_mov_b32_e32 v8, v34
	v_mov_b32_e32 v9, v34
	v_mov_b32_e32 v30, v34
	v_mov_b32_e32 v31, v34
	v_mov_b32_e32 v32, v34
	v_mov_b32_e32 v33, v34
	v_mov_b32_e32 v2, v34
	v_mov_b32_e32 v3, v34
	v_mov_b32_e32 v4, v34
	v_mov_b32_e32 v5, v34
	v_mov_b32_e32 v26, v34
	v_mov_b32_e32 v27, v34
	v_mov_b32_e32 v28, v34
	v_mov_b32_e32 v29, v34
	v_mov_b32_e32 v102, v34
	v_mov_b32_e32 v103, v34
	v_mov_b32_e32 v104, v34
	v_mov_b32_e32 v105, v34
	v_mov_b32_e32 v118, v34
	v_mov_b32_e32 v119, v34
	v_mov_b32_e32 v120, v34
	v_mov_b32_e32 v121, v34
	v_mov_b32_e32 v90, v34
	v_mov_b32_e32 v91, v34
	v_mov_b32_e32 v92, v34
	v_mov_b32_e32 v93, v34
	v_mov_b32_e32 v126, v34
	v_mov_b32_e32 v127, v34
	v_mov_b32_e32 v128, v34
	v_mov_b32_e32 v129, v34
	v_mov_b32_e32 v86, v34
	v_mov_b32_e32 v87, v34
	v_mov_b32_e32 v88, v34
	v_mov_b32_e32 v89, v34
	v_mov_b32_e32 v122, v34
	v_mov_b32_e32 v123, v34
	v_mov_b32_e32 v124, v34
	v_mov_b32_e32 v125, v34
	v_mov_b32_e32 v82, v34
	v_mov_b32_e32 v83, v34
	v_mov_b32_e32 v84, v34
	v_mov_b32_e32 v85, v34
	v_mov_b32_e32 v114, v34
	v_mov_b32_e32 v115, v34
	v_mov_b32_e32 v116, v34
	v_mov_b32_e32 v117, v34
	s_andn2_b64 vcc, exec, s[4:5]
	s_cbranch_vccnz .LBB0_1782
	s_branch .LBB0_1783

; #define PG8_STAGE(bufoff, gbase, voff) do { _Pragma("unroll") for (int _i = 0; _i < 2; ++_i) \
;         __builtin_amdgcn_global_load_lds((const unsigned*)((const char*)(gbase) + (voff)[_i]), (PG8_LAS unsigned*)(lds + (bufoff) + ldsw + _i * 8192), 16, 0, 0); } while (0)
; #define PG8_LDA(dst, b, h) do { _Pragma("unroll") for (int m = 0; m < 4; ++m) _Pragma("unroll") for (int k = 0; k < 2; ++k) dst[m][k] = *(const PG8_LAS bf16x8*)(lds + PG8_SA(b, h) + aoff + m * 2048 + k * 1024); } while (0)
; #define PG8_LDB(dst, b, h) do { _Pragma("unroll") for (int n = 0; n < 2; ++n) _Pragma("unroll") for (int k = 0; k < 2; ++k) dst[n][k] = *(const PG8_LAS bf16x8*)(lds + PG8_SB(b, h) + boff + n * 2048 + k * 1024); } while (0)
; #define PG8_MMA(ai, bj, At, Bt) do { __builtin_amdgcn_s_setprio(1); _Pragma("unroll") for (int m = 0; m < 4; ++m) _Pragma("unroll") for (int n = 0; n < 2; ++n) _Pragma("unroll") for (int k = 0; k < 2; ++k) \
;         acc[ai][bj][m][n] = __builtin_amdgcn_mfma_f32_16x16x32_bf16(Bt[n][k], At[m][k], acc[ai][bj][m][n], 0, 0, 0); __builtin_amdgcn_s_setprio(0); } while (0)
; #define PG8_WAIT_V(n) asm volatile("s_waitcnt vmcnt(" #n ")" ::: "memory")
; #define PG8_WAIT_L(n) asm volatile("s_waitcnt lgkmcnt(" #n ")" ::: "memory")
; #define PG8_BAR __builtin_amdgcn_s_barrier()
; #define PG8_SCHED __builtin_amdgcn_sched_barrier(0)
; template <class Epi, class Sched, bool ALIGN_EPI = false, bool SP2 = false>
; __device__ __forceinline__ void gemm_phase(PG8_LAS unsigned char* lds, const Gemm g, const Sched& S, const Epi& E) {
;     ...
;             const bool last = (t == nt - 2);
;             const char* a1 = cA + (size_t)(t + 1) * kstep;
;             const char* a2 = last ? nA : cA + (size_t)(t + 2) * kstep; const char* b2 = last ? nB : cB + (size_t)(t + 2) * kstep;
;             const char* a3 = a2 + kstep; const char* b3 = b2 + kstep;
;             if (last && has_next) S.a_ready(nxt);
;             if constexpr (SP2) {
;             PG8_LDB(B0, 0, 0); PG8_LDB(B1, 0, 1); PG8_SCHED; PG8_LDA(At, 0, 0); PG8_STAGE(PG8_SA(1, 1), a1 + hstep, voffA);
;             PG8_WAIT_V(8); PG8_WAIT_L(0); PG8_BAR; PG8_MMA(0, 0, At, B0); PG8_MMA(0, 1, At, B1); PG8_BAR; PG8_SCHED;
;             PG8_LDA(At, 0, 1); PG8_STAGE(PG8_SB(0, 0), b2, voffB); PG8_STAGE(PG8_SB(0, 1), b2 + hstep, voffB); PG8_STAGE(PG8_SA(0, 0), a2, voffA);
.LBB0_1940:
	v_add_u32_e32 v149, s54, v147
	ds_read_b128 v[150:153], v149
	ds_read_b128 v[154:157], v149 offset:1024
	ds_read_b128 v[158:161], v149 offset:2048
	ds_read_b128 v[162:165], v149 offset:3072
	v_add_u32_e32 v149, s55, v147
	s_add_u32 s28, s20, s26
	ds_read_b128 v[166:169], v149
	ds_read_b128 v[170:173], v149 offset:1024
	ds_read_b128 v[174:177], v149 offset:2048
	ds_read_b128 v[178:181], v149 offset:3072
	s_addc_u32 s29, s21, s27
	s_add_u32 s28, s28, 0x100
	s_addc_u32 s29, s29, 0
	s_add_u32 s60, s0, s26
	s_addc_u32 s61, s1, s27
	s_cmpk_eq_i32 s26, 0x1500
	s_cselect_b32 s31, s25, s29
	s_cselect_b32 s30, s24, s28
	s_cselect_b32 s29, s9, s61
	s_cselect_b32 s28, s8, s60
	v_lshl_add_u64 v[216:217], v[142:143], 0, s[26:27]
	s_add_i32 m0, s42, 0xc000
	ds_read_b128 v[182:185], v148
	ds_read_b128 v[188:191], v148 offset:1024
	ds_read_b128 v[192:195], v148 offset:2048
	ds_read_b128 v[196:199], v148 offset:3072
	ds_read_b128 v[200:203], v148 offset:4096
	ds_read_b128 v[204:207], v148 offset:5120
	ds_read_b128 v[208:211], v148 offset:6144
	ds_read_b128 v[212:215], v148 offset:7168
	global_load_lds_dwordx4 v[216:217], off
	v_lshl_add_u64 v[216:217], v[144:145], 0, s[26:27]
	s_add_i32 m0, s42, 0xe000
	s_nop 0
	global_load_lds_dwordx4 v[216:217], off
	s_waitcnt vmcnt(8)
	s_waitcnt lgkmcnt(0)
	s_barrier
	s_setprio 1
	s_waitcnt lgkmcnt(0)
	v_mfma_f32_16x16x32_bf16 v[114:117], v[150:153], v[182:185], v[114:117]
	v_mfma_f32_16x16x32_bf16 v[82:85], v[158:161], v[182:185], v[82:85]
	v_mfma_f32_16x16x32_bf16 v[122:125], v[150:153], v[192:195], v[122:125]
	v_mfma_f32_16x16x32_bf16 v[86:89], v[158:161], v[192:195], v[86:89]
	v_mfma_f32_16x16x32_bf16 v[126:129], v[150:153], v[200:203], v[126:129]
	v_mfma_f32_16x16x32_bf16 v[90:93], v[158:161], v[200:203], v[90:93]
	v_mfma_f32_16x16x32_bf16 v[118:121], v[150:153], v[208:211], v[118:121]
	v_mfma_f32_16x16x32_bf16 v[102:105], v[158:161], v[208:211], v[102:105]
	v_mfma_f32_16x16x32_bf16 v[114:117], v[154:157], v[188:191], v[114:117]
	v_mfma_f32_16x16x32_bf16 v[82:85], v[162:165], v[188:191], v[82:85]
	v_mfma_f32_16x16x32_bf16 v[122:125], v[154:157], v[196:199], v[122:125]
	v_mfma_f32_16x16x32_bf16 v[86:89], v[162:165], v[196:199], v[86:89]
	v_mfma_f32_16x16x32_bf16 v[126:129], v[154:157], v[204:207], v[126:129]
	v_mfma_f32_16x16x32_bf16 v[90:93], v[162:165], v[204:207], v[90:93]
	v_mfma_f32_16x16x32_bf16 v[118:121], v[154:157], v[212:215], v[118:121]
	v_mfma_f32_16x16x32_bf16 v[102:105], v[162:165], v[212:215], v[102:105]
	s_setprio 0
	s_setprio 1
	v_mfma_f32_16x16x32_bf16 v[26:29], v[166:169], v[182:185], v[26:29]
	v_mfma_f32_16x16x32_bf16 v[2:5], v[174:177], v[182:185], v[2:5]
	v_mfma_f32_16x16x32_bf16 v[30:33], v[166:169], v[192:195], v[30:33]
	v_mfma_f32_16x16x32_bf16 v[6:9], v[174:177], v[192:195], v[6:9]
	v_mfma_f32_16x16x32_bf16 v[42:45], v[166:169], v[200:203], v[42:45]
	v_mfma_f32_16x16x32_bf16 v[10:13], v[174:177], v[200:203], v[10:13]
	v_mfma_f32_16x16x32_bf16 v[58:61], v[166:169], v[208:211], v[58:61]
	v_mfma_f32_16x16x32_bf16 v[14:17], v[174:177], v[208:211], v[14:17]
	v_mfma_f32_16x16x32_bf16 v[26:29], v[170:173], v[188:191], v[26:29]
	v_mfma_f32_16x16x32_bf16 v[2:5], v[178:181], v[188:191], v[2:5]
	v_mfma_f32_16x16x32_bf16 v[30:33], v[170:173], v[196:199], v[30:33]
	v_mfma_f32_16x16x32_bf16 v[6:9], v[178:181], v[196:199], v[6:9]
	v_mfma_f32_16x16x32_bf16 v[42:45], v[170:173], v[204:207], v[42:45]
	v_mfma_f32_16x16x32_bf16 v[10:13], v[178:181], v[204:207], v[10:13]
	v_mfma_f32_16x16x32_bf16 v[58:61], v[170:173], v[212:215], v[58:61]
	v_mfma_f32_16x16x32_bf16 v[14:17], v[178:181], v[212:215], v[14:17]
	s_setprio 0
	s_barrier
	s_add_i32 s60, s54, s41
	v_lshl_add_u64 v[216:217], s[28:29], 0, v[130:131]
	s_mov_b32 m0, s60
	ds_read_b128 v[182:185], v148 offset:16384
	ds_read_b128 v[188:191], v148 offset:17408
	ds_read_b128 v[192:195], v148 offset:18432
	ds_read_b128 v[196:199], v148 offset:19456
	ds_read_b128 v[200:203], v148 offset:20480
	ds_read_b128 v[204:207], v148 offset:21504
	ds_read_b128 v[208:211], v148 offset:22528
	ds_read_b128 v[212:215], v148 offset:23552
	global_load_lds_dwordx4 v[216:217], off
	s_add_i32 m0, s60, 0x2000
	s_add_u32 s60, s28, 0xb0000
	v_lshl_add_u64 v[218:219], s[28:29], 0, v[132:133]
	s_addc_u32 s61, s29, 0
	s_add_i32 s62, s55, s41
	global_load_lds_dwordx4 v[218:219], off
	v_lshl_add_u64 v[220:221], s[60:61], 0, v[130:131]
	s_mov_b32 m0, s62
	v_lshl_add_u64 v[222:223], s[30:31], 0, v[132:133]
	global_load_lds_dwordx4 v[220:221], off
	v_lshl_add_u64 v[220:221], s[60:61], 0, v[132:133]
	s_add_i32 m0, s62, 0x2000
	s_nop 0
	global_load_lds_dwordx4 v[220:221], off
	v_lshl_add_u64 v[220:221], s[30:31], 0, v[130:131]
	s_mov_b32 m0, s42
	s_nop 0
	global_load_lds_dwordx4 v[220:221], off
	s_mov_b32 m0, s46
	s_nop 0
	global_load_lds_dwordx4 v[222:223], off
	s_waitcnt vmcnt(8)
	s_waitcnt lgkmcnt(0)
	s_barrier
; #define PG8_STAGE(bufoff, gbase, voff) do { _Pragma("unroll") for (int _i = 0; _i < 2; ++_i) \
;         __builtin_amdgcn_global_load_lds((const unsigned*)((const char*)(gbase) + (voff)[_i]), (PG8_LAS unsigned*)(lds + (bufoff) + ldsw + _i * 8192), 16, 0, 0); } while (0)
; #define PG8_LDA(dst, b, h) do { _Pragma("unroll") for (int m = 0; m < 4; ++m) _Pragma("unroll") for (int k = 0; k < 2; ++k) dst[m][k] = *(const PG8_LAS bf16x8*)(lds + PG8_SA(b, h) + aoff + m * 2048 + k * 1024); } while (0)
; #define PG8_LDB(dst, b, h) do { _Pragma("unroll") for (int n = 0; n < 2; ++n) _Pragma("unroll") for (int k = 0; k < 2; ++k) dst[n][k] = *(const PG8_LAS bf16x8*)(lds + PG8_SB(b, h) + boff + n * 2048 + k * 1024); } while (0)
; #define PG8_MMA(ai, bj, At, Bt) do { __builtin_amdgcn_s_setprio(1); _Pragma("unroll") for (int m = 0; m < 4; ++m) _Pragma("unroll") for (int n = 0; n < 2; ++n) _Pragma("unroll") for (int k = 0; k < 2; ++k) \
;         acc[ai][bj][m][n] = __builtin_amdgcn_mfma_f32_16x16x32_bf16(Bt[n][k], At[m][k], acc[ai][bj][m][n], 0, 0, 0); __builtin_amdgcn_s_setprio(0); } while (0)
; #define PG8_WAIT_V(n) asm volatile("s_waitcnt vmcnt(" #n ")" ::: "memory")
; #define PG8_WAIT_L(n) asm volatile("s_waitcnt lgkmcnt(" #n ")" ::: "memory")
; #define PG8_BAR __builtin_amdgcn_s_barrier()
; #define PG8_SCHED __builtin_amdgcn_sched_barrier(0)
; template <class Epi, class Sched, bool ALIGN_EPI = false, bool SP2 = false>
; __device__ __forceinline__ void gemm_phase(PG8_LAS unsigned char* lds, const Gemm g, const Sched& S, const Epi& E) {
;     ...
;             PG8_WAIT_V(8); PG8_WAIT_L(0); PG8_BAR; PG8_MMA(1, 0, At, B0); PG8_MMA(1, 1, At, B1); PG8_BAR; PG8_SCHED;
;             PG8_LDB(B0, 1, 0); PG8_LDB(B1, 1, 1); PG8_SCHED; PG8_LDA(At, 1, 0); PG8_STAGE(PG8_SA(0, 1), a2 + hstep, voffA);
;             PG8_WAIT_V(8); PG8_WAIT_L(0); PG8_BAR; PG8_MMA(0, 0, At, B0); PG8_MMA(0, 1, At, B1); PG8_BAR; PG8_SCHED;
	s_setprio 1
	s_waitcnt lgkmcnt(0)
	v_mfma_f32_16x16x32_bf16 v[110:113], v[150:153], v[182:185], v[110:113]
	v_mfma_f32_16x16x32_bf16 v[106:109], v[158:161], v[182:185], v[106:109]
	v_mfma_f32_16x16x32_bf16 v[98:101], v[150:153], v[192:195], v[98:101]
	v_mfma_f32_16x16x32_bf16 v[94:97], v[158:161], v[192:195], v[94:97]
	v_mfma_f32_16x16x32_bf16 v[74:77], v[150:153], v[200:203], v[74:77]
	v_mfma_f32_16x16x32_bf16 v[70:73], v[158:161], v[200:203], v[70:73]
	v_mfma_f32_16x16x32_bf16 v[54:57], v[150:153], v[208:211], v[54:57]
	v_mfma_f32_16x16x32_bf16 v[50:53], v[158:161], v[208:211], v[50:53]
	v_mfma_f32_16x16x32_bf16 v[110:113], v[154:157], v[188:191], v[110:113]
	v_mfma_f32_16x16x32_bf16 v[106:109], v[162:165], v[188:191], v[106:109]
	v_mfma_f32_16x16x32_bf16 v[98:101], v[154:157], v[196:199], v[98:101]
	v_mfma_f32_16x16x32_bf16 v[94:97], v[162:165], v[196:199], v[94:97]
	v_mfma_f32_16x16x32_bf16 v[74:77], v[154:157], v[204:207], v[74:77]
	v_mfma_f32_16x16x32_bf16 v[70:73], v[162:165], v[204:207], v[70:73]
	v_mfma_f32_16x16x32_bf16 v[54:57], v[154:157], v[212:215], v[54:57]
	v_mfma_f32_16x16x32_bf16 v[50:53], v[162:165], v[212:215], v[50:53]
	s_setprio 0
	s_setprio 1
	v_mfma_f32_16x16x32_bf16 v[66:69], v[166:169], v[182:185], v[66:69]
	v_mfma_f32_16x16x32_bf16 v[18:21], v[174:177], v[182:185], v[18:21]
	v_mfma_f32_16x16x32_bf16 v[78:81], v[166:169], v[192:195], v[78:81]
	v_mfma_f32_16x16x32_bf16 v[22:25], v[174:177], v[192:195], v[22:25]
	v_mfma_f32_16x16x32_bf16 v[62:65], v[166:169], v[200:203], v[62:65]
	v_mfma_f32_16x16x32_bf16 v[46:49], v[174:177], v[200:203], v[46:49]
	v_mfma_f32_16x16x32_bf16 v[38:41], v[166:169], v[208:211], v[38:41]
	v_mfma_f32_16x16x32_bf16 v[34:37], v[174:177], v[208:211], v[34:37]
	v_mfma_f32_16x16x32_bf16 v[66:69], v[170:173], v[188:191], v[66:69]
	v_mfma_f32_16x16x32_bf16 v[18:21], v[178:181], v[188:191], v[18:21]
	v_mfma_f32_16x16x32_bf16 v[78:81], v[170:173], v[196:199], v[78:81]
	v_mfma_f32_16x16x32_bf16 v[22:25], v[178:181], v[196:199], v[22:25]
	v_mfma_f32_16x16x32_bf16 v[62:65], v[170:173], v[204:207], v[62:65]
	v_mfma_f32_16x16x32_bf16 v[46:49], v[178:181], v[204:207], v[46:49]
	v_mfma_f32_16x16x32_bf16 v[38:41], v[170:173], v[212:215], v[38:41]
	v_mfma_f32_16x16x32_bf16 v[34:37], v[178:181], v[212:215], v[34:37]
	s_setprio 0
	s_barrier
	s_add_i32 s60, 0, 0x18000
	v_add_u32_e32 v149, s60, v147
	s_add_i32 s61, 0, 0x1c000
	ds_read_b128 v[150:153], v149
	ds_read_b128 v[154:157], v149 offset:1024
	ds_read_b128 v[158:161], v149 offset:2048
	ds_read_b128 v[162:165], v149 offset:3072
	v_add_u32_e32 v149, s61, v147
	ds_read_b128 v[166:169], v149
	ds_read_b128 v[170:173], v149 offset:1024
	ds_read_b128 v[174:177], v149 offset:2048
	ds_read_b128 v[178:181], v149 offset:3072
	s_add_u32 s30, s30, 0xb0000
	s_addc_u32 s31, s31, 0
	s_mov_b32 m0, s47
	v_lshl_add_u64 v[224:225], s[30:31], 0, v[130:131]
	ds_read_b128 v[182:185], v148 offset:32768
	ds_read_b128 v[188:191], v148 offset:33792
	ds_read_b128 v[192:195], v148 offset:34816
	ds_read_b128 v[196:199], v148 offset:35840
	ds_read_b128 v[200:203], v148 offset:36864
	ds_read_b128 v[204:207], v148 offset:37888
	ds_read_b128 v[208:211], v148 offset:38912
	ds_read_b128 v[212:215], v148 offset:39936
	global_load_lds_dwordx4 v[224:225], off
	v_lshl_add_u64 v[224:225], s[30:31], 0, v[132:133]
	s_mov_b32 m0, s48
	s_nop 0
	global_load_lds_dwordx4 v[224:225], off
	s_waitcnt vmcnt(8)
	s_waitcnt lgkmcnt(0)
	s_barrier
	s_setprio 1
	s_waitcnt lgkmcnt(0)
	v_mfma_f32_16x16x32_bf16 v[114:117], v[150:153], v[182:185], v[114:117]
	v_mfma_f32_16x16x32_bf16 v[82:85], v[158:161], v[182:185], v[82:85]
	v_mfma_f32_16x16x32_bf16 v[122:125], v[150:153], v[192:195], v[122:125]
	v_mfma_f32_16x16x32_bf16 v[86:89], v[158:161], v[192:195], v[86:89]
	v_mfma_f32_16x16x32_bf16 v[126:129], v[150:153], v[200:203], v[126:129]
	v_mfma_f32_16x16x32_bf16 v[90:93], v[158:161], v[200:203], v[90:93]
	v_mfma_f32_16x16x32_bf16 v[118:121], v[150:153], v[208:211], v[118:121]
	v_mfma_f32_16x16x32_bf16 v[102:105], v[158:161], v[208:211], v[102:105]
	v_mfma_f32_16x16x32_bf16 v[114:117], v[154:157], v[188:191], v[114:117]
	v_mfma_f32_16x16x32_bf16 v[82:85], v[162:165], v[188:191], v[82:85]
	v_mfma_f32_16x16x32_bf16 v[122:125], v[154:157], v[196:199], v[122:125]
	v_mfma_f32_16x16x32_bf16 v[86:89], v[162:165], v[196:199], v[86:89]
	v_mfma_f32_16x16x32_bf16 v[126:129], v[154:157], v[204:207], v[126:129]
	v_mfma_f32_16x16x32_bf16 v[90:93], v[162:165], v[204:207], v[90:93]
	v_mfma_f32_16x16x32_bf16 v[118:121], v[154:157], v[212:215], v[118:121]
	v_mfma_f32_16x16x32_bf16 v[102:105], v[162:165], v[212:215], v[102:105]
	s_setprio 0
	s_setprio 1
	v_mfma_f32_16x16x32_bf16 v[26:29], v[166:169], v[182:185], v[26:29]
	v_mfma_f32_16x16x32_bf16 v[2:5], v[174:177], v[182:185], v[2:5]
	v_mfma_f32_16x16x32_bf16 v[30:33], v[166:169], v[192:195], v[30:33]
	v_mfma_f32_16x16x32_bf16 v[6:9], v[174:177], v[192:195], v[6:9]
	v_mfma_f32_16x16x32_bf16 v[42:45], v[166:169], v[200:203], v[42:45]
	v_mfma_f32_16x16x32_bf16 v[10:13], v[174:177], v[200:203], v[10:13]
	v_mfma_f32_16x16x32_bf16 v[58:61], v[166:169], v[208:211], v[58:61]
	v_mfma_f32_16x16x32_bf16 v[14:17], v[174:177], v[208:211], v[14:17]
	v_mfma_f32_16x16x32_bf16 v[26:29], v[170:173], v[188:191], v[26:29]
	v_mfma_f32_16x16x32_bf16 v[2:5], v[178:181], v[188:191], v[2:5]
	v_mfma_f32_16x16x32_bf16 v[30:33], v[170:173], v[196:199], v[30:33]
	v_mfma_f32_16x16x32_bf16 v[6:9], v[178:181], v[196:199], v[6:9]
	v_mfma_f32_16x16x32_bf16 v[42:45], v[170:173], v[204:207], v[42:45]
	v_mfma_f32_16x16x32_bf16 v[10:13], v[178:181], v[204:207], v[10:13]
	v_mfma_f32_16x16x32_bf16 v[58:61], v[170:173], v[212:215], v[58:61]
	v_mfma_f32_16x16x32_bf16 v[14:17], v[178:181], v[212:215], v[14:17]
	s_setprio 0
	s_barrier
; #define PG8_STAGE(bufoff, gbase, voff) do { _Pragma("unroll") for (int _i = 0; _i < 2; ++_i) \
;         __builtin_amdgcn_global_load_lds((const unsigned*)((const char*)(gbase) + (voff)[_i]), (PG8_LAS unsigned*)(lds + (bufoff) + ldsw + _i * 8192), 16, 0, 0); } while (0)
; #define PG8_LDA(dst, b, h) do { _Pragma("unroll") for (int m = 0; m < 4; ++m) _Pragma("unroll") for (int k = 0; k < 2; ++k) dst[m][k] = *(const PG8_LAS bf16x8*)(lds + PG8_SA(b, h) + aoff + m * 2048 + k * 1024); } while (0)
; #define PG8_MMA(ai, bj, At, Bt) do { __builtin_amdgcn_s_setprio(1); _Pragma("unroll") for (int m = 0; m < 4; ++m) _Pragma("unroll") for (int n = 0; n < 2; ++n) _Pragma("unroll") for (int k = 0; k < 2; ++k) \
;         acc[ai][bj][m][n] = __builtin_amdgcn_mfma_f32_16x16x32_bf16(Bt[n][k], At[m][k], acc[ai][bj][m][n], 0, 0, 0); __builtin_amdgcn_s_setprio(0); } while (0)
; #define PG8_WAIT_V(n) asm volatile("s_waitcnt vmcnt(" #n ")" ::: "memory")
; #define PG8_WAIT_L(n) asm volatile("s_waitcnt lgkmcnt(" #n ")" ::: "memory")
; #define PG8_BAR __builtin_amdgcn_s_barrier()
; #define PG8_SCHED __builtin_amdgcn_sched_barrier(0)
; template <class Epi, class Sched, bool ALIGN_EPI = false, bool SP2 = false>
; __device__ __forceinline__ void gemm_phase(PG8_LAS unsigned char* lds, const Gemm g, const Sched& S, const Epi& E) {
;     ...
;             PG8_LDA(At, 1, 1); PG8_STAGE(PG8_SB(1, 0), b3, voffB); PG8_STAGE(PG8_SB(1, 1), b3 + hstep, voffB); PG8_STAGE(PG8_SA(1, 0), a3, voffA);
;             PG8_WAIT_V(8); PG8_WAIT_L(0); PG8_BAR; PG8_MMA(1, 0, At, B0); PG8_MMA(1, 1, At, B1); PG8_BAR; PG8_SCHED;
;     ...
; #pragma unroll
;         for (int a = 0; a < 2; ++a)
; #pragma unroll
;             for (int b = 0; b < 2; ++b)
; #pragma unroll
;                 for (int m = 0; m < 4; ++m)
; #pragma unroll
;                     for (int n = 0; n < 2; ++n) acc[a][b][m][n] = (f32x4){0.f, 0.f, 0.f, 0.f};
;         cur = nxt; cA = nA; cB = nB; ++ui;
	s_add_i32 s30, s60, s41
	v_lshl_add_u64 v[216:217], v[216:217], 0, s[22:23]
	s_mov_b32 m0, s30
	ds_read_b128 v[182:185], v148 offset:49152
	ds_read_b128 v[188:191], v148 offset:50176
	ds_read_b128 v[192:195], v148 offset:51200
	ds_read_b128 v[196:199], v148 offset:52224
	ds_read_b128 v[200:203], v148 offset:53248
	ds_read_b128 v[204:207], v148 offset:54272
	ds_read_b128 v[208:211], v148 offset:55296
	ds_read_b128 v[212:215], v148 offset:56320
	global_load_lds_dwordx4 v[216:217], off
	s_add_i32 m0, s30, 0x2000
	s_add_u32 s28, s28, 0xb0080
	v_lshl_add_u64 v[216:217], v[218:219], 0, s[22:23]
	s_addc_u32 s29, s29, 0
	s_add_i32 s30, s61, s41
	global_load_lds_dwordx4 v[216:217], off
	v_lshl_add_u64 v[216:217], s[28:29], 0, v[130:131]
	s_mov_b32 m0, s30
	s_nop 0
	global_load_lds_dwordx4 v[216:217], off
	v_lshl_add_u64 v[216:217], s[28:29], 0, v[132:133]
	s_add_i32 m0, s30, 0x2000
	s_nop 0
	global_load_lds_dwordx4 v[216:217], off
	v_lshl_add_u64 v[216:217], v[220:221], 0, s[22:23]
	s_mov_b32 m0, s51
	s_nop 0
	global_load_lds_dwordx4 v[216:217], off
	v_lshl_add_u64 v[216:217], v[222:223], 0, s[22:23]
	s_mov_b32 m0, s52
	s_nop 0
	global_load_lds_dwordx4 v[216:217], off
	s_waitcnt vmcnt(8)
	s_waitcnt lgkmcnt(0)
	s_barrier
	s_setprio 1
	s_waitcnt lgkmcnt(0)
	v_mfma_f32_16x16x32_bf16 v[110:113], v[150:153], v[182:185], v[110:113]
	v_mfma_f32_16x16x32_bf16 v[106:109], v[158:161], v[182:185], v[106:109]
	v_mfma_f32_16x16x32_bf16 v[98:101], v[150:153], v[192:195], v[98:101]
	v_mfma_f32_16x16x32_bf16 v[94:97], v[158:161], v[192:195], v[94:97]
	v_mfma_f32_16x16x32_bf16 v[74:77], v[150:153], v[200:203], v[74:77]
	v_mfma_f32_16x16x32_bf16 v[70:73], v[158:161], v[200:203], v[70:73]
	v_mfma_f32_16x16x32_bf16 v[54:57], v[150:153], v[208:211], v[54:57]
	v_mfma_f32_16x16x32_bf16 v[50:53], v[158:161], v[208:211], v[50:53]
	v_mfma_f32_16x16x32_bf16 v[110:113], v[154:157], v[188:191], v[110:113]
	v_mfma_f32_16x16x32_bf16 v[106:109], v[162:165], v[188:191], v[106:109]
	v_mfma_f32_16x16x32_bf16 v[98:101], v[154:157], v[196:199], v[98:101]
	v_mfma_f32_16x16x32_bf16 v[94:97], v[162:165], v[196:199], v[94:97]
	v_mfma_f32_16x16x32_bf16 v[74:77], v[154:157], v[204:207], v[74:77]
	v_mfma_f32_16x16x32_bf16 v[70:73], v[162:165], v[204:207], v[70:73]
	v_mfma_f32_16x16x32_bf16 v[54:57], v[154:157], v[212:215], v[54:57]
	v_mfma_f32_16x16x32_bf16 v[50:53], v[162:165], v[212:215], v[50:53]
	s_setprio 0
	s_setprio 1
	v_mfma_f32_16x16x32_bf16 v[66:69], v[166:169], v[182:185], v[66:69]
	v_mfma_f32_16x16x32_bf16 v[18:21], v[174:177], v[182:185], v[18:21]
	v_mfma_f32_16x16x32_bf16 v[78:81], v[166:169], v[192:195], v[78:81]
	v_mfma_f32_16x16x32_bf16 v[22:25], v[174:177], v[192:195], v[22:25]
	v_mfma_f32_16x16x32_bf16 v[62:65], v[166:169], v[200:203], v[62:65]
	v_mfma_f32_16x16x32_bf16 v[46:49], v[174:177], v[200:203], v[46:49]
	v_mfma_f32_16x16x32_bf16 v[38:41], v[166:169], v[208:211], v[38:41]
	v_mfma_f32_16x16x32_bf16 v[34:37], v[174:177], v[208:211], v[34:37]
	v_mfma_f32_16x16x32_bf16 v[66:69], v[170:173], v[188:191], v[66:69]
	v_mfma_f32_16x16x32_bf16 v[18:21], v[178:181], v[188:191], v[18:21]
	v_mfma_f32_16x16x32_bf16 v[78:81], v[170:173], v[196:199], v[78:81]
	v_mfma_f32_16x16x32_bf16 v[22:25], v[178:181], v[196:199], v[22:25]
	v_mfma_f32_16x16x32_bf16 v[62:65], v[170:173], v[204:207], v[62:65]
	v_mfma_f32_16x16x32_bf16 v[46:49], v[178:181], v[204:207], v[46:49]
	v_mfma_f32_16x16x32_bf16 v[38:41], v[170:173], v[212:215], v[38:41]
	v_mfma_f32_16x16x32_bf16 v[34:37], v[178:181], v[212:215], v[34:37]
	s_setprio 0
	s_add_i32 s59, s59, 2
	s_add_u32 s26, s26, 0x100
	s_addc_u32 s27, s27, 0
	s_cmp_gt_u32 s59, 41
	s_barrier
	s_cbranch_scc0 .LBB0_1940
	s_add_u32 s0, s0, 0xffffff00
	s_addc_u32 s1, s1, -1
	s_and_b64 vcc, exec, s[6:7]
	s_cbranch_vccnz .LBB0_1943
	v_mov_b32_e32 v34, 0
	s_mov_b32 s18, s56
	s_mov_b32 s35, s57
	s_mov_b64 s[20:21], s[24:25]
	s_mov_b32 s50, s58
	v_mov_b32_e32 v35, v34
	v_mov_b32_e32 v36, v34
	v_mov_b32_e32 v37, v34
	v_mov_b32_e32 v38, v34
	v_mov_b32_e32 v39, v34
	v_mov_b32_e32 v40, v34
	v_mov_b32_e32 v41, v34
	v_mov_b32_e32 v46, v34
	v_mov_b32_e32 v47, v34
	v_mov_b32_e32 v48, v34
	v_mov_b32_e32 v49, v34
	v_mov_b32_e32 v62, v34
	v_mov_b32_e32 v63, v34
	v_mov_b32_e32 v64, v34
	v_mov_b32_e32 v65, v34
	v_mov_b32_e32 v22, v34
	v_mov_b32_e32 v23, v34
	v_mov_b32_e32 v24, v34
	v_mov_b32_e32 v25, v34
	v_mov_b32_e32 v78, v34
	v_mov_b32_e32 v79, v34
	v_mov_b32_e32 v80, v34
	v_mov_b32_e32 v81, v34
	v_mov_b32_e32 v18, v34
	v_mov_b32_e32 v19, v34
	v_mov_b32_e32 v20, v34
	v_mov_b32_e32 v21, v34
	v_mov_b32_e32 v66, v34
	v_mov_b32_e32 v67, v34
	v_mov_b32_e32 v68, v34
	v_mov_b32_e32 v69, v34
	v_mov_b32_e32 v50, v34
	v_mov_b32_e32 v51, v34
	v_mov_b32_e32 v52, v34
	v_mov_b32_e32 v53, v34
	v_mov_b32_e32 v54, v34
	v_mov_b32_e32 v55, v34
	v_mov_b32_e32 v56, v34
	v_mov_b32_e32 v57, v34
	v_mov_b32_e32 v70, v34
	v_mov_b32_e32 v71, v34
	v_mov_b32_e32 v72, v34
	v_mov_b32_e32 v73, v34
	v_mov_b32_e32 v74, v34
	v_mov_b32_e32 v75, v34
	v_mov_b32_e32 v76, v34
	v_mov_b32_e32 v77, v34
	v_mov_b32_e32 v94, v34
	v_mov_b32_e32 v95, v34
	v_mov_b32_e32 v96, v34
	v_mov_b32_e32 v97, v34
	v_mov_b32_e32 v98, v34
	v_mov_b32_e32 v99, v34
	v_mov_b32_e32 v100, v34
	v_mov_b32_e32 v101, v34
	v_mov_b32_e32 v106, v34
	v_mov_b32_e32 v107, v34
	v_mov_b32_e32 v108, v34
	v_mov_b32_e32 v109, v34
	v_mov_b32_e32 v110, v34
	v_mov_b32_e32 v111, v34
	v_mov_b32_e32 v112, v34
	v_mov_b32_e32 v113, v34
	v_mov_b32_e32 v14, v34
	v_mov_b32_e32 v15, v34
	v_mov_b32_e32 v16, v34
	v_mov_b32_e32 v17, v34
	v_mov_b32_e32 v58, v34
	v_mov_b32_e32 v59, v34
	v_mov_b32_e32 v60, v34
	v_mov_b32_e32 v61, v34
	v_mov_b32_e32 v10, v34
	v_mov_b32_e32 v11, v34
	v_mov_b32_e32 v12, v34
	v_mov_b32_e32 v13, v34
	v_mov_b32_e32 v42, v34
	v_mov_b32_e32 v43, v34
	v_mov_b32_e32 v44, v34
	v_mov_b32_e32 v45, v34
	v_mov_b32_e32 v6, v34
	v_mov_b32_e32 v7, v34
	v_mov_b32_e32 v8, v34
	v_mov_b32_e32 v9, v34
	v_mov_b32_e32 v30, v34
	v_mov_b32_e32 v31, v34
	v_mov_b32_e32 v32, v34
	v_mov_b32_e32 v33, v34
	v_mov_b32_e32 v2, v34
	v_mov_b32_e32 v3, v34
	v_mov_b32_e32 v4, v34
	v_mov_b32_e32 v5, v34
	v_mov_b32_e32 v26, v34
	v_mov_b32_e32 v27, v34
	v_mov_b32_e32 v28, v34
	v_mov_b32_e32 v29, v34
	v_mov_b32_e32 v102, v34
	v_mov_b32_e32 v103, v34
	v_mov_b32_e32 v104, v34
	v_mov_b32_e32 v105, v34
	v_mov_b32_e32 v118, v34
	v_mov_b32_e32 v119, v34
	v_mov_b32_e32 v120, v34
	v_mov_b32_e32 v121, v34
	v_mov_b32_e32 v90, v34
	v_mov_b32_e32 v91, v34
	v_mov_b32_e32 v92, v34
	v_mov_b32_e32 v93, v34
	v_mov_b32_e32 v126, v34
	v_mov_b32_e32 v127, v34
	v_mov_b32_e32 v128, v34
	v_mov_b32_e32 v129, v34
	v_mov_b32_e32 v86, v34
	v_mov_b32_e32 v87, v34
	v_mov_b32_e32 v88, v34
	v_mov_b32_e32 v89, v34
	v_mov_b32_e32 v122, v34
	v_mov_b32_e32 v123, v34
	v_mov_b32_e32 v124, v34
	v_mov_b32_e32 v125, v34
	v_mov_b32_e32 v82, v34
	v_mov_b32_e32 v83, v34
	v_mov_b32_e32 v84, v34
	v_mov_b32_e32 v85, v34
	v_mov_b32_e32 v114, v34
	v_mov_b32_e32 v115, v34
	v_mov_b32_e32 v116, v34
	v_mov_b32_e32 v117, v34
	s_andn2_b64 vcc, exec, s[4:5]
	s_cbranch_vccnz .LBB0_1944
	s_branch .LBB0_1945
